# batched serialized load chains in mixer/conv/attprep code + ds_bpermute xor-shuffles replaced by exact DPP/permlane-swap lane permutations (bitwise same math)
# speedup vs baseline: 1.0547x; 1.0547x over previous
.LBB0_191:
	v_mov_b32_e32 v78, 0
	v_mov_b32_e32 v79, 0
	v_mov_b32_e32 v80, 0
	v_mov_b32_e32 v81, 0
	v_mov_b32_e32 v82, 0
	v_mov_b32_e32 v83, 0
	v_mov_b32_e32 v84, 0
	v_mov_b32_e32 v85, 0
	v_mov_b32_e32 v86, 0
	v_mov_b32_e32 v87, 0
	v_mov_b32_e32 v88, 0
	v_mov_b32_e32 v89, 0
	v_mov_b32_e32 v90, 0
	v_mov_b32_e32 v91, 0
	v_mov_b32_e32 v92, 0
	v_mov_b32_e32 v93, 0
	s_and_saveexec_b64 s[40:41], vcc
	s_cbranch_execz .Lwc_skip
	v_mul_lo_u32 v94, s12, v2
	v_mov_b32_e32 v95, 0
	v_lshlrev_b64 v[94:95], 2, v[94:95]
	v_lshl_add_u64 v[94:95], v[94:95], 0, v[0:1]
	s_mov_b32 s101, 0
	s_mul_i32 s100, s12, 0
	v_lshl_add_u64 v[102:103], s[100:101], 0, v[94:95]
	global_load_dword v78, v[102:103], off
	s_mul_i32 s100, s12, 4
	v_lshl_add_u64 v[102:103], s[100:101], 0, v[94:95]
	global_load_dword v79, v[102:103], off
	s_mul_i32 s100, s12, 32
	v_lshl_add_u64 v[102:103], s[100:101], 0, v[94:95]
	global_load_dword v80, v[102:103], off
	s_mul_i32 s100, s12, 36
	v_lshl_add_u64 v[102:103], s[100:101], 0, v[94:95]
	global_load_dword v81, v[102:103], off
	s_mul_i32 s100, s12, 64
	v_lshl_add_u64 v[102:103], s[100:101], 0, v[94:95]
	global_load_dword v82, v[102:103], off
	s_mul_i32 s100, s12, 68
	v_lshl_add_u64 v[102:103], s[100:101], 0, v[94:95]
	global_load_dword v83, v[102:103], off
	s_mul_i32 s100, s12, 96
	v_lshl_add_u64 v[102:103], s[100:101], 0, v[94:95]
	global_load_dword v84, v[102:103], off
	s_mul_i32 s100, s12, 100
	v_lshl_add_u64 v[102:103], s[100:101], 0, v[94:95]
	global_load_dword v85, v[102:103], off
	s_mul_i32 s100, s12, 128
	v_lshl_add_u64 v[102:103], s[100:101], 0, v[94:95]
	global_load_dword v86, v[102:103], off
	s_mul_i32 s100, s12, 132
	v_lshl_add_u64 v[102:103], s[100:101], 0, v[94:95]
	global_load_dword v87, v[102:103], off
	s_mul_i32 s100, s12, 160
	v_lshl_add_u64 v[102:103], s[100:101], 0, v[94:95]
	global_load_dword v88, v[102:103], off
	s_mul_i32 s100, s12, 164
	v_lshl_add_u64 v[102:103], s[100:101], 0, v[94:95]
	global_load_dword v89, v[102:103], off
	s_mul_i32 s100, s12, 192
	v_lshl_add_u64 v[102:103], s[100:101], 0, v[94:95]
	global_load_dword v90, v[102:103], off
	s_mul_i32 s100, s12, 196
	v_lshl_add_u64 v[102:103], s[100:101], 0, v[94:95]
	global_load_dword v91, v[102:103], off
	s_mul_i32 s100, s12, 224
	v_lshl_add_u64 v[102:103], s[100:101], 0, v[94:95]
	global_load_dword v92, v[102:103], off
	s_mul_i32 s100, s12, 228
	v_lshl_add_u64 v[102:103], s[100:101], 0, v[94:95]
	global_load_dword v93, v[102:103], off
.Lwc_skip:
	s_or_b64 exec, exec, s[40:41]
	s_waitcnt vmcnt(0)
	v_cvt_pk_bf16_f32 v104, v78, v79
	ds_write_b32 v3, v104
	v_cvt_pk_bf16_f32 v104, v80, v81
	ds_write_b32 v3, v104 offset:16
	v_cvt_pk_bf16_f32 v104, v82, v83
	ds_write_b32 v3, v104 offset:32
	v_cvt_pk_bf16_f32 v104, v84, v85
	ds_write_b32 v3, v104 offset:48
	v_cvt_pk_bf16_f32 v104, v86, v87
	ds_write_b32 v3, v104 offset:64
	v_cvt_pk_bf16_f32 v104, v88, v89
	ds_write_b32 v3, v104 offset:80
	v_cvt_pk_bf16_f32 v104, v90, v91
	ds_write_b32 v3, v104 offset:96
	v_cvt_pk_bf16_f32 v104, v92, v93
	ds_write_b32 v3, v104 offset:112
	s_branch .LBB0_154

.LBB0_263:
	s_nop 2
	v_mul_f32_e32 v133, 0xbfb8aa3b, v32
	v_exp_f32_e32 v133, v133
	v_mbcnt_hi_u32_b32 v96, -1, v195
	v_and_b32_e32 v99, 64, v96
	v_xor_b32_e32 v98, 32, v96
	v_add_f32_e32 v133, 1.0, v133
	v_rcp_f32_e32 v138, v133
	v_mul_f32_e32 v133, 0xbfb8aa3b, v33
	v_exp_f32_e32 v133, v133
	v_add_u32_e32 v99, 64, v99
	v_cmp_lt_i32_e32 vcc, v98, v99
	s_sext_i32_i16 s2, s2
	v_add_f32_e32 v133, 1.0, v133
	v_rcp_f32_e32 v139, v133
	v_cndmask_b32_e32 v96, v96, v98, vcc
	v_lshlrev_b32_e32 v96, 2, v96
	v_lshl_or_b32 v134, s2, 6, v174
	v_pk_mul_f32 v[32:33], v[32:33], v[138:139]
	v_lshl_add_u32 v132, s6, 7, v169
	v_pk_mul_f32 v[32:33], v[48:49], v[32:33]
	v_mul_f32_e32 v48, 0xbfb8aa3b, v34
	v_mul_f32_e32 v49, 0xbfb8aa3b, v35
	v_exp_f32_e32 v48, v48
	v_exp_f32_e32 v49, v49
	v_mov_b64_e32 v[98:99], s[56:57]
	v_ashrrev_i32_e32 v135, 31, v134
	v_add_f32_e32 v48, 1.0, v48
	v_add_f32_e32 v49, 1.0, v49
	v_rcp_f32_e32 v48, v48
	v_rcp_f32_e32 v49, v49
	v_mad_i64_i32 v[136:137], s[6:7], v132, s18, v[98:99]
	s_waitcnt lgkmcnt(0)
	v_pk_mul_f32 v[34:35], v[34:35], v[48:49]
	v_cvt_pk_bf16_f32 v48, v32, v33
	v_pk_mul_f32 v[34:35], v[50:51], v[34:35]
	v_mul_f32_e32 v32, 0xbfb8aa3b, v36
	v_cvt_pk_bf16_f32 v49, v34, v35
	v_mul_f32_e32 v33, 0xbfb8aa3b, v37
	v_mul_f32_e32 v34, 0xbfb8aa3b, v38
	v_mul_f32_e32 v35, 0xbfb8aa3b, v39
	v_exp_f32_e32 v32, v32
	v_exp_f32_e32 v33, v33
	v_exp_f32_e32 v34, v34
	v_exp_f32_e32 v35, v35
	v_add_f32_e32 v32, 1.0, v32
	v_add_f32_e32 v33, 1.0, v33
	v_add_f32_e32 v34, 1.0, v34
	v_add_f32_e32 v35, 1.0, v35
	v_rcp_f32_e32 v32, v32
	v_rcp_f32_e32 v33, v33
	v_rcp_f32_e32 v34, v34
	v_rcp_f32_e32 v35, v35
	s_barrier
	v_pk_mul_f32 v[32:33], v[36:37], v[32:33]
	v_pk_mul_f32 v[34:35], v[38:39], v[34:35]
	v_pk_mul_f32 v[32:33], v[52:53], v[32:33]
	v_pk_mul_f32 v[34:35], v[54:55], v[34:35]
	v_cvt_pk_bf16_f32 v32, v32, v33
	v_cvt_pk_bf16_f32 v33, v34, v35
	v_cndmask_b32_e64 v34, v48, v32, s[38:39]
	v_cndmask_b32_e64 v35, v49, v33, s[38:39]
	v_mov_b32_e32 v255, v34
	s_nop 1
	v_permlane32_swap_b32_e32 v34, v255
	s_nop 1
	v_mov_b32_dpp v34, v255 quad_perm:[0,1,2,3] row_mask:0x3 bank_mask:0xf
	v_mov_b32_e32 v255, v35
	s_nop 1
	v_permlane32_swap_b32_e32 v35, v255
	s_nop 1
	v_mov_b32_dpp v35, v255 quad_perm:[0,1,2,3] row_mask:0x3 bank_mask:0xf
	s_mov_b64 s[44:45], 0
	s_andn2_b64 vcc, exec, s[0:1]
	s_mov_b32 s2, s3
	s_nop 0
	v_cndmask_b32_e64 v38, v32, v34, s[38:39]
	s_nop 0
	v_cndmask_b32_e64 v39, v33, v35, s[38:39]
	v_lshlrev_b64 v[32:33], 1, v[134:135]
	v_cndmask_b32_e64 v37, v35, v49, s[38:39]
	v_cndmask_b32_e64 v36, v34, v48, s[38:39]
	v_lshl_add_u64 v[34:35], v[136:137], 0, v[32:33]
	global_store_dwordx4 v[34:35], v[36:39], off
	s_nop 1
	v_mul_f32_e32 v36, 0xbfb8aa3b, v40
	v_mul_f32_e32 v37, 0xbfb8aa3b, v41
	v_mul_f32_e32 v38, 0xbfb8aa3b, v42
	v_mul_f32_e32 v39, 0xbfb8aa3b, v43
	v_exp_f32_e32 v36, v36
	v_exp_f32_e32 v37, v37
	v_exp_f32_e32 v38, v38
	v_exp_f32_e32 v39, v39
	v_add_f32_e32 v36, 1.0, v36
	v_add_f32_e32 v37, 1.0, v37
	v_add_f32_e32 v38, 1.0, v38
	v_add_f32_e32 v39, 1.0, v39
	v_rcp_f32_e32 v36, v36
	v_rcp_f32_e32 v37, v37
	v_rcp_f32_e32 v38, v38
	v_rcp_f32_e32 v39, v39
	v_pk_mul_f32 v[36:37], v[40:41], v[36:37]
	s_nop 0
	v_pk_mul_f32 v[36:37], v[56:57], v[36:37]
	v_pk_mul_f32 v[38:39], v[42:43], v[38:39]
	v_cvt_pk_bf16_f32 v40, v36, v37
	v_pk_mul_f32 v[38:39], v[58:59], v[38:39]
	v_mul_f32_e32 v36, 0xbfb8aa3b, v44
	v_cvt_pk_bf16_f32 v41, v38, v39
	v_mul_f32_e32 v37, 0xbfb8aa3b, v45
	v_mul_f32_e32 v38, 0xbfb8aa3b, v46
	v_mul_f32_e32 v39, 0xbfb8aa3b, v47
	v_exp_f32_e32 v36, v36
	v_exp_f32_e32 v37, v37
	v_exp_f32_e32 v38, v38
	v_exp_f32_e32 v39, v39
	v_add_f32_e32 v36, 1.0, v36
	v_add_f32_e32 v37, 1.0, v37
	v_add_f32_e32 v38, 1.0, v38
	v_add_f32_e32 v39, 1.0, v39
	v_rcp_f32_e32 v36, v36
	v_rcp_f32_e32 v37, v37
	v_rcp_f32_e32 v38, v38
	v_rcp_f32_e32 v39, v39
	v_pk_mul_f32 v[36:37], v[44:45], v[36:37]
	s_nop 0
	v_pk_mul_f32 v[36:37], v[60:61], v[36:37]
	v_pk_mul_f32 v[38:39], v[46:47], v[38:39]
	v_cvt_pk_bf16_f32 v36, v36, v37
	v_pk_mul_f32 v[38:39], v[62:63], v[38:39]
	s_nop 0
	v_cvt_pk_bf16_f32 v37, v38, v39
	v_cndmask_b32_e64 v38, v40, v36, s[38:39]
	v_cndmask_b32_e64 v39, v41, v37, s[38:39]
	v_mov_b32_e32 v42, v38
	v_mov_b32_e32 v255, v38
	s_nop 1
	v_permlane32_swap_b32_e32 v42, v255
	s_nop 1
	v_mov_b32_dpp v42, v255 quad_perm:[0,1,2,3] row_mask:0x3 bank_mask:0xf
	v_mov_b32_e32 v43, v39
	v_mov_b32_e32 v255, v39
	s_nop 1
	v_permlane32_swap_b32_e32 v43, v255
	s_nop 1
	v_mov_b32_dpp v43, v255 quad_perm:[0,1,2,3] row_mask:0x3 bank_mask:0xf
	s_nop 0
	v_cndmask_b32_e64 v38, v36, v42, s[38:39]
	s_nop 0
	v_cndmask_b32_e64 v39, v37, v43, s[38:39]
	v_cndmask_b32_e64 v37, v43, v41, s[38:39]
	v_cndmask_b32_e64 v36, v42, v40, s[38:39]
	global_store_dwordx4 v[34:35], v[36:39], off offset:32
	v_or_b32_e32 v34, 32, v132
	v_mad_i64_i32 v[34:35], s[6:7], v34, s18, v[98:99]
	v_mul_f32_e32 v36, 0xbfb8aa3b, v0
	v_mul_f32_e32 v37, 0xbfb8aa3b, v1
	v_exp_f32_e32 v36, v36
	v_exp_f32_e32 v37, v37
	v_add_f32_e32 v36, 1.0, v36
	v_add_f32_e32 v37, 1.0, v37
	v_rcp_f32_e32 v36, v36
	v_rcp_f32_e32 v37, v37
	s_nop 0
	v_pk_mul_f32 v[0:1], v[0:1], v[36:37]
	s_nop 0
	v_pk_mul_f32 v[0:1], v[16:17], v[0:1]
	v_mul_f32_e32 v16, 0xbfb8aa3b, v2
	v_mul_f32_e32 v17, 0xbfb8aa3b, v3
	v_exp_f32_e32 v16, v16
	v_exp_f32_e32 v17, v17
	v_add_f32_e32 v16, 1.0, v16
	v_add_f32_e32 v17, 1.0, v17
	v_rcp_f32_e32 v16, v16
	v_rcp_f32_e32 v17, v17
	s_nop 0
	v_pk_mul_f32 v[2:3], v[2:3], v[16:17]
	s_nop 0
	v_pk_mul_f32 v[2:3], v[18:19], v[2:3]
	v_cvt_pk_bf16_f32 v16, v0, v1
	v_cvt_pk_bf16_f32 v17, v2, v3
	v_mul_f32_e32 v0, 0xbfb8aa3b, v4
	v_mul_f32_e32 v1, 0xbfb8aa3b, v5
	v_mul_f32_e32 v2, 0xbfb8aa3b, v6
	v_mul_f32_e32 v3, 0xbfb8aa3b, v7
	v_exp_f32_e32 v0, v0
	v_exp_f32_e32 v1, v1
	v_exp_f32_e32 v2, v2
	v_exp_f32_e32 v3, v3
	v_add_f32_e32 v0, 1.0, v0
	v_add_f32_e32 v1, 1.0, v1
	v_add_f32_e32 v2, 1.0, v2
	v_add_f32_e32 v3, 1.0, v3
	v_rcp_f32_e32 v0, v0
	v_rcp_f32_e32 v1, v1
	v_rcp_f32_e32 v2, v2
	v_rcp_f32_e32 v3, v3
	v_pk_mul_f32 v[0:1], v[4:5], v[0:1]
	s_nop 0
	v_pk_mul_f32 v[0:1], v[20:21], v[0:1]
	v_pk_mul_f32 v[2:3], v[6:7], v[2:3]
	v_cvt_pk_bf16_f32 v0, v0, v1
	v_pk_mul_f32 v[2:3], v[22:23], v[2:3]
	s_nop 0
	v_cvt_pk_bf16_f32 v1, v2, v3
	v_cndmask_b32_e64 v2, v16, v0, s[38:39]
	v_cndmask_b32_e64 v3, v17, v1, s[38:39]
	v_mov_b32_e32 v255, v2
	s_nop 1
	v_permlane32_swap_b32_e32 v2, v255
	s_nop 1
	v_mov_b32_dpp v2, v255 quad_perm:[0,1,2,3] row_mask:0x3 bank_mask:0xf
	v_mov_b32_e32 v255, v3
	s_nop 1
	v_permlane32_swap_b32_e32 v3, v255
	s_nop 1
	v_mov_b32_dpp v3, v255 quad_perm:[0,1,2,3] row_mask:0x3 bank_mask:0xf
	s_nop 0
	v_cndmask_b32_e64 v4, v0, v2, s[38:39]
	s_nop 0
	v_cndmask_b32_e64 v5, v1, v3, s[38:39]
	v_cndmask_b32_e64 v3, v3, v17, s[38:39]
	v_cndmask_b32_e64 v2, v2, v16, s[38:39]
	v_lshl_add_u64 v[0:1], v[34:35], 0, v[32:33]
	global_store_dwordx4 v[0:1], v[2:5], off
	s_nop 1
	v_mul_f32_e32 v2, 0xbfb8aa3b, v8
	v_mul_f32_e32 v3, 0xbfb8aa3b, v9
	v_mul_f32_e32 v4, 0xbfb8aa3b, v10
	v_mul_f32_e32 v5, 0xbfb8aa3b, v11
	v_exp_f32_e32 v2, v2
	v_exp_f32_e32 v3, v3
	v_exp_f32_e32 v4, v4
	v_exp_f32_e32 v5, v5
	v_add_f32_e32 v2, 1.0, v2
	v_add_f32_e32 v3, 1.0, v3
	v_add_f32_e32 v4, 1.0, v4
	v_add_f32_e32 v5, 1.0, v5
	v_rcp_f32_e32 v2, v2
	v_rcp_f32_e32 v3, v3
	v_rcp_f32_e32 v4, v4
	v_rcp_f32_e32 v5, v5
	v_pk_mul_f32 v[2:3], v[8:9], v[2:3]
	s_nop 0
	v_pk_mul_f32 v[2:3], v[24:25], v[2:3]
	v_pk_mul_f32 v[4:5], v[10:11], v[4:5]
	v_cvt_pk_bf16_f32 v6, v2, v3
	v_pk_mul_f32 v[4:5], v[26:27], v[4:5]
	v_mul_f32_e32 v2, 0xbfb8aa3b, v12
	v_cvt_pk_bf16_f32 v7, v4, v5
	v_mul_f32_e32 v3, 0xbfb8aa3b, v13
	v_mul_f32_e32 v4, 0xbfb8aa3b, v14
	v_mul_f32_e32 v5, 0xbfb8aa3b, v15
	v_exp_f32_e32 v2, v2
	v_exp_f32_e32 v3, v3
	v_exp_f32_e32 v4, v4
	v_exp_f32_e32 v5, v5
	v_add_f32_e32 v2, 1.0, v2
	v_add_f32_e32 v3, 1.0, v3
	v_add_f32_e32 v4, 1.0, v4
	v_add_f32_e32 v5, 1.0, v5
	v_rcp_f32_e32 v2, v2
	v_rcp_f32_e32 v3, v3
	v_rcp_f32_e32 v4, v4
	v_rcp_f32_e32 v5, v5
	v_pk_mul_f32 v[2:3], v[12:13], v[2:3]
	s_nop 0
	v_pk_mul_f32 v[2:3], v[28:29], v[2:3]
	v_pk_mul_f32 v[4:5], v[14:15], v[4:5]
	v_cvt_pk_bf16_f32 v2, v2, v3
	v_pk_mul_f32 v[4:5], v[30:31], v[4:5]
	s_nop 0
	v_cvt_pk_bf16_f32 v3, v4, v5
	v_cndmask_b32_e64 v4, v6, v2, s[38:39]
	v_cndmask_b32_e64 v5, v7, v3, s[38:39]
	v_mov_b32_e32 v8, v4
	v_mov_b32_e32 v255, v4
	s_nop 1
	v_permlane32_swap_b32_e32 v8, v255
	s_nop 1
	v_mov_b32_dpp v8, v255 quad_perm:[0,1,2,3] row_mask:0x3 bank_mask:0xf
	v_mov_b32_e32 v9, v5
	v_mov_b32_e32 v255, v5
	s_nop 1
	v_permlane32_swap_b32_e32 v9, v255
	s_nop 1
	v_mov_b32_dpp v9, v255 quad_perm:[0,1,2,3] row_mask:0x3 bank_mask:0xf
	s_nop 0
	v_cndmask_b32_e64 v4, v2, v8, s[38:39]
	s_nop 0
	v_cndmask_b32_e64 v5, v3, v9, s[38:39]
	v_cndmask_b32_e64 v3, v9, v7, s[38:39]
	v_cndmask_b32_e64 v2, v8, v6, s[38:39]
	global_store_dwordx4 v[0:1], v[2:5], off offset:32
	s_cbranch_vccz .LBB0_274

.LBB0_483:
	v_mbcnt_hi_u32_b32 v98, -1, v195
	v_and_b32_e32 v132, 64, v98
	v_xor_b32_e32 v99, 32, v98
	v_add_u32_e32 v132, 64, v132
	v_cmp_lt_i32_e32 vcc, v99, v132
	v_cvt_pk_bf16_f32 v48, v48, v49
	v_cvt_pk_bf16_f32 v49, v50, v51
	v_cndmask_b32_e32 v98, v98, v99, vcc
	v_cvt_pk_bf16_f32 v51, v54, v55
	v_cvt_pk_bf16_f32 v32, v32, v33
	v_cvt_pk_bf16_f32 v33, v34, v35
	v_cvt_pk_bf16_f32 v34, v36, v37
	v_lshlrev_b32_e32 v132, 2, v98
	v_cvt_pk_bf16_f32 v50, v52, v53
	v_cndmask_b32_e64 v53, v49, v51, s[38:39]
	v_cndmask_b32_e64 v36, v32, v34, s[38:39]
	v_mov_b32_e32 v133, v53
	v_mov_b32_e32 v255, v53
	s_nop 1
	v_permlane32_swap_b32_e32 v133, v255
	s_nop 1
	v_mov_b32_dpp v133, v255 quad_perm:[0,1,2,3] row_mask:0x3 bank_mask:0xf
	v_cvt_pk_bf16_f32 v35, v38, v39
	v_mov_b32_e32 v38, v36
	v_mov_b32_e32 v255, v36
	s_nop 1
	v_permlane32_swap_b32_e32 v38, v255
	s_nop 1
	v_mov_b32_dpp v38, v255 quad_perm:[0,1,2,3] row_mask:0x3 bank_mask:0xf
	v_cndmask_b32_e64 v52, v48, v50, s[38:39]
	v_mov_b32_e32 v99, v52
	v_mov_b32_e32 v255, v52
	s_nop 1
	v_permlane32_swap_b32_e32 v99, v255
	s_nop 1
	v_mov_b32_dpp v99, v255 quad_perm:[0,1,2,3] row_mask:0x3 bank_mask:0xf
	v_cvt_pk_bf16_f32 v16, v16, v17
	v_cvt_pk_bf16_f32 v17, v18, v19
	v_cvt_pk_bf16_f32 v18, v20, v21
	v_cvt_pk_bf16_f32 v19, v22, v23
	v_cvt_pk_bf16_f32 v0, v0, v1
	v_cvt_pk_bf16_f32 v1, v2, v3
	v_cvt_pk_bf16_f32 v2, v4, v5
	v_cvt_pk_bf16_f32 v3, v6, v7
	s_waitcnt lgkmcnt(0)
	v_cndmask_b32_e64 v49, v133, v49, s[38:39]
	v_cndmask_b32_e64 v51, v51, v133, s[38:39]
	v_cvt_pk_bf16_f32 v133, v56, v57
	v_cvt_pk_bf16_f32 v58, v58, v59
	v_cvt_pk_bf16_f32 v59, v60, v61
	v_cvt_pk_bf16_f32 v60, v62, v63
	v_cndmask_b32_e64 v37, v33, v35, s[38:39]
	s_nop 0
	v_cndmask_b32_e64 v32, v38, v32, s[38:39]
	v_cndmask_b32_e64 v34, v34, v38, s[38:39]
	v_cvt_pk_bf16_f32 v38, v40, v41
	v_cvt_pk_bf16_f32 v40, v42, v43
	v_cvt_pk_bf16_f32 v41, v44, v45
	v_cvt_pk_bf16_f32 v42, v46, v47
	v_cndmask_b32_e64 v20, v16, v18, s[38:39]
	v_cndmask_b32_e64 v21, v17, v19, s[38:39]
	v_cvt_pk_bf16_f32 v22, v24, v25
	v_cvt_pk_bf16_f32 v23, v26, v27
	v_cvt_pk_bf16_f32 v24, v28, v29
	v_cvt_pk_bf16_f32 v25, v30, v31
	v_cndmask_b32_e64 v4, v0, v2, s[38:39]
	v_cndmask_b32_e64 v5, v1, v3, s[38:39]
	v_cvt_pk_bf16_f32 v6, v8, v9
	v_cvt_pk_bf16_f32 v7, v10, v11
	v_cvt_pk_bf16_f32 v8, v12, v13
	v_cvt_pk_bf16_f32 v9, v14, v15
	v_cndmask_b32_e64 v56, v133, v59, s[38:39]
	v_cndmask_b32_e64 v57, v58, v60, s[38:39]
	v_mov_b32_e32 v39, v37
	v_mov_b32_e32 v255, v37
	s_nop 1
	v_permlane32_swap_b32_e32 v39, v255
	s_nop 1
	v_mov_b32_dpp v39, v255 quad_perm:[0,1,2,3] row_mask:0x3 bank_mask:0xf
	v_cndmask_b32_e64 v43, v38, v41, s[38:39]
	v_cndmask_b32_e64 v44, v40, v42, s[38:39]
	v_mov_b32_e32 v255, v20
	s_nop 1
	v_permlane32_swap_b32_e32 v20, v255
	s_nop 1
	v_mov_b32_dpp v20, v255 quad_perm:[0,1,2,3] row_mask:0x3 bank_mask:0xf
	v_mov_b32_e32 v255, v21
	s_nop 1
	v_permlane32_swap_b32_e32 v21, v255
	s_nop 1
	v_mov_b32_dpp v21, v255 quad_perm:[0,1,2,3] row_mask:0x3 bank_mask:0xf
	v_cndmask_b32_e64 v26, v22, v24, s[38:39]
	v_cndmask_b32_e64 v27, v23, v25, s[38:39]
	v_mov_b32_e32 v255, v4
	s_nop 1
	v_permlane32_swap_b32_e32 v4, v255
	s_nop 1
	v_mov_b32_dpp v4, v255 quad_perm:[0,1,2,3] row_mask:0x3 bank_mask:0xf
	v_mov_b32_e32 v255, v5
	s_nop 1
	v_permlane32_swap_b32_e32 v5, v255
	s_nop 1
	v_mov_b32_dpp v5, v255 quad_perm:[0,1,2,3] row_mask:0x3 bank_mask:0xf
	v_cndmask_b32_e64 v10, v6, v8, s[38:39]
	v_cndmask_b32_e64 v11, v7, v9, s[38:39]
	v_lshl_or_b32 v98, s2, 7, v176
	v_readlane_b32 s2, v249, 7
	v_mov_b32_e32 v61, v56
	v_mov_b32_e32 v255, v56
	s_nop 1
	v_permlane32_swap_b32_e32 v61, v255
	s_nop 1
	v_mov_b32_dpp v61, v255 quad_perm:[0,1,2,3] row_mask:0x3 bank_mask:0xf
	v_mov_b32_e32 v62, v57
	v_mov_b32_e32 v255, v57
	s_nop 1
	v_permlane32_swap_b32_e32 v62, v255
	s_nop 1
	v_mov_b32_dpp v62, v255 quad_perm:[0,1,2,3] row_mask:0x3 bank_mask:0xf
	v_mov_b32_e32 v255, v43
	s_nop 1
	v_permlane32_swap_b32_e32 v43, v255
	s_nop 1
	v_mov_b32_dpp v43, v255 quad_perm:[0,1,2,3] row_mask:0x3 bank_mask:0xf
	v_mov_b32_e32 v255, v44
	s_nop 1
	v_permlane32_swap_b32_e32 v44, v255
	s_nop 1
	v_mov_b32_dpp v44, v255 quad_perm:[0,1,2,3] row_mask:0x3 bank_mask:0xf
	v_mov_b32_e32 v255, v26
	s_nop 1
	v_permlane32_swap_b32_e32 v26, v255
	s_nop 1
	v_mov_b32_dpp v26, v255 quad_perm:[0,1,2,3] row_mask:0x3 bank_mask:0xf
	v_mov_b32_e32 v255, v27
	s_nop 1
	v_permlane32_swap_b32_e32 v27, v255
	s_nop 1
	v_mov_b32_dpp v27, v255 quad_perm:[0,1,2,3] row_mask:0x3 bank_mask:0xf
	v_mov_b32_e32 v255, v10
	s_nop 1
	v_permlane32_swap_b32_e32 v10, v255
	s_nop 1
	v_mov_b32_dpp v10, v255 quad_perm:[0,1,2,3] row_mask:0x3 bank_mask:0xf
	v_mov_b32_e32 v255, v11
	s_nop 1
	v_permlane32_swap_b32_e32 v11, v255
	s_nop 1
	v_mov_b32_dpp v11, v255 quad_perm:[0,1,2,3] row_mask:0x3 bank_mask:0xf
	v_lshl_add_u32 v96, s6, 7, v175
	v_readlane_b32 s3, v249, 8
	s_nop 0
	v_cndmask_b32_e64 v48, v99, v48, s[38:39]
	v_cndmask_b32_e64 v50, v50, v99, s[38:39]
	v_mov_b64_e32 v[52:53], s[2:3]
	v_ashrrev_i32_e32 v99, 31, v98
	v_or_b32_e32 v36, 32, v96
	v_mad_i64_i32 v[54:55], s[2:3], v96, s74, v[52:53]
	v_lshlrev_b64 v[56:57], 1, v[98:99]
	v_mad_i64_i32 v[36:37], s[2:3], v36, s74, v[52:53]
	v_lshl_add_u64 v[54:55], v[54:55], 0, v[56:57]
	s_nop 0
	v_cndmask_b32_e64 v33, v39, v33, s[38:39]
	v_cndmask_b32_e64 v35, v35, v39, s[38:39]
	v_lshl_add_u64 v[36:37], v[36:37], 0, v[56:57]
	s_nop 0
	v_cndmask_b32_e64 v16, v20, v16, s[38:39]
	s_nop 0
	v_cndmask_b32_e64 v17, v21, v17, s[38:39]
	v_cndmask_b32_e64 v18, v18, v20, s[38:39]
	v_cndmask_b32_e64 v19, v19, v21, s[38:39]
	s_nop 0
	v_cndmask_b32_e64 v0, v4, v0, s[38:39]
	s_nop 0
	v_cndmask_b32_e64 v1, v5, v1, s[38:39]
	v_cndmask_b32_e64 v2, v2, v4, s[38:39]
	v_cndmask_b32_e64 v3, v3, v5, s[38:39]
	global_store_dwordx4 v[54:55], v[48:51], off
	global_store_dwordx4 v[36:37], v[32:35], off
	global_store_dwordx4 v[54:55], v[16:19], off offset:64
	s_nop 0
	v_cndmask_b32_e64 v48, v61, v133, s[38:39]
	s_nop 0
	v_cndmask_b32_e64 v49, v62, v58, s[38:39]
	v_cndmask_b32_e64 v50, v59, v61, s[38:39]
	v_cndmask_b32_e64 v51, v60, v62, s[38:39]
	s_nop 0
	v_cndmask_b32_e64 v32, v43, v38, s[38:39]
	s_nop 0
	v_cndmask_b32_e64 v33, v44, v40, s[38:39]
	v_cndmask_b32_e64 v34, v41, v43, s[38:39]
	v_cndmask_b32_e64 v35, v42, v44, s[38:39]
	s_nop 0
	v_cndmask_b32_e64 v16, v26, v22, s[38:39]
	s_nop 0
	v_cndmask_b32_e64 v17, v27, v23, s[38:39]
	v_cndmask_b32_e64 v18, v24, v26, s[38:39]
	v_cndmask_b32_e64 v19, v25, v27, s[38:39]
	global_store_dwordx4 v[36:37], v[0:3], off offset:64
	global_store_dwordx4 v[54:55], v[48:51], off offset:32
	global_store_dwordx4 v[36:37], v[32:35], off offset:32
	s_nop 0
	v_cndmask_b32_e64 v0, v10, v6, s[38:39]
	s_nop 0
	v_cndmask_b32_e64 v1, v11, v7, s[38:39]
	v_cndmask_b32_e64 v2, v8, v10, s[38:39]
	v_cndmask_b32_e64 v3, v9, v11, s[38:39]
	global_store_dwordx4 v[54:55], v[16:19], off offset:96
	global_store_dwordx4 v[36:37], v[0:3], off offset:96
	s_branch .LBB0_442

.LBB0_540:
	s_or_b64 exec, exec, s[6:7]
	v_ashrrev_i32_e32 v9, 31, v8
	v_mad_i64_i32 v[6:7], s[0:1], v8, s74, v[0:1]
	v_lshlrev_b64 v[4:5], 8, v[8:9]
	v_lshlrev_b64 v[8:9], 10, v[8:9]
	v_lshl_add_u64 v[10:11], v[2:3], 0, v[8:9]
	global_load_ushort v8, v[6:7], off
	global_load_ushort v9, v[6:7], off offset:128
	global_load_ushort v78, v[6:7], off offset:256
	global_load_ushort v79, v[6:7], off offset:384
	global_load_ushort v80, v[6:7], off offset:512
	global_load_ushort v81, v[6:7], off offset:640
	global_load_ushort v82, v[6:7], off offset:768
	global_load_ushort v83, v[6:7], off offset:896
	global_load_ushort v84, v[6:7], off offset:1024
	global_load_ushort v85, v[6:7], off offset:1152
	s_mov_b32 s0, 0x358637bd
	v_lshl_add_u64 v[4:5], s[92:93], 0, v[4:5]
	v_lshl_add_u64 v[4:5], v[4:5], 0, v[96:97]
	s_mov_b32 s4, 0xc600000
	s_add_i32 s3, s3, 1
	s_cmp_lg_u32 s3, 8
	s_waitcnt vmcnt(9)
	v_lshlrev_b32_e32 v27, 16, v8
	s_waitcnt vmcnt(8)
	v_lshlrev_b32_e32 v26, 16, v9
	v_pk_mul_f32 v[8:9], v[26:27], v[26:27]
	v_mov_b32_e32 v255, v9
	s_nop 1
	v_permlane32_swap_b32_e32 v9, v255
	s_nop 1
	v_mov_b32_dpp v9, v255 quad_perm:[0,1,2,3] row_mask:0x3 bank_mask:0xf
	v_mov_b32_e32 v255, v8
	s_nop 1
	v_permlane32_swap_b32_e32 v8, v255
	s_nop 1
	v_mov_b32_dpp v8, v255 quad_perm:[0,1,2,3] row_mask:0x3 bank_mask:0xf
	s_waitcnt lgkmcnt(0)
	v_pk_fma_f32 v[8:9], v[26:27], v[26:27], v[8:9]
	v_mov_b32_e32 v29, v9
	v_mov_b32_e32 v255, v9
	s_nop 1
	v_permlane16_swap_b32_e32 v29, v255
	s_nop 1
	v_mov_b32_dpp v29, v255 quad_perm:[0,1,2,3] row_mask:0x5 bank_mask:0xf
	v_mov_b32_e32 v28, v8
	v_mov_b32_e32 v255, v8
	s_nop 1
	v_permlane16_swap_b32_e32 v28, v255
	s_nop 1
	v_mov_b32_dpp v28, v255 quad_perm:[0,1,2,3] row_mask:0x5 bank_mask:0xf
	s_nop 0
	v_pk_add_f32 v[8:9], v[8:9], v[28:29]
	s_nop 1
	v_mov_b32_dpp v29, v9 row_ror:8 row_mask:0xf bank_mask:0xf
	s_nop 1
	v_mov_b32_dpp v28, v8 row_ror:8 row_mask:0xf bank_mask:0xf
	s_nop 0
	v_pk_add_f32 v[8:9], v[8:9], v[28:29]
	s_nop 1
	v_mov_b32_dpp v29, v9 row_shl:4 row_mask:0xf bank_mask:0x5
	v_mov_b32_dpp v29, v9 row_shr:4 row_mask:0xf bank_mask:0xa
	s_nop 1
	v_mov_b32_dpp v28, v8 row_shl:4 row_mask:0xf bank_mask:0x5
	v_mov_b32_dpp v28, v8 row_shr:4 row_mask:0xf bank_mask:0xa
	s_nop 0
	v_pk_add_f32 v[8:9], v[8:9], v[28:29]
	s_nop 1
	v_mov_b32_dpp v29, v9 quad_perm:[2,3,0,1] row_mask:0xf bank_mask:0xf
	s_nop 1
	v_mov_b32_dpp v28, v8 quad_perm:[2,3,0,1] row_mask:0xf bank_mask:0xf
	s_nop 0
	v_pk_add_f32 v[8:9], v[8:9], v[28:29]
	s_nop 1
	v_mov_b32_dpp v29, v9 quad_perm:[1,0,3,2] row_mask:0xf bank_mask:0xf
	s_nop 1
	v_mov_b32_dpp v28, v8 quad_perm:[1,0,3,2] row_mask:0xf bank_mask:0xf
	s_nop 0
	v_pk_add_f32 v[28:29], v[8:9], v[28:29]
	v_mov_b64_e32 v[8:9], s[0:1]
	v_pk_fma_f32 v[28:29], v[28:29], s[10:11], v[8:9] op_sel_hi:[1,0,0]
	s_nop 0
	v_mul_f32_e32 v25, 0x4b800000, v29
	v_cmp_gt_f32_e64 s[40:41], s86, v29
	v_cmp_gt_f32_e64 s[0:1], s86, v28
	s_nop 0
	v_cndmask_b32_e64 v25, v29, v25, s[40:41]
	v_rsq_f32_e32 v25, v25
	s_nop 0
	v_mul_f32_e32 v29, 0x45800000, v25
	v_cndmask_b32_e64 v25, v25, v29, s[40:41]
	v_mul_f32_e32 v25, v25, v27
	v_mul_f32_e32 v25, v12, v25
	v_mov_b32_e32 v27, v25
	v_mov_b32_e32 v255, v25
	s_nop 1
	v_permlane16_swap_b32_e32 v27, v255
	s_nop 1
	v_mov_b32_dpp v27, v255 quad_perm:[0,1,2,3] row_mask:0x5 bank_mask:0xf
	v_mul_f32_e32 v25, v23, v25
	s_nop 0
	v_cndmask_b32_e64 v27, v27, -v27, vcc
	v_fmac_f32_e32 v25, v24, v27
	v_mul_f32_e32 v25, 0x3e000000, v25
	v_cvt_pk_bf16_f32 v25, v25, s0
	global_store_short v[10:11], v25, off
	v_mul_f32_e32 v25, 0x4b800000, v28
	v_cndmask_b32_e64 v25, v28, v25, s[0:1]
	v_rsq_f32_e32 v25, v25
	s_nop 0
	v_mul_f32_e32 v27, 0x45800000, v25
	v_cndmask_b32_e64 v25, v25, v27, s[0:1]
	v_mul_f32_e32 v25, v25, v26
	v_mul_f32_e32 v25, v12, v25
	v_mov_b32_e32 v26, v25
	v_mov_b32_e32 v255, v25
	s_nop 1
	v_permlane16_swap_b32_e32 v26, v255
	s_nop 1
	v_mov_b32_dpp v26, v255 quad_perm:[0,1,2,3] row_mask:0x5 bank_mask:0xf
	v_mul_f32_e32 v25, v23, v25
	s_nop 0
	v_cndmask_b32_e64 v26, v26, -v26, vcc
	v_fmac_f32_e32 v25, v24, v26
	v_mul_f32_e32 v25, 0x3e000000, v25
	v_cvt_pk_bf16_f32 v25, v25, s0
	global_store_short v[10:11], v25, off offset:128
	s_nop 0
	s_waitcnt vmcnt(9)
	v_mov_b32_e32 v25, v78
	v_lshlrev_b32_e32 v27, 16, v25
	s_waitcnt vmcnt(8)
	v_mov_b32_e32 v26, v79
	v_lshlrev_b32_e32 v26, 16, v26
	v_pk_mul_f32 v[28:29], v[26:27], v[26:27]
	v_mov_b32_e32 v255, v29
	s_nop 1
	v_permlane32_swap_b32_e32 v29, v255
	s_nop 1
	v_mov_b32_dpp v29, v255 quad_perm:[0,1,2,3] row_mask:0x3 bank_mask:0xf
	v_mov_b32_e32 v255, v28
	s_nop 1
	v_permlane32_swap_b32_e32 v28, v255
	s_nop 1
	v_mov_b32_dpp v28, v255 quad_perm:[0,1,2,3] row_mask:0x3 bank_mask:0xf
	s_nop 0
	v_pk_fma_f32 v[28:29], v[26:27], v[26:27], v[28:29]
	v_mov_b32_e32 v31, v29
	v_mov_b32_e32 v255, v29
	s_nop 1
	v_permlane16_swap_b32_e32 v31, v255
	s_nop 1
	v_mov_b32_dpp v31, v255 quad_perm:[0,1,2,3] row_mask:0x5 bank_mask:0xf
	v_mov_b32_e32 v30, v28
	v_mov_b32_e32 v255, v28
	s_nop 1
	v_permlane16_swap_b32_e32 v30, v255
	s_nop 1
	v_mov_b32_dpp v30, v255 quad_perm:[0,1,2,3] row_mask:0x5 bank_mask:0xf
	s_nop 0
	v_pk_add_f32 v[28:29], v[28:29], v[30:31]
	s_nop 1
	v_mov_b32_dpp v31, v29 row_ror:8 row_mask:0xf bank_mask:0xf
	s_nop 1
	v_mov_b32_dpp v30, v28 row_ror:8 row_mask:0xf bank_mask:0xf
	s_nop 0
	v_pk_add_f32 v[28:29], v[28:29], v[30:31]
	s_nop 1
	v_mov_b32_dpp v31, v29 row_shl:4 row_mask:0xf bank_mask:0x5
	v_mov_b32_dpp v31, v29 row_shr:4 row_mask:0xf bank_mask:0xa
	s_nop 1
	v_mov_b32_dpp v30, v28 row_shl:4 row_mask:0xf bank_mask:0x5
	v_mov_b32_dpp v30, v28 row_shr:4 row_mask:0xf bank_mask:0xa
	s_nop 0
	v_pk_add_f32 v[28:29], v[28:29], v[30:31]
	s_nop 1
	v_mov_b32_dpp v31, v29 quad_perm:[2,3,0,1] row_mask:0xf bank_mask:0xf
	s_nop 1
	v_mov_b32_dpp v30, v28 quad_perm:[2,3,0,1] row_mask:0xf bank_mask:0xf
	s_nop 0
	v_pk_add_f32 v[28:29], v[28:29], v[30:31]
	s_nop 1
	v_mov_b32_dpp v31, v29 quad_perm:[1,0,3,2] row_mask:0xf bank_mask:0xf
	s_nop 1
	v_mov_b32_dpp v30, v28 quad_perm:[1,0,3,2] row_mask:0xf bank_mask:0xf
	s_nop 0
	v_pk_add_f32 v[28:29], v[28:29], v[30:31]
	s_nop 0
	v_pk_fma_f32 v[28:29], v[28:29], s[10:11], v[8:9] op_sel_hi:[1,0,0]
	s_nop 0
	v_mul_f32_e32 v25, 0x4b800000, v29
	v_cmp_gt_f32_e64 s[40:41], s86, v29
	v_cmp_gt_f32_e64 s[0:1], s86, v28
	s_nop 0
	v_cndmask_b32_e64 v25, v29, v25, s[40:41]
	v_rsq_f32_e32 v25, v25
	s_nop 0
	v_mul_f32_e32 v29, 0x45800000, v25
	v_cndmask_b32_e64 v25, v25, v29, s[40:41]
	v_mul_f32_e32 v25, v25, v27
	v_mul_f32_e32 v25, v12, v25
	v_mov_b32_e32 v27, v25
	v_mov_b32_e32 v255, v25
	s_nop 1
	v_permlane16_swap_b32_e32 v27, v255
	s_nop 1
	v_mov_b32_dpp v27, v255 quad_perm:[0,1,2,3] row_mask:0x5 bank_mask:0xf
	v_mul_f32_e32 v25, v23, v25
	s_nop 0
	v_cndmask_b32_e64 v27, v27, -v27, vcc
	v_fmac_f32_e32 v25, v24, v27
	v_mul_f32_e32 v25, 0x3e000000, v25
	v_cvt_pk_bf16_f32 v25, v25, s0
	global_store_short v[10:11], v25, off offset:256
	v_mul_f32_e32 v25, 0x4b800000, v28
	v_cndmask_b32_e64 v25, v28, v25, s[0:1]
	v_rsq_f32_e32 v25, v25
	s_nop 0
	v_mul_f32_e32 v27, 0x45800000, v25
	v_cndmask_b32_e64 v25, v25, v27, s[0:1]
	v_mul_f32_e32 v25, v25, v26
	v_mul_f32_e32 v25, v12, v25
	v_mov_b32_e32 v26, v25
	v_mov_b32_e32 v255, v25
	s_nop 1
	v_permlane16_swap_b32_e32 v26, v255
	s_nop 1
	v_mov_b32_dpp v26, v255 quad_perm:[0,1,2,3] row_mask:0x5 bank_mask:0xf
	v_mul_f32_e32 v25, v23, v25
	s_nop 0
	v_cndmask_b32_e64 v26, v26, -v26, vcc
	v_fmac_f32_e32 v25, v24, v26
	v_mul_f32_e32 v25, 0x3e000000, v25
	v_cvt_pk_bf16_f32 v25, v25, s0
	global_store_short v[10:11], v25, off offset:384
	s_nop 0
	s_waitcnt vmcnt(9)
	v_mov_b32_e32 v25, v80
	v_lshlrev_b32_e32 v27, 16, v25
	s_waitcnt vmcnt(8)
	v_mov_b32_e32 v26, v81
	v_lshlrev_b32_e32 v26, 16, v26
	v_pk_mul_f32 v[28:29], v[26:27], v[26:27]
	v_mov_b32_e32 v255, v29
	s_nop 1
	v_permlane32_swap_b32_e32 v29, v255
	s_nop 1
	v_mov_b32_dpp v29, v255 quad_perm:[0,1,2,3] row_mask:0x3 bank_mask:0xf
	v_mov_b32_e32 v255, v28
	s_nop 1
	v_permlane32_swap_b32_e32 v28, v255
	s_nop 1
	v_mov_b32_dpp v28, v255 quad_perm:[0,1,2,3] row_mask:0x3 bank_mask:0xf
	s_nop 0
	v_pk_fma_f32 v[28:29], v[26:27], v[26:27], v[28:29]
	v_mov_b32_e32 v31, v29
	v_mov_b32_e32 v255, v29
	s_nop 1
	v_permlane16_swap_b32_e32 v31, v255
	s_nop 1
	v_mov_b32_dpp v31, v255 quad_perm:[0,1,2,3] row_mask:0x5 bank_mask:0xf
	v_mov_b32_e32 v30, v28
	v_mov_b32_e32 v255, v28
	s_nop 1
	v_permlane16_swap_b32_e32 v30, v255
	s_nop 1
	v_mov_b32_dpp v30, v255 quad_perm:[0,1,2,3] row_mask:0x5 bank_mask:0xf
	s_nop 0
	v_pk_add_f32 v[28:29], v[28:29], v[30:31]
	s_nop 1
	v_mov_b32_dpp v31, v29 row_ror:8 row_mask:0xf bank_mask:0xf
	s_nop 1
	v_mov_b32_dpp v30, v28 row_ror:8 row_mask:0xf bank_mask:0xf
	s_nop 0
	v_pk_add_f32 v[28:29], v[28:29], v[30:31]
	s_nop 1
	v_mov_b32_dpp v31, v29 row_shl:4 row_mask:0xf bank_mask:0x5
	v_mov_b32_dpp v31, v29 row_shr:4 row_mask:0xf bank_mask:0xa
	s_nop 1
	v_mov_b32_dpp v30, v28 row_shl:4 row_mask:0xf bank_mask:0x5
	v_mov_b32_dpp v30, v28 row_shr:4 row_mask:0xf bank_mask:0xa
	s_nop 0
	v_pk_add_f32 v[28:29], v[28:29], v[30:31]
	s_nop 1
	v_mov_b32_dpp v31, v29 quad_perm:[2,3,0,1] row_mask:0xf bank_mask:0xf
	s_nop 1
	v_mov_b32_dpp v30, v28 quad_perm:[2,3,0,1] row_mask:0xf bank_mask:0xf
	s_nop 0
	v_pk_add_f32 v[28:29], v[28:29], v[30:31]
	s_nop 1
	v_mov_b32_dpp v31, v29 quad_perm:[1,0,3,2] row_mask:0xf bank_mask:0xf
	s_nop 1
	v_mov_b32_dpp v30, v28 quad_perm:[1,0,3,2] row_mask:0xf bank_mask:0xf
	s_nop 0
	v_pk_add_f32 v[28:29], v[28:29], v[30:31]
	s_nop 0
	v_pk_fma_f32 v[28:29], v[28:29], s[10:11], v[8:9] op_sel_hi:[1,0,0]
	s_nop 0
	v_mul_f32_e32 v25, 0x4b800000, v29
	v_cmp_gt_f32_e64 s[40:41], s86, v29
	v_cmp_gt_f32_e64 s[0:1], s86, v28
	s_nop 0
	v_cndmask_b32_e64 v25, v29, v25, s[40:41]
	v_rsq_f32_e32 v25, v25
	s_nop 0
	v_mul_f32_e32 v29, 0x45800000, v25
	v_cndmask_b32_e64 v25, v25, v29, s[40:41]
	v_mul_f32_e32 v25, v25, v27
	v_mul_f32_e32 v25, v12, v25
	v_mov_b32_e32 v27, v25
	v_mov_b32_e32 v255, v25
	s_nop 1
	v_permlane16_swap_b32_e32 v27, v255
	s_nop 1
	v_mov_b32_dpp v27, v255 quad_perm:[0,1,2,3] row_mask:0x5 bank_mask:0xf
	v_mul_f32_e32 v25, v23, v25
	s_nop 0
	v_cndmask_b32_e64 v27, v27, -v27, vcc
	v_fmac_f32_e32 v25, v24, v27
	v_mul_f32_e32 v25, 0x3e000000, v25
	v_cvt_pk_bf16_f32 v25, v25, s0
	global_store_short v[10:11], v25, off offset:512
	v_mul_f32_e32 v25, 0x4b800000, v28
	v_cndmask_b32_e64 v25, v28, v25, s[0:1]
	v_rsq_f32_e32 v25, v25
	s_nop 0
	v_mul_f32_e32 v27, 0x45800000, v25
	v_cndmask_b32_e64 v25, v25, v27, s[0:1]
	v_mul_f32_e32 v25, v25, v26
	v_mul_f32_e32 v25, v12, v25
	v_mov_b32_e32 v26, v25
	v_mov_b32_e32 v255, v25
	s_nop 1
	v_permlane16_swap_b32_e32 v26, v255
	s_nop 1
	v_mov_b32_dpp v26, v255 quad_perm:[0,1,2,3] row_mask:0x5 bank_mask:0xf
	v_mul_f32_e32 v25, v23, v25
	s_nop 0
	v_cndmask_b32_e64 v26, v26, -v26, vcc
	v_fmac_f32_e32 v25, v24, v26
	v_mul_f32_e32 v25, 0x3e000000, v25
	v_cvt_pk_bf16_f32 v25, v25, s0
	global_store_short v[10:11], v25, off offset:640
	s_nop 0
	s_waitcnt vmcnt(9)
	v_mov_b32_e32 v25, v82
	v_lshlrev_b32_e32 v27, 16, v25
	s_waitcnt vmcnt(8)
	v_mov_b32_e32 v26, v83
	v_lshlrev_b32_e32 v26, 16, v26
	v_pk_mul_f32 v[28:29], v[26:27], v[26:27]
	v_mov_b32_e32 v255, v29
	s_nop 1
	v_permlane32_swap_b32_e32 v29, v255
	s_nop 1
	v_mov_b32_dpp v29, v255 quad_perm:[0,1,2,3] row_mask:0x3 bank_mask:0xf
	v_mov_b32_e32 v255, v28
	s_nop 1
	v_permlane32_swap_b32_e32 v28, v255
	s_nop 1
	v_mov_b32_dpp v28, v255 quad_perm:[0,1,2,3] row_mask:0x3 bank_mask:0xf
	s_nop 0
	v_pk_fma_f32 v[28:29], v[26:27], v[26:27], v[28:29]
	v_mov_b32_e32 v31, v29
	v_mov_b32_e32 v255, v29
	s_nop 1
	v_permlane16_swap_b32_e32 v31, v255
	s_nop 1
	v_mov_b32_dpp v31, v255 quad_perm:[0,1,2,3] row_mask:0x5 bank_mask:0xf
	v_mov_b32_e32 v30, v28
	v_mov_b32_e32 v255, v28
	s_nop 1
	v_permlane16_swap_b32_e32 v30, v255
	s_nop 1
	v_mov_b32_dpp v30, v255 quad_perm:[0,1,2,3] row_mask:0x5 bank_mask:0xf
	s_nop 0
	v_pk_add_f32 v[28:29], v[28:29], v[30:31]
	s_nop 1
	v_mov_b32_dpp v31, v29 row_ror:8 row_mask:0xf bank_mask:0xf
	s_nop 1
	v_mov_b32_dpp v30, v28 row_ror:8 row_mask:0xf bank_mask:0xf
	s_nop 0
	v_pk_add_f32 v[28:29], v[28:29], v[30:31]
	s_nop 1
	v_mov_b32_dpp v31, v29 row_shl:4 row_mask:0xf bank_mask:0x5
	v_mov_b32_dpp v31, v29 row_shr:4 row_mask:0xf bank_mask:0xa
	s_nop 1
	v_mov_b32_dpp v30, v28 row_shl:4 row_mask:0xf bank_mask:0x5
	v_mov_b32_dpp v30, v28 row_shr:4 row_mask:0xf bank_mask:0xa
	s_nop 0
	v_pk_add_f32 v[28:29], v[28:29], v[30:31]
	s_nop 1
	v_mov_b32_dpp v31, v29 quad_perm:[2,3,0,1] row_mask:0xf bank_mask:0xf
	s_nop 1
	v_mov_b32_dpp v30, v28 quad_perm:[2,3,0,1] row_mask:0xf bank_mask:0xf
	s_nop 0
	v_pk_add_f32 v[28:29], v[28:29], v[30:31]
	s_nop 1
	v_mov_b32_dpp v31, v29 quad_perm:[1,0,3,2] row_mask:0xf bank_mask:0xf
	s_nop 1
	v_mov_b32_dpp v30, v28 quad_perm:[1,0,3,2] row_mask:0xf bank_mask:0xf
	s_nop 0
	v_pk_add_f32 v[28:29], v[28:29], v[30:31]
	s_nop 0
	v_pk_fma_f32 v[28:29], v[28:29], s[10:11], v[8:9] op_sel_hi:[1,0,0]
	s_nop 0
	v_mul_f32_e32 v25, 0x4b800000, v29
	v_cmp_gt_f32_e64 s[40:41], s86, v29
	v_cmp_gt_f32_e64 s[0:1], s86, v28
	s_nop 0
	v_cndmask_b32_e64 v25, v29, v25, s[40:41]
	v_rsq_f32_e32 v25, v25
	s_nop 0
	v_mul_f32_e32 v29, 0x45800000, v25
	v_cndmask_b32_e64 v25, v25, v29, s[40:41]
	v_mul_f32_e32 v25, v25, v27
	v_mul_f32_e32 v25, v12, v25
	v_mov_b32_e32 v27, v25
	v_mov_b32_e32 v255, v25
	s_nop 1
	v_permlane16_swap_b32_e32 v27, v255
	s_nop 1
	v_mov_b32_dpp v27, v255 quad_perm:[0,1,2,3] row_mask:0x5 bank_mask:0xf
	v_mul_f32_e32 v25, v23, v25
	s_nop 0
	v_cndmask_b32_e64 v27, v27, -v27, vcc
	v_fmac_f32_e32 v25, v24, v27
	v_mul_f32_e32 v25, 0x3e000000, v25
	v_cvt_pk_bf16_f32 v25, v25, s0
	global_store_short v[10:11], v25, off offset:768
	v_mul_f32_e32 v25, 0x4b800000, v28
	v_cndmask_b32_e64 v25, v28, v25, s[0:1]
	v_rsq_f32_e32 v25, v25
	s_nop 0
	v_mul_f32_e32 v27, 0x45800000, v25
	v_cndmask_b32_e64 v25, v25, v27, s[0:1]
	v_mul_f32_e32 v25, v25, v26
	v_mul_f32_e32 v25, v12, v25
	v_mov_b32_e32 v26, v25
	v_mov_b32_e32 v255, v25
	s_nop 1
	v_permlane16_swap_b32_e32 v26, v255
	s_nop 1
	v_mov_b32_dpp v26, v255 quad_perm:[0,1,2,3] row_mask:0x5 bank_mask:0xf
	v_mul_f32_e32 v25, v23, v25
	s_nop 0
	v_cndmask_b32_e64 v26, v26, -v26, vcc
	v_fmac_f32_e32 v25, v24, v26
	v_mul_f32_e32 v25, 0x3e000000, v25
	v_cvt_pk_bf16_f32 v25, v25, s0
	global_store_short v[10:11], v25, off offset:896
	s_nop 0
	s_waitcnt vmcnt(9)
	v_mov_b32_e32 v10, v84
	v_lshlrev_b32_e32 v7, 16, v10
	s_waitcnt vmcnt(8)
	v_mov_b32_e32 v6, v85
	v_lshlrev_b32_e32 v6, 16, v6
	v_pk_mul_f32 v[10:11], v[6:7], v[6:7]
	v_mov_b32_e32 v255, v11
	s_nop 1
	v_permlane32_swap_b32_e32 v11, v255
	s_nop 1
	v_mov_b32_dpp v11, v255 quad_perm:[0,1,2,3] row_mask:0x3 bank_mask:0xf
	v_mov_b32_e32 v255, v10
	s_nop 1
	v_permlane32_swap_b32_e32 v10, v255
	s_nop 1
	v_mov_b32_dpp v10, v255 quad_perm:[0,1,2,3] row_mask:0x3 bank_mask:0xf
	s_nop 0
	v_pk_fma_f32 v[10:11], v[6:7], v[6:7], v[10:11]
	v_mov_b32_e32 v27, v11
	v_mov_b32_e32 v255, v11
	s_nop 1
	v_permlane16_swap_b32_e32 v27, v255
	s_nop 1
	v_mov_b32_dpp v27, v255 quad_perm:[0,1,2,3] row_mask:0x5 bank_mask:0xf
	v_mov_b32_e32 v26, v10
	v_mov_b32_e32 v255, v10
	s_nop 1
	v_permlane16_swap_b32_e32 v26, v255
	s_nop 1
	v_mov_b32_dpp v26, v255 quad_perm:[0,1,2,3] row_mask:0x5 bank_mask:0xf
	s_nop 0
	v_pk_add_f32 v[10:11], v[10:11], v[26:27]
	s_nop 1
	v_mov_b32_dpp v27, v11 row_ror:8 row_mask:0xf bank_mask:0xf
	s_nop 1
	v_mov_b32_dpp v26, v10 row_ror:8 row_mask:0xf bank_mask:0xf
	s_nop 0
	v_pk_add_f32 v[10:11], v[10:11], v[26:27]
	s_nop 1
	v_mov_b32_dpp v27, v11 row_shl:4 row_mask:0xf bank_mask:0x5
	v_mov_b32_dpp v27, v11 row_shr:4 row_mask:0xf bank_mask:0xa
	s_nop 1
	v_mov_b32_dpp v26, v10 row_shl:4 row_mask:0xf bank_mask:0x5
	v_mov_b32_dpp v26, v10 row_shr:4 row_mask:0xf bank_mask:0xa
	s_nop 0
	v_pk_add_f32 v[10:11], v[10:11], v[26:27]
	s_nop 1
	v_mov_b32_dpp v27, v11 quad_perm:[2,3,0,1] row_mask:0xf bank_mask:0xf
	s_nop 1
	v_mov_b32_dpp v26, v10 quad_perm:[2,3,0,1] row_mask:0xf bank_mask:0xf
	s_nop 0
	v_pk_add_f32 v[10:11], v[10:11], v[26:27]
	s_nop 1
	v_mov_b32_dpp v27, v11 quad_perm:[1,0,3,2] row_mask:0xf bank_mask:0xf
	s_nop 1
	v_mov_b32_dpp v26, v10 quad_perm:[1,0,3,2] row_mask:0xf bank_mask:0xf
	s_nop 0
	v_pk_add_f32 v[10:11], v[10:11], v[26:27]
	s_nop 0
	v_pk_fma_f32 v[8:9], v[10:11], s[10:11], v[8:9] op_sel_hi:[1,0,0]
	s_nop 0
	v_mul_f32_e32 v10, 0x4b800000, v9
	v_cmp_gt_f32_e64 s[40:41], s86, v9
	v_cmp_gt_f32_e64 s[0:1], s86, v8
	s_nop 0
	v_cndmask_b32_e64 v9, v9, v10, s[40:41]
	v_rsq_f32_e32 v9, v9
	s_nop 0
	v_mul_f32_e32 v10, 0x45800000, v9
	v_cndmask_b32_e64 v9, v9, v10, s[40:41]
	v_mul_f32_e32 v7, v9, v7
	v_mul_f32_e32 v7, v13, v7
	v_mov_b32_e32 v9, v7
	v_mov_b32_e32 v255, v7
	s_nop 1
	v_permlane16_swap_b32_e32 v9, v255
	s_nop 1
	v_mov_b32_dpp v9, v255 quad_perm:[0,1,2,3] row_mask:0x5 bank_mask:0xf
	v_mul_f32_e32 v7, v23, v7
	v_add_co_u32_e64 v4, s[40:41], s4, v4
	s_nop 0
	v_cndmask_b32_e64 v9, v9, -v9, vcc
	v_fmac_f32_e32 v7, v24, v9
	v_cvt_pk_bf16_f32 v7, v7, s0
	v_addc_co_u32_e64 v5, s[40:41], 0, v5, s[40:41]
	global_store_short v[4:5], v7, off
	v_mul_f32_e32 v7, 0x4b800000, v8
	v_cndmask_b32_e64 v7, v8, v7, s[0:1]
	v_rsq_f32_e32 v7, v7
	s_nop 0
	v_mul_f32_e32 v8, 0x45800000, v7
	v_cndmask_b32_e64 v7, v7, v8, s[0:1]
	v_mul_f32_e32 v6, v7, v6
	v_mul_f32_e32 v6, v13, v6
	v_mov_b32_e32 v7, v6
	v_mov_b32_e32 v255, v6
	s_nop 1
	v_permlane16_swap_b32_e32 v7, v255
	s_nop 1
	v_mov_b32_dpp v7, v255 quad_perm:[0,1,2,3] row_mask:0x5 bank_mask:0xf
	v_mul_f32_e32 v6, v23, v6
	s_nop 0
	v_cndmask_b32_e64 v7, v7, -v7, vcc
	v_fmac_f32_e32 v6, v24, v7
	v_cvt_pk_bf16_f32 v6, v6, s0
	global_store_short v[4:5], v6, off offset:128
	s_cbranch_scc0 .LBB0_543

.LBB0_544:
	s_and_b64 vcc, exec, s[0:1]
	s_cbranch_vccz .LBB0_639
	v_mov_b32_e32 v51, v162
	s_bfe_u32 s4, s2, 0x30001
	s_lshl_b32 s3, s4, 6
	s_waitcnt vmcnt(7)
	v_lshlrev_b32_e32 v66, 3, v51
	v_and_b32_e32 v50, 56, v66
	v_or_b32_e32 v14, s3, v50
	v_readlane_b32 s0, v248, 18
	v_readlane_b32 s8, v251, 4
	v_readlane_b32 s14, v251, 10
	s_waitcnt lgkmcnt(0)
	v_or_b32_e32 v0, s0, v14
	v_readlane_b32 s15, v251, 11
	v_mov_b32_e32 v1, v97
	s_mov_b64 s[0:1], 0x1000
	v_lshl_add_u64 v[8:9], v[0:1], 2, s[14:15]
	v_or_b32_e32 v96, s34, v14
	v_readlane_b32 s16, v251, 12
	v_readlane_b32 s17, v251, 13
	v_lshl_add_u64 v[10:11], v[8:9], 0, s[0:1]
	s_mov_b64 s[0:1], 0x1800
	v_lshl_add_u64 v[2:3], v[96:97], 2, s[16:17]
	v_lshl_add_u64 v[12:13], v[8:9], 0, s[0:1]
	s_movk_i32 s0, 0x1000
	s_barrier
	global_load_dwordx4 v[4:7], v[2:3], off offset:16
	s_nop 0
	global_load_dwordx4 v[0:3], v[2:3], off
	s_nop 0
	global_load_dwordx4 v[44:47], v[8:9], off offset:16
	global_load_dwordx4 v[40:43], v[8:9], off
	global_load_dwordx4 v[36:39], v[8:9], off offset:2064
	global_load_dwordx4 v[32:35], v[8:9], off offset:2048
	v_add_co_u32_e32 v8, vcc, s0, v8
	s_add_i32 s0, s2, 0xfffffb80
	s_nop 0
	v_addc_co_u32_e32 v9, vcc, 0, v9, vcc
	global_load_dwordx4 v[24:27], v[8:9], off
	global_load_dwordx4 v[16:19], v[8:9], off offset:2048
	global_load_dwordx4 v[28:31], v[10:11], off offset:16
	global_load_dwordx4 v[20:23], v[12:13], off offset:16
	s_lshr_b32 s1, s0, 4
	s_mul_i32 s6, s1, 57
	s_bfe_u32 s6, s6, 0x6000a
	s_mul_i32 s6, s6, 18
	s_sub_i32 s1, s1, s6
	s_mul_i32 s0, s0, 0xe38f
	s_and_b32 s43, s1, 0xff
	s_lshr_b32 s45, s0, 24
	s_lshl_b32 s0, s45, 8
	s_lshl_b32 s38, s43, 7
	s_lshl_b32 s1, s45, 11
	s_addk_i32 s0, 0x4000
	s_add_i32 s39, s38, 0xffffff00
	s_cmp_lt_u32 s43, 2
	s_movk_i32 s6, 0x800
	s_cselect_b32 s38, s38, s39
	v_ashrrev_i32_e32 v52, 3, v51
	s_cselect_b32 s7, 0x100, s6
	s_cselect_b32 s6, s0, s1
	v_readlane_b32 s0, v249, 7
	v_add_u32_e32 v53, s38, v52
	v_lshlrev_b32_e32 v96, 1, v14
	v_readlane_b32 s1, v249, 8
	v_add_u32_e32 v54, -2, v53
	v_cmp_lt_i32_e32 vcc, 1, v53
	v_lshl_add_u64 v[48:49], s[0:1], 0, v[96:97]
	v_cmp_gt_u32_e64 s[0:1], s7, v54
	s_and_b64 s[40:41], vcc, s[0:1]
	v_readlane_b32 s9, v251, 5
	v_readlane_b32 s10, v251, 6
	v_readlane_b32 s11, v251, 7
	v_readlane_b32 s12, v251, 8
	v_readlane_b32 s13, v251, 9
	v_readlane_b32 s18, v251, 14
	v_readlane_b32 s19, v251, 15
	v_readlane_b32 s20, v251, 16
	v_readlane_b32 s21, v251, 17
	v_readlane_b32 s22, v251, 18
	v_readlane_b32 s23, v251, 19
	s_waitcnt vmcnt(8)
	v_mov_b64_e32 v[14:15], v[6:7]
	v_mov_b64_e32 v[12:13], v[4:5]
	v_mov_b64_e32 v[10:11], v[2:3]
	v_mov_b64_e32 v[8:9], v[0:1]
	v_mov_b32_e32 v206, 0
	v_mov_b32_e32 v207, 0
	v_mov_b32_e32 v208, 0
	v_mov_b32_e32 v209, 0
	s_and_saveexec_b64 s[0:1], s[40:41]
	s_cbranch_execz .Lrg1_i
	v_add_u32_e32 v8, s6, v54
	v_mad_u64_u32 v[8:9], s[40:41], v8, s74, v[48:49]
	global_load_dwordx4 v[206:209], v[8:9], off
.Lrg1_i:
	s_or_b64 exec, exec, s[0:1]
	v_cmp_lt_i32_e32 vcc, 0, v53
	v_cmp_ge_i32_e64 s[0:1], s7, v53
	s_and_b64 s[40:41], vcc, s[0:1]
	v_mov_b32_e32 v210, 0
	v_mov_b32_e32 v211, 0
	v_mov_b32_e32 v212, 0
	v_mov_b32_e32 v213, 0
	s_and_saveexec_b64 s[0:1], s[40:41]
	s_cbranch_execz .Lrg2_i
	v_add3_u32 v54, s6, -1, v53
	v_mad_u64_u32 v[54:55], s[40:41], v54, s74, v[48:49]
	global_load_dwordx4 v[210:213], v[54:55], off
.Lrg2_i:
	s_or_b64 exec, exec, s[0:1]
	s_mov_b32 s0, 0xeffffb00
	v_cmp_gt_u32_e32 vcc, s0, v53
	v_cmp_gt_i32_e64 s[0:1], s7, v53
	s_and_b64 s[40:41], vcc, s[0:1]
	v_mov_b32_e32 v214, 0
	v_mov_b32_e32 v215, 0
	v_mov_b32_e32 v216, 0
	v_mov_b32_e32 v217, 0
	s_and_saveexec_b64 s[0:1], s[40:41]
	s_cbranch_execz .Lrg3_i
	v_add_u32_e32 v54, s6, v53
	v_mad_u64_u32 v[54:55], s[40:41], v54, s74, v[48:49]
	global_load_dwordx4 v[214:217], v[54:55], off
.Lrg3_i:
	s_or_b64 exec, exec, s[0:1]
	v_add_u32_e32 v54, 1, v53
	v_cmp_lt_i32_e32 vcc, -2, v53
	v_cmp_gt_u32_e64 s[0:1], s7, v54
	s_and_b64 s[40:41], vcc, s[0:1]
	v_mov_b32_e32 v218, 0
	v_mov_b32_e32 v219, 0
	v_mov_b32_e32 v220, 0
	v_mov_b32_e32 v221, 0
	s_and_saveexec_b64 s[0:1], s[40:41]
	s_cbranch_execz .Lrg4_i
	v_add_u32_e32 v53, s6, v54
	v_mad_u64_u32 v[54:55], s[40:41], v53, s74, v[48:49]
	global_load_dwordx4 v[218:221], v[54:55], off
.Lrg4_i:
	s_or_b64 exec, exec, s[0:1]
	s_waitcnt vmcnt(0)
	v_mov_b32_e32 v8, v206
	v_mov_b32_e32 v9, v207
	v_mov_b32_e32 v10, v208
	v_mov_b32_e32 v11, v209
	v_lshlrev_b32_e32 v54, 16, v8
	v_and_b32_e32 v55, 0xffff0000, v8
	v_lshlrev_b32_e32 v8, 16, v9
	v_and_b32_e32 v9, 0xffff0000, v9
	v_lshlrev_b32_e32 v12, 16, v10
	v_and_b32_e32 v13, 0xffff0000, v10
	v_lshlrev_b32_e32 v10, 16, v11
	v_and_b32_e32 v11, 0xffff0000, v11
	v_pk_fma_f32 v[14:15], v[46:47], v[10:11], v[6:7]
	v_pk_fma_f32 v[12:13], v[44:45], v[12:13], v[4:5]
	v_pk_fma_f32 v[10:11], v[42:43], v[8:9], v[2:3]
	v_pk_fma_f32 v[8:9], v[40:41], v[54:55], v[0:1]
	v_mov_b32_e32 v54, v210
	v_mov_b32_e32 v55, v211
	v_mov_b32_e32 v56, v212
	v_mov_b32_e32 v57, v213
	v_lshlrev_b32_e32 v58, 16, v54
	v_and_b32_e32 v59, 0xffff0000, v54
	v_lshlrev_b32_e32 v54, 16, v55
	v_and_b32_e32 v55, 0xffff0000, v55
	v_lshlrev_b32_e32 v60, 16, v56
	v_and_b32_e32 v61, 0xffff0000, v56
	v_lshlrev_b32_e32 v56, 16, v57
	v_and_b32_e32 v57, 0xffff0000, v57
	v_pk_fma_f32 v[14:15], v[38:39], v[56:57], v[14:15]
	v_pk_fma_f32 v[12:13], v[36:37], v[60:61], v[12:13]
	v_pk_fma_f32 v[10:11], v[34:35], v[54:55], v[10:11]
	v_pk_fma_f32 v[8:9], v[32:33], v[58:59], v[8:9]
	v_mov_b32_e32 v54, v214
	v_mov_b32_e32 v55, v215
	v_mov_b32_e32 v56, v216
	v_mov_b32_e32 v57, v217
	v_lshlrev_b32_e32 v58, 16, v54
	v_and_b32_e32 v59, 0xffff0000, v54
	v_lshlrev_b32_e32 v54, 16, v55
	v_and_b32_e32 v55, 0xffff0000, v55
	v_lshlrev_b32_e32 v60, 16, v56
	v_and_b32_e32 v61, 0xffff0000, v56
	v_lshlrev_b32_e32 v56, 16, v57
	v_and_b32_e32 v57, 0xffff0000, v57
	v_pk_fma_f32 v[14:15], v[30:31], v[56:57], v[14:15]
	v_pk_fma_f32 v[12:13], v[28:29], v[60:61], v[12:13]
	v_pk_fma_f32 v[10:11], v[26:27], v[54:55], v[10:11]
	v_pk_fma_f32 v[8:9], v[24:25], v[58:59], v[8:9]
	v_mov_b32_e32 v54, v218
	v_mov_b32_e32 v55, v219
	v_mov_b32_e32 v56, v220
	v_mov_b32_e32 v57, v221
	v_lshlrev_b32_e32 v58, 16, v54
	v_and_b32_e32 v59, 0xffff0000, v54
	v_lshlrev_b32_e32 v54, 16, v55
	v_and_b32_e32 v55, 0xffff0000, v55
	v_lshlrev_b32_e32 v60, 16, v56
	v_and_b32_e32 v61, 0xffff0000, v56
	v_lshlrev_b32_e32 v56, 16, v57
	v_and_b32_e32 v57, 0xffff0000, v57
	v_pk_fma_f32 v[14:15], v[22:23], v[56:57], v[14:15]
	v_pk_fma_f32 v[12:13], v[20:21], v[60:61], v[12:13]
	v_pk_fma_f32 v[10:11], v[18:19], v[54:55], v[10:11]
	v_pk_fma_f32 v[8:9], v[16:17], v[58:59], v[8:9]
	v_lshl_add_u32 v53, v50, 2, 0
	v_lshl_add_u32 v54, v52, 8, v53
	v_lshlrev_b32_e32 v50, 1, v50
	ds_write_b128 v54, v[8:11] offset:36864
	ds_write_b128 v54, v[12:15] offset:36880
	v_add_u32_e32 v54, 32, v52
	v_sub_u32_e32 v50, v53, v50
	s_movk_i32 s0, 0x90
	v_add_u32_e32 v55, s38, v54
	v_cvt_pk_bf16_f32 v8, v8, v9
	v_cvt_pk_bf16_f32 v9, v10, v11
	v_cvt_pk_bf16_f32 v10, v12, v13
	v_cvt_pk_bf16_f32 v11, v14, v15
	v_mad_u64_u32 v[12:13], s[0:1], v52, s0, v[50:51]
	v_add_u32_e32 v56, -2, v55
	ds_write_b128 v12, v[8:11]
	v_cmp_lt_i32_e32 vcc, 1, v55
	v_cmp_gt_u32_e64 s[0:1], s7, v56
	v_mov_b64_e32 v[14:15], v[6:7]
	s_and_b64 s[40:41], vcc, s[0:1]
	v_mov_b64_e32 v[12:13], v[4:5]
	v_mov_b64_e32 v[10:11], v[2:3]
	v_mov_b64_e32 v[8:9], v[0:1]
	v_mov_b32_e32 v206, 0
	v_mov_b32_e32 v207, 0
	v_mov_b32_e32 v208, 0
	v_mov_b32_e32 v209, 0
	s_and_saveexec_b64 s[0:1], s[40:41]
	s_cbranch_execz .Lrg5_i
	v_add_u32_e32 v8, s6, v56
	v_mad_u64_u32 v[8:9], s[40:41], v8, s74, v[48:49]
	global_load_dwordx4 v[206:209], v[8:9], off
.Lrg5_i:
	s_or_b64 exec, exec, s[0:1]
	v_cmp_lt_i32_e32 vcc, 0, v55
	v_cmp_ge_i32_e64 s[0:1], s7, v55
	s_and_b64 s[40:41], vcc, s[0:1]
	v_mov_b32_e32 v210, 0
	v_mov_b32_e32 v211, 0
	v_mov_b32_e32 v212, 0
	v_mov_b32_e32 v213, 0
	s_and_saveexec_b64 s[0:1], s[40:41]
	s_cbranch_execz .Lrg6_i
	v_add3_u32 v56, s6, -1, v55
	v_mad_u64_u32 v[56:57], s[40:41], v56, s74, v[48:49]
	global_load_dwordx4 v[210:213], v[56:57], off
.Lrg6_i:
	s_or_b64 exec, exec, s[0:1]
	s_mov_b32 s0, 0xeffffb20
	v_cmp_gt_u32_e32 vcc, s0, v55
	v_cmp_gt_i32_e64 s[0:1], s7, v55
	s_and_b64 s[40:41], vcc, s[0:1]
	v_mov_b32_e32 v214, 0
	v_mov_b32_e32 v215, 0
	v_mov_b32_e32 v216, 0
	v_mov_b32_e32 v217, 0
	s_and_saveexec_b64 s[0:1], s[40:41]
	s_cbranch_execz .Lrg7_i
	v_add_u32_e32 v56, s6, v55
	v_mad_u64_u32 v[56:57], s[40:41], v56, s74, v[48:49]
	global_load_dwordx4 v[214:217], v[56:57], off
.Lrg7_i:
	s_or_b64 exec, exec, s[0:1]
	v_add_u32_e32 v56, 1, v55
	v_cmp_lt_i32_e32 vcc, -2, v55
	v_cmp_gt_u32_e64 s[0:1], s7, v56
	s_and_b64 s[40:41], vcc, s[0:1]
	v_mov_b32_e32 v218, 0
	v_mov_b32_e32 v219, 0
	v_mov_b32_e32 v220, 0
	v_mov_b32_e32 v221, 0
	s_and_saveexec_b64 s[0:1], s[40:41]
	s_cbranch_execz .Lrg8_i
	v_add_u32_e32 v55, s6, v56
	v_mad_u64_u32 v[56:57], s[40:41], v55, s74, v[48:49]
	global_load_dwordx4 v[218:221], v[56:57], off
.Lrg8_i:
	s_or_b64 exec, exec, s[0:1]
	s_waitcnt vmcnt(0)
	v_mov_b32_e32 v8, v206
	v_mov_b32_e32 v9, v207
	v_mov_b32_e32 v10, v208
	v_mov_b32_e32 v11, v209
	v_lshlrev_b32_e32 v56, 16, v8
	v_and_b32_e32 v57, 0xffff0000, v8
	v_lshlrev_b32_e32 v8, 16, v9
	v_and_b32_e32 v9, 0xffff0000, v9
	v_lshlrev_b32_e32 v12, 16, v10
	v_and_b32_e32 v13, 0xffff0000, v10
	v_lshlrev_b32_e32 v10, 16, v11
	v_and_b32_e32 v11, 0xffff0000, v11
	v_pk_fma_f32 v[14:15], v[46:47], v[10:11], v[6:7]
	v_pk_fma_f32 v[12:13], v[44:45], v[12:13], v[4:5]
	v_pk_fma_f32 v[10:11], v[42:43], v[8:9], v[2:3]
	v_pk_fma_f32 v[8:9], v[40:41], v[56:57], v[0:1]
	v_mov_b32_e32 v56, v210
	v_mov_b32_e32 v57, v211
	v_mov_b32_e32 v58, v212
	v_mov_b32_e32 v59, v213
	v_lshlrev_b32_e32 v60, 16, v56
	v_and_b32_e32 v61, 0xffff0000, v56
	v_lshlrev_b32_e32 v56, 16, v57
	v_and_b32_e32 v57, 0xffff0000, v57
	v_lshlrev_b32_e32 v62, 16, v58
	v_and_b32_e32 v63, 0xffff0000, v58
	v_lshlrev_b32_e32 v58, 16, v59
	v_and_b32_e32 v59, 0xffff0000, v59
	v_pk_fma_f32 v[14:15], v[38:39], v[58:59], v[14:15]
	v_pk_fma_f32 v[12:13], v[36:37], v[62:63], v[12:13]
	v_pk_fma_f32 v[10:11], v[34:35], v[56:57], v[10:11]
	v_pk_fma_f32 v[8:9], v[32:33], v[60:61], v[8:9]
	v_mov_b32_e32 v56, v214
	v_mov_b32_e32 v57, v215
	v_mov_b32_e32 v58, v216
	v_mov_b32_e32 v59, v217
	v_lshlrev_b32_e32 v60, 16, v56
	v_and_b32_e32 v61, 0xffff0000, v56
	v_lshlrev_b32_e32 v56, 16, v57
	v_and_b32_e32 v57, 0xffff0000, v57
	v_lshlrev_b32_e32 v62, 16, v58
	v_and_b32_e32 v63, 0xffff0000, v58
	v_lshlrev_b32_e32 v58, 16, v59
	v_and_b32_e32 v59, 0xffff0000, v59
	v_pk_fma_f32 v[14:15], v[30:31], v[58:59], v[14:15]
	v_pk_fma_f32 v[12:13], v[28:29], v[62:63], v[12:13]
	v_pk_fma_f32 v[10:11], v[26:27], v[56:57], v[10:11]
	v_pk_fma_f32 v[8:9], v[24:25], v[60:61], v[8:9]
	v_mov_b32_e32 v56, v218
	v_mov_b32_e32 v57, v219
	v_mov_b32_e32 v58, v220
	v_mov_b32_e32 v59, v221
	v_lshlrev_b32_e32 v60, 16, v56
	v_and_b32_e32 v61, 0xffff0000, v56
	v_lshlrev_b32_e32 v56, 16, v57
	v_and_b32_e32 v57, 0xffff0000, v57
	v_lshlrev_b32_e32 v62, 16, v58
	v_and_b32_e32 v63, 0xffff0000, v58
	v_lshlrev_b32_e32 v58, 16, v59
	v_and_b32_e32 v59, 0xffff0000, v59
	v_pk_fma_f32 v[14:15], v[22:23], v[58:59], v[14:15]
	v_pk_fma_f32 v[12:13], v[20:21], v[62:63], v[12:13]
	v_pk_fma_f32 v[10:11], v[18:19], v[56:57], v[10:11]
	v_pk_fma_f32 v[8:9], v[16:17], v[60:61], v[8:9]
	v_lshl_add_u32 v55, v54, 8, v53
	s_movk_i32 s0, 0x90
	ds_write_b128 v55, v[8:11] offset:36864
	ds_write_b128 v55, v[12:15] offset:36880
	v_cvt_pk_bf16_f32 v8, v8, v9
	v_cvt_pk_bf16_f32 v9, v10, v11
	v_cvt_pk_bf16_f32 v10, v12, v13
	v_mad_u64_u32 v[12:13], s[0:1], v54, s0, v[50:51]
	v_add_u32_e32 v54, 64, v52
	v_add_u32_e32 v55, s38, v54
	v_cvt_pk_bf16_f32 v11, v14, v15
	v_add_u32_e32 v56, -2, v55
	ds_write_b128 v12, v[8:11]
	v_cmp_lt_i32_e32 vcc, 1, v55
	v_cmp_gt_u32_e64 s[0:1], s7, v56
	v_mov_b64_e32 v[14:15], v[6:7]
	s_and_b64 s[40:41], vcc, s[0:1]
	v_mov_b64_e32 v[12:13], v[4:5]
	v_mov_b64_e32 v[10:11], v[2:3]
	v_mov_b64_e32 v[8:9], v[0:1]
	v_mov_b32_e32 v206, 0
	v_mov_b32_e32 v207, 0
	v_mov_b32_e32 v208, 0
	v_mov_b32_e32 v209, 0
	s_and_saveexec_b64 s[0:1], s[40:41]
	s_cbranch_execz .Lrg9_i
	v_add_u32_e32 v8, s6, v56
	v_mad_u64_u32 v[8:9], s[40:41], v8, s74, v[48:49]
	global_load_dwordx4 v[206:209], v[8:9], off

.Lrg10_i:
	s_or_b64 exec, exec, s[0:1]
	s_mov_b32 s0, 0xeffffb40
	v_cmp_gt_u32_e32 vcc, s0, v55
	v_cmp_gt_i32_e64 s[0:1], s7, v55
	s_and_b64 s[40:41], vcc, s[0:1]
	v_mov_b32_e32 v214, 0
	v_mov_b32_e32 v215, 0
	v_mov_b32_e32 v216, 0
	v_mov_b32_e32 v217, 0
	s_and_saveexec_b64 s[0:1], s[40:41]
	s_cbranch_execz .Lrg11_i
	v_add_u32_e32 v56, s6, v55
	v_mad_u64_u32 v[56:57], s[40:41], v56, s74, v[48:49]
	global_load_dwordx4 v[214:217], v[56:57], off

.Lrg12_i:
	s_or_b64 exec, exec, s[0:1]
	s_waitcnt vmcnt(0)
	v_mov_b32_e32 v8, v206
	v_mov_b32_e32 v9, v207
	v_mov_b32_e32 v10, v208
	v_mov_b32_e32 v11, v209
	v_lshlrev_b32_e32 v56, 16, v8
	v_and_b32_e32 v57, 0xffff0000, v8
	v_lshlrev_b32_e32 v8, 16, v9
	v_and_b32_e32 v9, 0xffff0000, v9
	v_lshlrev_b32_e32 v12, 16, v10
	v_and_b32_e32 v13, 0xffff0000, v10
	v_lshlrev_b32_e32 v10, 16, v11
	v_and_b32_e32 v11, 0xffff0000, v11
	v_pk_fma_f32 v[14:15], v[46:47], v[10:11], v[6:7]
	v_pk_fma_f32 v[12:13], v[44:45], v[12:13], v[4:5]
	v_pk_fma_f32 v[10:11], v[42:43], v[8:9], v[2:3]
	v_pk_fma_f32 v[8:9], v[40:41], v[56:57], v[0:1]
	v_mov_b32_e32 v56, v210
	v_mov_b32_e32 v57, v211
	v_mov_b32_e32 v58, v212
	v_mov_b32_e32 v59, v213
	v_lshlrev_b32_e32 v60, 16, v56
	v_and_b32_e32 v61, 0xffff0000, v56
	v_lshlrev_b32_e32 v56, 16, v57
	v_and_b32_e32 v57, 0xffff0000, v57
	v_lshlrev_b32_e32 v62, 16, v58
	v_and_b32_e32 v63, 0xffff0000, v58
	v_lshlrev_b32_e32 v58, 16, v59
	v_and_b32_e32 v59, 0xffff0000, v59
	v_pk_fma_f32 v[14:15], v[38:39], v[58:59], v[14:15]
	v_pk_fma_f32 v[12:13], v[36:37], v[62:63], v[12:13]
	v_pk_fma_f32 v[10:11], v[34:35], v[56:57], v[10:11]
	v_pk_fma_f32 v[8:9], v[32:33], v[60:61], v[8:9]
	v_mov_b32_e32 v56, v214
	v_mov_b32_e32 v57, v215
	v_mov_b32_e32 v58, v216
	v_mov_b32_e32 v59, v217
	v_lshlrev_b32_e32 v60, 16, v56
	v_and_b32_e32 v61, 0xffff0000, v56
	v_lshlrev_b32_e32 v56, 16, v57
	v_and_b32_e32 v57, 0xffff0000, v57
	v_lshlrev_b32_e32 v62, 16, v58
	v_and_b32_e32 v63, 0xffff0000, v58
	v_lshlrev_b32_e32 v58, 16, v59
	v_and_b32_e32 v59, 0xffff0000, v59
	v_pk_fma_f32 v[14:15], v[30:31], v[58:59], v[14:15]
	v_pk_fma_f32 v[12:13], v[28:29], v[62:63], v[12:13]
	v_pk_fma_f32 v[10:11], v[26:27], v[56:57], v[10:11]
	v_pk_fma_f32 v[8:9], v[24:25], v[60:61], v[8:9]
	v_mov_b32_e32 v56, v218
	v_mov_b32_e32 v57, v219
	v_mov_b32_e32 v58, v220
	v_mov_b32_e32 v59, v221
	v_lshlrev_b32_e32 v60, 16, v56
	v_and_b32_e32 v61, 0xffff0000, v56
	v_lshlrev_b32_e32 v56, 16, v57
	v_and_b32_e32 v57, 0xffff0000, v57
	v_lshlrev_b32_e32 v62, 16, v58
	v_and_b32_e32 v63, 0xffff0000, v58
	v_lshlrev_b32_e32 v58, 16, v59
	v_and_b32_e32 v59, 0xffff0000, v59
	v_pk_fma_f32 v[14:15], v[22:23], v[58:59], v[14:15]
	v_pk_fma_f32 v[12:13], v[20:21], v[62:63], v[12:13]
	v_pk_fma_f32 v[10:11], v[18:19], v[56:57], v[10:11]
	v_pk_fma_f32 v[8:9], v[16:17], v[60:61], v[8:9]
	v_lshl_add_u32 v55, v54, 8, v53
	s_movk_i32 s0, 0x90
	ds_write_b128 v55, v[8:11] offset:36864
	ds_write_b128 v55, v[12:15] offset:36880
	v_cvt_pk_bf16_f32 v8, v8, v9
	v_cvt_pk_bf16_f32 v9, v10, v11
	v_cvt_pk_bf16_f32 v10, v12, v13
	v_cvt_pk_bf16_f32 v11, v14, v15
	v_mad_u64_u32 v[12:13], s[0:1], v54, s0, v[50:51]
	ds_write_b128 v12, v[8:11]
	v_add_u32_e32 v8, 0x60, v52
	v_add_u32_e32 v9, s38, v8
	v_add_u32_e32 v10, -2, v9
	v_cmp_lt_i32_e32 vcc, 1, v9
	v_cmp_gt_u32_e64 s[0:1], s7, v10
	s_and_b64 s[38:39], vcc, s[0:1]
	v_mov_b32_e32 v206, 0
	v_mov_b32_e32 v207, 0
	v_mov_b32_e32 v208, 0
	v_mov_b32_e32 v209, 0
	s_and_saveexec_b64 s[0:1], s[38:39]
	s_cbranch_execz .Lrg13_i
	v_add_u32_e32 v10, s6, v10
	v_mad_u64_u32 v[10:11], s[38:39], v10, s74, v[48:49]
	global_load_dwordx4 v[206:209], v[10:11], off
.Lrg13_i:
	s_or_b64 exec, exec, s[0:1]
	v_cmp_lt_i32_e32 vcc, 0, v9
	v_cmp_ge_i32_e64 s[0:1], s7, v9
	s_and_b64 s[38:39], vcc, s[0:1]
	v_mov_b32_e32 v210, 0
	v_mov_b32_e32 v211, 0
	v_mov_b32_e32 v212, 0
	v_mov_b32_e32 v213, 0
	s_and_saveexec_b64 s[0:1], s[38:39]
	s_cbranch_execz .Lrg14_i
	v_add3_u32 v10, s6, -1, v9
	v_mad_u64_u32 v[10:11], s[38:39], v10, s74, v[48:49]
	global_load_dwordx4 v[210:213], v[10:11], off
.Lrg14_i:
	s_or_b64 exec, exec, s[0:1]
	s_mov_b32 s0, 0xeffffb60
	v_cmp_gt_u32_e32 vcc, s0, v9
	v_cmp_gt_i32_e64 s[0:1], s7, v9
	s_and_b64 s[38:39], vcc, s[0:1]
	v_mov_b32_e32 v214, 0
	v_mov_b32_e32 v215, 0
	v_mov_b32_e32 v216, 0
	v_mov_b32_e32 v217, 0
	s_and_saveexec_b64 s[0:1], s[38:39]
	s_cbranch_execz .Lrg15_i
	v_add_u32_e32 v10, s6, v9
	v_mad_u64_u32 v[10:11], s[38:39], v10, s74, v[48:49]
	global_load_dwordx4 v[214:217], v[10:11], off
.Lrg15_i:
	s_or_b64 exec, exec, s[0:1]
	v_add_u32_e32 v10, 1, v9
	v_cmp_lt_i32_e32 vcc, -2, v9
	v_cmp_gt_u32_e64 s[0:1], s7, v10
	s_and_b64 s[38:39], vcc, s[0:1]
	v_mov_b32_e32 v218, 0
	v_mov_b32_e32 v219, 0
	v_mov_b32_e32 v220, 0
	v_mov_b32_e32 v221, 0
	s_and_saveexec_b64 s[0:1], s[38:39]
	s_cbranch_execz .Lrg16_i
	v_add_u32_e32 v9, s6, v10
	v_mad_u64_u32 v[10:11], s[6:7], v9, s74, v[48:49]
	global_load_dwordx4 v[218:221], v[10:11], off
.Lrg16_i:
	s_or_b64 exec, exec, s[0:1]
	s_waitcnt vmcnt(0)
	v_mov_b32_e32 v10, v206
	v_mov_b32_e32 v11, v207
	v_mov_b32_e32 v12, v208
	v_mov_b32_e32 v13, v209
	v_lshlrev_b32_e32 v14, 16, v10
	v_and_b32_e32 v15, 0xffff0000, v10
	v_lshlrev_b32_e32 v10, 16, v11
	v_and_b32_e32 v11, 0xffff0000, v11
	v_lshlrev_b32_e32 v54, 16, v12
	v_and_b32_e32 v55, 0xffff0000, v12
	v_lshlrev_b32_e32 v12, 16, v13
	v_and_b32_e32 v13, 0xffff0000, v13
	v_pk_fma_f32 v[6:7], v[46:47], v[12:13], v[6:7]
	v_pk_fma_f32 v[4:5], v[44:45], v[54:55], v[4:5]
	v_pk_fma_f32 v[2:3], v[42:43], v[10:11], v[2:3]
	v_pk_fma_f32 v[0:1], v[40:41], v[14:15], v[0:1]
	v_mov_b32_e32 v10, v210
	v_mov_b32_e32 v11, v211
	v_mov_b32_e32 v12, v212
	v_mov_b32_e32 v13, v213
	v_lshlrev_b32_e32 v14, 16, v10
	v_and_b32_e32 v15, 0xffff0000, v10
	v_lshlrev_b32_e32 v10, 16, v11
	v_and_b32_e32 v11, 0xffff0000, v11
	v_lshlrev_b32_e32 v40, 16, v12
	v_and_b32_e32 v41, 0xffff0000, v12
	v_lshlrev_b32_e32 v12, 16, v13
	v_and_b32_e32 v13, 0xffff0000, v13
	v_pk_fma_f32 v[6:7], v[38:39], v[12:13], v[6:7]
	v_pk_fma_f32 v[4:5], v[36:37], v[40:41], v[4:5]
	v_pk_fma_f32 v[2:3], v[34:35], v[10:11], v[2:3]
	v_pk_fma_f32 v[0:1], v[32:33], v[14:15], v[0:1]
	v_mov_b32_e32 v10, v214
	v_mov_b32_e32 v11, v215
	v_mov_b32_e32 v12, v216
	v_mov_b32_e32 v13, v217
	v_lshlrev_b32_e32 v14, 16, v10
	v_and_b32_e32 v15, 0xffff0000, v10
	v_lshlrev_b32_e32 v10, 16, v11
	v_and_b32_e32 v11, 0xffff0000, v11
	v_lshlrev_b32_e32 v32, 16, v12
	v_and_b32_e32 v33, 0xffff0000, v12
	v_lshlrev_b32_e32 v12, 16, v13
	v_and_b32_e32 v13, 0xffff0000, v13
	v_pk_fma_f32 v[6:7], v[30:31], v[12:13], v[6:7]
	v_pk_fma_f32 v[4:5], v[28:29], v[32:33], v[4:5]
	v_pk_fma_f32 v[2:3], v[26:27], v[10:11], v[2:3]
	v_pk_fma_f32 v[0:1], v[24:25], v[14:15], v[0:1]
	v_mov_b32_e32 v10, v218
	v_mov_b32_e32 v11, v219
	v_mov_b32_e32 v12, v220
	v_mov_b32_e32 v13, v221
	v_lshlrev_b32_e32 v14, 16, v10
	v_and_b32_e32 v15, 0xffff0000, v10
	v_lshlrev_b32_e32 v10, 16, v11
	v_and_b32_e32 v11, 0xffff0000, v11
	v_lshlrev_b32_e32 v24, 16, v12
	v_and_b32_e32 v25, 0xffff0000, v12
	v_lshlrev_b32_e32 v12, 16, v13
	v_and_b32_e32 v13, 0xffff0000, v13
	v_pk_fma_f32 v[6:7], v[22:23], v[12:13], v[6:7]
	v_pk_fma_f32 v[4:5], v[20:21], v[24:25], v[4:5]
	v_pk_fma_f32 v[2:3], v[18:19], v[10:11], v[2:3]
	v_pk_fma_f32 v[0:1], v[16:17], v[14:15], v[0:1]
	s_and_b32 s38, s2, 1
	v_lshl_add_u32 v10, v8, 8, v53
	s_movk_i32 s0, 0x90
	ds_write_b128 v10, v[0:3] offset:36864
	ds_write_b128 v10, v[4:7] offset:36880
	v_cvt_pk_bf16_f32 v0, v0, v1
	v_cvt_pk_bf16_f32 v1, v2, v3
	v_cvt_pk_bf16_f32 v2, v4, v5
	v_mad_u64_u32 v[4:5], s[0:1], v8, s0, v[50:51]
	s_or_b32 s39, s38, s46
	s_lshl_b32 s0, s39, 15
	s_lshl_b32 s1, s4, 12
	s_or_b32 s4, s0, s1
	v_readlane_b32 s8, v251, 4
	s_lshl_b64 s[6:7], s[4:5], 2
	v_readlane_b32 s18, v251, 14
	v_readlane_b32 s19, v251, 15
	s_add_u32 s0, s18, s6
	v_readlane_b32 s22, v251, 18
	s_addc_u32 s1, s19, s7
	v_and_b32_e32 v9, 63, v51
	v_cvt_pk_bf16_f32 v3, v6, v7
	v_ashrrev_i32_e32 v64, 6, v51
	v_readlane_b32 s23, v251, 19
	s_add_u32 s6, s22, s6
	ds_write_b128 v4, v[0:3]
	s_addc_u32 s7, s23, s7
	v_mul_u32_u24_e32 v1, 0x90, v9
	v_lshlrev_b32_e32 v2, 2, v64
	s_add_i32 s4, 0, 0x4800
	v_lshl_or_b32 v0, v64, 7, v9
	v_add3_u32 v1, v1, v2, s4
	s_mov_b32 s4, 0
	v_readlane_b32 s9, v251, 5
	v_readlane_b32 s10, v251, 6
	v_readlane_b32 s11, v251, 7
	v_readlane_b32 s12, v251, 8
	v_readlane_b32 s13, v251, 9
	v_readlane_b32 s14, v251, 10
	v_readlane_b32 s15, v251, 11
	v_readlane_b32 s16, v251, 12
	v_readlane_b32 s17, v251, 13
	v_readlane_b32 s20, v251, 16
	v_readlane_b32 s21, v251, 17
.LBB0_578:
	v_add_u32_e32 v2, s4, v0
	s_addk_i32 s4, 0x800
	v_mov_b32_e32 v222, v2
	v_ashrrev_i32_e32 v223, 31, v222
	v_lshlrev_b64 v[222:223], 2, v[222:223]
	v_lshl_add_u64 v[224:225], s[0:1], 0, v[222:223]
	global_load_dword v206, v[224:225], off
	global_load_dword v207, v[224:225], off offset:256
	v_lshl_add_u64 v[224:225], s[6:7], 0, v[222:223]
	global_load_dword v208, v[224:225], off
	global_load_dword v209, v[224:225], off offset:256
	v_add_u32_e32 v222, 0x200, v2
	v_ashrrev_i32_e32 v223, 31, v222
	v_lshlrev_b64 v[222:223], 2, v[222:223]
	v_lshl_add_u64 v[224:225], s[0:1], 0, v[222:223]
	global_load_dword v210, v[224:225], off
	global_load_dword v211, v[224:225], off offset:256
	v_lshl_add_u64 v[224:225], s[6:7], 0, v[222:223]
	global_load_dword v212, v[224:225], off
	global_load_dword v213, v[224:225], off offset:256
	v_add_u32_e32 v222, 0x400, v2
	v_ashrrev_i32_e32 v223, 31, v222
	v_lshlrev_b64 v[222:223], 2, v[222:223]
	v_lshl_add_u64 v[224:225], s[0:1], 0, v[222:223]
	global_load_dword v214, v[224:225], off
	global_load_dword v215, v[224:225], off offset:256
	v_lshl_add_u64 v[224:225], s[6:7], 0, v[222:223]
	global_load_dword v216, v[224:225], off
	global_load_dword v217, v[224:225], off offset:256
	v_add_u32_e32 v222, 0x600, v2
	v_ashrrev_i32_e32 v223, 31, v222
	v_lshlrev_b64 v[222:223], 2, v[222:223]
	v_lshl_add_u64 v[224:225], s[0:1], 0, v[222:223]
	global_load_dword v218, v[224:225], off
	global_load_dword v219, v[224:225], off offset:256
	v_lshl_add_u64 v[224:225], s[6:7], 0, v[222:223]
	global_load_dword v220, v[224:225], off
	global_load_dword v221, v[224:225], off offset:256
	v_add_u32_e32 v9, 0x2400, v1
	s_waitcnt vmcnt(0)
	v_cvt_pk_bf16_f32 v226, v206, v207
	v_cvt_pk_bf16_f32 v230, v208, v209
	v_cvt_pk_bf16_f32 v227, v210, v211
	v_cvt_pk_bf16_f32 v231, v212, v213
	v_cvt_pk_bf16_f32 v228, v214, v215
	v_cvt_pk_bf16_f32 v232, v216, v217
	v_cvt_pk_bf16_f32 v229, v218, v219
	v_cvt_pk_bf16_f32 v233, v220, v221
	ds_write2_b32 v1, v226, v227 offset1:4
	ds_write2_b32 v9, v230, v231 offset1:4
	ds_write2_b32 v1, v228, v229 offset0:8 offset1:12
	ds_write2_b32 v9, v232, v233 offset0:8 offset1:12
	v_add_u32_e32 v1, 64, v1
	s_cmpk_eq_i32 s4, 0x1000
	s_cbranch_scc0 .LBB0_578
	v_and_b32_e32 v71, 31, v51
	v_mul_u32_u24_e32 v0, 0x48, v71
	v_lshrrev_b32_e32 v1, 1, v51
	v_lshlrev_b32_e32 v0, 1, v0
	v_and_b32_e32 v1, 16, v1
	s_movk_i32 s0, 0x1200
	v_add3_u32 v67, 0, v0, v1
	v_mov_b32_e32 v0, 0
	v_mul_lo_u32 v65, v64, s0
	s_mov_b32 s0, -16
	v_mov_b32_e32 v1, v0
	v_mov_b32_e32 v2, v0
	v_mov_b32_e32 v3, v0
	v_mov_b32_e32 v4, v0
	v_mov_b32_e32 v5, v0
	v_mov_b32_e32 v6, v0
	v_mov_b32_e32 v7, v0
	v_mov_b32_e32 v8, v0
	v_mov_b32_e32 v9, v0
	v_mov_b32_e32 v10, v0
	v_mov_b32_e32 v11, v0
	v_mov_b32_e32 v12, v0
	v_mov_b32_e32 v13, v0
	v_mov_b32_e32 v14, v0
	v_mov_b32_e32 v15, v0
	v_mov_b32_e32 v32, v0
	v_mov_b32_e32 v33, v0
	v_mov_b32_e32 v34, v0
	v_mov_b32_e32 v35, v0
	v_mov_b32_e32 v36, v0
	v_mov_b32_e32 v37, v0
	v_mov_b32_e32 v38, v0
	v_mov_b32_e32 v39, v0
	v_mov_b32_e32 v40, v0
	v_mov_b32_e32 v41, v0
	v_mov_b32_e32 v42, v0
	v_mov_b32_e32 v43, v0
	v_mov_b32_e32 v44, v0
	v_mov_b32_e32 v45, v0
	v_mov_b32_e32 v46, v0
	v_mov_b32_e32 v47, v0
	v_mov_b32_e32 v16, v0
	v_mov_b32_e32 v17, v0
	v_mov_b32_e32 v18, v0
	v_mov_b32_e32 v19, v0
	v_mov_b32_e32 v20, v0
	v_mov_b32_e32 v21, v0
	v_mov_b32_e32 v22, v0
	v_mov_b32_e32 v23, v0
	v_mov_b32_e32 v24, v0
	v_mov_b32_e32 v25, v0
	v_mov_b32_e32 v26, v0
	v_mov_b32_e32 v27, v0
	v_mov_b32_e32 v28, v0
	v_mov_b32_e32 v29, v0
	v_mov_b32_e32 v30, v0
	v_mov_b32_e32 v31, v0
	v_mov_b32_e32 v48, v0
	v_mov_b32_e32 v49, v0
	v_mov_b32_e32 v50, v0
	v_mov_b32_e32 v51, v0
	v_mov_b32_e32 v52, v0
	v_mov_b32_e32 v53, v0
	v_mov_b32_e32 v54, v0
	v_mov_b32_e32 v55, v0
	v_mov_b32_e32 v56, v0
	v_mov_b32_e32 v57, v0
	v_mov_b32_e32 v58, v0
	v_mov_b32_e32 v59, v0
	v_mov_b32_e32 v60, v0
	v_mov_b32_e32 v61, v0
	v_mov_b32_e32 v62, v0
	v_mov_b32_e32 v63, v0
	s_waitcnt lgkmcnt(0)
	s_barrier

.LBB0_636:
	s_waitcnt vmcnt(3)
	v_add_u32_e32 v82, v69, v67
	ds_read_b128 v[70:73], v69 offset:34816
	ds_read_b128 v[74:77], v82
	s_add_i32 s0, s0, 32
	s_cmpk_lt_u32 s0, 0x70
	s_waitcnt lgkmcnt(0)
	v_mfma_f32_32x32x16_bf16 v[48:63], v[74:77], v[70:73], v[48:63]
	ds_read_b128 v[70:73], v69 offset:43520
	s_waitcnt lgkmcnt(0)
	v_mfma_f32_32x32x16_bf16 v[32:47], v[74:77], v[70:73], v[32:47]
	ds_read_b128 v[70:73], v69 offset:52224
	s_waitcnt lgkmcnt(0)
	v_mfma_f32_32x32x16_bf16 v[16:31], v[74:77], v[70:73], v[16:31]
	ds_read_b128 v[70:73], v69 offset:60928
	ds_read_b128 v[78:81], v69 offset:34848
	s_waitcnt lgkmcnt(1)
	v_mfma_f32_32x32x16_bf16 v[0:15], v[74:77], v[70:73], v[0:15]
	ds_read_b128 v[70:73], v82 offset:32
	ds_read_b128 v[74:77], v69 offset:43552
	s_waitcnt lgkmcnt(0)
	v_mfma_f32_32x32x16_bf16 v[32:47], v[70:73], v[74:77], v[32:47]
	ds_read_b128 v[74:77], v69 offset:52256
	s_waitcnt lgkmcnt(0)
	v_mfma_f32_32x32x16_bf16 v[16:31], v[70:73], v[74:77], v[16:31]
	ds_read_b128 v[74:77], v69 offset:60960
	v_add_u32_e32 v69, 64, v69
	v_mfma_f32_32x32x16_bf16 v[48:63], v[70:73], v[78:81], v[48:63]
	s_waitcnt lgkmcnt(0)
	v_mfma_f32_32x32x16_bf16 v[0:15], v[70:73], v[74:77], v[0:15]
	s_cbranch_scc1 .LBB0_636
	v_lshrrev_b32_e32 v67, 3, v65
	s_ashr_i32 s3, s2, 31
	v_and_or_b32 v66, v67, 4, v66
	s_lshl_b64 s[0:1], s[2:3], 16
	v_lshlrev_b32_e32 v69, 7, v66
	s_add_u32 s0, s56, s0
	v_or_b32_e32 v66, v69, v68
	s_addc_u32 s1, s57, s1
	v_ashrrev_i32_e32 v67, 31, v66
	v_mul_f32_e32 v48, 0x3db504f3, v48
	v_lshl_add_u64 v[70:71], v[66:67], 2, s[0:1]
	v_ashrrev_i32_e32 v67, 31, v69
	global_store_dword v[70:71], v48, off
	v_mul_f32_e32 v70, 0x3db504f3, v49
	v_lshl_add_u64 v[48:49], v[66:67], 2, s[0:1]
	v_mul_f32_e32 v50, 0x3db504f3, v50
	global_store_dword v[48:49], v70, off offset:512
	global_store_dword v[48:49], v50, off offset:1024
	v_mul_f32_e32 v50, 0x3db504f3, v51
	v_or_b32_e32 v70, 0x400, v69
	global_store_dword v[48:49], v50, off offset:1536
	v_or_b32_e32 v50, v70, v68
	v_ashrrev_i32_e32 v51, 31, v50
	v_mul_f32_e32 v52, 0x3db504f3, v52
	v_lshl_add_u64 v[50:51], v[50:51], 2, s[0:1]
	global_store_dword v[50:51], v52, off
	v_mul_f32_e32 v52, 0x3db504f3, v53
	v_or_b32_e32 v53, 0x480, v69
	v_or_b32_e32 v50, v53, v68
	v_ashrrev_i32_e32 v51, 31, v50
	v_lshl_add_u64 v[50:51], v[50:51], 2, s[0:1]
	global_store_dword v[50:51], v52, off
	v_mul_f32_e32 v52, 0x3db504f3, v54
	v_or_b32_e32 v54, 0x500, v69
	v_or_b32_e32 v50, v54, v68
	v_ashrrev_i32_e32 v51, 31, v50
	v_lshl_add_u64 v[50:51], v[50:51], 2, s[0:1]
	global_store_dword v[50:51], v52, off
	v_mul_f32_e32 v52, 0x3db504f3, v55
	v_or_b32_e32 v55, 0x580, v69
	v_or_b32_e32 v50, v55, v68
	v_ashrrev_i32_e32 v51, 31, v50
	v_lshl_add_u64 v[50:51], v[50:51], 2, s[0:1]
	global_store_dword v[50:51], v52, off
	v_mul_f32_e32 v52, 0x3db504f3, v56
	v_or_b32_e32 v56, 0x800, v69
	v_or_b32_e32 v50, v56, v68
	v_ashrrev_i32_e32 v51, 31, v50
	v_lshl_add_u64 v[50:51], v[50:51], 2, s[0:1]
	global_store_dword v[50:51], v52, off
	v_mul_f32_e32 v52, 0x3db504f3, v57
	v_or_b32_e32 v57, 0x880, v69
	v_or_b32_e32 v50, v57, v68
	v_ashrrev_i32_e32 v51, 31, v50
	v_lshl_add_u64 v[50:51], v[50:51], 2, s[0:1]
	global_store_dword v[50:51], v52, off
	v_mul_f32_e32 v52, 0x3db504f3, v58
	v_or_b32_e32 v58, 0x900, v69
	v_or_b32_e32 v50, v58, v68
	v_ashrrev_i32_e32 v51, 31, v50
	v_lshl_add_u64 v[50:51], v[50:51], 2, s[0:1]
	global_store_dword v[50:51], v52, off
	v_mul_f32_e32 v52, 0x3db504f3, v59
	v_or_b32_e32 v59, 0x980, v69
	v_or_b32_e32 v50, v59, v68
	v_ashrrev_i32_e32 v51, 31, v50
	v_lshl_add_u64 v[50:51], v[50:51], 2, s[0:1]
	global_store_dword v[50:51], v52, off
	v_mul_f32_e32 v52, 0x3db504f3, v60
	v_or_b32_e32 v60, 0xc00, v69
	v_or_b32_e32 v50, v60, v68
	v_ashrrev_i32_e32 v51, 31, v50
	v_lshl_add_u64 v[50:51], v[50:51], 2, s[0:1]
	global_store_dword v[50:51], v52, off
	v_mul_f32_e32 v52, 0x3db504f3, v61
	v_or_b32_e32 v61, 0xc80, v69
	v_or_b32_e32 v50, v61, v68
	v_ashrrev_i32_e32 v51, 31, v50
	v_lshl_add_u64 v[50:51], v[50:51], 2, s[0:1]
	global_store_dword v[50:51], v52, off
	v_mul_f32_e32 v52, 0x3db504f3, v62
	v_or_b32_e32 v62, 0xd00, v69
	v_or_b32_e32 v50, v62, v68
	v_ashrrev_i32_e32 v51, 31, v50
	v_lshl_add_u64 v[50:51], v[50:51], 2, s[0:1]
	global_store_dword v[50:51], v52, off
	v_mul_f32_e32 v52, 0x3db504f3, v63
	v_or_b32_e32 v63, 0xd80, v69
	v_or_b32_e32 v50, v63, v68
	v_ashrrev_i32_e32 v51, 31, v50
	v_lshl_add_u64 v[50:51], v[50:51], 2, s[0:1]
	global_store_dword v[50:51], v52, off
	v_or_b32_e32 v50, 32, v68
	v_mul_f32_e32 v32, 0x3db504f3, v32
	v_or_b32_e32 v66, v69, v50
	global_store_dword v[48:49], v32, off offset:128
	v_mul_f32_e32 v51, 0x3db504f3, v33
	v_lshl_add_u64 v[32:33], v[66:67], 2, s[0:1]
	v_mul_f32_e32 v34, 0x3db504f3, v34
	global_store_dword v[32:33], v34, off offset:1024
	v_mul_f32_e32 v34, 0x3db504f3, v35
	global_store_dword v[32:33], v51, off offset:512
	global_store_dword v[32:33], v34, off offset:1536
	v_or_b32_e32 v32, v70, v50
	v_ashrrev_i32_e32 v33, 31, v32
	v_mul_f32_e32 v34, 0x3db504f3, v36
	v_lshl_add_u64 v[32:33], v[32:33], 2, s[0:1]
	global_store_dword v[32:33], v34, off
	v_or_b32_e32 v32, v53, v50
	v_ashrrev_i32_e32 v33, 31, v32
	v_mul_f32_e32 v34, 0x3db504f3, v37
	v_lshl_add_u64 v[32:33], v[32:33], 2, s[0:1]
	global_store_dword v[32:33], v34, off
	v_or_b32_e32 v32, v54, v50
	v_ashrrev_i32_e32 v33, 31, v32
	v_mul_f32_e32 v34, 0x3db504f3, v38
	v_lshl_add_u64 v[32:33], v[32:33], 2, s[0:1]
	global_store_dword v[32:33], v34, off
	v_or_b32_e32 v32, v55, v50
	v_ashrrev_i32_e32 v33, 31, v32
	v_mul_f32_e32 v34, 0x3db504f3, v39
	v_lshl_add_u64 v[32:33], v[32:33], 2, s[0:1]
	global_store_dword v[32:33], v34, off
	v_or_b32_e32 v32, v56, v50
	v_ashrrev_i32_e32 v33, 31, v32
	v_mul_f32_e32 v34, 0x3db504f3, v40
	v_lshl_add_u64 v[32:33], v[32:33], 2, s[0:1]
	global_store_dword v[32:33], v34, off
	v_or_b32_e32 v32, v57, v50
	v_ashrrev_i32_e32 v33, 31, v32
	v_mul_f32_e32 v34, 0x3db504f3, v41
	v_lshl_add_u64 v[32:33], v[32:33], 2, s[0:1]
	global_store_dword v[32:33], v34, off
	v_or_b32_e32 v32, v58, v50
	v_ashrrev_i32_e32 v33, 31, v32
	v_mul_f32_e32 v34, 0x3db504f3, v42
	v_lshl_add_u64 v[32:33], v[32:33], 2, s[0:1]
	global_store_dword v[32:33], v34, off
	v_or_b32_e32 v32, v59, v50
	v_ashrrev_i32_e32 v33, 31, v32
	v_mul_f32_e32 v34, 0x3db504f3, v43
	v_lshl_add_u64 v[32:33], v[32:33], 2, s[0:1]
	global_store_dword v[32:33], v34, off
	v_or_b32_e32 v32, v60, v50
	v_ashrrev_i32_e32 v33, 31, v32
	v_mul_f32_e32 v34, 0x3db504f3, v44
	v_lshl_add_u64 v[32:33], v[32:33], 2, s[0:1]
	global_store_dword v[32:33], v34, off
	v_or_b32_e32 v32, v61, v50
	v_ashrrev_i32_e32 v33, 31, v32
	v_mul_f32_e32 v34, 0x3db504f3, v45
	v_lshl_add_u64 v[32:33], v[32:33], 2, s[0:1]
	global_store_dword v[32:33], v34, off
	v_or_b32_e32 v32, v62, v50
	v_ashrrev_i32_e32 v33, 31, v32
	v_mul_f32_e32 v34, 0x3db504f3, v46
	v_lshl_add_u64 v[32:33], v[32:33], 2, s[0:1]
	global_store_dword v[32:33], v34, off
	v_or_b32_e32 v32, v63, v50
	v_ashrrev_i32_e32 v33, 31, v32
	v_mul_f32_e32 v34, 0x3db504f3, v47
	v_lshl_add_u64 v[32:33], v[32:33], 2, s[0:1]
	global_store_dword v[32:33], v34, off
	v_or_b32_e32 v32, 64, v68
	v_mul_f32_e32 v16, 0x3db504f3, v16
	v_or_b32_e32 v66, v69, v32
	global_store_dword v[48:49], v16, off offset:256
	v_mul_f32_e32 v33, 0x3db504f3, v17
	v_lshl_add_u64 v[16:17], v[66:67], 2, s[0:1]
	v_mul_f32_e32 v18, 0x3db504f3, v18
	global_store_dword v[16:17], v18, off offset:1024
	v_mul_f32_e32 v18, 0x3db504f3, v19
	global_store_dword v[16:17], v33, off offset:512
	global_store_dword v[16:17], v18, off offset:1536
	v_or_b32_e32 v16, v70, v32
	v_ashrrev_i32_e32 v17, 31, v16
	v_mul_f32_e32 v18, 0x3db504f3, v20
	v_lshl_add_u64 v[16:17], v[16:17], 2, s[0:1]
	global_store_dword v[16:17], v18, off
	v_or_b32_e32 v16, v53, v32
	v_ashrrev_i32_e32 v17, 31, v16
	v_mul_f32_e32 v18, 0x3db504f3, v21
	v_lshl_add_u64 v[16:17], v[16:17], 2, s[0:1]
	global_store_dword v[16:17], v18, off
	v_or_b32_e32 v16, v54, v32
	v_ashrrev_i32_e32 v17, 31, v16
	v_mul_f32_e32 v18, 0x3db504f3, v22
	v_lshl_add_u64 v[16:17], v[16:17], 2, s[0:1]
	global_store_dword v[16:17], v18, off
	v_or_b32_e32 v16, v55, v32
	v_ashrrev_i32_e32 v17, 31, v16
	v_mul_f32_e32 v18, 0x3db504f3, v23
	v_lshl_add_u64 v[16:17], v[16:17], 2, s[0:1]
	global_store_dword v[16:17], v18, off
	v_or_b32_e32 v16, v56, v32
	v_ashrrev_i32_e32 v17, 31, v16
	v_mul_f32_e32 v18, 0x3db504f3, v24
	v_lshl_add_u64 v[16:17], v[16:17], 2, s[0:1]
	global_store_dword v[16:17], v18, off
	v_or_b32_e32 v16, v57, v32
	v_ashrrev_i32_e32 v17, 31, v16
	v_mul_f32_e32 v18, 0x3db504f3, v25
	v_lshl_add_u64 v[16:17], v[16:17], 2, s[0:1]
	global_store_dword v[16:17], v18, off
	v_or_b32_e32 v16, v58, v32
	v_ashrrev_i32_e32 v17, 31, v16
	v_mul_f32_e32 v18, 0x3db504f3, v26
	v_lshl_add_u64 v[16:17], v[16:17], 2, s[0:1]
	global_store_dword v[16:17], v18, off
	v_or_b32_e32 v16, v59, v32
	v_ashrrev_i32_e32 v17, 31, v16
	v_mul_f32_e32 v18, 0x3db504f3, v27
	v_lshl_add_u64 v[16:17], v[16:17], 2, s[0:1]
	global_store_dword v[16:17], v18, off
	v_or_b32_e32 v16, v60, v32
	v_ashrrev_i32_e32 v17, 31, v16
	v_mul_f32_e32 v18, 0x3db504f3, v28
	v_lshl_add_u64 v[16:17], v[16:17], 2, s[0:1]
	global_store_dword v[16:17], v18, off
	v_or_b32_e32 v16, v61, v32
	v_ashrrev_i32_e32 v17, 31, v16
	v_mul_f32_e32 v18, 0x3db504f3, v29
	v_lshl_add_u64 v[16:17], v[16:17], 2, s[0:1]
	global_store_dword v[16:17], v18, off
	v_or_b32_e32 v16, v62, v32
	v_ashrrev_i32_e32 v17, 31, v16
	v_mul_f32_e32 v18, 0x3db504f3, v30
	v_lshl_add_u64 v[16:17], v[16:17], 2, s[0:1]
	global_store_dword v[16:17], v18, off
	v_or_b32_e32 v16, v63, v32
	v_ashrrev_i32_e32 v17, 31, v16
	v_mul_f32_e32 v18, 0x3db504f3, v31
	v_lshl_add_u64 v[16:17], v[16:17], 2, s[0:1]
	global_store_dword v[16:17], v18, off
	v_or_b32_e32 v16, 0x60, v68
	v_mul_f32_e32 v0, 0x3db504f3, v0
	v_or_b32_e32 v66, v69, v16
	global_store_dword v[48:49], v0, off offset:384
	v_mul_f32_e32 v17, 0x3db504f3, v1
	v_lshl_add_u64 v[0:1], v[66:67], 2, s[0:1]
	v_mul_f32_e32 v2, 0x3db504f3, v2
	global_store_dword v[0:1], v2, off offset:1024
	v_mul_f32_e32 v2, 0x3db504f3, v3
	global_store_dword v[0:1], v17, off offset:512
	global_store_dword v[0:1], v2, off offset:1536
	v_or_b32_e32 v0, v70, v16
	v_ashrrev_i32_e32 v1, 31, v0
	v_mul_f32_e32 v2, 0x3db504f3, v4
	v_lshl_add_u64 v[0:1], v[0:1], 2, s[0:1]
	global_store_dword v[0:1], v2, off
	v_or_b32_e32 v0, v53, v16
	v_ashrrev_i32_e32 v1, 31, v0
	v_mul_f32_e32 v2, 0x3db504f3, v5
	v_lshl_add_u64 v[0:1], v[0:1], 2, s[0:1]
	global_store_dword v[0:1], v2, off
	v_or_b32_e32 v0, v54, v16
	v_ashrrev_i32_e32 v1, 31, v0
	v_mul_f32_e32 v2, 0x3db504f3, v6
	v_lshl_add_u64 v[0:1], v[0:1], 2, s[0:1]
	global_store_dword v[0:1], v2, off
	v_or_b32_e32 v0, v55, v16
	v_ashrrev_i32_e32 v1, 31, v0
	v_mul_f32_e32 v2, 0x3db504f3, v7
	v_lshl_add_u64 v[0:1], v[0:1], 2, s[0:1]
	global_store_dword v[0:1], v2, off
	v_or_b32_e32 v0, v56, v16
	v_ashrrev_i32_e32 v1, 31, v0
	v_mul_f32_e32 v2, 0x3db504f3, v8
	v_lshl_add_u64 v[0:1], v[0:1], 2, s[0:1]
	global_store_dword v[0:1], v2, off
	v_or_b32_e32 v0, v57, v16
	v_ashrrev_i32_e32 v1, 31, v0
	v_mul_f32_e32 v2, 0x3db504f3, v9
	v_lshl_add_u64 v[0:1], v[0:1], 2, s[0:1]
	global_store_dword v[0:1], v2, off
	v_or_b32_e32 v0, v58, v16
	v_ashrrev_i32_e32 v1, 31, v0
	v_mul_f32_e32 v2, 0x3db504f3, v10
	v_lshl_add_u64 v[0:1], v[0:1], 2, s[0:1]
	global_store_dword v[0:1], v2, off
	v_or_b32_e32 v0, v59, v16
	v_ashrrev_i32_e32 v1, 31, v0
	v_mul_f32_e32 v2, 0x3db504f3, v11
	v_lshl_add_u64 v[0:1], v[0:1], 2, s[0:1]
	global_store_dword v[0:1], v2, off
	v_or_b32_e32 v0, v60, v16
	v_ashrrev_i32_e32 v1, 31, v0
	v_mul_f32_e32 v2, 0x3db504f3, v12
	v_lshl_add_u64 v[0:1], v[0:1], 2, s[0:1]
	global_store_dword v[0:1], v2, off
	v_or_b32_e32 v0, v61, v16
	v_ashrrev_i32_e32 v1, 31, v0
	v_mul_f32_e32 v2, 0x3db504f3, v13
	v_lshl_add_u64 v[0:1], v[0:1], 2, s[0:1]
	global_store_dword v[0:1], v2, off
	v_or_b32_e32 v0, v62, v16
	v_ashrrev_i32_e32 v1, 31, v0
	v_mul_f32_e32 v2, 0x3db504f3, v14
	v_lshl_add_u64 v[0:1], v[0:1], 2, s[0:1]
	global_store_dword v[0:1], v2, off
	v_or_b32_e32 v0, v63, v16
	v_ashrrev_i32_e32 v1, 31, v0
	v_mul_f32_e32 v2, 0x3db504f3, v15
	v_lshl_add_u64 v[0:1], v[0:1], 2, s[0:1]
	v_and_b32_e32 v4, 1, v65
	global_store_dword v[0:1], v2, off
	v_mul_lo_u32 v0, v64, s87
	v_lshlrev_b32_e32 v1, 7, v4
	v_add3_u32 v7, 0, v0, v1
	v_lshl_add_u32 v6, v4, 8, 0
	ds_read_b128 v[8:11], v7 offset:34816
	ds_read_b128 v[12:15], v7 offset:34832
	ds_read_b128 v[16:19], v7 offset:34848
	ds_read_b128 v[0:3], v7 offset:34864
	v_add_u32_e32 v6, 0x11600, v6
	ds_read_b128 v[20:23], v6
	ds_read_b128 v[24:27], v6 offset:16
	ds_read_b128 v[28:31], v6 offset:32
	ds_read_b128 v[32:35], v6 offset:48
	s_waitcnt lgkmcnt(7)
	v_lshlrev_b32_e32 v5, 16, v8
	s_waitcnt lgkmcnt(3)
	v_fma_f32 v5, v20, v5, 0
	v_and_b32_e32 v8, 0xffff0000, v8
	v_fmac_f32_e32 v5, v21, v8
	v_lshlrev_b32_e32 v8, 16, v9
	v_fmac_f32_e32 v5, v22, v8
	v_and_b32_e32 v8, 0xffff0000, v9
	v_fmac_f32_e32 v5, v23, v8
	v_lshlrev_b32_e32 v8, 16, v10
	s_waitcnt lgkmcnt(2)
	v_fmac_f32_e32 v5, v24, v8
	v_and_b32_e32 v8, 0xffff0000, v10
	v_fmac_f32_e32 v5, v25, v8
	v_lshlrev_b32_e32 v8, 16, v11
	v_fmac_f32_e32 v5, v26, v8
	v_and_b32_e32 v8, 0xffff0000, v11
	v_fmac_f32_e32 v5, v27, v8
	v_lshlrev_b32_e32 v8, 16, v12
	s_waitcnt lgkmcnt(1)
	v_fmac_f32_e32 v5, v28, v8
	v_and_b32_e32 v8, 0xffff0000, v12
	v_fmac_f32_e32 v5, v29, v8
	v_lshlrev_b32_e32 v8, 16, v13
	v_fmac_f32_e32 v5, v30, v8
	v_and_b32_e32 v8, 0xffff0000, v13
	v_fmac_f32_e32 v5, v31, v8
	v_lshlrev_b32_e32 v8, 16, v14
	s_waitcnt lgkmcnt(0)
	v_fmac_f32_e32 v5, v32, v8
	v_and_b32_e32 v8, 0xffff0000, v14
	v_fmac_f32_e32 v5, v33, v8
	v_lshlrev_b32_e32 v8, 16, v15
	v_fmac_f32_e32 v5, v34, v8
	v_and_b32_e32 v8, 0xffff0000, v15
	v_fmac_f32_e32 v5, v35, v8
	ds_read_b128 v[8:11], v6 offset:64
	v_lshlrev_b32_e32 v12, 16, v16
	s_waitcnt lgkmcnt(0)
	v_fmac_f32_e32 v5, v8, v12
	v_and_b32_e32 v8, 0xffff0000, v16
	v_fmac_f32_e32 v5, v9, v8
	v_lshlrev_b32_e32 v8, 16, v17
	v_fmac_f32_e32 v5, v10, v8
	v_and_b32_e32 v8, 0xffff0000, v17
	v_fmac_f32_e32 v5, v11, v8
	ds_read_b128 v[8:11], v6 offset:80
	v_lshlrev_b32_e32 v12, 16, v18
	s_waitcnt lgkmcnt(0)
	v_fmac_f32_e32 v5, v8, v12
	v_and_b32_e32 v8, 0xffff0000, v18
	v_fmac_f32_e32 v5, v9, v8
	v_lshlrev_b32_e32 v8, 16, v19
	v_fmac_f32_e32 v5, v10, v8
	v_and_b32_e32 v8, 0xffff0000, v19
	v_fmac_f32_e32 v5, v11, v8
	ds_read_b128 v[8:11], v6 offset:96
	v_lshlrev_b32_e32 v12, 16, v0
	v_and_b32_e32 v0, 0xffff0000, v0
	s_waitcnt lgkmcnt(0)
	v_fmac_f32_e32 v5, v8, v12
	v_fmac_f32_e32 v5, v9, v0
	v_lshlrev_b32_e32 v0, 16, v1
	v_fmac_f32_e32 v5, v10, v0
	v_and_b32_e32 v0, 0xffff0000, v1
	v_fmac_f32_e32 v5, v11, v0
	ds_read_b128 v[8:11], v6 offset:112
	v_lshlrev_b32_e32 v0, 16, v2
	s_waitcnt lgkmcnt(0)
	v_fmac_f32_e32 v5, v8, v0
	v_and_b32_e32 v0, 0xffff0000, v2
	v_fmac_f32_e32 v5, v9, v0
	v_lshlrev_b32_e32 v0, 16, v3
	v_fmac_f32_e32 v5, v10, v0
	v_and_b32_e32 v0, 0xffff0000, v3
	v_fmac_f32_e32 v5, v11, v0
	ds_read_b128 v[0:3], v7 offset:34880
	ds_read_b128 v[8:11], v6 offset:128
	s_waitcnt lgkmcnt(1)
	v_lshlrev_b32_e32 v12, 16, v0
	s_waitcnt lgkmcnt(0)
	v_fmac_f32_e32 v5, v8, v12
	v_and_b32_e32 v0, 0xffff0000, v0
	v_fmac_f32_e32 v5, v9, v0
	v_lshlrev_b32_e32 v0, 16, v1
	v_fmac_f32_e32 v5, v10, v0
	v_and_b32_e32 v0, 0xffff0000, v1
	v_fmac_f32_e32 v5, v11, v0
	ds_read_b128 v[8:11], v6 offset:144
	v_lshlrev_b32_e32 v0, 16, v2
	s_waitcnt lgkmcnt(0)
	v_fmac_f32_e32 v5, v8, v0
	v_and_b32_e32 v0, 0xffff0000, v2
	v_fmac_f32_e32 v5, v9, v0
	v_lshlrev_b32_e32 v0, 16, v3
	v_fmac_f32_e32 v5, v10, v0
	v_and_b32_e32 v0, 0xffff0000, v3
	v_fmac_f32_e32 v5, v11, v0
	ds_read_b128 v[0:3], v7 offset:34896
	ds_read_b128 v[8:11], v6 offset:160
	s_waitcnt lgkmcnt(1)
	v_lshlrev_b32_e32 v12, 16, v0
	s_waitcnt lgkmcnt(0)
	v_fmac_f32_e32 v5, v8, v12
	v_and_b32_e32 v0, 0xffff0000, v0
	v_fmac_f32_e32 v5, v9, v0
	v_lshlrev_b32_e32 v0, 16, v1
	v_fmac_f32_e32 v5, v10, v0
	v_and_b32_e32 v0, 0xffff0000, v1
	v_fmac_f32_e32 v5, v11, v0
	ds_read_b128 v[8:11], v6 offset:176
	v_lshlrev_b32_e32 v0, 16, v2
	s_waitcnt lgkmcnt(0)
	v_fmac_f32_e32 v5, v8, v0
	v_and_b32_e32 v0, 0xffff0000, v2
	v_fmac_f32_e32 v5, v9, v0
	v_lshlrev_b32_e32 v0, 16, v3
	v_fmac_f32_e32 v5, v10, v0
	v_and_b32_e32 v0, 0xffff0000, v3
	v_fmac_f32_e32 v5, v11, v0
	ds_read_b128 v[0:3], v7 offset:34912
	ds_read_b128 v[8:11], v6 offset:192
	s_waitcnt lgkmcnt(1)
	v_lshlrev_b32_e32 v12, 16, v0
	s_waitcnt lgkmcnt(0)
	v_fmac_f32_e32 v5, v8, v12
	v_and_b32_e32 v0, 0xffff0000, v0
	v_fmac_f32_e32 v5, v9, v0
	v_lshlrev_b32_e32 v0, 16, v1
	v_fmac_f32_e32 v5, v10, v0
	v_and_b32_e32 v0, 0xffff0000, v1
	v_fmac_f32_e32 v5, v11, v0
	ds_read_b128 v[8:11], v6 offset:208
	v_lshlrev_b32_e32 v0, 16, v2
	s_waitcnt lgkmcnt(0)
	v_fmac_f32_e32 v5, v8, v0
	v_and_b32_e32 v0, 0xffff0000, v2
	v_fmac_f32_e32 v5, v9, v0
	v_lshlrev_b32_e32 v0, 16, v3
	v_fmac_f32_e32 v5, v10, v0
	v_and_b32_e32 v0, 0xffff0000, v3
	v_fmac_f32_e32 v5, v11, v0
	ds_read_b128 v[0:3], v7 offset:34928
	ds_read_b128 v[8:11], v6 offset:224
	s_waitcnt lgkmcnt(1)
	v_lshlrev_b32_e32 v7, 16, v0
	s_waitcnt lgkmcnt(0)
	v_fmac_f32_e32 v5, v8, v7
	v_and_b32_e32 v0, 0xffff0000, v0
	v_fmac_f32_e32 v5, v9, v0
	ds_read_b128 v[6:9], v6 offset:240
	v_lshlrev_b32_e32 v0, 16, v1
	v_fmac_f32_e32 v5, v10, v0
	v_and_b32_e32 v0, 0xffff0000, v1
	v_fmac_f32_e32 v5, v11, v0
	v_lshlrev_b32_e32 v0, 16, v2
	s_waitcnt lgkmcnt(0)
	v_fmac_f32_e32 v5, v6, v0
	v_and_b32_e32 v0, 0xffff0000, v2
	v_fmac_f32_e32 v5, v7, v0
	v_lshlrev_b32_e32 v0, 16, v3
	v_fmac_f32_e32 v5, v8, v0
	v_and_b32_e32 v0, 0xffff0000, v3
	v_fmac_f32_e32 v5, v9, v0
	v_mbcnt_hi_u32_b32 v0, -1, v195
	v_and_b32_e32 v2, 64, v0
	v_xor_b32_e32 v1, 1, v0
	v_add_u32_e32 v2, 64, v2
	v_cmp_lt_i32_e32 vcc, v1, v2
	s_nop 1
	v_cndmask_b32_e32 v0, v0, v1, vcc
	v_lshlrev_b32_e32 v0, 2, v0
	v_mov_b32_dpp v0, v5 quad_perm:[1,0,3,2] row_mask:0xf bank_mask:0xf
	v_cmp_eq_u32_e32 vcc, 0, v4
	s_and_saveexec_b64 s[0:1], vcc
	s_cbranch_execz .LBB0_535
	s_lshl_b64 s[6:7], s[2:3], 9
	v_readlane_b32 s8, v249, 21
	v_readlane_b32 s9, v249, 22
	s_add_u32 s6, s8, s6
	s_addc_u32 s7, s9, s7
	v_ashrrev_i32_e32 v65, 31, v64
	s_waitcnt lgkmcnt(0)
	v_add_f32_e32 v0, v5, v0
	v_lshl_add_u64 v[2:3], v[64:65], 2, s[6:7]
	v_mul_f32_e32 v0, 0x3db504f3, v0
	global_store_dword v[2:3], v0, off
	s_branch .LBB0_535

.LBB0_713:
	v_lshrrev_b32_e32 v48, 3, v32
	v_and_b32_e32 v49, 7, v32
	v_lshlrev_b32_e32 v50, 8, v48
	v_lshl_add_u32 v50, v49, 4, v50
	v_mov_b32_e32 v51, 0
	v_lshl_add_u64 v[50:51], s[38:39], 0, v[50:51]
	s_mov_b32 s40, 0x2000
	s_mov_b32 s41, 0
	global_load_dwordx4 v[52:55], v[50:51], off
	v_lshl_add_u64 v[68:69], s[40:41], 0, v[50:51]
	global_load_dwordx4 v[56:59], v[68:69], off
	v_lshl_add_u64 v[68:69], s[40:41], 1, v[50:51]
	global_load_dwordx4 v[60:63], v[68:69], off
	v_lshl_add_u64 v[68:69], s[40:41], 0, v[68:69]
	global_load_dwordx4 v[64:67], v[68:69], off
	v_mul_u32_u24_e32 v70, 0x90, v48
	v_lshl_add_u32 v70, v49, 4, v70

.LBB0_717:
	s_or_b64 exec, exec, s[6:7]
	ds_write_b128 v70, v[52:55]
	ds_write_b128 v70, v[56:59] offset:4608
	ds_write_b128 v70, v[60:63] offset:9216
	ds_write_b128 v70, v[64:67] offset:13824
	s_waitcnt lgkmcnt(0)
	s_barrier
	ds_read_b128 v[32:35], v158
	ds_read_b128 v[36:39], v158 offset:4608
	s_waitcnt lgkmcnt(1)
	v_mfma_f32_32x32x16_bf16 v[80:95], v[98:101], v[32:35], 0
	s_waitcnt lgkmcnt(0)
	v_mfma_f32_32x32x16_bf16 v[48:63], v[98:101], v[36:39], 0
	ds_read_b128 v[32:35], v158 offset:9216
	ds_read_b128 v[36:39], v158 offset:13824
	s_waitcnt lgkmcnt(1)
	v_mfma_f32_32x32x16_bf16 v[64:79], v[98:101], v[32:35], 0
	s_waitcnt lgkmcnt(0)
	v_mfma_f32_32x32x16_bf16 v[32:47], v[98:101], v[36:39], 0
	ds_read_b128 v[148:151], v158 offset:32
	s_waitcnt lgkmcnt(0)
	v_mfma_f32_32x32x16_bf16 v[80:95], v[102:105], v[148:151], v[80:95]
	ds_read_b128 v[148:151], v158 offset:4640
	s_waitcnt lgkmcnt(0)
	v_mfma_f32_32x32x16_bf16 v[48:63], v[102:105], v[148:151], v[48:63]
	ds_read_b128 v[148:151], v158 offset:9248
	s_waitcnt lgkmcnt(0)
	v_mfma_f32_32x32x16_bf16 v[64:79], v[102:105], v[148:151], v[64:79]
	ds_read_b128 v[148:151], v158 offset:13856
	s_waitcnt lgkmcnt(0)
	v_mfma_f32_32x32x16_bf16 v[32:47], v[102:105], v[148:151], v[32:47]
	ds_read_b128 v[148:151], v158 offset:64
	s_waitcnt lgkmcnt(0)
	v_mfma_f32_32x32x16_bf16 v[80:95], v[106:109], v[148:151], v[80:95]
	ds_read_b128 v[148:151], v158 offset:4672
	s_waitcnt lgkmcnt(0)
	v_mfma_f32_32x32x16_bf16 v[48:63], v[106:109], v[148:151], v[48:63]
	ds_read_b128 v[148:151], v158 offset:9280
	s_waitcnt lgkmcnt(0)
	v_mfma_f32_32x32x16_bf16 v[64:79], v[106:109], v[148:151], v[64:79]
	ds_read_b128 v[148:151], v158 offset:13888
	s_waitcnt lgkmcnt(0)
	v_mfma_f32_32x32x16_bf16 v[32:47], v[106:109], v[148:151], v[32:47]
	ds_read_b128 v[148:151], v158 offset:96
	s_waitcnt lgkmcnt(0)
	v_mfma_f32_32x32x16_bf16 v[80:95], v[110:113], v[148:151], v[80:95]
	ds_read_b128 v[148:151], v158 offset:4704
	s_waitcnt lgkmcnt(0)
	v_mfma_f32_32x32x16_bf16 v[48:63], v[110:113], v[148:151], v[48:63]
	ds_read_b128 v[148:151], v158 offset:9312
	s_waitcnt lgkmcnt(0)
	v_mfma_f32_32x32x16_bf16 v[64:79], v[110:113], v[148:151], v[64:79]
	ds_read_b128 v[148:151], v158 offset:13920
	s_waitcnt lgkmcnt(0)
	v_mfma_f32_32x32x16_bf16 v[32:47], v[110:113], v[148:151], v[32:47]
	s_add_i32 s6, s53, s49
	v_mbcnt_hi_u32_b32 v148, -1, v195
	v_lshl_add_u32 v96, s6, 7, v183
	v_and_b32_e32 v147, 64, v148
	v_add_u32_e32 v149, 64, v147
	v_sub_u32_e32 v147, v96, v159
	v_cmp_gt_u32_e32 vcc, s58, v147
	s_or_b64 vcc, s[2:3], vcc
	v_add_u32_e32 v150, 32, v147
	v_cndmask_b32_e32 v80, v204, v80, vcc
	v_cmp_gt_u32_e32 vcc, s58, v150
	s_or_b64 vcc, s[2:3], vcc
	v_add_u32_e32 v151, 64, v147
	v_cndmask_b32_e32 v48, v204, v48, vcc
	v_cmp_gt_u32_e32 vcc, s58, v151
	s_or_b64 vcc, s[2:3], vcc
	v_add_u32_e32 v147, 0x60, v147
	v_cndmask_b32_e32 v64, v204, v64, vcc
	v_cmp_gt_u32_e32 vcc, s58, v147
	s_or_b64 vcc, s[2:3], vcc
	v_xor_b32_e32 v147, 16, v148
	v_cndmask_b32_e32 v32, v204, v32, vcc
	v_cmp_lt_i32_e32 vcc, v147, v149
	v_max3_f32 v150, v80, s59, v48
	v_max3_f32 v150, v150, v64, v32
	v_cndmask_b32_e32 v147, v148, v147, vcc
	v_lshlrev_b32_e32 v147, 2, v147
	v_mov_b32_e32 v151, v150
	v_mov_b32_e32 v255, v150
	s_nop 1
	v_permlane16_swap_b32_e32 v151, v255
	s_nop 1
	v_mov_b32_dpp v151, v255 quad_perm:[0,1,2,3] row_mask:0x5 bank_mask:0xf
	v_add_u32_e32 v187, 0x8800, v186
	v_add_u32_e32 v215, 0x9000, v186
	s_nop 0
	v_max_f32_e32 v151, v151, v151
	v_max_f32_e32 v150, v150, v151
	v_xor_b32_e32 v151, 8, v148
	v_cmp_lt_i32_e32 vcc, v151, v149
	s_nop 1
	v_cndmask_b32_e32 v151, v148, v151, vcc
	v_lshlrev_b32_e32 v208, 2, v151
	v_mov_b32_dpp v151, v150 row_ror:8 row_mask:0xf bank_mask:0xf
	s_nop 0
	v_max_f32_e32 v151, v151, v151
	v_max_f32_e32 v150, v150, v151
	v_xor_b32_e32 v151, 4, v148
	v_cmp_lt_i32_e32 vcc, v151, v149
	s_nop 1
	v_cndmask_b32_e32 v151, v148, v151, vcc
	v_lshlrev_b32_e32 v209, 2, v151
	v_mov_b32_dpp v151, v150 row_shl:4 row_mask:0xf bank_mask:0x5
	v_mov_b32_dpp v151, v150 row_shr:4 row_mask:0xf bank_mask:0xa
	s_nop 0
	v_max_f32_e32 v151, v151, v151
	v_max_f32_e32 v150, v150, v151
	v_xor_b32_e32 v151, 2, v148
	v_cmp_lt_i32_e32 vcc, v151, v149
	s_nop 1
	v_cndmask_b32_e32 v151, v148, v151, vcc
	v_lshlrev_b32_e32 v210, 2, v151
	v_mov_b32_dpp v151, v150 quad_perm:[2,3,0,1] row_mask:0xf bank_mask:0xf
	s_nop 0
	v_max_f32_e32 v151, v151, v151
	v_max_f32_e32 v150, v150, v151
	v_xor_b32_e32 v151, 1, v148
	v_cmp_lt_i32_e32 vcc, v151, v149
	v_sub_u32_e32 v149, v96, v161
	s_nop 0
	v_cndmask_b32_e32 v148, v148, v151, vcc
	v_cmp_gt_u32_e32 vcc, s58, v149
	s_or_b64 vcc, s[2:3], vcc
	v_lshlrev_b32_e32 v211, 2, v148
	v_cndmask_b32_e32 v151, v204, v81, vcc
	v_add_u32_e32 v81, 32, v149
	v_cmp_gt_u32_e32 vcc, s58, v81
	s_or_b64 vcc, s[2:3], vcc
	v_add_u32_e32 v81, 64, v149
	v_cndmask_b32_e32 v152, v204, v49, vcc
	v_cmp_gt_u32_e32 vcc, s58, v81
	s_or_b64 vcc, s[2:3], vcc
	v_max3_f32 v49, v151, s59, v152
	v_cndmask_b32_e32 v153, v204, v65, vcc
	v_add_u32_e32 v65, 0x60, v149
	v_cmp_gt_u32_e32 vcc, s58, v65
	s_or_b64 vcc, s[2:3], vcc
	v_mov_b32_dpp v148, v150 quad_perm:[1,0,3,2] row_mask:0xf bank_mask:0xf
	v_cndmask_b32_e32 v154, v204, v33, vcc
	v_max3_f32 v33, v49, v153, v154
	v_mov_b32_e32 v49, v33
	v_mov_b32_e32 v255, v33
	s_nop 1
	v_permlane16_swap_b32_e32 v49, v255
	s_nop 1
	v_mov_b32_dpp v49, v255 quad_perm:[0,1,2,3] row_mask:0x5 bank_mask:0xf
	s_nop 0
	v_max3_f32 v207, v130, v150, v148
	v_sub_f32_e32 v48, v48, v207
	v_mul_f32_e32 v48, 0x3fb8aa3b, v48
	s_nop 0
	v_max_f32_e32 v49, v49, v49
	v_max_f32_e32 v49, v33, v49
	s_nop 1
	v_mov_b32_dpp v65, v49 row_ror:8 row_mask:0xf bank_mask:0xf
	v_sub_f32_e32 v33, v80, v207
	v_sub_f32_e32 v32, v32, v207
	v_mul_f32_e32 v32, 0x3fb8aa3b, v32
	v_sub_f32_e32 v130, v130, v207
	s_nop 0
	v_max_f32_e32 v65, v65, v65
	v_max_f32_e32 v65, v49, v65
	s_nop 1
	v_mov_b32_dpp v80, v65 row_shl:4 row_mask:0xf bank_mask:0x5
	v_mov_b32_dpp v80, v65 row_shr:4 row_mask:0xf bank_mask:0xa
	v_exp_f32_e32 v49, v48
	v_sub_f32_e32 v48, v64, v207
	v_mul_f32_e32 v48, 0x3fb8aa3b, v48
	v_exp_f32_e32 v81, v48
	s_nop 0
	v_max_f32_e32 v64, v80, v80
	v_max_f32_e32 v64, v65, v64
	s_nop 1
	v_mov_b32_dpp v80, v64 quad_perm:[2,3,0,1] row_mask:0xf bank_mask:0xf
	v_exp_f32_e32 v65, v32
	v_mul_f32_e32 v33, 0x3fb8aa3b, v33
	v_exp_f32_e32 v33, v33
	s_nop 0
	v_max_f32_e32 v32, v80, v80
	v_max_f32_e32 v32, v64, v32
	s_nop 1
	v_mov_b32_dpp v48, v32 quad_perm:[1,0,3,2] row_mask:0xf bank_mask:0xf
	v_mul_f32_e32 v64, 0x3fb8aa3b, v130
	v_exp_f32_e32 v130, v64
	v_cvt_pk_bf16_f32 v148, v33, v49
	v_cvt_pk_bf16_f32 v149, v81, v65
	s_nop 0
	v_max3_f32 v206, v131, v32, v48
	v_sub_u32_e32 v32, v96, v169
	v_cmp_gt_u32_e32 vcc, s58, v32
	s_or_b64 vcc, s[2:3], vcc
	v_add_u32_e32 v48, 32, v32
	v_cndmask_b32_e32 v82, v204, v82, vcc
	v_cmp_gt_u32_e32 vcc, s58, v48
	s_or_b64 vcc, s[2:3], vcc
	v_add_u32_e32 v64, 64, v32
	v_cndmask_b32_e32 v50, v204, v50, vcc
	v_cmp_gt_u32_e32 vcc, s58, v64
	s_or_b64 vcc, s[2:3], vcc
	v_add_u32_e32 v32, 0x60, v32
	v_cndmask_b32_e32 v66, v204, v66, vcc
	v_cmp_gt_u32_e32 vcc, s58, v32
	s_or_b64 vcc, s[2:3], vcc
	v_max3_f32 v48, v82, s59, v50
	v_cndmask_b32_e32 v34, v204, v34, vcc
	v_max3_f32 v48, v48, v66, v34
	v_mov_b32_e32 v64, v48
	v_mov_b32_e32 v255, v48
	s_nop 1
	v_permlane16_swap_b32_e32 v64, v255
	s_nop 1
	v_mov_b32_dpp v64, v255 quad_perm:[0,1,2,3] row_mask:0x5 bank_mask:0xf
	v_sub_f32_e32 v32, v151, v206
	v_sub_f32_e32 v80, v152, v206
	v_mul_f32_e32 v32, 0x3fb8aa3b, v32
	v_exp_f32_e32 v32, v32
	s_nop 0
	v_max_f32_e32 v64, v64, v64
	v_max_f32_e32 v64, v48, v64
	s_nop 1
	v_mov_b32_dpp v150, v64 row_ror:8 row_mask:0xf bank_mask:0xf
	v_mul_f32_e32 v48, 0x3fb8aa3b, v80
	v_sub_f32_e32 v80, v153, v206
	v_mul_f32_e32 v80, 0x3fb8aa3b, v80
	v_exp_f32_e32 v48, v48
	s_nop 0
	v_max_f32_e32 v150, v150, v150
	v_max_f32_e32 v150, v64, v150
	v_sub_f32_e32 v64, v154, v206
	v_sub_u32_e32 v154, v96, v170
	v_cmp_gt_u32_e32 vcc, s58, v154
	s_or_b64 vcc, s[2:3], vcc
	v_mov_b32_dpp v151, v150 row_shl:4 row_mask:0xf bank_mask:0x5
	v_mov_b32_dpp v151, v150 row_shr:4 row_mask:0xf bank_mask:0xa
	v_cndmask_b32_e32 v155, v204, v83, vcc
	v_add_u32_e32 v83, 32, v154
	v_cmp_gt_u32_e32 vcc, s58, v83
	s_or_b64 vcc, s[2:3], vcc
	v_add_u32_e32 v83, 64, v154
	v_cndmask_b32_e32 v156, v204, v51, vcc
	v_cmp_gt_u32_e32 vcc, s58, v83
	s_or_b64 vcc, s[2:3], vcc
	v_max3_f32 v51, v155, s59, v156
	v_cndmask_b32_e32 v160, v204, v67, vcc
	v_add_u32_e32 v67, 0x60, v154
	v_cmp_gt_u32_e32 vcc, s58, v67
	s_or_b64 vcc, s[2:3], vcc
	s_nop 0
	v_max_f32_e32 v151, v151, v151
	v_cndmask_b32_e32 v154, v204, v35, vcc
	v_max3_f32 v35, v51, v160, v154
	v_max_f32_e32 v152, v150, v151
	v_mov_b32_e32 v51, v35
	v_mov_b32_e32 v255, v35
	s_nop 1
	v_permlane16_swap_b32_e32 v51, v255
	s_nop 1
	v_mov_b32_dpp v51, v255 quad_perm:[0,1,2,3] row_mask:0x5 bank_mask:0xf
	s_nop 1
	v_mov_b32_dpp v153, v152 quad_perm:[2,3,0,1] row_mask:0xf bank_mask:0xf
	v_mul_f32_e32 v64, 0x3fb8aa3b, v64
	v_exp_f32_e32 v80, v80
	v_exp_f32_e32 v64, v64
	s_nop 0
	v_max_f32_e32 v51, v51, v51
	s_nop 0
	v_max_f32_e32 v153, v153, v153
	v_max_f32_e32 v51, v35, v51
	v_max_f32_e32 v152, v152, v153
	s_nop 1
	v_mov_b32_dpp v67, v51 row_ror:8 row_mask:0xf bank_mask:0xf
	s_nop 1
	v_mov_b32_dpp v153, v152 quad_perm:[1,0,3,2] row_mask:0xf bank_mask:0xf
	v_cvt_pk_bf16_f32 v150, v32, v48
	v_cvt_pk_bf16_f32 v151, v80, v64
	ds_write2_b64 v187, v[148:149], v[150:151] offset0:128 offset1:162
	s_nop 0
	v_max_f32_e32 v67, v67, v67
	s_nop 0
	v_max3_f32 v189, v132, v152, v153
	v_max_f32_e32 v67, v51, v67
	v_sub_f32_e32 v35, v82, v189
	s_nop 1
	v_mov_b32_dpp v82, v67 row_shl:4 row_mask:0xf bank_mask:0x5
	v_mov_b32_dpp v82, v67 row_shr:4 row_mask:0xf bank_mask:0xa
	v_sub_f32_e32 v50, v50, v189
	v_mul_f32_e32 v50, 0x3fb8aa3b, v50
	v_exp_f32_e32 v51, v50
	v_sub_f32_e32 v50, v66, v189
	s_waitcnt lgkmcnt(0)
	v_max_f32_e32 v66, v82, v82
	v_max_f32_e32 v66, v67, v66
	s_nop 1
	v_mov_b32_dpp v82, v66 quad_perm:[2,3,0,1] row_mask:0xf bank_mask:0xf
	v_sub_f32_e32 v34, v34, v189
	v_mul_f32_e32 v34, 0x3fb8aa3b, v34
	v_exp_f32_e32 v67, v34
	v_mul_f32_e32 v50, 0x3fb8aa3b, v50
	s_nop 0
	v_max_f32_e32 v34, v82, v82
	v_max_f32_e32 v34, v66, v34
	v_exp_f32_e32 v83, v50
	s_nop 1
	v_mov_b32_dpp v50, v34 quad_perm:[1,0,3,2] row_mask:0xf bank_mask:0xf
	v_sub_f32_e32 v132, v132, v189
	v_mul_f32_e32 v66, 0x3fb8aa3b, v132
	v_exp_f32_e32 v132, v66
	v_mul_f32_e32 v35, 0x3fb8aa3b, v35
	s_nop 0
	v_max3_f32 v188, v133, v34, v50
	v_sub_u32_e32 v34, v96, v171
	v_cmp_gt_u32_e32 vcc, s58, v34
	s_or_b64 vcc, s[2:3], vcc
	v_add_u32_e32 v50, 32, v34
	v_cndmask_b32_e32 v84, v204, v84, vcc
	v_cmp_gt_u32_e32 vcc, s58, v50
	s_or_b64 vcc, s[2:3], vcc
	v_add_u32_e32 v66, 64, v34
	v_cndmask_b32_e32 v52, v204, v52, vcc
	v_cmp_gt_u32_e32 vcc, s58, v66
	s_or_b64 vcc, s[2:3], vcc
	v_add_u32_e32 v34, 0x60, v34
	v_cndmask_b32_e32 v68, v204, v68, vcc
	v_cmp_gt_u32_e32 vcc, s58, v34
	s_or_b64 vcc, s[2:3], vcc
	v_max3_f32 v50, v84, s59, v52
	v_cndmask_b32_e32 v150, v204, v36, vcc
	v_max3_f32 v34, v50, v68, v150
	v_mov_b32_e32 v36, v34
	v_mov_b32_e32 v255, v34
	s_nop 1
	v_permlane16_swap_b32_e32 v36, v255
	s_nop 1
	v_mov_b32_dpp v36, v255 quad_perm:[0,1,2,3] row_mask:0x5 bank_mask:0xf
	v_sub_f32_e32 v151, v154, v188
	v_sub_f32_e32 v50, v133, v188
	v_mul_f32_e32 v133, 0x3fb8aa3b, v50
	v_sub_f32_e32 v50, v155, v188
	s_nop 0
	v_max_f32_e32 v36, v36, v36
	v_max_f32_e32 v36, v34, v36
	s_nop 1
	v_mov_b32_dpp v66, v36 row_ror:8 row_mask:0xf bank_mask:0xf
	v_mul_f32_e32 v50, 0x3fb8aa3b, v50
	v_exp_f32_e32 v34, v50
	v_sub_f32_e32 v50, v156, v188
	v_sub_f32_e32 v82, v160, v188
	s_nop 0
	v_max_f32_e32 v66, v66, v66
	v_max_f32_e32 v36, v36, v66
	s_nop 1
	v_mov_b32_dpp v66, v36 row_shl:4 row_mask:0xf bank_mask:0x5
	v_mov_b32_dpp v66, v36 row_shr:4 row_mask:0xf bank_mask:0xa
	v_mul_f32_e32 v50, 0x3fb8aa3b, v50
	v_mul_f32_e32 v82, 0x3fb8aa3b, v82
	v_exp_f32_e32 v35, v35
	v_exp_f32_e32 v50, v50
	s_nop 0
	v_max_f32_e32 v66, v66, v66
	v_max_f32_e32 v152, v36, v66
	s_nop 1
	v_mov_b32_dpp v153, v152 quad_perm:[2,3,0,1] row_mask:0xf bank_mask:0xf
	v_mul_f32_e32 v36, 0x3fb8aa3b, v151
	v_exp_f32_e32 v82, v82
	v_exp_f32_e32 v66, v36
	v_cvt_pk_bf16_f32 v148, v35, v51
	s_nop 0
	v_max_f32_e32 v151, v153, v153
	v_sub_u32_e32 v153, v96, v172
	v_cmp_gt_u32_e32 vcc, s58, v153
	s_or_b64 vcc, s[2:3], vcc
	v_cvt_pk_bf16_f32 v149, v83, v67
	v_cndmask_b32_e32 v154, v204, v85, vcc
	v_add_u32_e32 v85, 32, v153
	v_cmp_gt_u32_e32 vcc, s58, v85
	s_or_b64 vcc, s[2:3], vcc
	v_add_u32_e32 v85, 64, v153
	v_cndmask_b32_e32 v155, v204, v53, vcc
	v_cmp_gt_u32_e32 vcc, s58, v85
	s_or_b64 vcc, s[2:3], vcc
	v_max3_f32 v53, v154, s59, v155
	v_cndmask_b32_e32 v156, v204, v69, vcc
	v_add_u32_e32 v69, 0x60, v153
	v_cmp_gt_u32_e32 vcc, s58, v69
	s_or_b64 vcc, s[2:3], vcc
	v_cvt_pk_bf16_f32 v36, v34, v50
	v_cndmask_b32_e32 v153, v204, v37, vcc
	v_max3_f32 v53, v53, v156, v153
	v_mov_b32_e32 v69, v53
	v_mov_b32_e32 v255, v53
	s_nop 1
	v_permlane16_swap_b32_e32 v69, v255
	s_nop 1
	v_mov_b32_dpp v69, v255 quad_perm:[0,1,2,3] row_mask:0x5 bank_mask:0xf
	v_cvt_pk_bf16_f32 v37, v82, v66
	ds_write2_b64 v187, v[148:149], v[36:37] offset0:196 offset1:230
	v_max_f32_e32 v151, v152, v151
	s_nop 1
	v_mov_b32_dpp v152, v151 quad_perm:[1,0,3,2] row_mask:0xf bank_mask:0xf
	s_nop 0
	v_max_f32_e32 v37, v69, v69
	v_max_f32_e32 v53, v53, v37
	s_nop 1
	v_mov_b32_dpp v69, v53 row_ror:8 row_mask:0xf bank_mask:0xf
	v_sub_f32_e32 v131, v131, v206
	s_waitcnt lgkmcnt(0)
	v_max3_f32 v187, v134, v151, v152
	v_sub_f32_e32 v37, v84, v187
	v_sub_f32_e32 v52, v52, v187
	s_nop 0
	v_max_f32_e32 v69, v69, v69
	v_max_f32_e32 v69, v53, v69
	s_nop 1
	v_mov_b32_dpp v84, v69 row_shl:4 row_mask:0xf bank_mask:0x5
	v_mov_b32_dpp v84, v69 row_shr:4 row_mask:0xf bank_mask:0xa
	v_mul_f32_e32 v52, 0x3fb8aa3b, v52
	v_exp_f32_e32 v53, v52
	v_sub_f32_e32 v52, v68, v187
	v_mul_f32_e32 v52, 0x3fb8aa3b, v52
	s_nop 0
	v_max_f32_e32 v68, v84, v84
	v_max_f32_e32 v68, v69, v68
	s_nop 1
	v_mov_b32_dpp v84, v68 quad_perm:[2,3,0,1] row_mask:0xf bank_mask:0xf
	v_exp_f32_e32 v85, v52
	v_sub_f32_e32 v52, v150, v187
	v_mul_f32_e32 v52, 0x3fb8aa3b, v52
	v_exp_f32_e32 v69, v52
	s_nop 0
	v_max_f32_e32 v52, v84, v84
	v_max_f32_e32 v52, v68, v52
	s_nop 1
	v_mov_b32_dpp v68, v52 quad_perm:[1,0,3,2] row_mask:0xf bank_mask:0xf
	v_sub_f32_e32 v36, v134, v187
	v_mul_f32_e32 v36, 0x3fb8aa3b, v36
	v_exp_f32_e32 v134, v36
	v_sub_u32_e32 v36, v96, v173
	v_cmp_gt_u32_e32 vcc, s58, v36
	s_nop 0
	v_max3_f32 v160, v135, v52, v68
	s_or_b64 vcc, s[2:3], vcc
	v_add_u32_e32 v52, 32, v36
	v_cndmask_b32_e32 v86, v204, v86, vcc
	v_cmp_gt_u32_e32 vcc, s58, v52
	s_or_b64 vcc, s[2:3], vcc
	v_add_u32_e32 v68, 64, v36
	v_cndmask_b32_e32 v54, v204, v54, vcc
	v_cmp_gt_u32_e32 vcc, s58, v68
	s_or_b64 vcc, s[2:3], vcc
	v_add_u32_e32 v36, 0x60, v36
	v_cndmask_b32_e32 v70, v204, v70, vcc
	v_cmp_gt_u32_e32 vcc, s58, v36
	s_or_b64 vcc, s[2:3], vcc
	v_max3_f32 v52, v86, s59, v54
	v_cndmask_b32_e32 v38, v204, v38, vcc
	v_max3_f32 v52, v52, v70, v38
	v_mov_b32_e32 v68, v52
	v_mov_b32_e32 v255, v52
	s_nop 1
	v_permlane16_swap_b32_e32 v68, v255
	s_nop 1
	v_mov_b32_dpp v68, v255 quad_perm:[0,1,2,3] row_mask:0x5 bank_mask:0xf
	v_sub_f32_e32 v36, v154, v160
	v_sub_u32_e32 v154, v96, v174
	v_cmp_gt_u32_e32 vcc, s58, v154
	s_or_b64 vcc, s[2:3], vcc
	s_nop 0
	v_max_f32_e32 v68, v68, v68
	v_max_f32_e32 v68, v52, v68
	s_nop 1
	v_mov_b32_dpp v150, v68 row_ror:8 row_mask:0xf bank_mask:0xf
	v_cndmask_b32_e32 v212, v204, v87, vcc
	v_add_u32_e32 v87, 32, v154
	v_cmp_gt_u32_e32 vcc, s58, v87
	s_or_b64 vcc, s[2:3], vcc
	s_nop 0
	v_max_f32_e32 v150, v150, v150
	v_add_u32_e32 v87, 64, v154
	v_max_f32_e32 v150, v68, v150
	v_cndmask_b32_e32 v213, v204, v55, vcc
	v_cmp_gt_u32_e32 vcc, s58, v87
	v_mov_b32_dpp v151, v150 row_shl:4 row_mask:0xf bank_mask:0x5
	v_mov_b32_dpp v151, v150 row_shr:4 row_mask:0xf bank_mask:0xa
	s_or_b64 vcc, s[2:3], vcc
	v_cndmask_b32_e32 v214, v204, v71, vcc
	v_add_u32_e32 v71, 0x60, v154
	v_cmp_gt_u32_e32 vcc, s58, v71
	s_or_b64 vcc, s[2:3], vcc
	v_max3_f32 v55, v212, s59, v213
	v_cndmask_b32_e32 v154, v204, v39, vcc
	s_nop 0
	v_max_f32_e32 v151, v151, v151
	v_max3_f32 v39, v55, v214, v154
	v_max_f32_e32 v152, v150, v151
	v_mov_b32_e32 v55, v39
	v_mov_b32_e32 v255, v39
	s_nop 1
	v_permlane16_swap_b32_e32 v55, v255
	s_nop 1
	v_mov_b32_dpp v55, v255 quad_perm:[0,1,2,3] row_mask:0x5 bank_mask:0xf
	v_sub_f32_e32 v68, v153, v160
	v_mov_b32_dpp v153, v152 quad_perm:[2,3,0,1] row_mask:0xf bank_mask:0xf
	v_sub_f32_e32 v84, v155, v160
	v_mul_f32_e32 v52, 0x3fb8aa3b, v84
	s_nop 0
	v_max_f32_e32 v55, v55, v55
	v_max_f32_e32 v55, v39, v55
	s_nop 0
	v_max_f32_e32 v153, v153, v153
	v_max_f32_e32 v152, v152, v153
	v_mov_b32_dpp v71, v55 row_ror:8 row_mask:0xf bank_mask:0xf
	s_nop 1
	v_mov_b32_dpp v153, v152 quad_perm:[1,0,3,2] row_mask:0xf bank_mask:0xf
	v_sub_f32_e32 v84, v156, v160
	v_mul_f32_e32 v37, 0x3fb8aa3b, v37
	v_mul_f32_e32 v36, 0x3fb8aa3b, v36
	s_nop 0
	v_max_f32_e32 v71, v71, v71
	s_nop 0
	v_max3_f32 v156, v136, v152, v153
	v_max_f32_e32 v71, v55, v71
	v_sub_f32_e32 v39, v86, v156
	s_nop 1
	v_mov_b32_dpp v86, v71 row_shl:4 row_mask:0xf bank_mask:0x5
	v_mov_b32_dpp v86, v71 row_shr:4 row_mask:0xf bank_mask:0xa
	v_sub_f32_e32 v54, v54, v156
	v_mul_f32_e32 v54, 0x3fb8aa3b, v54
	v_exp_f32_e32 v55, v54
	v_sub_f32_e32 v54, v70, v156
	s_nop 0
	v_max_f32_e32 v70, v86, v86
	v_max_f32_e32 v70, v71, v70
	s_nop 1
	v_mov_b32_dpp v86, v70 quad_perm:[2,3,0,1] row_mask:0xf bank_mask:0xf
	v_sub_f32_e32 v38, v38, v156
	v_mul_f32_e32 v38, 0x3fb8aa3b, v38
	v_exp_f32_e32 v71, v38
	v_mul_f32_e32 v54, 0x3fb8aa3b, v54
	s_nop 0
	v_max_f32_e32 v38, v86, v86
	v_max_f32_e32 v38, v70, v38
	v_exp_f32_e32 v87, v54
	s_nop 1
	v_mov_b32_dpp v54, v38 quad_perm:[1,0,3,2] row_mask:0xf bank_mask:0xf
	v_sub_f32_e32 v136, v136, v156
	v_mul_f32_e32 v84, 0x3fb8aa3b, v84
	v_mul_f32_e32 v68, 0x3fb8aa3b, v68
	v_mul_f32_e32 v70, 0x3fb8aa3b, v136
	s_nop 0
	v_max3_f32 v155, v137, v38, v54
	v_sub_u32_e32 v38, v96, v175
	v_cmp_gt_u32_e32 vcc, s58, v38
	s_or_b64 vcc, s[2:3], vcc
	v_add_u32_e32 v54, 32, v38
	v_cndmask_b32_e32 v88, v204, v88, vcc
	v_cmp_gt_u32_e32 vcc, s58, v54
	v_exp_f32_e32 v37, v37
	v_exp_f32_e32 v36, v36
	v_exp_f32_e32 v52, v52
	v_exp_f32_e32 v84, v84
	v_exp_f32_e32 v68, v68
	v_exp_f32_e32 v136, v70
	s_or_b64 vcc, s[2:3], vcc
	v_add_u32_e32 v70, 64, v38
	v_cndmask_b32_e32 v56, v204, v56, vcc
	v_cmp_gt_u32_e32 vcc, s58, v70
	s_or_b64 vcc, s[2:3], vcc
	v_add_u32_e32 v38, 0x60, v38
	v_cndmask_b32_e32 v72, v204, v72, vcc
	v_cmp_gt_u32_e32 vcc, s58, v38
	v_cvt_pk_bf16_f32 v148, v37, v53
	v_cvt_pk_bf16_f32 v149, v85, v69
	v_cvt_pk_bf16_f32 v150, v36, v52
	v_cvt_pk_bf16_f32 v151, v84, v68
	s_or_b64 vcc, s[2:3], vcc
	ds_write2_b64 v215, v[148:149], v[150:151] offset0:144 offset1:178
	v_max3_f32 v54, v88, s59, v56
	v_cndmask_b32_e32 v150, v204, v40, vcc
	v_max3_f32 v38, v54, v72, v150
	v_mov_b32_e32 v40, v38
	v_mov_b32_e32 v255, v38
	s_nop 1
	v_permlane16_swap_b32_e32 v40, v255
	s_nop 1
	v_mov_b32_dpp v40, v255 quad_perm:[0,1,2,3] row_mask:0x5 bank_mask:0xf
	v_sub_f32_e32 v151, v154, v155
	v_sub_f32_e32 v54, v137, v155
	v_mul_f32_e32 v137, 0x3fb8aa3b, v54
	v_sub_f32_e32 v54, v212, v155
	s_waitcnt lgkmcnt(0)
	v_max_f32_e32 v40, v40, v40
	v_max_f32_e32 v40, v38, v40
	s_nop 1
	v_mov_b32_dpp v70, v40 row_ror:8 row_mask:0xf bank_mask:0xf
	v_mul_f32_e32 v54, 0x3fb8aa3b, v54
	v_exp_f32_e32 v38, v54
	v_sub_f32_e32 v54, v213, v155
	v_sub_f32_e32 v86, v214, v155
	s_nop 0
	v_max_f32_e32 v70, v70, v70
	v_max_f32_e32 v40, v40, v70
	s_nop 1
	v_mov_b32_dpp v70, v40 row_shl:4 row_mask:0xf bank_mask:0x5
	v_mov_b32_dpp v70, v40 row_shr:4 row_mask:0xf bank_mask:0xa
	v_mul_f32_e32 v39, 0x3fb8aa3b, v39
	v_mul_f32_e32 v54, 0x3fb8aa3b, v54
	v_mul_f32_e32 v86, 0x3fb8aa3b, v86
	v_exp_f32_e32 v39, v39
	s_nop 0
	v_max_f32_e32 v70, v70, v70
	v_max_f32_e32 v152, v40, v70
	s_nop 1
	v_mov_b32_dpp v153, v152 quad_perm:[2,3,0,1] row_mask:0xf bank_mask:0xf
	v_mul_f32_e32 v40, 0x3fb8aa3b, v151
	v_exp_f32_e32 v54, v54
	v_exp_f32_e32 v86, v86
	v_exp_f32_e32 v70, v40
	s_nop 0
	v_max_f32_e32 v151, v153, v153
	v_sub_u32_e32 v153, v96, v176
	v_cmp_gt_u32_e32 vcc, s58, v153
	s_or_b64 vcc, s[2:3], vcc
	v_cvt_pk_bf16_f32 v148, v39, v55
	v_cndmask_b32_e32 v212, v204, v89, vcc
	v_add_u32_e32 v89, 32, v153
	v_cmp_gt_u32_e32 vcc, s58, v89
	s_or_b64 vcc, s[2:3], vcc
	v_add_u32_e32 v89, 64, v153
	v_cndmask_b32_e32 v213, v204, v57, vcc
	v_cmp_gt_u32_e32 vcc, s58, v89
	s_or_b64 vcc, s[2:3], vcc
	v_max3_f32 v57, v212, s59, v213
	v_cndmask_b32_e32 v214, v204, v73, vcc
	v_add_u32_e32 v73, 0x60, v153
	v_cmp_gt_u32_e32 vcc, s58, v73
	s_or_b64 vcc, s[2:3], vcc
	v_cvt_pk_bf16_f32 v149, v87, v71
	v_cndmask_b32_e32 v216, v204, v41, vcc
	v_max3_f32 v57, v57, v214, v216
	v_mov_b32_e32 v73, v57
	v_mov_b32_e32 v255, v57
	s_nop 1
	v_permlane16_swap_b32_e32 v73, v255
	s_nop 1
	v_mov_b32_dpp v73, v255 quad_perm:[0,1,2,3] row_mask:0x5 bank_mask:0xf
	v_cvt_pk_bf16_f32 v40, v38, v54
	v_cvt_pk_bf16_f32 v41, v86, v70
	ds_write2_b64 v215, v[148:149], v[40:41] offset0:212 offset1:246
	v_max_f32_e32 v151, v152, v151
	s_nop 0
	v_max_f32_e32 v41, v73, v73
	v_max_f32_e32 v57, v57, v41
	s_nop 1
	v_mov_b32_dpp v73, v57 row_ror:8 row_mask:0xf bank_mask:0xf
	v_mov_b32_dpp v152, v151 quad_perm:[1,0,3,2] row_mask:0xf bank_mask:0xf
	v_sub_f32_e32 v135, v135, v160
	v_mul_f32_e32 v131, 0x3fb8aa3b, v131
	v_mul_f32_e32 v135, 0x3fb8aa3b, v135
	s_waitcnt lgkmcnt(0)
	v_max_f32_e32 v73, v73, v73
	s_nop 0
	v_max3_f32 v154, v138, v151, v152
	v_max_f32_e32 v73, v57, v73
	v_sub_f32_e32 v41, v88, v154
	s_nop 1
	v_mov_b32_dpp v88, v73 row_shl:4 row_mask:0xf bank_mask:0x5
	v_mov_b32_dpp v88, v73 row_shr:4 row_mask:0xf bank_mask:0xa
	v_sub_f32_e32 v56, v56, v154
	v_mul_f32_e32 v56, 0x3fb8aa3b, v56
	v_exp_f32_e32 v57, v56
	v_sub_f32_e32 v56, v72, v154
	s_nop 0
	v_max_f32_e32 v72, v88, v88
	v_max_f32_e32 v72, v73, v72
	s_nop 1
	v_mov_b32_dpp v88, v72 quad_perm:[2,3,0,1] row_mask:0xf bank_mask:0xf
	v_mul_f32_e32 v56, 0x3fb8aa3b, v56
	v_exp_f32_e32 v89, v56
	v_sub_f32_e32 v56, v150, v154
	v_mul_f32_e32 v56, 0x3fb8aa3b, v56
	v_exp_f32_e32 v73, v56
	s_nop 0
	v_max_f32_e32 v56, v88, v88
	v_max_f32_e32 v56, v72, v56
	s_nop 1
	v_mov_b32_dpp v72, v56 quad_perm:[1,0,3,2] row_mask:0xf bank_mask:0xf
	v_sub_f32_e32 v40, v138, v154
	v_mul_f32_e32 v40, 0x3fb8aa3b, v40
	v_exp_f32_e32 v138, v40
	v_sub_u32_e32 v40, v96, v177
	v_cmp_gt_u32_e32 vcc, s58, v40
	s_nop 0
	v_max3_f32 v153, v139, v56, v72
	s_or_b64 vcc, s[2:3], vcc
	v_add_u32_e32 v56, 32, v40
	v_cndmask_b32_e32 v90, v204, v90, vcc
	v_cmp_gt_u32_e32 vcc, s58, v56
	s_or_b64 vcc, s[2:3], vcc
	v_add_u32_e32 v72, 64, v40
	v_cndmask_b32_e32 v58, v204, v58, vcc
	v_cmp_gt_u32_e32 vcc, s58, v72
	s_or_b64 vcc, s[2:3], vcc
	v_add_u32_e32 v40, 0x60, v40
	v_cndmask_b32_e32 v74, v204, v74, vcc
	v_cmp_gt_u32_e32 vcc, s58, v40
	s_or_b64 vcc, s[2:3], vcc
	v_max3_f32 v56, v90, s59, v58
	v_cndmask_b32_e32 v42, v204, v42, vcc
	v_max3_f32 v56, v56, v74, v42
	v_mov_b32_e32 v72, v56
	v_mov_b32_e32 v255, v56
	s_nop 1
	v_permlane16_swap_b32_e32 v72, v255
	s_nop 1
	v_mov_b32_dpp v72, v255 quad_perm:[0,1,2,3] row_mask:0x5 bank_mask:0xf
	v_sub_f32_e32 v88, v213, v153
	v_sub_u32_e32 v213, v96, v178
	v_cmp_gt_u32_e32 vcc, s58, v213
	s_or_b64 vcc, s[2:3], vcc
	s_nop 0
	v_max_f32_e32 v72, v72, v72
	v_max_f32_e32 v72, v56, v72
	s_nop 1
	v_mov_b32_dpp v150, v72 row_ror:8 row_mask:0xf bank_mask:0xf
	v_mul_f32_e32 v56, 0x3fb8aa3b, v88
	v_sub_f32_e32 v88, v214, v153
	v_cndmask_b32_e32 v214, v204, v91, vcc
	v_add_u32_e32 v91, 32, v213
	v_cmp_gt_u32_e32 vcc, s58, v91
	s_nop 0
	v_max_f32_e32 v150, v150, v150
	s_or_b64 vcc, s[2:3], vcc
	v_add_u32_e32 v91, 64, v213
	v_max_f32_e32 v150, v72, v150
	v_cndmask_b32_e32 v215, v204, v59, vcc
	v_cmp_gt_u32_e32 vcc, s58, v91
	v_mov_b32_dpp v151, v150 row_shl:4 row_mask:0xf bank_mask:0x5
	v_mov_b32_dpp v151, v150 row_shr:4 row_mask:0xf bank_mask:0xa
	s_or_b64 vcc, s[2:3], vcc
	v_sub_f32_e32 v72, v216, v153
	v_cndmask_b32_e32 v216, v204, v75, vcc
	v_add_u32_e32 v75, 0x60, v213
	v_cmp_gt_u32_e32 vcc, s58, v75
	s_or_b64 vcc, s[2:3], vcc
	v_max3_f32 v59, v214, s59, v215
	v_cndmask_b32_e32 v213, v204, v43, vcc
	s_nop 0
	v_max_f32_e32 v151, v151, v151
	v_max3_f32 v43, v59, v216, v213
	v_sub_f32_e32 v40, v212, v153
	v_max_f32_e32 v152, v150, v151
	v_mov_b32_e32 v59, v43
	v_mov_b32_e32 v255, v43
	s_nop 1
	v_permlane16_swap_b32_e32 v59, v255
	s_nop 1
	v_mov_b32_dpp v59, v255 quad_perm:[0,1,2,3] row_mask:0x5 bank_mask:0xf
	v_mul_f32_e32 v41, 0x3fb8aa3b, v41
	v_mul_f32_e32 v40, 0x3fb8aa3b, v40
	v_mul_f32_e32 v88, 0x3fb8aa3b, v88
	v_mul_f32_e32 v72, 0x3fb8aa3b, v72
	v_mov_b32_dpp v212, v152 quad_perm:[2,3,0,1] row_mask:0xf bank_mask:0xf
	v_exp_f32_e32 v41, v41
	v_exp_f32_e32 v40, v40
	v_exp_f32_e32 v56, v56
	v_exp_f32_e32 v88, v88
	v_exp_f32_e32 v72, v72
	s_nop 0
	v_max_f32_e32 v59, v59, v59
	v_cvt_pk_bf16_f32 v148, v41, v57
	v_cvt_pk_bf16_f32 v149, v89, v73
	v_cvt_pk_bf16_f32 v150, v40, v56
	v_cvt_pk_bf16_f32 v151, v88, v72
	s_nop 0
	v_max_f32_e32 v212, v212, v212
	v_add_u32_e32 v75, 0x9800, v186
	v_max_f32_e32 v59, v43, v59
	v_max_f32_e32 v152, v152, v212
	ds_write2_b64 v75, v[148:149], v[150:151] offset0:160 offset1:194
	v_mov_b32_dpp v75, v59 row_ror:8 row_mask:0xf bank_mask:0xf
	v_mov_b32_dpp v212, v152 quad_perm:[1,0,3,2] row_mask:0xf bank_mask:0xf
	v_sub_f32_e32 v139, v139, v153
	v_mul_f32_e32 v139, 0x3fb8aa3b, v139
	v_exp_f32_e32 v131, v131
	s_waitcnt lgkmcnt(0)
	v_max_f32_e32 v75, v75, v75
	s_nop 0
	v_max3_f32 v152, v140, v152, v212
	v_max_f32_e32 v75, v59, v75
	v_sub_f32_e32 v43, v90, v152
	s_nop 1
	v_mov_b32_dpp v90, v75 row_shl:4 row_mask:0xf bank_mask:0x5
	v_mov_b32_dpp v90, v75 row_shr:4 row_mask:0xf bank_mask:0xa
	v_sub_f32_e32 v58, v58, v152
	v_mul_f32_e32 v58, 0x3fb8aa3b, v58
	v_exp_f32_e32 v59, v58
	v_sub_f32_e32 v58, v74, v152
	s_nop 0
	v_max_f32_e32 v74, v90, v90
	v_max_f32_e32 v74, v75, v74
	s_nop 1
	v_mov_b32_dpp v90, v74 quad_perm:[2,3,0,1] row_mask:0xf bank_mask:0xf
	v_sub_f32_e32 v42, v42, v152
	v_mul_f32_e32 v42, 0x3fb8aa3b, v42
	v_exp_f32_e32 v75, v42
	v_mul_f32_e32 v58, 0x3fb8aa3b, v58
	s_nop 0
	v_max_f32_e32 v42, v90, v90
	v_max_f32_e32 v42, v74, v42
	v_exp_f32_e32 v91, v58
	s_nop 1
	v_mov_b32_dpp v58, v42 quad_perm:[1,0,3,2] row_mask:0xf bank_mask:0xf
	v_sub_f32_e32 v140, v140, v152
	v_mul_f32_e32 v74, 0x3fb8aa3b, v140
	v_exp_f32_e32 v140, v74
	v_mul_f32_e32 v43, 0x3fb8aa3b, v43
	s_nop 0
	v_max3_f32 v151, v141, v42, v58
	v_sub_u32_e32 v42, v96, v179
	v_cmp_gt_u32_e32 vcc, s58, v42
	s_or_b64 vcc, s[2:3], vcc
	v_add_u32_e32 v58, 32, v42
	v_cndmask_b32_e32 v92, v204, v92, vcc
	v_cmp_gt_u32_e32 vcc, s58, v58
	s_or_b64 vcc, s[2:3], vcc
	v_add_u32_e32 v74, 64, v42
	v_cndmask_b32_e32 v60, v204, v60, vcc
	v_cmp_gt_u32_e32 vcc, s58, v74
	s_or_b64 vcc, s[2:3], vcc
	v_add_u32_e32 v42, 0x60, v42
	v_cndmask_b32_e32 v76, v204, v76, vcc
	v_cmp_gt_u32_e32 vcc, s58, v42
	s_or_b64 vcc, s[2:3], vcc
	v_max3_f32 v58, v92, s59, v60
	v_cndmask_b32_e32 v44, v204, v44, vcc
	v_max3_f32 v58, v58, v76, v44
	v_mov_b32_e32 v74, v58
	v_mov_b32_e32 v255, v58
	s_nop 1
	v_permlane16_swap_b32_e32 v74, v255
	s_nop 1
	v_mov_b32_dpp v74, v255 quad_perm:[0,1,2,3] row_mask:0x5 bank_mask:0xf
	v_sub_f32_e32 v90, v215, v151
	v_sub_u32_e32 v215, v96, v180
	v_cmp_gt_u32_e32 vcc, s58, v215
	s_or_b64 vcc, s[2:3], vcc
	s_nop 0
	v_max_f32_e32 v74, v74, v74
	v_max_f32_e32 v74, v58, v74
	s_nop 1
	v_mov_b32_dpp v150, v74 row_ror:8 row_mask:0xf bank_mask:0xf
	v_mul_f32_e32 v58, 0x3fb8aa3b, v90
	v_sub_f32_e32 v90, v216, v151
	v_cndmask_b32_e32 v216, v204, v93, vcc
	v_add_u32_e32 v93, 32, v215
	v_cmp_gt_u32_e32 vcc, s58, v93
	s_nop 0
	v_max_f32_e32 v150, v150, v150
	s_or_b64 vcc, s[2:3], vcc
	v_add_u32_e32 v93, 64, v215
	v_max_f32_e32 v150, v74, v150
	v_cndmask_b32_e32 v217, v204, v61, vcc
	v_cmp_gt_u32_e32 vcc, s58, v93
	v_mov_b32_dpp v212, v150 row_shl:4 row_mask:0xf bank_mask:0x5
	v_mov_b32_dpp v212, v150 row_shr:4 row_mask:0xf bank_mask:0xa
	s_or_b64 vcc, s[2:3], vcc
	v_cndmask_b32_e32 v218, v204, v77, vcc
	v_add_u32_e32 v77, 0x60, v215
	v_cmp_gt_u32_e32 vcc, s58, v77
	s_or_b64 vcc, s[2:3], vcc
	v_max3_f32 v61, v216, s59, v217
	v_cndmask_b32_e32 v215, v204, v45, vcc
	s_nop 0
	v_max_f32_e32 v212, v212, v212
	v_max3_f32 v45, v61, v218, v215
	v_sub_f32_e32 v42, v214, v151
	v_sub_f32_e32 v74, v213, v151
	v_max_f32_e32 v150, v150, v212
	v_mov_b32_e32 v61, v45
	v_mov_b32_e32 v255, v45
	s_nop 1
	v_permlane16_swap_b32_e32 v61, v255
	s_nop 1
	v_mov_b32_dpp v61, v255 quad_perm:[0,1,2,3] row_mask:0x5 bank_mask:0xf
	v_mul_f32_e32 v42, 0x3fb8aa3b, v42
	v_mul_f32_e32 v90, 0x3fb8aa3b, v90
	v_mul_f32_e32 v74, 0x3fb8aa3b, v74
	v_mov_b32_dpp v214, v150 quad_perm:[2,3,0,1] row_mask:0xf bank_mask:0xf
	v_exp_f32_e32 v43, v43
	v_exp_f32_e32 v42, v42
	v_exp_f32_e32 v58, v58
	v_exp_f32_e32 v90, v90
	v_exp_f32_e32 v74, v74
	s_nop 0
	v_max_f32_e32 v61, v61, v61
	v_cvt_pk_bf16_f32 v148, v43, v59
	v_cvt_pk_bf16_f32 v149, v91, v75
	v_cvt_pk_bf16_f32 v212, v42, v58
	v_cvt_pk_bf16_f32 v213, v90, v74
	s_nop 0
	v_max_f32_e32 v214, v214, v214
	v_add_u32_e32 v77, 0x9c00, v186
	v_max_f32_e32 v61, v45, v61
	v_max_f32_e32 v150, v150, v214
	ds_write2_b64 v77, v[148:149], v[212:213] offset0:100 offset1:134
	v_mov_b32_dpp v77, v61 row_ror:8 row_mask:0xf bank_mask:0xf
	v_mov_b32_dpp v214, v150 quad_perm:[1,0,3,2] row_mask:0xf bank_mask:0xf
	v_sub_f32_e32 v141, v141, v151
	v_mul_f32_e32 v141, 0x3fb8aa3b, v141
	v_exp_f32_e32 v133, v133
	s_waitcnt lgkmcnt(0)
	v_max_f32_e32 v77, v77, v77
	s_nop 0
	v_max3_f32 v150, v142, v150, v214
	v_max_f32_e32 v77, v61, v77
	v_sub_f32_e32 v45, v92, v150
	s_nop 1
	v_mov_b32_dpp v92, v77 row_shl:4 row_mask:0xf bank_mask:0x5
	v_mov_b32_dpp v92, v77 row_shr:4 row_mask:0xf bank_mask:0xa
	v_sub_f32_e32 v60, v60, v150
	v_mul_f32_e32 v60, 0x3fb8aa3b, v60
	v_exp_f32_e32 v61, v60
	v_sub_f32_e32 v60, v76, v150
	s_nop 0
	v_max_f32_e32 v76, v92, v92
	v_max_f32_e32 v76, v77, v76
	s_nop 1
	v_mov_b32_dpp v92, v76 quad_perm:[2,3,0,1] row_mask:0xf bank_mask:0xf
	v_sub_f32_e32 v44, v44, v150
	v_mul_f32_e32 v44, 0x3fb8aa3b, v44
	v_exp_f32_e32 v77, v44
	v_mul_f32_e32 v60, 0x3fb8aa3b, v60
	s_nop 0
	v_max_f32_e32 v44, v92, v92
	v_max_f32_e32 v44, v76, v44
	v_exp_f32_e32 v93, v60
	s_nop 1
	v_mov_b32_dpp v60, v44 quad_perm:[1,0,3,2] row_mask:0xf bank_mask:0xf
	v_sub_f32_e32 v142, v142, v150
	v_mul_f32_e32 v76, 0x3fb8aa3b, v142
	v_exp_f32_e32 v142, v76
	v_mul_f32_e32 v45, 0x3fb8aa3b, v45
	s_nop 0
	v_max3_f32 v149, v143, v44, v60
	v_sub_u32_e32 v44, v96, v181
	v_cmp_gt_u32_e32 vcc, s58, v44
	s_or_b64 vcc, s[2:3], vcc
	v_add_u32_e32 v60, 32, v44
	v_cndmask_b32_e32 v94, v204, v94, vcc
	v_cmp_gt_u32_e32 vcc, s58, v60
	s_or_b64 vcc, s[2:3], vcc
	v_add_u32_e32 v76, 64, v44
	v_cndmask_b32_e32 v62, v204, v62, vcc
	v_cmp_gt_u32_e32 vcc, s58, v76
	s_or_b64 vcc, s[2:3], vcc
	v_add_u32_e32 v44, 0x60, v44
	v_cndmask_b32_e32 v78, v204, v78, vcc
	v_cmp_gt_u32_e32 vcc, s58, v44
	s_or_b64 vcc, s[2:3], vcc
	v_max3_f32 v60, v94, s59, v62
	v_cndmask_b32_e32 v46, v204, v46, vcc
	v_max3_f32 v60, v60, v78, v46
	v_mov_b32_e32 v76, v60
	v_mov_b32_e32 v255, v60
	s_nop 1
	v_permlane16_swap_b32_e32 v76, v255
	s_nop 1
	v_mov_b32_dpp v76, v255 quad_perm:[0,1,2,3] row_mask:0x5 bank_mask:0xf
	v_sub_u32_e32 v96, v96, v182
	v_cmp_gt_u32_e32 vcc, s58, v96
	s_or_b64 vcc, s[2:3], vcc
	v_sub_f32_e32 v92, v217, v149
	s_nop 0
	v_max_f32_e32 v76, v76, v76
	v_max_f32_e32 v76, v60, v76
	s_nop 1
	v_mov_b32_dpp v148, v76 row_ror:8 row_mask:0xf bank_mask:0xf
	v_cndmask_b32_e32 v217, v204, v95, vcc
	v_add_u32_e32 v95, 32, v96
	v_cmp_gt_u32_e32 vcc, s58, v95
	s_or_b64 vcc, s[2:3], vcc
	s_nop 0
	v_max_f32_e32 v148, v148, v148
	v_add_u32_e32 v95, 64, v96
	v_mul_f32_e32 v60, 0x3fb8aa3b, v92
	v_sub_f32_e32 v92, v218, v149
	v_max_f32_e32 v148, v76, v148
	v_cndmask_b32_e32 v218, v204, v63, vcc
	v_cmp_gt_u32_e32 vcc, s58, v95
	v_mov_b32_dpp v214, v148 row_shl:4 row_mask:0xf bank_mask:0x5
	v_mov_b32_dpp v214, v148 row_shr:4 row_mask:0xf bank_mask:0xa
	s_or_b64 vcc, s[2:3], vcc
	v_cndmask_b32_e32 v219, v204, v79, vcc
	v_add_u32_e32 v79, 0x60, v96
	v_cmp_gt_u32_e32 vcc, s58, v79
	s_or_b64 vcc, s[2:3], vcc
	v_max3_f32 v63, v217, s59, v218
	v_cndmask_b32_e32 v96, v204, v47, vcc
	s_nop 0
	v_max_f32_e32 v214, v214, v214
	v_max3_f32 v47, v63, v219, v96
	v_sub_f32_e32 v44, v216, v149
	v_sub_f32_e32 v76, v215, v149
	v_max_f32_e32 v148, v148, v214
	v_mov_b32_e32 v63, v47
	v_mov_b32_e32 v255, v47
	s_nop 1
	v_permlane16_swap_b32_e32 v63, v255
	s_nop 1
	v_mov_b32_dpp v63, v255 quad_perm:[0,1,2,3] row_mask:0x5 bank_mask:0xf
	v_mul_f32_e32 v44, 0x3fb8aa3b, v44
	v_mul_f32_e32 v92, 0x3fb8aa3b, v92
	v_mul_f32_e32 v76, 0x3fb8aa3b, v76
	v_mov_b32_dpp v216, v148 quad_perm:[2,3,0,1] row_mask:0xf bank_mask:0xf
	v_exp_f32_e32 v45, v45
	v_exp_f32_e32 v44, v44
	v_exp_f32_e32 v60, v60
	v_exp_f32_e32 v92, v92
	v_exp_f32_e32 v76, v76
	s_nop 0
	v_max_f32_e32 v63, v63, v63
	v_cvt_pk_bf16_f32 v212, v45, v61
	v_cvt_pk_bf16_f32 v213, v93, v77
	v_cvt_pk_bf16_f32 v214, v44, v60
	v_cvt_pk_bf16_f32 v215, v92, v76
	s_nop 0
	v_max_f32_e32 v216, v216, v216
	v_add_u32_e32 v79, 0xa000, v186
	v_max_f32_e32 v63, v47, v63
	v_max_f32_e32 v148, v148, v216
	ds_write2_b64 v79, v[212:213], v[214:215] offset0:176 offset1:210
	v_mov_b32_dpp v79, v63 row_ror:8 row_mask:0xf bank_mask:0xf
	v_mov_b32_dpp v216, v148 quad_perm:[1,0,3,2] row_mask:0xf bank_mask:0xf
	v_sub_f32_e32 v143, v143, v149
	v_mul_f32_e32 v143, 0x3fb8aa3b, v143
	v_exp_f32_e32 v135, v135
	s_waitcnt lgkmcnt(0)
	v_max_f32_e32 v79, v79, v79
	s_nop 0
	v_max3_f32 v148, v144, v148, v216
	v_max_f32_e32 v79, v63, v79
	v_sub_f32_e32 v47, v94, v148
	s_nop 1
	v_mov_b32_dpp v94, v79 row_shl:4 row_mask:0xf bank_mask:0x5
	v_mov_b32_dpp v94, v79 row_shr:4 row_mask:0xf bank_mask:0xa
	v_sub_f32_e32 v62, v62, v148
	v_mul_f32_e32 v62, 0x3fb8aa3b, v62
	v_exp_f32_e32 v63, v62
	v_sub_f32_e32 v62, v78, v148
	s_nop 0
	v_max_f32_e32 v78, v94, v94
	v_max_f32_e32 v78, v79, v78
	s_nop 1
	v_mov_b32_dpp v94, v78 quad_perm:[2,3,0,1] row_mask:0xf bank_mask:0xf
	v_sub_f32_e32 v46, v46, v148
	v_mul_f32_e32 v46, 0x3fb8aa3b, v46
	v_exp_f32_e32 v79, v46
	v_mul_f32_e32 v62, 0x3fb8aa3b, v62
	s_nop 0
	v_max_f32_e32 v46, v94, v94
	v_max_f32_e32 v46, v78, v46
	v_exp_f32_e32 v95, v62
	s_nop 1
	v_mov_b32_dpp v62, v46 quad_perm:[1,0,3,2] row_mask:0xf bank_mask:0xf
	v_sub_f32_e32 v144, v144, v148
	v_mul_f32_e32 v78, 0x3fb8aa3b, v144
	v_exp_f32_e32 v144, v78
	v_mul_f32_e32 v47, 0x3fb8aa3b, v47
	s_nop 0
	v_max3_f32 v147, v145, v46, v62
	v_sub_f32_e32 v78, v219, v147
	v_mul_f32_e32 v78, 0x3fb8aa3b, v78
	v_sub_f32_e32 v46, v217, v147
	v_sub_f32_e32 v62, v218, v147
	v_exp_f32_e32 v94, v78
	v_sub_f32_e32 v78, v96, v147
	v_sub_f32_e32 v145, v145, v147
	v_mul_f32_e32 v46, 0x3fb8aa3b, v46
	v_mul_f32_e32 v62, 0x3fb8aa3b, v62
	v_mul_f32_e32 v78, 0x3fb8aa3b, v78
	v_exp_f32_e32 v47, v47
	v_exp_f32_e32 v46, v46
	v_exp_f32_e32 v62, v62
	v_exp_f32_e32 v78, v78
	v_mul_f32_e32 v96, 0x3fb8aa3b, v145
	v_exp_f32_e32 v137, v137
	v_exp_f32_e32 v139, v139
	v_exp_f32_e32 v141, v141
	v_exp_f32_e32 v143, v143
	v_exp_f32_e32 v145, v96
	v_cvt_pk_bf16_f32 v208, v47, v63
	v_cvt_pk_bf16_f32 v209, v95, v79
	v_cvt_pk_bf16_f32 v210, v46, v62
	v_cvt_pk_bf16_f32 v211, v94, v78
	v_add_u32_e32 v96, 0xa400, v186
	ds_write2_b64 v96, v[208:209], v[210:211] offset0:116 offset1:150
	v_pk_mul_f32 v[14:15], v[14:15], v[144:145]
	v_pk_mul_f32 v[12:13], v[12:13], v[142:143]
	v_pk_mul_f32 v[10:11], v[10:11], v[140:141]
	v_pk_mul_f32 v[8:9], v[8:9], v[138:139]
	v_pk_mul_f32 v[6:7], v[6:7], v[136:137]
	v_pk_mul_f32 v[4:5], v[4:5], v[134:135]
	v_pk_mul_f32 v[2:3], v[2:3], v[132:133]
	v_pk_mul_f32 v[0:1], v[0:1], v[130:131]
	v_pk_mul_f32 v[30:31], v[30:31], v[144:145]
	v_pk_mul_f32 v[28:29], v[28:29], v[142:143]
	v_pk_mul_f32 v[26:27], v[26:27], v[140:141]
	v_pk_mul_f32 v[24:25], v[24:25], v[138:139]
	v_pk_mul_f32 v[22:23], v[22:23], v[136:137]
	v_pk_mul_f32 v[20:21], v[20:21], v[134:135]
	v_pk_mul_f32 v[18:19], v[18:19], v[132:133]
	v_pk_mul_f32 v[16:17], v[16:17], v[130:131]
	s_mov_b32 s2, -16
	v_mov_b32_e32 v96, v185
	v_mov_b32_e32 v208, v184
	s_waitcnt lgkmcnt(0)
	s_barrier

.LBB0_722:
	v_mbcnt_hi_u32_b32 v35, -1, v195
	v_and_b32_e32 v32, 64, v35
	v_add_u32_e32 v36, 64, v32
	v_xor_b32_e32 v37, 16, v35
	v_cmp_lt_i32_e32 vcc, v37, v36
	v_xor_b32_e32 v38, 8, v35
	s_lshl_b32 s0, s42, 1
	v_cndmask_b32_e32 v37, v35, v37, vcc
	v_lshlrev_b32_e32 v39, 2, v37
	v_mov_b32_e32 v37, v129
	v_mov_b32_e32 v255, v129
	s_nop 1
	v_permlane16_swap_b32_e32 v37, v255
	s_nop 1
	v_mov_b32_dpp v37, v255 quad_perm:[0,1,2,3] row_mask:0x5 bank_mask:0xf
	v_cmp_lt_i32_e32 vcc, v38, v36
	v_readlane_b32 s1, v249, 25
	s_add_u32 s0, s1, s0
	v_cndmask_b32_e32 v38, v35, v38, vcc
	s_waitcnt lgkmcnt(0)
	v_add_f32_e32 v37, v129, v37
	v_lshlrev_b32_e32 v40, 2, v38
	s_nop 1
	v_mov_b32_dpp v38, v37 row_ror:8 row_mask:0xf bank_mask:0xf
	v_readlane_b32 s1, v249, 26
	s_addc_u32 s1, s1, 0
	v_lshlrev_b32_e32 v96, 1, v157
	v_lshl_add_u64 v[32:33], s[0:1], 0, v[96:97]
	s_nop 0
	v_add_f32_e32 v37, v37, v38
	v_xor_b32_e32 v38, 4, v35
	v_cmp_lt_i32_e32 vcc, v38, v36
	v_add_u32_e32 v34, s4, v159
	s_nop 0
	v_cndmask_b32_e32 v38, v35, v38, vcc
	v_lshlrev_b32_e32 v38, 2, v38
	v_mov_b32_dpp v41, v37 row_shl:4 row_mask:0xf bank_mask:0x5
	v_mov_b32_dpp v41, v37 row_shr:4 row_mask:0xf bank_mask:0xa
	s_nop 0
	v_add_f32_e32 v41, v37, v41
	v_xor_b32_e32 v37, 2, v35
	v_cmp_lt_i32_e32 vcc, v37, v36
	s_nop 1
	v_cndmask_b32_e32 v37, v35, v37, vcc
	v_lshlrev_b32_e32 v37, 2, v37
	v_mov_b32_dpp v42, v41 quad_perm:[2,3,0,1] row_mask:0xf bank_mask:0xf
	s_nop 0
	v_add_f32_e32 v41, v41, v42
	v_xor_b32_e32 v42, 1, v35
	v_cmp_lt_i32_e32 vcc, v42, v36
	s_nop 1
	v_cndmask_b32_e32 v35, v35, v42, vcc
	v_lshlrev_b32_e32 v36, 2, v35
	v_mov_b32_dpp v35, v41 quad_perm:[1,0,3,2] row_mask:0xf bank_mask:0xf
	s_nop 0
	v_add_f32_e32 v35, v41, v35
	v_sub_f32_e32 v41, v146, v207
	v_mul_f32_e32 v41, 0x3fb8aa3b, v41
	v_exp_f32_e32 v41, v41
	s_nop 0
	v_add_f32_e32 v35, v41, v35
	v_div_scale_f32 v41, s[0:1], v35, v35, 1.0
	v_rcp_f32_e32 v42, v41
	s_nop 0
	v_fma_f32 v43, -v41, v42, 1.0
	v_fmac_f32_e32 v42, v43, v42
	v_div_scale_f32 v43, vcc, 1.0, v35, 1.0
	v_mul_f32_e32 v44, v43, v42
	v_fma_f32 v45, -v41, v44, v43
	v_fmac_f32_e32 v44, v45, v42
	v_fma_f32 v41, -v41, v44, v43
	v_div_fmas_f32 v41, v41, v42, v44
	v_div_fixup_f32 v41, v41, v35, 1.0
	v_ashrrev_i32_e32 v35, 31, v34
	v_mul_f32_e32 v0, v0, v41
	v_lshlrev_b64 v[42:43], 10, v[34:35]
	v_cvt_pk_bf16_f32 v0, v0, s0
	v_lshl_add_u64 v[42:43], v[32:33], 0, v[42:43]
	global_store_short v[42:43], v0, off
	v_mul_f32_e32 v0, v16, v41
	v_cvt_pk_bf16_f32 v0, v0, s0
	global_store_short v[42:43], v0, off offset:64
	v_mov_b32_e32 v0, v128
	v_mov_b32_e32 v255, v128
	s_nop 1
	v_permlane16_swap_b32_e32 v0, v255
	s_nop 1
	v_mov_b32_dpp v0, v255 quad_perm:[0,1,2,3] row_mask:0x5 bank_mask:0xf
	s_nop 0
	v_add_f32_e32 v0, v128, v0
	s_nop 1
	v_mov_b32_dpp v16, v0 row_ror:8 row_mask:0xf bank_mask:0xf
	s_nop 0
	v_add_f32_e32 v0, v0, v16
	s_nop 1
	v_mov_b32_dpp v16, v0 row_shl:4 row_mask:0xf bank_mask:0x5
	v_mov_b32_dpp v16, v0 row_shr:4 row_mask:0xf bank_mask:0xa
	s_nop 0
	v_add_f32_e32 v0, v0, v16
	s_nop 1
	v_mov_b32_dpp v16, v0 quad_perm:[2,3,0,1] row_mask:0xf bank_mask:0xf
	s_nop 0
	v_add_f32_e32 v0, v0, v16
	s_nop 1
	v_mov_b32_dpp v16, v0 quad_perm:[1,0,3,2] row_mask:0xf bank_mask:0xf
	s_nop 0
	v_add_f32_e32 v0, v0, v16
	v_sub_f32_e32 v16, v146, v206
	v_mul_f32_e32 v16, 0x3fb8aa3b, v16
	v_exp_f32_e32 v16, v16
	s_nop 0
	v_add_f32_e32 v0, v16, v0
	v_div_scale_f32 v16, s[0:1], v0, v0, 1.0
	v_rcp_f32_e32 v35, v16
	s_nop 0
	v_fma_f32 v41, -v16, v35, 1.0
	v_fmac_f32_e32 v35, v41, v35
	v_div_scale_f32 v41, vcc, 1.0, v0, 1.0
	v_mul_f32_e32 v42, v41, v35
	v_fma_f32 v43, -v16, v42, v41
	v_fmac_f32_e32 v42, v43, v35
	v_fma_f32 v16, -v16, v42, v41
	v_div_fmas_f32 v16, v16, v35, v42
	v_div_fixup_f32 v16, v16, v0, 1.0
	v_add_u32_e32 v0, 1, v34
	v_mul_f32_e32 v1, v1, v16
	v_cvt_pk_bf16_f32 v35, v1, s0
	v_ashrrev_i32_e32 v1, 31, v0
	v_lshlrev_b64 v[0:1], 10, v[0:1]
	v_mul_f32_e32 v16, v17, v16
	v_lshl_add_u64 v[0:1], v[32:33], 0, v[0:1]
	v_cvt_pk_bf16_f32 v16, v16, s0
	global_store_short v[0:1], v35, off
	global_store_short v[0:1], v16, off offset:64
	v_mov_b32_e32 v0, v127
	v_mov_b32_e32 v255, v127
	s_nop 1
	v_permlane16_swap_b32_e32 v0, v255
	s_nop 1
	v_mov_b32_dpp v0, v255 quad_perm:[0,1,2,3] row_mask:0x5 bank_mask:0xf
	s_nop 0
	v_add_f32_e32 v0, v127, v0
	s_nop 1
	v_mov_b32_dpp v1, v0 row_ror:8 row_mask:0xf bank_mask:0xf
	s_nop 0
	v_add_f32_e32 v0, v0, v1
	s_nop 1
	v_mov_b32_dpp v1, v0 row_shl:4 row_mask:0xf bank_mask:0x5
	v_mov_b32_dpp v1, v0 row_shr:4 row_mask:0xf bank_mask:0xa
	s_nop 0
	v_add_f32_e32 v0, v0, v1
	s_nop 1
	v_mov_b32_dpp v1, v0 quad_perm:[2,3,0,1] row_mask:0xf bank_mask:0xf
	s_nop 0
	v_add_f32_e32 v0, v0, v1
	s_nop 1
	v_mov_b32_dpp v1, v0 quad_perm:[1,0,3,2] row_mask:0xf bank_mask:0xf
	s_nop 0
	v_add_f32_e32 v0, v0, v1
	v_sub_f32_e32 v1, v146, v189
	v_mul_f32_e32 v1, 0x3fb8aa3b, v1
	v_exp_f32_e32 v1, v1
	s_nop 0
	v_add_f32_e32 v0, v1, v0
	v_div_scale_f32 v1, s[0:1], v0, v0, 1.0
	v_rcp_f32_e32 v16, v1
	s_nop 0
	v_fma_f32 v17, -v1, v16, 1.0
	v_fmac_f32_e32 v16, v17, v16
	v_div_scale_f32 v17, vcc, 1.0, v0, 1.0
	v_mul_f32_e32 v35, v17, v16
	v_fma_f32 v41, -v1, v35, v17
	v_fmac_f32_e32 v35, v41, v16
	v_fma_f32 v1, -v1, v35, v17
	v_div_fmas_f32 v1, v1, v16, v35
	v_div_fixup_f32 v16, v1, v0, 1.0
	v_add_u32_e32 v0, 2, v34
	v_mul_f32_e32 v1, v2, v16
	v_cvt_pk_bf16_f32 v2, v1, s0
	v_ashrrev_i32_e32 v1, 31, v0
	v_lshlrev_b64 v[0:1], 10, v[0:1]
	v_lshl_add_u64 v[0:1], v[32:33], 0, v[0:1]
	global_store_short v[0:1], v2, off
	v_mul_f32_e32 v2, v18, v16
	v_cvt_pk_bf16_f32 v2, v2, s0
	global_store_short v[0:1], v2, off offset:64
	v_mov_b32_e32 v0, v126
	v_mov_b32_e32 v255, v126
	s_nop 1
	v_permlane16_swap_b32_e32 v0, v255
	s_nop 1
	v_mov_b32_dpp v0, v255 quad_perm:[0,1,2,3] row_mask:0x5 bank_mask:0xf
	s_nop 0
	v_add_f32_e32 v0, v126, v0
	s_nop 1
	v_mov_b32_dpp v1, v0 row_ror:8 row_mask:0xf bank_mask:0xf
	s_nop 0
	v_add_f32_e32 v0, v0, v1
	s_nop 1
	v_mov_b32_dpp v1, v0 row_shl:4 row_mask:0xf bank_mask:0x5
	v_mov_b32_dpp v1, v0 row_shr:4 row_mask:0xf bank_mask:0xa
	s_nop 0
	v_add_f32_e32 v0, v0, v1
	s_nop 1
	v_mov_b32_dpp v1, v0 quad_perm:[2,3,0,1] row_mask:0xf bank_mask:0xf
	s_nop 0
	v_add_f32_e32 v0, v0, v1
	s_nop 1
	v_mov_b32_dpp v1, v0 quad_perm:[1,0,3,2] row_mask:0xf bank_mask:0xf
	s_nop 0
	v_add_f32_e32 v0, v0, v1
	v_sub_f32_e32 v1, v146, v188
	v_mul_f32_e32 v1, 0x3fb8aa3b, v1
	v_exp_f32_e32 v1, v1
	s_nop 0
	v_add_f32_e32 v0, v1, v0
	v_div_scale_f32 v1, s[0:1], v0, v0, 1.0
	v_rcp_f32_e32 v2, v1
	s_nop 0
	v_fma_f32 v16, -v1, v2, 1.0
	v_fmac_f32_e32 v2, v16, v2
	v_div_scale_f32 v16, vcc, 1.0, v0, 1.0
	v_mul_f32_e32 v17, v16, v2
	v_fma_f32 v18, -v1, v17, v16
	v_fmac_f32_e32 v17, v18, v2
	v_fma_f32 v1, -v1, v17, v16
	v_div_fmas_f32 v1, v1, v2, v17
	v_div_fixup_f32 v2, v1, v0, 1.0
	v_add_u32_e32 v0, 3, v34
	v_mul_f32_e32 v1, v3, v2
	v_cvt_pk_bf16_f32 v3, v1, s0
	v_ashrrev_i32_e32 v1, 31, v0
	v_lshlrev_b64 v[0:1], 10, v[0:1]
	v_mul_f32_e32 v2, v19, v2
	v_lshl_add_u64 v[0:1], v[32:33], 0, v[0:1]
	v_cvt_pk_bf16_f32 v2, v2, s0
	global_store_short v[0:1], v3, off
	global_store_short v[0:1], v2, off offset:64
	v_mov_b32_e32 v0, v125
	v_mov_b32_e32 v255, v125
	s_nop 1
	v_permlane16_swap_b32_e32 v0, v255
	s_nop 1
	v_mov_b32_dpp v0, v255 quad_perm:[0,1,2,3] row_mask:0x5 bank_mask:0xf
	s_nop 0
	v_add_f32_e32 v0, v125, v0
	s_nop 1
	v_mov_b32_dpp v1, v0 row_ror:8 row_mask:0xf bank_mask:0xf
	s_nop 0
	v_add_f32_e32 v0, v0, v1
	s_nop 1
	v_mov_b32_dpp v1, v0 row_shl:4 row_mask:0xf bank_mask:0x5
	v_mov_b32_dpp v1, v0 row_shr:4 row_mask:0xf bank_mask:0xa
	s_nop 0
	v_add_f32_e32 v0, v0, v1
	s_nop 1
	v_mov_b32_dpp v1, v0 quad_perm:[2,3,0,1] row_mask:0xf bank_mask:0xf
	s_nop 0
	v_add_f32_e32 v0, v0, v1
	s_nop 1
	v_mov_b32_dpp v1, v0 quad_perm:[1,0,3,2] row_mask:0xf bank_mask:0xf
	s_nop 0
	v_add_f32_e32 v0, v0, v1
	v_sub_f32_e32 v1, v146, v187
	v_mul_f32_e32 v1, 0x3fb8aa3b, v1
	v_exp_f32_e32 v1, v1
	s_nop 0
	v_add_f32_e32 v0, v1, v0
	v_div_scale_f32 v1, s[0:1], v0, v0, 1.0
	v_rcp_f32_e32 v2, v1
	s_nop 0
	v_fma_f32 v3, -v1, v2, 1.0
	v_fmac_f32_e32 v2, v3, v2
	v_div_scale_f32 v3, vcc, 1.0, v0, 1.0
	v_mul_f32_e32 v16, v3, v2
	v_fma_f32 v17, -v1, v16, v3
	v_fmac_f32_e32 v16, v17, v2
	v_fma_f32 v1, -v1, v16, v3
	v_div_fmas_f32 v1, v1, v2, v16
	v_div_fixup_f32 v2, v1, v0, 1.0
	v_add_u32_e32 v0, 8, v34
	v_mul_f32_e32 v1, v4, v2
	v_cvt_pk_bf16_f32 v3, v1, s0
	v_ashrrev_i32_e32 v1, 31, v0
	v_lshlrev_b64 v[0:1], 10, v[0:1]
	v_mul_f32_e32 v2, v20, v2
	v_lshl_add_u64 v[0:1], v[32:33], 0, v[0:1]
	v_cvt_pk_bf16_f32 v2, v2, s0
	global_store_short v[0:1], v3, off
	global_store_short v[0:1], v2, off offset:64
	v_mov_b32_e32 v0, v124
	v_mov_b32_e32 v255, v124
	s_nop 1
	v_permlane16_swap_b32_e32 v0, v255
	s_nop 1
	v_mov_b32_dpp v0, v255 quad_perm:[0,1,2,3] row_mask:0x5 bank_mask:0xf
	s_nop 0
	v_add_f32_e32 v0, v124, v0
	s_nop 1
	v_mov_b32_dpp v1, v0 row_ror:8 row_mask:0xf bank_mask:0xf
	s_nop 0
	v_add_f32_e32 v0, v0, v1
	s_nop 1
	v_mov_b32_dpp v1, v0 row_shl:4 row_mask:0xf bank_mask:0x5
	v_mov_b32_dpp v1, v0 row_shr:4 row_mask:0xf bank_mask:0xa
	s_nop 0
	v_add_f32_e32 v0, v0, v1
	s_nop 1
	v_mov_b32_dpp v1, v0 quad_perm:[2,3,0,1] row_mask:0xf bank_mask:0xf
	s_nop 0
	v_add_f32_e32 v0, v0, v1
	s_nop 1
	v_mov_b32_dpp v1, v0 quad_perm:[1,0,3,2] row_mask:0xf bank_mask:0xf
	s_nop 0
	v_add_f32_e32 v0, v0, v1
	v_sub_f32_e32 v1, v146, v160
	v_mul_f32_e32 v1, 0x3fb8aa3b, v1
	v_exp_f32_e32 v1, v1
	s_nop 0
	v_add_f32_e32 v0, v1, v0
	v_div_scale_f32 v1, s[0:1], v0, v0, 1.0
	v_rcp_f32_e32 v2, v1
	s_nop 0
	v_fma_f32 v3, -v1, v2, 1.0
	v_fmac_f32_e32 v2, v3, v2
	v_div_scale_f32 v3, vcc, 1.0, v0, 1.0
	v_mul_f32_e32 v4, v3, v2
	v_fma_f32 v16, -v1, v4, v3
	v_fmac_f32_e32 v4, v16, v2
	v_fma_f32 v1, -v1, v4, v3
	v_div_fmas_f32 v1, v1, v2, v4
	v_div_fixup_f32 v2, v1, v0, 1.0
	v_add_u32_e32 v0, 9, v34
	v_mul_f32_e32 v1, v5, v2
	v_cvt_pk_bf16_f32 v3, v1, s0
	v_ashrrev_i32_e32 v1, 31, v0
	v_lshlrev_b64 v[0:1], 10, v[0:1]
	v_mul_f32_e32 v2, v21, v2
	v_lshl_add_u64 v[0:1], v[32:33], 0, v[0:1]
	v_cvt_pk_bf16_f32 v2, v2, s0
	global_store_short v[0:1], v3, off
	global_store_short v[0:1], v2, off offset:64
	v_mov_b32_e32 v0, v123
	v_mov_b32_e32 v255, v123
	s_nop 1
	v_permlane16_swap_b32_e32 v0, v255
	s_nop 1
	v_mov_b32_dpp v0, v255 quad_perm:[0,1,2,3] row_mask:0x5 bank_mask:0xf
	s_nop 0
	v_add_f32_e32 v0, v123, v0
	s_nop 1
	v_mov_b32_dpp v1, v0 row_ror:8 row_mask:0xf bank_mask:0xf
	s_nop 0
	v_add_f32_e32 v0, v0, v1
	s_nop 1
	v_mov_b32_dpp v1, v0 row_shl:4 row_mask:0xf bank_mask:0x5
	v_mov_b32_dpp v1, v0 row_shr:4 row_mask:0xf bank_mask:0xa
	s_nop 0
	v_add_f32_e32 v0, v0, v1
	s_nop 1
	v_mov_b32_dpp v1, v0 quad_perm:[2,3,0,1] row_mask:0xf bank_mask:0xf
	s_nop 0
	v_add_f32_e32 v0, v0, v1
	s_nop 1
	v_mov_b32_dpp v1, v0 quad_perm:[1,0,3,2] row_mask:0xf bank_mask:0xf
	s_nop 0
	v_add_f32_e32 v0, v0, v1
	v_sub_f32_e32 v1, v146, v156
	v_mul_f32_e32 v1, 0x3fb8aa3b, v1
	v_exp_f32_e32 v1, v1
	s_nop 0
	v_add_f32_e32 v0, v1, v0
	v_div_scale_f32 v1, s[0:1], v0, v0, 1.0
	v_rcp_f32_e32 v2, v1
	s_nop 0
	v_fma_f32 v3, -v1, v2, 1.0
	v_fmac_f32_e32 v2, v3, v2
	v_div_scale_f32 v3, vcc, 1.0, v0, 1.0
	v_mul_f32_e32 v4, v3, v2
	v_fma_f32 v5, -v1, v4, v3
	v_fmac_f32_e32 v4, v5, v2
	v_fma_f32 v1, -v1, v4, v3
	v_div_fmas_f32 v1, v1, v2, v4
	v_div_fixup_f32 v2, v1, v0, 1.0
	v_add_u32_e32 v0, 10, v34
	v_mul_f32_e32 v1, v6, v2
	v_cvt_pk_bf16_f32 v3, v1, s0
	v_ashrrev_i32_e32 v1, 31, v0
	v_lshlrev_b64 v[0:1], 10, v[0:1]
	v_mul_f32_e32 v2, v22, v2
	v_lshl_add_u64 v[0:1], v[32:33], 0, v[0:1]
	v_cvt_pk_bf16_f32 v2, v2, s0
	global_store_short v[0:1], v3, off
	global_store_short v[0:1], v2, off offset:64
	v_mov_b32_e32 v0, v122
	v_mov_b32_e32 v255, v122
	s_nop 1
	v_permlane16_swap_b32_e32 v0, v255
	s_nop 1
	v_mov_b32_dpp v0, v255 quad_perm:[0,1,2,3] row_mask:0x5 bank_mask:0xf
	s_nop 0
	v_add_f32_e32 v0, v122, v0
	s_nop 1
	v_mov_b32_dpp v1, v0 row_ror:8 row_mask:0xf bank_mask:0xf
	s_nop 0
	v_add_f32_e32 v0, v0, v1
	s_nop 1
	v_mov_b32_dpp v1, v0 row_shl:4 row_mask:0xf bank_mask:0x5
	v_mov_b32_dpp v1, v0 row_shr:4 row_mask:0xf bank_mask:0xa
	s_nop 0
	v_add_f32_e32 v0, v0, v1
	s_nop 1
	v_mov_b32_dpp v1, v0 quad_perm:[2,3,0,1] row_mask:0xf bank_mask:0xf
	s_nop 0
	v_add_f32_e32 v0, v0, v1
	s_nop 1
	v_mov_b32_dpp v1, v0 quad_perm:[1,0,3,2] row_mask:0xf bank_mask:0xf
	s_nop 0
	v_add_f32_e32 v0, v0, v1
	v_sub_f32_e32 v1, v146, v155
	v_mul_f32_e32 v1, 0x3fb8aa3b, v1
	v_exp_f32_e32 v1, v1
	s_nop 0
	v_add_f32_e32 v0, v1, v0
	v_div_scale_f32 v1, s[0:1], v0, v0, 1.0
	v_rcp_f32_e32 v2, v1
	s_nop 0
	v_fma_f32 v3, -v1, v2, 1.0
	v_fmac_f32_e32 v2, v3, v2
	v_div_scale_f32 v3, vcc, 1.0, v0, 1.0
	v_mul_f32_e32 v4, v3, v2
	v_fma_f32 v5, -v1, v4, v3
	v_fmac_f32_e32 v4, v5, v2
	v_fma_f32 v1, -v1, v4, v3
	v_div_fmas_f32 v1, v1, v2, v4
	v_div_fixup_f32 v2, v1, v0, 1.0
	v_add_u32_e32 v0, 11, v34
	v_mul_f32_e32 v1, v7, v2
	v_cvt_pk_bf16_f32 v3, v1, s0
	v_ashrrev_i32_e32 v1, 31, v0
	v_lshlrev_b64 v[0:1], 10, v[0:1]
	v_mul_f32_e32 v2, v23, v2
	v_lshl_add_u64 v[0:1], v[32:33], 0, v[0:1]
	v_cvt_pk_bf16_f32 v2, v2, s0
	global_store_short v[0:1], v3, off
	global_store_short v[0:1], v2, off offset:64
	v_mov_b32_e32 v0, v121
	v_mov_b32_e32 v255, v121
	s_nop 1
	v_permlane16_swap_b32_e32 v0, v255
	s_nop 1
	v_mov_b32_dpp v0, v255 quad_perm:[0,1,2,3] row_mask:0x5 bank_mask:0xf
	s_nop 0
	v_add_f32_e32 v0, v121, v0
	s_nop 1
	v_mov_b32_dpp v1, v0 row_ror:8 row_mask:0xf bank_mask:0xf
	s_nop 0
	v_add_f32_e32 v0, v0, v1
	s_nop 1
	v_mov_b32_dpp v1, v0 row_shl:4 row_mask:0xf bank_mask:0x5
	v_mov_b32_dpp v1, v0 row_shr:4 row_mask:0xf bank_mask:0xa
	s_nop 0
	v_add_f32_e32 v0, v0, v1
	s_nop 1
	v_mov_b32_dpp v1, v0 quad_perm:[2,3,0,1] row_mask:0xf bank_mask:0xf
	s_nop 0
	v_add_f32_e32 v0, v0, v1
	s_nop 1
	v_mov_b32_dpp v1, v0 quad_perm:[1,0,3,2] row_mask:0xf bank_mask:0xf
	s_nop 0
	v_add_f32_e32 v0, v0, v1
	v_sub_f32_e32 v1, v146, v154
	v_mul_f32_e32 v1, 0x3fb8aa3b, v1
	v_exp_f32_e32 v1, v1
	s_nop 0
	v_add_f32_e32 v0, v1, v0
	v_div_scale_f32 v1, s[0:1], v0, v0, 1.0
	v_rcp_f32_e32 v2, v1
	s_nop 0
	v_fma_f32 v3, -v1, v2, 1.0
	v_fmac_f32_e32 v2, v3, v2
	v_div_scale_f32 v3, vcc, 1.0, v0, 1.0
	v_mul_f32_e32 v4, v3, v2
	v_fma_f32 v5, -v1, v4, v3
	v_fmac_f32_e32 v4, v5, v2
	v_fma_f32 v1, -v1, v4, v3
	v_div_fmas_f32 v1, v1, v2, v4
	v_div_fixup_f32 v2, v1, v0, 1.0
	v_add_u32_e32 v0, 16, v34
	v_mul_f32_e32 v1, v8, v2
	v_cvt_pk_bf16_f32 v3, v1, s0
	v_ashrrev_i32_e32 v1, 31, v0
	v_lshlrev_b64 v[0:1], 10, v[0:1]
	v_mul_f32_e32 v2, v24, v2
	v_lshl_add_u64 v[0:1], v[32:33], 0, v[0:1]
	v_cvt_pk_bf16_f32 v2, v2, s0
	global_store_short v[0:1], v3, off
	global_store_short v[0:1], v2, off offset:64
	v_mov_b32_e32 v0, v120
	v_mov_b32_e32 v255, v120
	s_nop 1
	v_permlane16_swap_b32_e32 v0, v255
	s_nop 1
	v_mov_b32_dpp v0, v255 quad_perm:[0,1,2,3] row_mask:0x5 bank_mask:0xf
	s_nop 0
	v_add_f32_e32 v0, v120, v0
	s_nop 1
	v_mov_b32_dpp v1, v0 row_ror:8 row_mask:0xf bank_mask:0xf
	s_nop 0
	v_add_f32_e32 v0, v0, v1
	s_nop 1
	v_mov_b32_dpp v1, v0 row_shl:4 row_mask:0xf bank_mask:0x5
	v_mov_b32_dpp v1, v0 row_shr:4 row_mask:0xf bank_mask:0xa
	s_nop 0
	v_add_f32_e32 v0, v0, v1
	s_nop 1
	v_mov_b32_dpp v1, v0 quad_perm:[2,3,0,1] row_mask:0xf bank_mask:0xf
	s_nop 0
	v_add_f32_e32 v0, v0, v1
	s_nop 1
	v_mov_b32_dpp v1, v0 quad_perm:[1,0,3,2] row_mask:0xf bank_mask:0xf
	s_nop 0
	v_add_f32_e32 v0, v0, v1
	v_sub_f32_e32 v1, v146, v153
	v_mul_f32_e32 v1, 0x3fb8aa3b, v1
	v_exp_f32_e32 v1, v1
	s_nop 0
	v_add_f32_e32 v0, v1, v0
	v_div_scale_f32 v1, s[0:1], v0, v0, 1.0
	v_rcp_f32_e32 v2, v1
	s_nop 0
	v_fma_f32 v3, -v1, v2, 1.0
	v_fmac_f32_e32 v2, v3, v2
	v_div_scale_f32 v3, vcc, 1.0, v0, 1.0
	v_mul_f32_e32 v4, v3, v2
	v_fma_f32 v5, -v1, v4, v3
	v_fmac_f32_e32 v4, v5, v2
	v_fma_f32 v1, -v1, v4, v3
	v_div_fmas_f32 v1, v1, v2, v4
	v_div_fixup_f32 v2, v1, v0, 1.0
	v_add_u32_e32 v0, 17, v34
	v_mul_f32_e32 v1, v9, v2
	v_cvt_pk_bf16_f32 v3, v1, s0
	v_ashrrev_i32_e32 v1, 31, v0
	v_lshlrev_b64 v[0:1], 10, v[0:1]
	v_mul_f32_e32 v2, v25, v2
	v_lshl_add_u64 v[0:1], v[32:33], 0, v[0:1]
	v_cvt_pk_bf16_f32 v2, v2, s0
	global_store_short v[0:1], v3, off
	global_store_short v[0:1], v2, off offset:64
	v_mov_b32_e32 v0, v119
	v_mov_b32_e32 v255, v119
	s_nop 1
	v_permlane16_swap_b32_e32 v0, v255
	s_nop 1
	v_mov_b32_dpp v0, v255 quad_perm:[0,1,2,3] row_mask:0x5 bank_mask:0xf
	s_nop 0
	v_add_f32_e32 v0, v119, v0
	s_nop 1
	v_mov_b32_dpp v1, v0 row_ror:8 row_mask:0xf bank_mask:0xf
	s_nop 0
	v_add_f32_e32 v0, v0, v1
	s_nop 1
	v_mov_b32_dpp v1, v0 row_shl:4 row_mask:0xf bank_mask:0x5
	v_mov_b32_dpp v1, v0 row_shr:4 row_mask:0xf bank_mask:0xa
	s_nop 0
	v_add_f32_e32 v0, v0, v1
	s_nop 1
	v_mov_b32_dpp v1, v0 quad_perm:[2,3,0,1] row_mask:0xf bank_mask:0xf
	s_nop 0
	v_add_f32_e32 v0, v0, v1
	s_nop 1
	v_mov_b32_dpp v1, v0 quad_perm:[1,0,3,2] row_mask:0xf bank_mask:0xf
	s_nop 0
	v_add_f32_e32 v0, v0, v1
	v_sub_f32_e32 v1, v146, v152
	v_mul_f32_e32 v1, 0x3fb8aa3b, v1
	v_exp_f32_e32 v1, v1
	s_nop 0
	v_add_f32_e32 v0, v1, v0
	v_div_scale_f32 v1, s[0:1], v0, v0, 1.0
	v_rcp_f32_e32 v2, v1
	s_nop 0
	v_fma_f32 v3, -v1, v2, 1.0
	v_fmac_f32_e32 v2, v3, v2
	v_div_scale_f32 v3, vcc, 1.0, v0, 1.0
	v_mul_f32_e32 v4, v3, v2
	v_fma_f32 v5, -v1, v4, v3
	v_fmac_f32_e32 v4, v5, v2
	v_fma_f32 v1, -v1, v4, v3
	v_div_fmas_f32 v1, v1, v2, v4
	v_div_fixup_f32 v2, v1, v0, 1.0
	v_add_u32_e32 v0, 18, v34
	v_mul_f32_e32 v1, v10, v2
	v_cvt_pk_bf16_f32 v3, v1, s0
	v_ashrrev_i32_e32 v1, 31, v0
	v_lshlrev_b64 v[0:1], 10, v[0:1]
	v_mul_f32_e32 v2, v26, v2
	v_lshl_add_u64 v[0:1], v[32:33], 0, v[0:1]
	v_cvt_pk_bf16_f32 v2, v2, s0
	global_store_short v[0:1], v3, off
	global_store_short v[0:1], v2, off offset:64
	v_mov_b32_e32 v0, v118
	v_mov_b32_e32 v255, v118
	s_nop 1
	v_permlane16_swap_b32_e32 v0, v255
	s_nop 1
	v_mov_b32_dpp v0, v255 quad_perm:[0,1,2,3] row_mask:0x5 bank_mask:0xf
	s_nop 0
	v_add_f32_e32 v0, v118, v0
	s_nop 1
	v_mov_b32_dpp v1, v0 row_ror:8 row_mask:0xf bank_mask:0xf
	s_nop 0
	v_add_f32_e32 v0, v0, v1
	s_nop 1
	v_mov_b32_dpp v1, v0 row_shl:4 row_mask:0xf bank_mask:0x5
	v_mov_b32_dpp v1, v0 row_shr:4 row_mask:0xf bank_mask:0xa
	s_nop 0
	v_add_f32_e32 v0, v0, v1
	s_nop 1
	v_mov_b32_dpp v1, v0 quad_perm:[2,3,0,1] row_mask:0xf bank_mask:0xf
	s_nop 0
	v_add_f32_e32 v0, v0, v1
	s_nop 1
	v_mov_b32_dpp v1, v0 quad_perm:[1,0,3,2] row_mask:0xf bank_mask:0xf
	s_nop 0
	v_add_f32_e32 v0, v0, v1
	v_sub_f32_e32 v1, v146, v151
	v_mul_f32_e32 v1, 0x3fb8aa3b, v1
	v_exp_f32_e32 v1, v1
	s_nop 0
	v_add_f32_e32 v0, v1, v0
	v_div_scale_f32 v1, s[0:1], v0, v0, 1.0
	v_rcp_f32_e32 v2, v1
	s_nop 0
	v_fma_f32 v3, -v1, v2, 1.0
	v_fmac_f32_e32 v2, v3, v2
	v_div_scale_f32 v3, vcc, 1.0, v0, 1.0
	v_mul_f32_e32 v4, v3, v2
	v_fma_f32 v5, -v1, v4, v3
	v_fmac_f32_e32 v4, v5, v2
	v_fma_f32 v1, -v1, v4, v3
	v_div_fmas_f32 v1, v1, v2, v4
	v_div_fixup_f32 v2, v1, v0, 1.0
	v_add_u32_e32 v0, 19, v34
	v_mul_f32_e32 v1, v11, v2
	v_cvt_pk_bf16_f32 v3, v1, s0
	v_ashrrev_i32_e32 v1, 31, v0
	v_lshlrev_b64 v[0:1], 10, v[0:1]
	v_mul_f32_e32 v2, v27, v2
	v_lshl_add_u64 v[0:1], v[32:33], 0, v[0:1]
	v_cvt_pk_bf16_f32 v2, v2, s0
	global_store_short v[0:1], v3, off
	global_store_short v[0:1], v2, off offset:64
	v_mov_b32_e32 v0, v117
	v_mov_b32_e32 v255, v117
	s_nop 1
	v_permlane16_swap_b32_e32 v0, v255
	s_nop 1
	v_mov_b32_dpp v0, v255 quad_perm:[0,1,2,3] row_mask:0x5 bank_mask:0xf
	s_nop 0
	v_add_f32_e32 v0, v117, v0
	s_nop 1
	v_mov_b32_dpp v1, v0 row_ror:8 row_mask:0xf bank_mask:0xf
	s_nop 0
	v_add_f32_e32 v0, v0, v1
	s_nop 1
	v_mov_b32_dpp v1, v0 row_shl:4 row_mask:0xf bank_mask:0x5
	v_mov_b32_dpp v1, v0 row_shr:4 row_mask:0xf bank_mask:0xa
	s_nop 0
	v_add_f32_e32 v0, v0, v1
	s_nop 1
	v_mov_b32_dpp v1, v0 quad_perm:[2,3,0,1] row_mask:0xf bank_mask:0xf
	s_nop 0
	v_add_f32_e32 v0, v0, v1
	s_nop 1
	v_mov_b32_dpp v1, v0 quad_perm:[1,0,3,2] row_mask:0xf bank_mask:0xf
	s_nop 0
	v_add_f32_e32 v0, v0, v1
	v_sub_f32_e32 v1, v146, v150
	v_mul_f32_e32 v1, 0x3fb8aa3b, v1
	v_exp_f32_e32 v1, v1
	s_nop 0
	v_add_f32_e32 v0, v1, v0
	v_div_scale_f32 v1, s[0:1], v0, v0, 1.0
	v_rcp_f32_e32 v2, v1
	s_nop 0
	v_fma_f32 v3, -v1, v2, 1.0
	v_fmac_f32_e32 v2, v3, v2
	v_div_scale_f32 v3, vcc, 1.0, v0, 1.0
	v_mul_f32_e32 v4, v3, v2
	v_fma_f32 v5, -v1, v4, v3
	v_fmac_f32_e32 v4, v5, v2
	v_fma_f32 v1, -v1, v4, v3
	v_div_fmas_f32 v1, v1, v2, v4
	v_div_fixup_f32 v2, v1, v0, 1.0
	v_add_u32_e32 v0, 24, v34
	v_mul_f32_e32 v1, v12, v2
	v_cvt_pk_bf16_f32 v3, v1, s0
	v_ashrrev_i32_e32 v1, 31, v0
	v_lshlrev_b64 v[0:1], 10, v[0:1]
	v_mul_f32_e32 v2, v28, v2
	v_lshl_add_u64 v[0:1], v[32:33], 0, v[0:1]
	v_cvt_pk_bf16_f32 v2, v2, s0
	global_store_short v[0:1], v3, off
	global_store_short v[0:1], v2, off offset:64
	v_mov_b32_e32 v0, v116
	v_mov_b32_e32 v255, v116
	s_nop 1
	v_permlane16_swap_b32_e32 v0, v255
	s_nop 1
	v_mov_b32_dpp v0, v255 quad_perm:[0,1,2,3] row_mask:0x5 bank_mask:0xf
	s_nop 0
	v_add_f32_e32 v0, v116, v0
	s_nop 1
	v_mov_b32_dpp v1, v0 row_ror:8 row_mask:0xf bank_mask:0xf
	s_nop 0
	v_add_f32_e32 v0, v0, v1
	s_nop 1
	v_mov_b32_dpp v1, v0 row_shl:4 row_mask:0xf bank_mask:0x5
	v_mov_b32_dpp v1, v0 row_shr:4 row_mask:0xf bank_mask:0xa
	s_nop 0
	v_add_f32_e32 v0, v0, v1
	s_nop 1
	v_mov_b32_dpp v1, v0 quad_perm:[2,3,0,1] row_mask:0xf bank_mask:0xf
	s_nop 0
	v_add_f32_e32 v0, v0, v1
	s_nop 1
	v_mov_b32_dpp v1, v0 quad_perm:[1,0,3,2] row_mask:0xf bank_mask:0xf
	s_nop 0
	v_add_f32_e32 v0, v0, v1
	v_sub_f32_e32 v1, v146, v149
	v_mul_f32_e32 v1, 0x3fb8aa3b, v1
	v_exp_f32_e32 v1, v1
	s_nop 0
	v_add_f32_e32 v0, v1, v0
	v_div_scale_f32 v1, s[0:1], v0, v0, 1.0
	v_rcp_f32_e32 v2, v1
	s_nop 0
	v_fma_f32 v3, -v1, v2, 1.0
	v_fmac_f32_e32 v2, v3, v2
	v_div_scale_f32 v3, vcc, 1.0, v0, 1.0
	v_mul_f32_e32 v4, v3, v2
	v_fma_f32 v5, -v1, v4, v3
	v_fmac_f32_e32 v4, v5, v2
	v_fma_f32 v1, -v1, v4, v3
	v_div_fmas_f32 v1, v1, v2, v4
	v_div_fixup_f32 v2, v1, v0, 1.0
	v_add_u32_e32 v0, 25, v34
	v_mul_f32_e32 v1, v13, v2
	v_cvt_pk_bf16_f32 v3, v1, s0
	v_ashrrev_i32_e32 v1, 31, v0
	v_lshlrev_b64 v[0:1], 10, v[0:1]
	v_mul_f32_e32 v2, v29, v2
	v_lshl_add_u64 v[0:1], v[32:33], 0, v[0:1]
	v_cvt_pk_bf16_f32 v2, v2, s0
	global_store_short v[0:1], v3, off
	global_store_short v[0:1], v2, off offset:64
	v_mov_b32_e32 v0, v115
	v_mov_b32_e32 v255, v115
	s_nop 1
	v_permlane16_swap_b32_e32 v0, v255
	s_nop 1
	v_mov_b32_dpp v0, v255 quad_perm:[0,1,2,3] row_mask:0x5 bank_mask:0xf
	s_nop 0
	v_add_f32_e32 v0, v115, v0
	s_nop 1
	v_mov_b32_dpp v1, v0 row_ror:8 row_mask:0xf bank_mask:0xf
	s_nop 0
	v_add_f32_e32 v0, v0, v1
	s_nop 1
	v_mov_b32_dpp v1, v0 row_shl:4 row_mask:0xf bank_mask:0x5
	v_mov_b32_dpp v1, v0 row_shr:4 row_mask:0xf bank_mask:0xa
	s_nop 0
	v_add_f32_e32 v0, v0, v1
	s_nop 1
	v_mov_b32_dpp v1, v0 quad_perm:[2,3,0,1] row_mask:0xf bank_mask:0xf
	s_nop 0
	v_add_f32_e32 v0, v0, v1
	s_nop 1
	v_mov_b32_dpp v1, v0 quad_perm:[1,0,3,2] row_mask:0xf bank_mask:0xf
	s_nop 0
	v_add_f32_e32 v0, v0, v1
	v_sub_f32_e32 v1, v146, v148
	v_mul_f32_e32 v1, 0x3fb8aa3b, v1
	v_exp_f32_e32 v1, v1
	s_nop 0
	v_add_f32_e32 v0, v1, v0
	v_div_scale_f32 v1, s[0:1], v0, v0, 1.0
	v_rcp_f32_e32 v2, v1
	s_nop 0
	v_fma_f32 v3, -v1, v2, 1.0
	v_fmac_f32_e32 v2, v3, v2
	v_div_scale_f32 v3, vcc, 1.0, v0, 1.0
	v_mul_f32_e32 v4, v3, v2
	v_fma_f32 v5, -v1, v4, v3
	v_fmac_f32_e32 v4, v5, v2
	v_fma_f32 v1, -v1, v4, v3
	v_div_fmas_f32 v1, v1, v2, v4
	v_div_fixup_f32 v2, v1, v0, 1.0
	v_add_u32_e32 v0, 26, v34
	v_mul_f32_e32 v1, v14, v2
	v_cvt_pk_bf16_f32 v3, v1, s0
	v_ashrrev_i32_e32 v1, 31, v0
	v_lshlrev_b64 v[0:1], 10, v[0:1]
	v_mul_f32_e32 v2, v30, v2
	v_lshl_add_u64 v[0:1], v[32:33], 0, v[0:1]
	v_cvt_pk_bf16_f32 v2, v2, s0
	global_store_short v[0:1], v3, off
	global_store_short v[0:1], v2, off offset:64
	v_mov_b32_e32 v0, v114
	v_mov_b32_e32 v255, v114
	s_nop 1
	v_permlane16_swap_b32_e32 v0, v255
	s_nop 1
	v_mov_b32_dpp v0, v255 quad_perm:[0,1,2,3] row_mask:0x5 bank_mask:0xf
	s_nop 0
	v_add_f32_e32 v0, v114, v0
	s_nop 1
	v_mov_b32_dpp v1, v0 row_ror:8 row_mask:0xf bank_mask:0xf
	s_nop 0
	v_add_f32_e32 v0, v0, v1
	s_nop 1
	v_mov_b32_dpp v1, v0 row_shl:4 row_mask:0xf bank_mask:0x5
	v_mov_b32_dpp v1, v0 row_shr:4 row_mask:0xf bank_mask:0xa
	s_nop 0
	v_add_f32_e32 v0, v0, v1
	s_nop 1
	v_mov_b32_dpp v1, v0 quad_perm:[2,3,0,1] row_mask:0xf bank_mask:0xf
	s_nop 0
	v_add_f32_e32 v0, v0, v1
	s_nop 1
	v_mov_b32_dpp v1, v0 quad_perm:[1,0,3,2] row_mask:0xf bank_mask:0xf
	s_nop 0
	v_add_f32_e32 v0, v0, v1
	v_sub_f32_e32 v1, v146, v147
	v_mul_f32_e32 v1, 0x3fb8aa3b, v1
	v_exp_f32_e32 v1, v1
	s_nop 0
	v_add_f32_e32 v0, v1, v0
	v_div_scale_f32 v1, s[0:1], v0, v0, 1.0
	v_rcp_f32_e32 v2, v1
	s_nop 0
	v_fma_f32 v3, -v1, v2, 1.0
	v_fmac_f32_e32 v2, v3, v2
	v_div_scale_f32 v3, vcc, 1.0, v0, 1.0
	v_mul_f32_e32 v4, v3, v2
	v_fma_f32 v5, -v1, v4, v3
	v_fmac_f32_e32 v4, v5, v2
	v_fma_f32 v1, -v1, v4, v3
	v_div_fmas_f32 v1, v1, v2, v4
	v_div_fixup_f32 v2, v1, v0, 1.0
	v_add_u32_e32 v0, 27, v34
	v_mul_f32_e32 v1, v15, v2
	v_cvt_pk_bf16_f32 v3, v1, s0
	v_ashrrev_i32_e32 v1, 31, v0
	v_lshlrev_b64 v[0:1], 10, v[0:1]
	v_mul_f32_e32 v2, v31, v2
	v_lshl_add_u64 v[0:1], v[32:33], 0, v[0:1]
	v_cvt_pk_bf16_f32 v2, v2, s0
	s_mov_b64 s[0:1], 0
	global_store_short v[0:1], v3, off
	global_store_short v[0:1], v2, off offset:64

.LBB0_824:
	v_mov_b32_e32 v51, v162
	s_and_b32 s2, s6, 7
	s_lshl_b32 s13, s2, 6
	v_lshlrev_b32_e32 v68, 3, v51
	v_and_b32_e32 v50, 56, v68
	v_or_b32_e32 v14, s13, v50
	v_readlane_b32 s3, v248, 18
	v_readlane_b32 s16, v251, 4
	v_readlane_b32 s22, v251, 10
	v_or_b32_e32 v0, s3, v14
	v_readlane_b32 s23, v251, 11
	v_mov_b32_e32 v1, v97
	v_or_b32_e32 v96, s34, v14
	v_readlane_b32 s24, v251, 12
	v_readlane_b32 s25, v251, 13
	v_lshl_add_u64 v[8:9], v[0:1], 2, s[22:23]
	s_mov_b64 s[8:9], 0x1000
	v_lshl_add_u64 v[2:3], v[96:97], 2, s[24:25]
	v_lshl_add_u64 v[10:11], v[8:9], 0, s[8:9]
	s_mov_b64 s[8:9], 0x1800
	s_movk_i32 s3, 0x1000
	s_barrier
	v_lshl_add_u64 v[12:13], v[8:9], 0, s[8:9]
	global_load_dwordx4 v[4:7], v[2:3], off offset:16
	s_nop 0
	global_load_dwordx4 v[0:3], v[2:3], off
	s_nop 0
	global_load_dwordx4 v[44:47], v[8:9], off offset:16
	global_load_dwordx4 v[40:43], v[8:9], off
	global_load_dwordx4 v[36:39], v[8:9], off offset:2064
	global_load_dwordx4 v[32:35], v[8:9], off offset:2048
	v_add_co_u32_e32 v8, vcc, s3, v8
	s_add_i32 s3, s4, 0xffffff00
	s_nop 0
	v_addc_co_u32_e32 v9, vcc, 0, v9, vcc
	global_load_dwordx4 v[24:27], v[8:9], off
	global_load_dwordx4 v[16:19], v[8:9], off offset:2048
	global_load_dwordx4 v[28:31], v[10:11], off offset:16
	global_load_dwordx4 v[20:23], v[12:13], off offset:16
	s_and_b64 s[0:1], s[0:1], exec
	s_cselect_b32 s68, s4, s3
	v_ashrrev_i32_e32 v52, 3, v51
	v_readlane_b32 s0, v249, 7
	v_add_u32_e32 v53, s68, v52
	v_lshlrev_b32_e32 v96, 1, v14
	v_readlane_b32 s1, v249, 8
	v_add_u32_e32 v54, -2, v53
	v_cmp_lt_i32_e32 vcc, 1, v53
	v_lshl_add_u64 v[48:49], s[0:1], 0, v[96:97]
	v_cmp_gt_u32_e64 s[0:1], s39, v54
	s_and_b64 s[42:43], vcc, s[0:1]
	v_readlane_b32 s17, v251, 5
	v_readlane_b32 s18, v251, 6
	v_readlane_b32 s19, v251, 7
	v_readlane_b32 s20, v251, 8
	v_readlane_b32 s21, v251, 9
	v_readlane_b32 s26, v251, 14
	v_readlane_b32 s27, v251, 15
	v_readlane_b32 s28, v251, 16
	v_readlane_b32 s29, v251, 17
	v_readlane_b32 s30, v251, 18
	v_readlane_b32 s31, v251, 19
	s_waitcnt vmcnt(8)
	v_mov_b64_e32 v[14:15], v[6:7]
	v_mov_b64_e32 v[12:13], v[4:5]
	v_mov_b64_e32 v[10:11], v[2:3]
	v_mov_b64_e32 v[8:9], v[0:1]
	v_mov_b32_e32 v206, 0
	v_mov_b32_e32 v207, 0
	v_mov_b32_e32 v208, 0
	v_mov_b32_e32 v209, 0
	s_and_saveexec_b64 s[0:1], s[42:43]
	s_cbranch_execz .Lrg17_i
	v_add_u32_e32 v8, s38, v54
	v_mad_u64_u32 v[8:9], s[42:43], v8, s74, v[48:49]
	global_load_dwordx4 v[206:209], v[8:9], off
.Lrg17_i:
	s_or_b64 exec, exec, s[0:1]
	v_cmp_lt_i32_e32 vcc, 0, v53
	v_cmp_ge_i32_e64 s[0:1], s39, v53
	s_add_i32 s71, s38, -1
	s_and_b64 s[42:43], vcc, s[0:1]
	v_mov_b32_e32 v210, 0
	v_mov_b32_e32 v211, 0
	v_mov_b32_e32 v212, 0
	v_mov_b32_e32 v213, 0
	s_and_saveexec_b64 s[0:1], s[42:43]
	s_movk_i32 s3, 0x90
	s_cbranch_execz .Lrg18_i
	v_add_u32_e32 v54, s71, v53
	v_mad_u64_u32 v[54:55], s[42:43], v54, s74, v[48:49]
	global_load_dwordx4 v[210:213], v[54:55], off
.Lrg18_i:
	s_or_b64 exec, exec, s[0:1]
	s_mov_b32 s0, 0xeffffb00
	v_cmp_gt_u32_e32 vcc, s0, v53
	v_cmp_gt_i32_e64 s[0:1], s39, v53
	s_and_b64 s[42:43], vcc, s[0:1]
	v_mov_b32_e32 v214, 0
	v_mov_b32_e32 v215, 0
	v_mov_b32_e32 v216, 0
	v_mov_b32_e32 v217, 0
	s_and_saveexec_b64 s[0:1], s[42:43]
	s_cbranch_execz .Lrg19_i
	v_add_u32_e32 v54, s38, v53
	v_mad_u64_u32 v[54:55], s[42:43], v54, s74, v[48:49]
	global_load_dwordx4 v[214:217], v[54:55], off
.Lrg19_i:
	s_or_b64 exec, exec, s[0:1]
	v_add_u32_e32 v54, 1, v53
	v_cmp_lt_i32_e32 vcc, -2, v53
	v_cmp_gt_u32_e64 s[0:1], s39, v54
	s_and_b64 s[42:43], vcc, s[0:1]
	v_mov_b32_e32 v218, 0
	v_mov_b32_e32 v219, 0
	v_mov_b32_e32 v220, 0
	v_mov_b32_e32 v221, 0
	s_and_saveexec_b64 s[0:1], s[42:43]
	s_cbranch_execz .Lrg20_i
	v_add_u32_e32 v53, s38, v54
	v_mad_u64_u32 v[54:55], s[42:43], v53, s74, v[48:49]
	global_load_dwordx4 v[218:221], v[54:55], off
.Lrg20_i:
	s_or_b64 exec, exec, s[0:1]
	s_waitcnt vmcnt(0)
	v_mov_b32_e32 v8, v206
	v_mov_b32_e32 v9, v207
	v_mov_b32_e32 v10, v208
	v_mov_b32_e32 v11, v209
	v_lshlrev_b32_e32 v54, 16, v8
	v_and_b32_e32 v55, 0xffff0000, v8
	v_lshlrev_b32_e32 v8, 16, v9
	v_and_b32_e32 v9, 0xffff0000, v9
	v_lshlrev_b32_e32 v12, 16, v10
	v_and_b32_e32 v13, 0xffff0000, v10
	v_lshlrev_b32_e32 v10, 16, v11
	v_and_b32_e32 v11, 0xffff0000, v11
	v_pk_fma_f32 v[14:15], v[46:47], v[10:11], v[6:7]
	v_pk_fma_f32 v[12:13], v[44:45], v[12:13], v[4:5]
	v_pk_fma_f32 v[10:11], v[42:43], v[8:9], v[2:3]
	v_pk_fma_f32 v[8:9], v[40:41], v[54:55], v[0:1]
	v_mov_b32_e32 v54, v210
	v_mov_b32_e32 v55, v211
	v_mov_b32_e32 v56, v212
	v_mov_b32_e32 v57, v213
	v_lshlrev_b32_e32 v58, 16, v54
	v_and_b32_e32 v59, 0xffff0000, v54
	v_lshlrev_b32_e32 v54, 16, v55
	v_and_b32_e32 v55, 0xffff0000, v55
	v_lshlrev_b32_e32 v60, 16, v56
	v_and_b32_e32 v61, 0xffff0000, v56
	v_lshlrev_b32_e32 v56, 16, v57
	v_and_b32_e32 v57, 0xffff0000, v57
	v_pk_fma_f32 v[14:15], v[38:39], v[56:57], v[14:15]
	v_pk_fma_f32 v[12:13], v[36:37], v[60:61], v[12:13]
	v_pk_fma_f32 v[10:11], v[34:35], v[54:55], v[10:11]
	v_pk_fma_f32 v[8:9], v[32:33], v[58:59], v[8:9]
	v_mov_b32_e32 v54, v214
	v_mov_b32_e32 v55, v215
	v_mov_b32_e32 v56, v216
	v_mov_b32_e32 v57, v217
	v_lshlrev_b32_e32 v58, 16, v54
	v_and_b32_e32 v59, 0xffff0000, v54
	v_lshlrev_b32_e32 v54, 16, v55
	v_and_b32_e32 v55, 0xffff0000, v55
	v_lshlrev_b32_e32 v60, 16, v56
	v_and_b32_e32 v61, 0xffff0000, v56
	v_lshlrev_b32_e32 v56, 16, v57
	v_and_b32_e32 v57, 0xffff0000, v57
	v_pk_fma_f32 v[14:15], v[30:31], v[56:57], v[14:15]
	v_pk_fma_f32 v[12:13], v[28:29], v[60:61], v[12:13]
	v_pk_fma_f32 v[10:11], v[26:27], v[54:55], v[10:11]
	v_pk_fma_f32 v[8:9], v[24:25], v[58:59], v[8:9]
	v_mov_b32_e32 v54, v218
	v_mov_b32_e32 v55, v219
	v_mov_b32_e32 v56, v220
	v_mov_b32_e32 v57, v221
	v_lshlrev_b32_e32 v58, 16, v54
	v_and_b32_e32 v59, 0xffff0000, v54
	v_lshlrev_b32_e32 v54, 16, v55
	v_and_b32_e32 v55, 0xffff0000, v55
	v_lshlrev_b32_e32 v60, 16, v56
	v_and_b32_e32 v61, 0xffff0000, v56
	v_lshlrev_b32_e32 v56, 16, v57
	v_and_b32_e32 v57, 0xffff0000, v57
	v_pk_fma_f32 v[14:15], v[22:23], v[56:57], v[14:15]
	v_pk_fma_f32 v[12:13], v[20:21], v[60:61], v[12:13]
	v_pk_fma_f32 v[10:11], v[18:19], v[54:55], v[10:11]
	v_pk_fma_f32 v[8:9], v[16:17], v[58:59], v[8:9]
	v_lshl_add_u32 v53, v50, 2, 0
	v_lshl_add_u32 v54, v52, 8, v53
	v_lshlrev_b32_e32 v50, 1, v50
	ds_write_b128 v54, v[8:11] offset:36864
	ds_write_b128 v54, v[12:15] offset:36880
	v_add_u32_e32 v54, 32, v52
	v_sub_u32_e32 v50, v53, v50
	v_add_u32_e32 v55, s68, v54
	v_cvt_pk_bf16_f32 v8, v8, v9
	v_cvt_pk_bf16_f32 v9, v10, v11
	v_cvt_pk_bf16_f32 v10, v12, v13
	v_cvt_pk_bf16_f32 v11, v14, v15
	v_mad_u64_u32 v[12:13], s[0:1], v52, s3, v[50:51]
	v_add_u32_e32 v56, -2, v55
	ds_write_b128 v12, v[8:11]
	v_cmp_lt_i32_e32 vcc, 1, v55
	v_cmp_gt_u32_e64 s[0:1], s39, v56
	v_mov_b64_e32 v[14:15], v[6:7]
	s_and_b64 s[42:43], vcc, s[0:1]
	v_mov_b64_e32 v[12:13], v[4:5]
	v_mov_b64_e32 v[10:11], v[2:3]
	v_mov_b64_e32 v[8:9], v[0:1]
	v_mov_b32_e32 v206, 0
	v_mov_b32_e32 v207, 0
	v_mov_b32_e32 v208, 0
	v_mov_b32_e32 v209, 0
	s_and_saveexec_b64 s[0:1], s[42:43]
	s_cbranch_execz .Lrg21_i
	v_add_u32_e32 v8, s38, v56
	v_mad_u64_u32 v[8:9], s[42:43], v8, s74, v[48:49]
	global_load_dwordx4 v[206:209], v[8:9], off
.Lrg21_i:
	s_or_b64 exec, exec, s[0:1]
	v_cmp_lt_i32_e32 vcc, 0, v55
	v_cmp_ge_i32_e64 s[0:1], s39, v55
	s_and_b64 s[42:43], vcc, s[0:1]
	v_mov_b32_e32 v210, 0
	v_mov_b32_e32 v211, 0
	v_mov_b32_e32 v212, 0
	v_mov_b32_e32 v213, 0
	s_and_saveexec_b64 s[0:1], s[42:43]
	s_cbranch_execz .Lrg22_i
	v_add_u32_e32 v56, s71, v55
	v_mad_u64_u32 v[56:57], s[42:43], v56, s74, v[48:49]
	global_load_dwordx4 v[210:213], v[56:57], off
.Lrg22_i:
	s_or_b64 exec, exec, s[0:1]
	s_mov_b32 s0, 0xeffffb20
	v_cmp_gt_u32_e32 vcc, s0, v55
	v_cmp_gt_i32_e64 s[0:1], s39, v55
	s_and_b64 s[42:43], vcc, s[0:1]
	v_mov_b32_e32 v214, 0
	v_mov_b32_e32 v215, 0
	v_mov_b32_e32 v216, 0
	v_mov_b32_e32 v217, 0
	s_and_saveexec_b64 s[0:1], s[42:43]
	s_cbranch_execz .Lrg23_i
	v_add_u32_e32 v56, s38, v55
	v_mad_u64_u32 v[56:57], s[42:43], v56, s74, v[48:49]
	global_load_dwordx4 v[214:217], v[56:57], off
.Lrg23_i:
	s_or_b64 exec, exec, s[0:1]
	v_add_u32_e32 v56, 1, v55
	v_cmp_lt_i32_e32 vcc, -2, v55
	v_cmp_gt_u32_e64 s[0:1], s39, v56
	s_and_b64 s[42:43], vcc, s[0:1]
	v_mov_b32_e32 v218, 0
	v_mov_b32_e32 v219, 0
	v_mov_b32_e32 v220, 0
	v_mov_b32_e32 v221, 0
	s_and_saveexec_b64 s[0:1], s[42:43]
	s_cbranch_execz .Lrg24_i
	v_add_u32_e32 v55, s38, v56
	v_mad_u64_u32 v[56:57], s[42:43], v55, s74, v[48:49]
	global_load_dwordx4 v[218:221], v[56:57], off
.Lrg24_i:
	s_or_b64 exec, exec, s[0:1]
	s_waitcnt vmcnt(0)
	v_mov_b32_e32 v8, v206
	v_mov_b32_e32 v9, v207
	v_mov_b32_e32 v10, v208
	v_mov_b32_e32 v11, v209
	v_lshlrev_b32_e32 v56, 16, v8
	v_and_b32_e32 v57, 0xffff0000, v8
	v_lshlrev_b32_e32 v8, 16, v9
	v_and_b32_e32 v9, 0xffff0000, v9
	v_lshlrev_b32_e32 v12, 16, v10
	v_and_b32_e32 v13, 0xffff0000, v10
	v_lshlrev_b32_e32 v10, 16, v11
	v_and_b32_e32 v11, 0xffff0000, v11
	v_pk_fma_f32 v[14:15], v[46:47], v[10:11], v[6:7]
	v_pk_fma_f32 v[12:13], v[44:45], v[12:13], v[4:5]
	v_pk_fma_f32 v[10:11], v[42:43], v[8:9], v[2:3]
	v_pk_fma_f32 v[8:9], v[40:41], v[56:57], v[0:1]
	v_mov_b32_e32 v56, v210
	v_mov_b32_e32 v57, v211
	v_mov_b32_e32 v58, v212
	v_mov_b32_e32 v59, v213
	v_lshlrev_b32_e32 v60, 16, v56
	v_and_b32_e32 v61, 0xffff0000, v56
	v_lshlrev_b32_e32 v56, 16, v57
	v_and_b32_e32 v57, 0xffff0000, v57
	v_lshlrev_b32_e32 v62, 16, v58
	v_and_b32_e32 v63, 0xffff0000, v58
	v_lshlrev_b32_e32 v58, 16, v59
	v_and_b32_e32 v59, 0xffff0000, v59
	v_pk_fma_f32 v[14:15], v[38:39], v[58:59], v[14:15]
	v_pk_fma_f32 v[12:13], v[36:37], v[62:63], v[12:13]
	v_pk_fma_f32 v[10:11], v[34:35], v[56:57], v[10:11]
	v_pk_fma_f32 v[8:9], v[32:33], v[60:61], v[8:9]
	v_mov_b32_e32 v56, v214
	v_mov_b32_e32 v57, v215
	v_mov_b32_e32 v58, v216
	v_mov_b32_e32 v59, v217
	v_lshlrev_b32_e32 v60, 16, v56
	v_and_b32_e32 v61, 0xffff0000, v56
	v_lshlrev_b32_e32 v56, 16, v57
	v_and_b32_e32 v57, 0xffff0000, v57
	v_lshlrev_b32_e32 v62, 16, v58
	v_and_b32_e32 v63, 0xffff0000, v58
	v_lshlrev_b32_e32 v58, 16, v59
	v_and_b32_e32 v59, 0xffff0000, v59
	v_pk_fma_f32 v[14:15], v[30:31], v[58:59], v[14:15]
	v_pk_fma_f32 v[12:13], v[28:29], v[62:63], v[12:13]
	v_pk_fma_f32 v[10:11], v[26:27], v[56:57], v[10:11]
	v_pk_fma_f32 v[8:9], v[24:25], v[60:61], v[8:9]
	v_mov_b32_e32 v56, v218
	v_mov_b32_e32 v57, v219
	v_mov_b32_e32 v58, v220
	v_mov_b32_e32 v59, v221
	v_lshlrev_b32_e32 v60, 16, v56
	v_and_b32_e32 v61, 0xffff0000, v56
	v_lshlrev_b32_e32 v56, 16, v57
	v_and_b32_e32 v57, 0xffff0000, v57
	v_lshlrev_b32_e32 v62, 16, v58
	v_and_b32_e32 v63, 0xffff0000, v58
	v_lshlrev_b32_e32 v58, 16, v59
	v_and_b32_e32 v59, 0xffff0000, v59
	v_pk_fma_f32 v[14:15], v[22:23], v[58:59], v[14:15]
	v_pk_fma_f32 v[12:13], v[20:21], v[62:63], v[12:13]
	v_pk_fma_f32 v[10:11], v[18:19], v[56:57], v[10:11]
	v_pk_fma_f32 v[8:9], v[16:17], v[60:61], v[8:9]
	v_lshl_add_u32 v55, v54, 8, v53
	ds_write_b128 v55, v[8:11] offset:36864
	ds_write_b128 v55, v[12:15] offset:36880
	v_cvt_pk_bf16_f32 v8, v8, v9
	v_cvt_pk_bf16_f32 v9, v10, v11
	v_cvt_pk_bf16_f32 v10, v12, v13
	v_mad_u64_u32 v[12:13], s[0:1], v54, s3, v[50:51]
	v_add_u32_e32 v54, 64, v52
	v_add_u32_e32 v55, s68, v54
	v_cvt_pk_bf16_f32 v11, v14, v15
	v_add_u32_e32 v56, -2, v55
	ds_write_b128 v12, v[8:11]
	v_cmp_lt_i32_e32 vcc, 1, v55
	v_cmp_gt_u32_e64 s[0:1], s39, v56
	v_mov_b64_e32 v[14:15], v[6:7]
	s_and_b64 s[42:43], vcc, s[0:1]
	v_mov_b64_e32 v[12:13], v[4:5]
	v_mov_b64_e32 v[10:11], v[2:3]
	v_mov_b64_e32 v[8:9], v[0:1]
	v_mov_b32_e32 v206, 0
	v_mov_b32_e32 v207, 0
	v_mov_b32_e32 v208, 0
	v_mov_b32_e32 v209, 0
	s_and_saveexec_b64 s[0:1], s[42:43]
	s_cbranch_execz .Lrg25_i
	v_add_u32_e32 v8, s38, v56
	v_mad_u64_u32 v[8:9], s[42:43], v8, s74, v[48:49]
	global_load_dwordx4 v[206:209], v[8:9], off

.Lrg26_i:
	s_or_b64 exec, exec, s[0:1]
	s_mov_b32 s0, 0xeffffb40
	v_cmp_gt_u32_e32 vcc, s0, v55
	v_cmp_gt_i32_e64 s[0:1], s39, v55
	s_and_b64 s[42:43], vcc, s[0:1]
	v_mov_b32_e32 v214, 0
	v_mov_b32_e32 v215, 0
	v_mov_b32_e32 v216, 0
	v_mov_b32_e32 v217, 0
	s_and_saveexec_b64 s[0:1], s[42:43]
	s_cbranch_execz .Lrg27_i
	v_add_u32_e32 v56, s38, v55
	v_mad_u64_u32 v[56:57], s[42:43], v56, s74, v[48:49]
	global_load_dwordx4 v[214:217], v[56:57], off

.Lrg28_i:
	s_or_b64 exec, exec, s[0:1]
	s_waitcnt vmcnt(0)
	v_mov_b32_e32 v8, v206
	v_mov_b32_e32 v9, v207
	v_mov_b32_e32 v10, v208
	v_mov_b32_e32 v11, v209
	v_lshlrev_b32_e32 v56, 16, v8
	v_and_b32_e32 v57, 0xffff0000, v8
	v_lshlrev_b32_e32 v8, 16, v9
	v_and_b32_e32 v9, 0xffff0000, v9
	v_lshlrev_b32_e32 v12, 16, v10
	v_and_b32_e32 v13, 0xffff0000, v10
	v_lshlrev_b32_e32 v10, 16, v11
	v_and_b32_e32 v11, 0xffff0000, v11
	v_pk_fma_f32 v[14:15], v[46:47], v[10:11], v[6:7]
	v_pk_fma_f32 v[12:13], v[44:45], v[12:13], v[4:5]
	v_pk_fma_f32 v[10:11], v[42:43], v[8:9], v[2:3]
	v_pk_fma_f32 v[8:9], v[40:41], v[56:57], v[0:1]
	v_mov_b32_e32 v56, v210
	v_mov_b32_e32 v57, v211
	v_mov_b32_e32 v58, v212
	v_mov_b32_e32 v59, v213
	v_lshlrev_b32_e32 v60, 16, v56
	v_and_b32_e32 v61, 0xffff0000, v56
	v_lshlrev_b32_e32 v56, 16, v57
	v_and_b32_e32 v57, 0xffff0000, v57
	v_lshlrev_b32_e32 v62, 16, v58
	v_and_b32_e32 v63, 0xffff0000, v58
	v_lshlrev_b32_e32 v58, 16, v59
	v_and_b32_e32 v59, 0xffff0000, v59
	v_pk_fma_f32 v[14:15], v[38:39], v[58:59], v[14:15]
	v_pk_fma_f32 v[12:13], v[36:37], v[62:63], v[12:13]
	v_pk_fma_f32 v[10:11], v[34:35], v[56:57], v[10:11]
	v_pk_fma_f32 v[8:9], v[32:33], v[60:61], v[8:9]
	v_mov_b32_e32 v56, v214
	v_mov_b32_e32 v57, v215
	v_mov_b32_e32 v58, v216
	v_mov_b32_e32 v59, v217
	v_lshlrev_b32_e32 v60, 16, v56
	v_and_b32_e32 v61, 0xffff0000, v56
	v_lshlrev_b32_e32 v56, 16, v57
	v_and_b32_e32 v57, 0xffff0000, v57
	v_lshlrev_b32_e32 v62, 16, v58
	v_and_b32_e32 v63, 0xffff0000, v58
	v_lshlrev_b32_e32 v58, 16, v59
	v_and_b32_e32 v59, 0xffff0000, v59
	v_pk_fma_f32 v[14:15], v[30:31], v[58:59], v[14:15]
	v_pk_fma_f32 v[12:13], v[28:29], v[62:63], v[12:13]
	v_pk_fma_f32 v[10:11], v[26:27], v[56:57], v[10:11]
	v_pk_fma_f32 v[8:9], v[24:25], v[60:61], v[8:9]
	v_mov_b32_e32 v56, v218
	v_mov_b32_e32 v57, v219
	v_mov_b32_e32 v58, v220
	v_mov_b32_e32 v59, v221
	v_lshlrev_b32_e32 v60, 16, v56
	v_and_b32_e32 v61, 0xffff0000, v56
	v_lshlrev_b32_e32 v56, 16, v57
	v_and_b32_e32 v57, 0xffff0000, v57
	v_lshlrev_b32_e32 v62, 16, v58
	v_and_b32_e32 v63, 0xffff0000, v58
	v_lshlrev_b32_e32 v58, 16, v59
	v_and_b32_e32 v59, 0xffff0000, v59
	v_pk_fma_f32 v[14:15], v[22:23], v[58:59], v[14:15]
	v_pk_fma_f32 v[12:13], v[20:21], v[62:63], v[12:13]
	v_pk_fma_f32 v[10:11], v[18:19], v[56:57], v[10:11]
	v_pk_fma_f32 v[8:9], v[16:17], v[60:61], v[8:9]
	v_lshl_add_u32 v55, v54, 8, v53
	ds_write_b128 v55, v[8:11] offset:36864
	ds_write_b128 v55, v[12:15] offset:36880
	v_cvt_pk_bf16_f32 v8, v8, v9
	v_cvt_pk_bf16_f32 v9, v10, v11
	v_cvt_pk_bf16_f32 v10, v12, v13
	v_cvt_pk_bf16_f32 v11, v14, v15
	v_mad_u64_u32 v[12:13], s[0:1], v54, s3, v[50:51]
	ds_write_b128 v12, v[8:11]
	v_add_u32_e32 v8, 0x60, v52
	v_add_u32_e32 v9, s68, v8
	v_add_u32_e32 v10, -2, v9
	v_cmp_lt_i32_e32 vcc, 1, v9
	v_cmp_gt_u32_e64 s[0:1], s39, v10
	s_and_b64 s[42:43], vcc, s[0:1]
	v_mov_b32_e32 v206, 0
	v_mov_b32_e32 v207, 0
	v_mov_b32_e32 v208, 0
	v_mov_b32_e32 v209, 0
	s_and_saveexec_b64 s[0:1], s[42:43]
	s_cbranch_execz .Lrg29_i
	v_add_u32_e32 v10, s38, v10
	v_mad_u64_u32 v[10:11], s[42:43], v10, s74, v[48:49]
	global_load_dwordx4 v[206:209], v[10:11], off
.Lrg29_i:
	s_or_b64 exec, exec, s[0:1]
	v_cmp_lt_i32_e32 vcc, 0, v9
	v_cmp_ge_i32_e64 s[0:1], s39, v9
	s_and_b64 s[42:43], vcc, s[0:1]
	v_mov_b32_e32 v210, 0
	v_mov_b32_e32 v211, 0
	v_mov_b32_e32 v212, 0
	v_mov_b32_e32 v213, 0
	s_and_saveexec_b64 s[0:1], s[42:43]
	s_cbranch_execz .Lrg30_i
	v_add_u32_e32 v10, s71, v9
	v_mad_u64_u32 v[10:11], s[42:43], v10, s74, v[48:49]
	global_load_dwordx4 v[210:213], v[10:11], off
.Lrg30_i:
	s_or_b64 exec, exec, s[0:1]
	s_mov_b32 s0, 0xeffffb60
	v_cmp_gt_u32_e32 vcc, s0, v9
	v_cmp_gt_i32_e64 s[0:1], s39, v9
	s_and_b64 s[42:43], vcc, s[0:1]
	v_mov_b32_e32 v214, 0
	v_mov_b32_e32 v215, 0
	v_mov_b32_e32 v216, 0
	v_mov_b32_e32 v217, 0
	s_and_saveexec_b64 s[0:1], s[42:43]
	s_cbranch_execz .Lrg31_i
	v_add_u32_e32 v10, s38, v9
	v_mad_u64_u32 v[10:11], s[42:43], v10, s74, v[48:49]
	global_load_dwordx4 v[214:217], v[10:11], off
.Lrg31_i:
	s_or_b64 exec, exec, s[0:1]
	v_add_u32_e32 v10, 1, v9
	v_cmp_lt_i32_e32 vcc, -2, v9
	v_cmp_gt_u32_e64 s[0:1], s39, v10
	s_and_b64 s[42:43], vcc, s[0:1]
	v_mov_b32_e32 v218, 0
	v_mov_b32_e32 v219, 0
	v_mov_b32_e32 v220, 0
	v_mov_b32_e32 v221, 0
	s_and_saveexec_b64 s[0:1], s[42:43]
	s_cbranch_execz .Lrg32_i
	v_add_u32_e32 v9, s38, v10
	v_mad_u64_u32 v[10:11], s[42:43], v9, s74, v[48:49]
	global_load_dwordx4 v[218:221], v[10:11], off
.Lrg32_i:
	s_or_b64 exec, exec, s[0:1]
	s_waitcnt vmcnt(0)
	v_mov_b32_e32 v10, v206
	v_mov_b32_e32 v11, v207
	v_mov_b32_e32 v12, v208
	v_mov_b32_e32 v13, v209
	v_lshlrev_b32_e32 v14, 16, v10
	v_and_b32_e32 v15, 0xffff0000, v10
	v_lshlrev_b32_e32 v10, 16, v11
	v_and_b32_e32 v11, 0xffff0000, v11
	v_lshlrev_b32_e32 v54, 16, v12
	v_and_b32_e32 v55, 0xffff0000, v12
	v_lshlrev_b32_e32 v12, 16, v13
	v_and_b32_e32 v13, 0xffff0000, v13
	v_pk_fma_f32 v[6:7], v[46:47], v[12:13], v[6:7]
	v_pk_fma_f32 v[4:5], v[44:45], v[54:55], v[4:5]
	v_pk_fma_f32 v[2:3], v[42:43], v[10:11], v[2:3]
	v_pk_fma_f32 v[0:1], v[40:41], v[14:15], v[0:1]
	v_mov_b32_e32 v10, v210
	v_mov_b32_e32 v11, v211
	v_mov_b32_e32 v12, v212
	v_mov_b32_e32 v13, v213
	v_lshlrev_b32_e32 v14, 16, v10
	v_and_b32_e32 v15, 0xffff0000, v10
	v_lshlrev_b32_e32 v10, 16, v11
	v_and_b32_e32 v11, 0xffff0000, v11
	v_lshlrev_b32_e32 v40, 16, v12
	v_and_b32_e32 v41, 0xffff0000, v12
	v_lshlrev_b32_e32 v12, 16, v13
	v_and_b32_e32 v13, 0xffff0000, v13
	v_pk_fma_f32 v[6:7], v[38:39], v[12:13], v[6:7]
	v_pk_fma_f32 v[4:5], v[36:37], v[40:41], v[4:5]
	v_pk_fma_f32 v[2:3], v[34:35], v[10:11], v[2:3]
	v_pk_fma_f32 v[0:1], v[32:33], v[14:15], v[0:1]
	v_mov_b32_e32 v10, v214
	v_mov_b32_e32 v11, v215
	v_mov_b32_e32 v12, v216
	v_mov_b32_e32 v13, v217
	v_lshlrev_b32_e32 v14, 16, v10
	v_and_b32_e32 v15, 0xffff0000, v10
	v_lshlrev_b32_e32 v10, 16, v11
	v_and_b32_e32 v11, 0xffff0000, v11
	v_lshlrev_b32_e32 v32, 16, v12
	v_and_b32_e32 v33, 0xffff0000, v12
	v_lshlrev_b32_e32 v12, 16, v13
	v_and_b32_e32 v13, 0xffff0000, v13
	v_pk_fma_f32 v[6:7], v[30:31], v[12:13], v[6:7]
	v_pk_fma_f32 v[4:5], v[28:29], v[32:33], v[4:5]
	v_pk_fma_f32 v[2:3], v[26:27], v[10:11], v[2:3]
	v_pk_fma_f32 v[0:1], v[24:25], v[14:15], v[0:1]
	v_mov_b32_e32 v10, v218
	v_mov_b32_e32 v11, v219
	v_mov_b32_e32 v12, v220
	v_mov_b32_e32 v13, v221
	v_lshlrev_b32_e32 v14, 16, v10
	v_and_b32_e32 v15, 0xffff0000, v10
	v_lshlrev_b32_e32 v10, 16, v11
	v_and_b32_e32 v11, 0xffff0000, v11
	v_lshlrev_b32_e32 v24, 16, v12
	v_and_b32_e32 v25, 0xffff0000, v12
	v_lshlrev_b32_e32 v12, 16, v13
	v_and_b32_e32 v13, 0xffff0000, v13
	v_pk_fma_f32 v[6:7], v[22:23], v[12:13], v[6:7]
	v_pk_fma_f32 v[4:5], v[20:21], v[24:25], v[4:5]
	v_pk_fma_f32 v[2:3], v[18:19], v[10:11], v[2:3]
	v_pk_fma_f32 v[0:1], v[16:17], v[14:15], v[0:1]
	v_lshl_add_u32 v10, v8, 8, v53
	ds_write_b128 v10, v[0:3] offset:36864
	ds_write_b128 v10, v[4:7] offset:36880
	v_cvt_pk_bf16_f32 v0, v0, v1
	v_cvt_pk_bf16_f32 v1, v2, v3
	v_cvt_pk_bf16_f32 v2, v4, v5
	v_mad_u64_u32 v[4:5], s[0:1], v8, s3, v[50:51]
	s_lshl_b32 s69, s2, 12
	v_readlane_b32 s0, v248, 24
	s_or_b32 s4, s69, s0
	v_readlane_b32 s16, v251, 4
	s_lshl_b64 s[2:3], s[4:5], 2
	v_readlane_b32 s26, v251, 14
	v_readlane_b32 s27, v251, 15
	s_add_u32 s0, s26, s2
	v_readlane_b32 s30, v251, 18
	s_addc_u32 s1, s27, s3
	v_and_b32_e32 v9, 63, v51
	v_cvt_pk_bf16_f32 v3, v6, v7
	v_ashrrev_i32_e32 v66, 6, v51
	v_readlane_b32 s31, v251, 19
	s_add_u32 s2, s30, s2
	ds_write_b128 v4, v[0:3]
	s_addc_u32 s3, s31, s3
	v_mul_u32_u24_e32 v1, 0x90, v9
	v_lshlrev_b32_e32 v2, 2, v66
	s_add_i32 s73, 0, 0x4800
	v_lshl_or_b32 v0, v66, 7, v9
	v_add3_u32 v1, v1, v2, s73
	s_mov_b32 s4, 0
	v_readlane_b32 s17, v251, 5
	v_readlane_b32 s18, v251, 6
	v_readlane_b32 s19, v251, 7
	v_readlane_b32 s20, v251, 8
	v_readlane_b32 s21, v251, 9
	v_readlane_b32 s22, v251, 10
	v_readlane_b32 s23, v251, 11
	v_readlane_b32 s24, v251, 12
	v_readlane_b32 s25, v251, 13
	v_readlane_b32 s28, v251, 16
	v_readlane_b32 s29, v251, 17
.LBB0_857:
	v_add_u32_e32 v2, s4, v0
	s_addk_i32 s4, 0x800
	v_mov_b32_e32 v222, v2
	v_ashrrev_i32_e32 v223, 31, v222
	v_lshlrev_b64 v[222:223], 2, v[222:223]
	v_lshl_add_u64 v[224:225], s[0:1], 0, v[222:223]
	global_load_dword v206, v[224:225], off
	global_load_dword v207, v[224:225], off offset:256
	v_lshl_add_u64 v[224:225], s[2:3], 0, v[222:223]
	global_load_dword v208, v[224:225], off
	global_load_dword v209, v[224:225], off offset:256
	v_add_u32_e32 v222, 0x200, v2
	v_ashrrev_i32_e32 v223, 31, v222
	v_lshlrev_b64 v[222:223], 2, v[222:223]
	v_lshl_add_u64 v[224:225], s[0:1], 0, v[222:223]
	global_load_dword v210, v[224:225], off
	global_load_dword v211, v[224:225], off offset:256
	v_lshl_add_u64 v[224:225], s[2:3], 0, v[222:223]
	global_load_dword v212, v[224:225], off
	global_load_dword v213, v[224:225], off offset:256
	v_add_u32_e32 v222, 0x400, v2
	v_ashrrev_i32_e32 v223, 31, v222
	v_lshlrev_b64 v[222:223], 2, v[222:223]
	v_lshl_add_u64 v[224:225], s[0:1], 0, v[222:223]
	global_load_dword v214, v[224:225], off
	global_load_dword v215, v[224:225], off offset:256
	v_lshl_add_u64 v[224:225], s[2:3], 0, v[222:223]
	global_load_dword v216, v[224:225], off
	global_load_dword v217, v[224:225], off offset:256
	v_add_u32_e32 v222, 0x600, v2
	v_ashrrev_i32_e32 v223, 31, v222
	v_lshlrev_b64 v[222:223], 2, v[222:223]
	v_lshl_add_u64 v[224:225], s[0:1], 0, v[222:223]
	global_load_dword v218, v[224:225], off
	global_load_dword v219, v[224:225], off offset:256
	v_lshl_add_u64 v[224:225], s[2:3], 0, v[222:223]
	global_load_dword v220, v[224:225], off
	global_load_dword v221, v[224:225], off offset:256
	v_add_u32_e32 v9, 0x2400, v1
	s_waitcnt vmcnt(0)
	v_cvt_pk_bf16_f32 v226, v206, v207
	v_cvt_pk_bf16_f32 v230, v208, v209
	v_cvt_pk_bf16_f32 v227, v210, v211
	v_cvt_pk_bf16_f32 v231, v212, v213
	v_cvt_pk_bf16_f32 v228, v214, v215
	v_cvt_pk_bf16_f32 v232, v216, v217
	v_cvt_pk_bf16_f32 v229, v218, v219
	v_cvt_pk_bf16_f32 v233, v220, v221
	ds_write2_b32 v1, v226, v227 offset1:4
	ds_write2_b32 v9, v230, v231 offset1:4
	ds_write2_b32 v1, v228, v229 offset0:8 offset1:12
	ds_write2_b32 v9, v232, v233 offset0:8 offset1:12
	v_add_u32_e32 v1, 64, v1
	s_cmpk_eq_i32 s4, 0x1000
	s_cbranch_scc0 .LBB0_857
	v_and_b32_e32 v74, 31, v51
	v_mul_u32_u24_e32 v0, 0x48, v74
	v_lshrrev_b32_e32 v1, 1, v51
	v_lshlrev_b32_e32 v0, 1, v0
	v_and_b32_e32 v1, 16, v1
	s_movk_i32 s0, 0x1200
	v_add3_u32 v65, 0, v0, v1
	v_mov_b32_e32 v0, 0
	v_mul_lo_u32 v64, v66, s0
	s_mov_b32 s0, -16
	v_mov_b32_e32 v1, v0
	v_mov_b32_e32 v2, v0
	v_mov_b32_e32 v3, v0
	v_mov_b32_e32 v4, v0
	v_mov_b32_e32 v5, v0
	v_mov_b32_e32 v6, v0
	v_mov_b32_e32 v7, v0
	v_mov_b32_e32 v8, v0
	v_mov_b32_e32 v9, v0
	v_mov_b32_e32 v10, v0
	v_mov_b32_e32 v11, v0
	v_mov_b32_e32 v12, v0
	v_mov_b32_e32 v13, v0
	v_mov_b32_e32 v14, v0
	v_mov_b32_e32 v15, v0
	v_mov_b32_e32 v32, v0
	v_mov_b32_e32 v33, v0
	v_mov_b32_e32 v34, v0
	v_mov_b32_e32 v35, v0
	v_mov_b32_e32 v36, v0
	v_mov_b32_e32 v37, v0
	v_mov_b32_e32 v38, v0
	v_mov_b32_e32 v39, v0
	v_mov_b32_e32 v40, v0
	v_mov_b32_e32 v41, v0
	v_mov_b32_e32 v42, v0
	v_mov_b32_e32 v43, v0
	v_mov_b32_e32 v44, v0
	v_mov_b32_e32 v45, v0
	v_mov_b32_e32 v46, v0
	v_mov_b32_e32 v47, v0
	v_mov_b32_e32 v16, v0
	v_mov_b32_e32 v17, v0
	v_mov_b32_e32 v18, v0
	v_mov_b32_e32 v19, v0
	v_mov_b32_e32 v20, v0
	v_mov_b32_e32 v21, v0
	v_mov_b32_e32 v22, v0
	v_mov_b32_e32 v23, v0
	v_mov_b32_e32 v24, v0
	v_mov_b32_e32 v25, v0
	v_mov_b32_e32 v26, v0
	v_mov_b32_e32 v27, v0
	v_mov_b32_e32 v28, v0
	v_mov_b32_e32 v29, v0
	v_mov_b32_e32 v30, v0
	v_mov_b32_e32 v31, v0
	v_mov_b32_e32 v48, v0
	v_mov_b32_e32 v49, v0
	v_mov_b32_e32 v50, v0
	v_mov_b32_e32 v51, v0
	v_mov_b32_e32 v52, v0
	v_mov_b32_e32 v53, v0
	v_mov_b32_e32 v54, v0
	v_mov_b32_e32 v55, v0
	v_mov_b32_e32 v56, v0
	v_mov_b32_e32 v57, v0
	v_mov_b32_e32 v58, v0
	v_mov_b32_e32 v59, v0
	v_mov_b32_e32 v60, v0
	v_mov_b32_e32 v61, v0
	v_mov_b32_e32 v62, v0
	v_mov_b32_e32 v63, v0
	s_waitcnt lgkmcnt(0)
	s_barrier

.LBB0_873:
	s_or_b64 exec, exec, s[0:1]
	v_mov_b32_e32 v51, v162
	ds_read2st64_b32 v[102:103], v98 offset1:1
	ds_read2st64_b32 v[104:105], v98 offset0:2 offset1:3
	ds_read2st64_b32 v[106:107], v98 offset0:4 offset1:5
	ds_read2st64_b32 v[108:109], v98 offset0:6 offset1:7
	ds_read2st64_b32 v[66:67], v98 offset0:144 offset1:145
	ds_read2st64_b32 v[68:69], v98 offset0:146 offset1:147
	ds_read2st64_b32 v[70:71], v98 offset0:148 offset1:149
	ds_read2st64_b32 v[72:73], v98 offset0:150 offset1:151
	ds_read2st64_b32 v[110:111], v98 offset0:8 offset1:9
	ds_read2st64_b32 v[112:113], v98 offset0:10 offset1:11
	ds_read2st64_b32 v[114:115], v98 offset0:12 offset1:13
	ds_read2st64_b32 v[116:117], v98 offset0:14 offset1:15
	ds_read2st64_b32 v[74:75], v98 offset0:152 offset1:153
	ds_read2st64_b32 v[76:77], v98 offset0:154 offset1:155
	ds_read2st64_b32 v[78:79], v98 offset0:156 offset1:157
	ds_read2st64_b32 v[80:81], v98 offset0:158 offset1:159
	ds_read2st64_b32 v[118:119], v98 offset0:16 offset1:17
	ds_read2st64_b32 v[120:121], v98 offset0:18 offset1:19
	ds_read2st64_b32 v[122:123], v98 offset0:20 offset1:21
	ds_read2st64_b32 v[124:125], v98 offset0:22 offset1:23
	ds_read2st64_b32 v[82:83], v98 offset0:160 offset1:161
	ds_read2st64_b32 v[84:85], v98 offset0:162 offset1:163
	ds_read2st64_b32 v[86:87], v98 offset0:164 offset1:165
	ds_read2st64_b32 v[88:89], v98 offset0:166 offset1:167
	ds_read2st64_b32 v[126:127], v98 offset0:24 offset1:25
	ds_read2st64_b32 v[128:129], v98 offset0:26 offset1:27
	ds_read2st64_b32 v[130:131], v98 offset0:28 offset1:29
	ds_read2st64_b32 v[132:133], v98 offset0:30 offset1:31
	ds_read2st64_b32 v[90:91], v98 offset0:168 offset1:169
	ds_read2st64_b32 v[92:93], v98 offset0:170 offset1:171
	ds_read2st64_b32 v[94:95], v98 offset0:172 offset1:173
	ds_read2st64_b32 v[100:101], v98 offset0:174 offset1:175
	v_readlane_b32 s0, v248, 18
	v_lshlrev_b32_e32 v136, 3, v51
	v_and_b32_e32 v50, 56, v136
	v_or_b32_e32 v14, s13, v50
	v_readlane_b32 s16, v251, 4
	v_or_b32_e32 v0, s0, v14
	v_readlane_b32 s22, v251, 10
	v_readlane_b32 s23, v251, 11
	v_mov_b32_e32 v1, v97
	s_mov_b64 s[0:1], 0x1000
	v_lshl_add_u64 v[8:9], v[0:1], 2, s[22:23]
	v_or_b32_e32 v96, s34, v14
	v_readlane_b32 s24, v251, 12
	v_readlane_b32 s25, v251, 13
	v_lshl_add_u64 v[10:11], v[8:9], 0, s[0:1]
	s_mov_b64 s[0:1], 0x1800
	v_lshl_add_u64 v[2:3], v[96:97], 2, s[24:25]
	v_lshl_add_u64 v[12:13], v[8:9], 0, s[0:1]
	s_movk_i32 s0, 0x1000
	s_waitcnt lgkmcnt(0)
	s_barrier
	global_load_dwordx4 v[4:7], v[2:3], off offset:16
	s_nop 0
	global_load_dwordx4 v[0:3], v[2:3], off
	s_nop 0
	global_load_dwordx4 v[44:47], v[8:9], off offset:16
	global_load_dwordx4 v[40:43], v[8:9], off
	global_load_dwordx4 v[36:39], v[8:9], off offset:2064
	global_load_dwordx4 v[32:35], v[8:9], off offset:2048
	v_add_co_u32_e32 v8, vcc, s0, v8
	v_ashrrev_i32_e32 v52, 3, v51
	s_nop 0
	v_addc_co_u32_e32 v9, vcc, 0, v9, vcc
	global_load_dwordx4 v[24:27], v[8:9], off
	global_load_dwordx4 v[16:19], v[8:9], off offset:2048
	global_load_dwordx4 v[28:31], v[10:11], off offset:16
	global_load_dwordx4 v[20:23], v[12:13], off offset:16
	v_readlane_b32 s0, v249, 7
	v_add_u32_e32 v53, s68, v52
	v_lshlrev_b32_e32 v96, 1, v14
	v_readlane_b32 s1, v249, 8
	v_add_u32_e32 v54, -2, v53
	v_cmp_lt_i32_e32 vcc, 1, v53
	v_lshl_add_u64 v[48:49], s[0:1], 0, v[96:97]
	v_cmp_gt_u32_e64 s[0:1], s39, v54
	s_and_b64 s[2:3], vcc, s[0:1]
	v_readlane_b32 s17, v251, 5
	v_readlane_b32 s18, v251, 6
	v_readlane_b32 s19, v251, 7
	v_readlane_b32 s20, v251, 8
	v_readlane_b32 s21, v251, 9
	v_readlane_b32 s26, v251, 14
	v_readlane_b32 s27, v251, 15
	v_readlane_b32 s28, v251, 16
	v_readlane_b32 s29, v251, 17
	v_readlane_b32 s30, v251, 18
	v_readlane_b32 s31, v251, 19
	s_waitcnt vmcnt(8)
	v_mov_b64_e32 v[14:15], v[6:7]
	v_mov_b64_e32 v[12:13], v[4:5]
	v_mov_b64_e32 v[10:11], v[2:3]
	v_mov_b64_e32 v[8:9], v[0:1]
	v_mov_b32_e32 v206, 0
	v_mov_b32_e32 v207, 0
	v_mov_b32_e32 v208, 0
	v_mov_b32_e32 v209, 0
	s_and_saveexec_b64 s[0:1], s[2:3]
	s_cbranch_execz .Lrg33_i
	v_add_u32_e32 v8, s38, v54
	v_mad_u64_u32 v[8:9], s[2:3], v8, s74, v[48:49]
	global_load_dwordx4 v[206:209], v[8:9], off
.Lrg33_i:
	s_or_b64 exec, exec, s[0:1]
	v_cmp_lt_i32_e32 vcc, 0, v53
	v_cmp_ge_i32_e64 s[0:1], s39, v53
	s_and_b64 s[2:3], vcc, s[0:1]
	v_mov_b32_e32 v210, 0
	v_mov_b32_e32 v211, 0
	v_mov_b32_e32 v212, 0
	v_mov_b32_e32 v213, 0
	s_and_saveexec_b64 s[0:1], s[2:3]
	s_movk_i32 s8, 0x90
	s_cbranch_execz .Lrg34_i
	v_add_u32_e32 v54, s71, v53
	v_mad_u64_u32 v[54:55], s[2:3], v54, s74, v[48:49]
	global_load_dwordx4 v[210:213], v[54:55], off
.Lrg34_i:
	s_or_b64 exec, exec, s[0:1]
	s_mov_b32 s0, 0xeffffb00
	v_cmp_gt_u32_e32 vcc, s0, v53
	v_cmp_gt_i32_e64 s[0:1], s39, v53
	s_and_b64 s[2:3], vcc, s[0:1]
	v_mov_b32_e32 v214, 0
	v_mov_b32_e32 v215, 0
	v_mov_b32_e32 v216, 0
	v_mov_b32_e32 v217, 0
	s_and_saveexec_b64 s[0:1], s[2:3]
	s_cbranch_execz .Lrg35_i
	v_add_u32_e32 v54, s38, v53
	v_mad_u64_u32 v[54:55], s[2:3], v54, s74, v[48:49]
	global_load_dwordx4 v[214:217], v[54:55], off
.Lrg35_i:
	s_or_b64 exec, exec, s[0:1]
	v_add_u32_e32 v54, 1, v53
	v_cmp_lt_i32_e32 vcc, -2, v53
	v_cmp_gt_u32_e64 s[0:1], s39, v54
	s_and_b64 s[2:3], vcc, s[0:1]
	v_mov_b32_e32 v218, 0
	v_mov_b32_e32 v219, 0
	v_mov_b32_e32 v220, 0
	v_mov_b32_e32 v221, 0
	s_and_saveexec_b64 s[0:1], s[2:3]
	s_cbranch_execz .Lrg36_i
	v_add_u32_e32 v53, s38, v54
	v_mad_u64_u32 v[54:55], s[2:3], v53, s74, v[48:49]
	global_load_dwordx4 v[218:221], v[54:55], off
.Lrg36_i:
	s_or_b64 exec, exec, s[0:1]
	s_waitcnt vmcnt(0)
	v_mov_b32_e32 v8, v206
	v_mov_b32_e32 v9, v207
	v_mov_b32_e32 v10, v208
	v_mov_b32_e32 v11, v209
	v_lshlrev_b32_e32 v54, 16, v8
	v_and_b32_e32 v55, 0xffff0000, v8
	v_lshlrev_b32_e32 v8, 16, v9
	v_and_b32_e32 v9, 0xffff0000, v9
	v_lshlrev_b32_e32 v12, 16, v10
	v_and_b32_e32 v13, 0xffff0000, v10
	v_lshlrev_b32_e32 v10, 16, v11
	v_and_b32_e32 v11, 0xffff0000, v11
	v_pk_fma_f32 v[14:15], v[46:47], v[10:11], v[6:7]
	v_pk_fma_f32 v[12:13], v[44:45], v[12:13], v[4:5]
	v_pk_fma_f32 v[10:11], v[42:43], v[8:9], v[2:3]
	v_pk_fma_f32 v[8:9], v[40:41], v[54:55], v[0:1]
	v_mov_b32_e32 v54, v210
	v_mov_b32_e32 v55, v211
	v_mov_b32_e32 v56, v212
	v_mov_b32_e32 v57, v213
	v_lshlrev_b32_e32 v58, 16, v54
	v_and_b32_e32 v59, 0xffff0000, v54
	v_lshlrev_b32_e32 v54, 16, v55
	v_and_b32_e32 v55, 0xffff0000, v55
	v_lshlrev_b32_e32 v60, 16, v56
	v_and_b32_e32 v61, 0xffff0000, v56
	v_lshlrev_b32_e32 v56, 16, v57
	v_and_b32_e32 v57, 0xffff0000, v57
	v_pk_fma_f32 v[14:15], v[38:39], v[56:57], v[14:15]
	v_pk_fma_f32 v[12:13], v[36:37], v[60:61], v[12:13]
	v_pk_fma_f32 v[10:11], v[34:35], v[54:55], v[10:11]
	v_pk_fma_f32 v[8:9], v[32:33], v[58:59], v[8:9]
	v_mov_b32_e32 v54, v214
	v_mov_b32_e32 v55, v215
	v_mov_b32_e32 v56, v216
	v_mov_b32_e32 v57, v217
	v_lshlrev_b32_e32 v58, 16, v54
	v_and_b32_e32 v59, 0xffff0000, v54
	v_lshlrev_b32_e32 v54, 16, v55
	v_and_b32_e32 v55, 0xffff0000, v55
	v_lshlrev_b32_e32 v60, 16, v56
	v_and_b32_e32 v61, 0xffff0000, v56
	v_lshlrev_b32_e32 v56, 16, v57
	v_and_b32_e32 v57, 0xffff0000, v57
	v_pk_fma_f32 v[14:15], v[30:31], v[56:57], v[14:15]
	v_pk_fma_f32 v[12:13], v[28:29], v[60:61], v[12:13]
	v_pk_fma_f32 v[10:11], v[26:27], v[54:55], v[10:11]
	v_pk_fma_f32 v[8:9], v[24:25], v[58:59], v[8:9]
	v_mov_b32_e32 v54, v218
	v_mov_b32_e32 v55, v219
	v_mov_b32_e32 v56, v220
	v_mov_b32_e32 v57, v221
	v_lshlrev_b32_e32 v58, 16, v54
	v_and_b32_e32 v59, 0xffff0000, v54
	v_lshlrev_b32_e32 v54, 16, v55
	v_and_b32_e32 v55, 0xffff0000, v55
	v_lshlrev_b32_e32 v60, 16, v56
	v_and_b32_e32 v61, 0xffff0000, v56
	v_lshlrev_b32_e32 v56, 16, v57
	v_and_b32_e32 v57, 0xffff0000, v57
	v_pk_fma_f32 v[14:15], v[22:23], v[56:57], v[14:15]
	v_pk_fma_f32 v[12:13], v[20:21], v[60:61], v[12:13]
	v_pk_fma_f32 v[10:11], v[18:19], v[54:55], v[10:11]
	v_pk_fma_f32 v[8:9], v[16:17], v[58:59], v[8:9]
	v_lshl_add_u32 v53, v50, 2, 0
	v_lshl_add_u32 v54, v52, 8, v53
	v_lshlrev_b32_e32 v50, 1, v50
	ds_write_b128 v54, v[8:11] offset:36864
	ds_write_b128 v54, v[12:15] offset:36880
	v_add_u32_e32 v54, 32, v52
	v_sub_u32_e32 v50, v53, v50
	v_add_u32_e32 v55, s68, v54
	v_cvt_pk_bf16_f32 v8, v8, v9
	v_cvt_pk_bf16_f32 v9, v10, v11
	v_cvt_pk_bf16_f32 v10, v12, v13
	v_cvt_pk_bf16_f32 v11, v14, v15
	v_mad_u64_u32 v[12:13], s[0:1], v52, s8, v[50:51]
	v_add_u32_e32 v56, -2, v55
	ds_write_b128 v12, v[8:11]
	v_cmp_lt_i32_e32 vcc, 1, v55
	v_cmp_gt_u32_e64 s[0:1], s39, v56
	v_mov_b64_e32 v[14:15], v[6:7]
	s_and_b64 s[2:3], vcc, s[0:1]
	v_mov_b64_e32 v[12:13], v[4:5]
	v_mov_b64_e32 v[10:11], v[2:3]
	v_mov_b64_e32 v[8:9], v[0:1]
	v_mov_b32_e32 v206, 0
	v_mov_b32_e32 v207, 0
	v_mov_b32_e32 v208, 0
	v_mov_b32_e32 v209, 0
	s_and_saveexec_b64 s[0:1], s[2:3]
	s_cbranch_execz .Lrg37_i
	v_add_u32_e32 v8, s38, v56
	v_mad_u64_u32 v[8:9], s[2:3], v8, s74, v[48:49]
	global_load_dwordx4 v[206:209], v[8:9], off
.Lrg37_i:
	s_or_b64 exec, exec, s[0:1]
	v_cmp_lt_i32_e32 vcc, 0, v55
	v_cmp_ge_i32_e64 s[0:1], s39, v55
	s_and_b64 s[2:3], vcc, s[0:1]
	v_mov_b32_e32 v210, 0
	v_mov_b32_e32 v211, 0
	v_mov_b32_e32 v212, 0
	v_mov_b32_e32 v213, 0
	s_and_saveexec_b64 s[0:1], s[2:3]
	s_cbranch_execz .Lrg38_i
	v_add_u32_e32 v56, s71, v55
	v_mad_u64_u32 v[56:57], s[2:3], v56, s74, v[48:49]
	global_load_dwordx4 v[210:213], v[56:57], off
.Lrg38_i:
	s_or_b64 exec, exec, s[0:1]
	s_mov_b32 s0, 0xeffffb20
	v_cmp_gt_u32_e32 vcc, s0, v55
	v_cmp_gt_i32_e64 s[0:1], s39, v55
	s_and_b64 s[2:3], vcc, s[0:1]
	v_mov_b32_e32 v214, 0
	v_mov_b32_e32 v215, 0
	v_mov_b32_e32 v216, 0
	v_mov_b32_e32 v217, 0
	s_and_saveexec_b64 s[0:1], s[2:3]
	s_cbranch_execz .Lrg39_i
	v_add_u32_e32 v56, s38, v55
	v_mad_u64_u32 v[56:57], s[2:3], v56, s74, v[48:49]
	global_load_dwordx4 v[214:217], v[56:57], off
.Lrg39_i:
	s_or_b64 exec, exec, s[0:1]
	v_add_u32_e32 v56, 1, v55
	v_cmp_lt_i32_e32 vcc, -2, v55
	v_cmp_gt_u32_e64 s[0:1], s39, v56
	s_and_b64 s[2:3], vcc, s[0:1]
	v_mov_b32_e32 v218, 0
	v_mov_b32_e32 v219, 0
	v_mov_b32_e32 v220, 0
	v_mov_b32_e32 v221, 0
	s_and_saveexec_b64 s[0:1], s[2:3]
	s_cbranch_execz .Lrg40_i
	v_add_u32_e32 v55, s38, v56
	v_mad_u64_u32 v[56:57], s[2:3], v55, s74, v[48:49]
	global_load_dwordx4 v[218:221], v[56:57], off
.Lrg40_i:
	s_or_b64 exec, exec, s[0:1]
	s_waitcnt vmcnt(0)
	v_mov_b32_e32 v8, v206
	v_mov_b32_e32 v9, v207
	v_mov_b32_e32 v10, v208
	v_mov_b32_e32 v11, v209
	v_lshlrev_b32_e32 v56, 16, v8
	v_and_b32_e32 v57, 0xffff0000, v8
	v_lshlrev_b32_e32 v8, 16, v9
	v_and_b32_e32 v9, 0xffff0000, v9
	v_lshlrev_b32_e32 v12, 16, v10
	v_and_b32_e32 v13, 0xffff0000, v10
	v_lshlrev_b32_e32 v10, 16, v11
	v_and_b32_e32 v11, 0xffff0000, v11
	v_pk_fma_f32 v[14:15], v[46:47], v[10:11], v[6:7]
	v_pk_fma_f32 v[12:13], v[44:45], v[12:13], v[4:5]
	v_pk_fma_f32 v[10:11], v[42:43], v[8:9], v[2:3]
	v_pk_fma_f32 v[8:9], v[40:41], v[56:57], v[0:1]
	v_mov_b32_e32 v56, v210
	v_mov_b32_e32 v57, v211
	v_mov_b32_e32 v58, v212
	v_mov_b32_e32 v59, v213
	v_lshlrev_b32_e32 v60, 16, v56
	v_and_b32_e32 v61, 0xffff0000, v56
	v_lshlrev_b32_e32 v56, 16, v57
	v_and_b32_e32 v57, 0xffff0000, v57
	v_lshlrev_b32_e32 v62, 16, v58
	v_and_b32_e32 v63, 0xffff0000, v58
	v_lshlrev_b32_e32 v58, 16, v59
	v_and_b32_e32 v59, 0xffff0000, v59
	v_pk_fma_f32 v[14:15], v[38:39], v[58:59], v[14:15]
	v_pk_fma_f32 v[12:13], v[36:37], v[62:63], v[12:13]
	v_pk_fma_f32 v[10:11], v[34:35], v[56:57], v[10:11]
	v_pk_fma_f32 v[8:9], v[32:33], v[60:61], v[8:9]
	v_mov_b32_e32 v56, v214
	v_mov_b32_e32 v57, v215
	v_mov_b32_e32 v58, v216
	v_mov_b32_e32 v59, v217
	v_lshlrev_b32_e32 v60, 16, v56
	v_and_b32_e32 v61, 0xffff0000, v56
	v_lshlrev_b32_e32 v56, 16, v57
	v_and_b32_e32 v57, 0xffff0000, v57
	v_lshlrev_b32_e32 v62, 16, v58
	v_and_b32_e32 v63, 0xffff0000, v58
	v_lshlrev_b32_e32 v58, 16, v59
	v_and_b32_e32 v59, 0xffff0000, v59
	v_pk_fma_f32 v[14:15], v[30:31], v[58:59], v[14:15]
	v_pk_fma_f32 v[12:13], v[28:29], v[62:63], v[12:13]
	v_pk_fma_f32 v[10:11], v[26:27], v[56:57], v[10:11]
	v_pk_fma_f32 v[8:9], v[24:25], v[60:61], v[8:9]
	v_mov_b32_e32 v56, v218
	v_mov_b32_e32 v57, v219
	v_mov_b32_e32 v58, v220
	v_mov_b32_e32 v59, v221
	v_lshlrev_b32_e32 v60, 16, v56
	v_and_b32_e32 v61, 0xffff0000, v56
	v_lshlrev_b32_e32 v56, 16, v57
	v_and_b32_e32 v57, 0xffff0000, v57
	v_lshlrev_b32_e32 v62, 16, v58
	v_and_b32_e32 v63, 0xffff0000, v58
	v_lshlrev_b32_e32 v58, 16, v59
	v_and_b32_e32 v59, 0xffff0000, v59
	v_pk_fma_f32 v[14:15], v[22:23], v[58:59], v[14:15]
	v_pk_fma_f32 v[12:13], v[20:21], v[62:63], v[12:13]
	v_pk_fma_f32 v[10:11], v[18:19], v[56:57], v[10:11]
	v_pk_fma_f32 v[8:9], v[16:17], v[60:61], v[8:9]
	v_lshl_add_u32 v55, v54, 8, v53
	ds_write_b128 v55, v[8:11] offset:36864
	ds_write_b128 v55, v[12:15] offset:36880
	v_cvt_pk_bf16_f32 v8, v8, v9
	v_cvt_pk_bf16_f32 v9, v10, v11
	v_cvt_pk_bf16_f32 v10, v12, v13
	v_mad_u64_u32 v[12:13], s[0:1], v54, s8, v[50:51]
	v_add_u32_e32 v54, 64, v52
	v_add_u32_e32 v55, s68, v54
	v_cvt_pk_bf16_f32 v11, v14, v15
	v_add_u32_e32 v56, -2, v55
	ds_write_b128 v12, v[8:11]
	v_cmp_lt_i32_e32 vcc, 1, v55
	v_cmp_gt_u32_e64 s[0:1], s39, v56
	v_mov_b64_e32 v[14:15], v[6:7]
	s_and_b64 s[2:3], vcc, s[0:1]
	v_mov_b64_e32 v[12:13], v[4:5]
	v_mov_b64_e32 v[10:11], v[2:3]
	v_mov_b64_e32 v[8:9], v[0:1]
	v_mov_b32_e32 v206, 0
	v_mov_b32_e32 v207, 0
	v_mov_b32_e32 v208, 0
	v_mov_b32_e32 v209, 0
	s_and_saveexec_b64 s[0:1], s[2:3]
	s_cbranch_execz .Lrg41_i
	v_add_u32_e32 v8, s38, v56
	v_mad_u64_u32 v[8:9], s[2:3], v8, s74, v[48:49]
	global_load_dwordx4 v[206:209], v[8:9], off

.Lrg42_i:
	s_or_b64 exec, exec, s[0:1]
	s_mov_b32 s0, 0xeffffb40
	v_cmp_gt_u32_e32 vcc, s0, v55
	v_cmp_gt_i32_e64 s[0:1], s39, v55
	s_and_b64 s[2:3], vcc, s[0:1]
	v_mov_b32_e32 v214, 0
	v_mov_b32_e32 v215, 0
	v_mov_b32_e32 v216, 0
	v_mov_b32_e32 v217, 0
	s_and_saveexec_b64 s[0:1], s[2:3]
	s_cbranch_execz .Lrg43_i
	v_add_u32_e32 v56, s38, v55
	v_mad_u64_u32 v[56:57], s[2:3], v56, s74, v[48:49]
	global_load_dwordx4 v[214:217], v[56:57], off

.Lrg44_i:
	s_or_b64 exec, exec, s[0:1]
	s_waitcnt vmcnt(0)
	v_mov_b32_e32 v8, v206
	v_mov_b32_e32 v9, v207
	v_mov_b32_e32 v10, v208
	v_mov_b32_e32 v11, v209
	v_lshlrev_b32_e32 v56, 16, v8
	v_and_b32_e32 v57, 0xffff0000, v8
	v_lshlrev_b32_e32 v8, 16, v9
	v_and_b32_e32 v9, 0xffff0000, v9
	v_lshlrev_b32_e32 v12, 16, v10
	v_and_b32_e32 v13, 0xffff0000, v10
	v_lshlrev_b32_e32 v10, 16, v11
	v_and_b32_e32 v11, 0xffff0000, v11
	v_pk_fma_f32 v[14:15], v[46:47], v[10:11], v[6:7]
	v_pk_fma_f32 v[12:13], v[44:45], v[12:13], v[4:5]
	v_pk_fma_f32 v[10:11], v[42:43], v[8:9], v[2:3]
	v_pk_fma_f32 v[8:9], v[40:41], v[56:57], v[0:1]
	v_mov_b32_e32 v56, v210
	v_mov_b32_e32 v57, v211
	v_mov_b32_e32 v58, v212
	v_mov_b32_e32 v59, v213
	v_lshlrev_b32_e32 v60, 16, v56
	v_and_b32_e32 v61, 0xffff0000, v56
	v_lshlrev_b32_e32 v56, 16, v57
	v_and_b32_e32 v57, 0xffff0000, v57
	v_lshlrev_b32_e32 v62, 16, v58
	v_and_b32_e32 v63, 0xffff0000, v58
	v_lshlrev_b32_e32 v58, 16, v59
	v_and_b32_e32 v59, 0xffff0000, v59
	v_pk_fma_f32 v[14:15], v[38:39], v[58:59], v[14:15]
	v_pk_fma_f32 v[12:13], v[36:37], v[62:63], v[12:13]
	v_pk_fma_f32 v[10:11], v[34:35], v[56:57], v[10:11]
	v_pk_fma_f32 v[8:9], v[32:33], v[60:61], v[8:9]
	v_mov_b32_e32 v56, v214
	v_mov_b32_e32 v57, v215
	v_mov_b32_e32 v58, v216
	v_mov_b32_e32 v59, v217
	v_lshlrev_b32_e32 v60, 16, v56
	v_and_b32_e32 v61, 0xffff0000, v56
	v_lshlrev_b32_e32 v56, 16, v57
	v_and_b32_e32 v57, 0xffff0000, v57
	v_lshlrev_b32_e32 v62, 16, v58
	v_and_b32_e32 v63, 0xffff0000, v58
	v_lshlrev_b32_e32 v58, 16, v59
	v_and_b32_e32 v59, 0xffff0000, v59
	v_pk_fma_f32 v[14:15], v[30:31], v[58:59], v[14:15]
	v_pk_fma_f32 v[12:13], v[28:29], v[62:63], v[12:13]
	v_pk_fma_f32 v[10:11], v[26:27], v[56:57], v[10:11]
	v_pk_fma_f32 v[8:9], v[24:25], v[60:61], v[8:9]
	v_mov_b32_e32 v56, v218
	v_mov_b32_e32 v57, v219
	v_mov_b32_e32 v58, v220
	v_mov_b32_e32 v59, v221
	v_lshlrev_b32_e32 v60, 16, v56
	v_and_b32_e32 v61, 0xffff0000, v56
	v_lshlrev_b32_e32 v56, 16, v57
	v_and_b32_e32 v57, 0xffff0000, v57
	v_lshlrev_b32_e32 v62, 16, v58
	v_and_b32_e32 v63, 0xffff0000, v58
	v_lshlrev_b32_e32 v58, 16, v59
	v_and_b32_e32 v59, 0xffff0000, v59
	v_pk_fma_f32 v[14:15], v[22:23], v[58:59], v[14:15]
	v_pk_fma_f32 v[12:13], v[20:21], v[62:63], v[12:13]
	v_pk_fma_f32 v[10:11], v[18:19], v[56:57], v[10:11]
	v_pk_fma_f32 v[8:9], v[16:17], v[60:61], v[8:9]
	v_lshl_add_u32 v55, v54, 8, v53
	ds_write_b128 v55, v[8:11] offset:36864
	ds_write_b128 v55, v[12:15] offset:36880
	v_cvt_pk_bf16_f32 v8, v8, v9
	v_cvt_pk_bf16_f32 v9, v10, v11
	v_cvt_pk_bf16_f32 v10, v12, v13
	v_cvt_pk_bf16_f32 v11, v14, v15
	v_mad_u64_u32 v[12:13], s[0:1], v54, s8, v[50:51]
	ds_write_b128 v12, v[8:11]
	v_add_u32_e32 v8, 0x60, v52
	v_add_u32_e32 v9, s68, v8
	v_add_u32_e32 v10, -2, v9
	v_cmp_lt_i32_e32 vcc, 1, v9
	v_cmp_gt_u32_e64 s[0:1], s39, v10
	s_and_b64 s[2:3], vcc, s[0:1]
	v_mov_b32_e32 v206, 0
	v_mov_b32_e32 v207, 0
	v_mov_b32_e32 v208, 0
	v_mov_b32_e32 v209, 0
	s_and_saveexec_b64 s[0:1], s[2:3]
	s_cbranch_execz .Lrg45_i
	v_add_u32_e32 v10, s38, v10
	v_mad_u64_u32 v[10:11], s[2:3], v10, s74, v[48:49]
	global_load_dwordx4 v[206:209], v[10:11], off
.Lrg45_i:
	s_or_b64 exec, exec, s[0:1]
	v_cmp_lt_i32_e32 vcc, 0, v9
	v_cmp_ge_i32_e64 s[0:1], s39, v9
	s_and_b64 s[2:3], vcc, s[0:1]
	v_mov_b32_e32 v210, 0
	v_mov_b32_e32 v211, 0
	v_mov_b32_e32 v212, 0
	v_mov_b32_e32 v213, 0
	s_and_saveexec_b64 s[0:1], s[2:3]
	s_cbranch_execz .Lrg46_i
	v_add_u32_e32 v10, s71, v9
	v_mad_u64_u32 v[10:11], s[2:3], v10, s74, v[48:49]
	global_load_dwordx4 v[210:213], v[10:11], off
.Lrg46_i:
	s_or_b64 exec, exec, s[0:1]
	s_mov_b32 s0, 0xeffffb60
	v_cmp_gt_u32_e32 vcc, s0, v9
	v_cmp_gt_i32_e64 s[0:1], s39, v9
	s_and_b64 s[2:3], vcc, s[0:1]
	v_mov_b32_e32 v214, 0
	v_mov_b32_e32 v215, 0
	v_mov_b32_e32 v216, 0
	v_mov_b32_e32 v217, 0
	s_and_saveexec_b64 s[0:1], s[2:3]
	s_cbranch_execz .Lrg47_i
	v_add_u32_e32 v10, s38, v9
	v_mad_u64_u32 v[10:11], s[2:3], v10, s74, v[48:49]
	global_load_dwordx4 v[214:217], v[10:11], off
.Lrg47_i:
	s_or_b64 exec, exec, s[0:1]
	v_add_u32_e32 v10, 1, v9
	v_cmp_lt_i32_e32 vcc, -2, v9
	v_cmp_gt_u32_e64 s[0:1], s39, v10
	s_and_b64 s[2:3], vcc, s[0:1]
	v_mov_b32_e32 v218, 0
	v_mov_b32_e32 v219, 0
	v_mov_b32_e32 v220, 0
	v_mov_b32_e32 v221, 0
	s_and_saveexec_b64 s[0:1], s[2:3]
	s_cbranch_execz .Lrg48_i
	v_add_u32_e32 v9, s38, v10
	v_mad_u64_u32 v[10:11], s[2:3], v9, s74, v[48:49]
	global_load_dwordx4 v[218:221], v[10:11], off
.Lrg48_i:
	s_or_b64 exec, exec, s[0:1]
	s_waitcnt vmcnt(0)
	v_mov_b32_e32 v10, v206
	v_mov_b32_e32 v11, v207
	v_mov_b32_e32 v12, v208
	v_mov_b32_e32 v13, v209
	v_lshlrev_b32_e32 v14, 16, v10
	v_and_b32_e32 v15, 0xffff0000, v10
	v_lshlrev_b32_e32 v10, 16, v11
	v_and_b32_e32 v11, 0xffff0000, v11
	v_lshlrev_b32_e32 v54, 16, v12
	v_and_b32_e32 v55, 0xffff0000, v12
	v_lshlrev_b32_e32 v12, 16, v13
	v_and_b32_e32 v13, 0xffff0000, v13
	v_pk_fma_f32 v[6:7], v[46:47], v[12:13], v[6:7]
	v_pk_fma_f32 v[4:5], v[44:45], v[54:55], v[4:5]
	v_pk_fma_f32 v[2:3], v[42:43], v[10:11], v[2:3]
	v_pk_fma_f32 v[0:1], v[40:41], v[14:15], v[0:1]
	v_mov_b32_e32 v10, v210
	v_mov_b32_e32 v11, v211
	v_mov_b32_e32 v12, v212
	v_mov_b32_e32 v13, v213
	v_lshlrev_b32_e32 v14, 16, v10
	v_and_b32_e32 v15, 0xffff0000, v10
	v_lshlrev_b32_e32 v10, 16, v11
	v_and_b32_e32 v11, 0xffff0000, v11
	v_lshlrev_b32_e32 v40, 16, v12
	v_and_b32_e32 v41, 0xffff0000, v12
	v_lshlrev_b32_e32 v12, 16, v13
	v_and_b32_e32 v13, 0xffff0000, v13
	v_pk_fma_f32 v[6:7], v[38:39], v[12:13], v[6:7]
	v_pk_fma_f32 v[4:5], v[36:37], v[40:41], v[4:5]
	v_pk_fma_f32 v[2:3], v[34:35], v[10:11], v[2:3]
	v_pk_fma_f32 v[0:1], v[32:33], v[14:15], v[0:1]
	v_mov_b32_e32 v10, v214
	v_mov_b32_e32 v11, v215
	v_mov_b32_e32 v12, v216
	v_mov_b32_e32 v13, v217
	v_lshlrev_b32_e32 v14, 16, v10
	v_and_b32_e32 v15, 0xffff0000, v10
	v_lshlrev_b32_e32 v10, 16, v11
	v_and_b32_e32 v11, 0xffff0000, v11
	v_lshlrev_b32_e32 v32, 16, v12
	v_and_b32_e32 v33, 0xffff0000, v12
	v_lshlrev_b32_e32 v12, 16, v13
	v_and_b32_e32 v13, 0xffff0000, v13
	v_pk_fma_f32 v[6:7], v[30:31], v[12:13], v[6:7]
	v_pk_fma_f32 v[4:5], v[28:29], v[32:33], v[4:5]
	v_pk_fma_f32 v[2:3], v[26:27], v[10:11], v[2:3]
	v_pk_fma_f32 v[0:1], v[24:25], v[14:15], v[0:1]
	v_mov_b32_e32 v10, v218
	v_mov_b32_e32 v11, v219
	v_mov_b32_e32 v12, v220
	v_mov_b32_e32 v13, v221
	v_lshlrev_b32_e32 v14, 16, v10
	v_and_b32_e32 v15, 0xffff0000, v10
	v_lshlrev_b32_e32 v10, 16, v11
	v_and_b32_e32 v11, 0xffff0000, v11
	v_lshlrev_b32_e32 v24, 16, v12
	v_and_b32_e32 v25, 0xffff0000, v12
	v_lshlrev_b32_e32 v12, 16, v13
	v_and_b32_e32 v13, 0xffff0000, v13
	v_pk_fma_f32 v[6:7], v[22:23], v[12:13], v[6:7]
	v_pk_fma_f32 v[4:5], v[20:21], v[24:25], v[4:5]
	v_pk_fma_f32 v[2:3], v[18:19], v[10:11], v[2:3]
	v_pk_fma_f32 v[0:1], v[16:17], v[14:15], v[0:1]
	v_lshl_add_u32 v10, v8, 8, v53
	ds_write_b128 v10, v[0:3] offset:36864
	ds_write_b128 v10, v[4:7] offset:36880
	v_cvt_pk_bf16_f32 v0, v0, v1
	v_cvt_pk_bf16_f32 v1, v2, v3
	v_cvt_pk_bf16_f32 v2, v4, v5
	v_mad_u64_u32 v[4:5], s[0:1], v8, s8, v[50:51]
	v_readlane_b32 s0, v248, 26
	s_or_b32 s0, s69, s0
	s_mov_b32 s1, s5
	v_readlane_b32 s16, v251, 4
	s_lshl_b64 s[2:3], s[0:1], 2
	v_readlane_b32 s26, v251, 14
	v_readlane_b32 s27, v251, 15
	s_add_u32 s0, s26, s2
	v_and_b32_e32 v9, 63, v51
	v_cvt_pk_bf16_f32 v3, v6, v7
	v_ashrrev_i32_e32 v96, 6, v51
	v_readlane_b32 s30, v251, 18
	s_addc_u32 s1, s27, s3
	ds_write_b128 v4, v[0:3]
	v_readlane_b32 s31, v251, 19
	s_add_u32 s2, s30, s2
	v_mul_u32_u24_e32 v1, 0x90, v9
	v_lshlrev_b32_e32 v2, 2, v96
	s_addc_u32 s3, s31, s3
	v_lshl_or_b32 v0, v96, 7, v9
	v_add3_u32 v1, v1, v2, s73
	s_mov_b32 s38, 0
	v_readlane_b32 s17, v251, 5
	v_readlane_b32 s18, v251, 6
	v_readlane_b32 s19, v251, 7
	v_readlane_b32 s20, v251, 8
	v_readlane_b32 s21, v251, 9
	v_readlane_b32 s22, v251, 10
	v_readlane_b32 s23, v251, 11
	v_readlane_b32 s24, v251, 12
	v_readlane_b32 s25, v251, 13
	v_readlane_b32 s28, v251, 16
	v_readlane_b32 s29, v251, 17
.LBB0_906:
	v_add_u32_e32 v2, s38, v0
	s_addk_i32 s38, 0x800
	v_mov_b32_e32 v222, v2
	v_ashrrev_i32_e32 v223, 31, v222
	v_lshlrev_b64 v[222:223], 2, v[222:223]
	v_lshl_add_u64 v[224:225], s[0:1], 0, v[222:223]
	global_load_dword v206, v[224:225], off
	global_load_dword v207, v[224:225], off offset:256
	v_lshl_add_u64 v[224:225], s[2:3], 0, v[222:223]
	global_load_dword v208, v[224:225], off
	global_load_dword v209, v[224:225], off offset:256
	v_add_u32_e32 v222, 0x200, v2
	v_ashrrev_i32_e32 v223, 31, v222
	v_lshlrev_b64 v[222:223], 2, v[222:223]
	v_lshl_add_u64 v[224:225], s[0:1], 0, v[222:223]
	global_load_dword v210, v[224:225], off
	global_load_dword v211, v[224:225], off offset:256
	v_lshl_add_u64 v[224:225], s[2:3], 0, v[222:223]
	global_load_dword v212, v[224:225], off
	global_load_dword v213, v[224:225], off offset:256
	v_add_u32_e32 v222, 0x400, v2
	v_ashrrev_i32_e32 v223, 31, v222
	v_lshlrev_b64 v[222:223], 2, v[222:223]
	v_lshl_add_u64 v[224:225], s[0:1], 0, v[222:223]
	global_load_dword v214, v[224:225], off
	global_load_dword v215, v[224:225], off offset:256
	v_lshl_add_u64 v[224:225], s[2:3], 0, v[222:223]
	global_load_dword v216, v[224:225], off
	global_load_dword v217, v[224:225], off offset:256
	v_add_u32_e32 v222, 0x600, v2
	v_ashrrev_i32_e32 v223, 31, v222
	v_lshlrev_b64 v[222:223], 2, v[222:223]
	v_lshl_add_u64 v[224:225], s[0:1], 0, v[222:223]
	global_load_dword v218, v[224:225], off
	global_load_dword v219, v[224:225], off offset:256
	v_lshl_add_u64 v[224:225], s[2:3], 0, v[222:223]
	global_load_dword v220, v[224:225], off
	global_load_dword v221, v[224:225], off offset:256
	v_add_u32_e32 v9, 0x2400, v1
	s_waitcnt vmcnt(0)
	v_cvt_pk_bf16_f32 v226, v206, v207
	v_cvt_pk_bf16_f32 v230, v208, v209
	v_cvt_pk_bf16_f32 v227, v210, v211
	v_cvt_pk_bf16_f32 v231, v212, v213
	v_cvt_pk_bf16_f32 v228, v214, v215
	v_cvt_pk_bf16_f32 v232, v216, v217
	v_cvt_pk_bf16_f32 v229, v218, v219
	v_cvt_pk_bf16_f32 v233, v220, v221
	ds_write2_b32 v1, v226, v227 offset1:4
	ds_write2_b32 v9, v230, v231 offset1:4
	ds_write2_b32 v1, v228, v229 offset0:8 offset1:12
	ds_write2_b32 v9, v232, v233 offset0:8 offset1:12
	v_add_u32_e32 v1, 64, v1
	s_cmpk_lg_i32 s38, 0x1000
	s_cbranch_scc1 .LBB0_906
	v_and_b32_e32 v145, 31, v51
	v_mul_u32_u24_e32 v0, 0x48, v145
	v_lshrrev_b32_e32 v1, 1, v51
	v_lshlrev_b32_e32 v0, 1, v0
	v_and_b32_e32 v1, 16, v1
	s_movk_i32 s0, 0x1200
	v_add3_u32 v135, 0, v0, v1
	v_mov_b32_e32 v0, 0
	v_mul_lo_u32 v134, v96, s0
	s_mov_b32 s0, -16
	v_mov_b32_e32 v1, v0
	v_mov_b32_e32 v2, v0
	v_mov_b32_e32 v3, v0
	v_mov_b32_e32 v4, v0
	v_mov_b32_e32 v5, v0
	v_mov_b32_e32 v6, v0
	v_mov_b32_e32 v7, v0
	v_mov_b32_e32 v8, v0
	v_mov_b32_e32 v9, v0
	v_mov_b32_e32 v10, v0
	v_mov_b32_e32 v11, v0
	v_mov_b32_e32 v12, v0
	v_mov_b32_e32 v13, v0
	v_mov_b32_e32 v14, v0
	v_mov_b32_e32 v15, v0
	v_mov_b32_e32 v32, v0
	v_mov_b32_e32 v33, v0
	v_mov_b32_e32 v34, v0
	v_mov_b32_e32 v35, v0
	v_mov_b32_e32 v36, v0
	v_mov_b32_e32 v37, v0
	v_mov_b32_e32 v38, v0
	v_mov_b32_e32 v39, v0
	v_mov_b32_e32 v40, v0
	v_mov_b32_e32 v41, v0
	v_mov_b32_e32 v42, v0
	v_mov_b32_e32 v43, v0
	v_mov_b32_e32 v44, v0
	v_mov_b32_e32 v45, v0
	v_mov_b32_e32 v46, v0
	v_mov_b32_e32 v47, v0
	v_mov_b32_e32 v16, v0
	v_mov_b32_e32 v17, v0
	v_mov_b32_e32 v18, v0
	v_mov_b32_e32 v19, v0
	v_mov_b32_e32 v20, v0
	v_mov_b32_e32 v21, v0
	v_mov_b32_e32 v22, v0
	v_mov_b32_e32 v23, v0
	v_mov_b32_e32 v24, v0
	v_mov_b32_e32 v25, v0
	v_mov_b32_e32 v26, v0
	v_mov_b32_e32 v27, v0
	v_mov_b32_e32 v28, v0
	v_mov_b32_e32 v29, v0
	v_mov_b32_e32 v30, v0
	v_mov_b32_e32 v31, v0
	v_mov_b32_e32 v48, v0
	v_mov_b32_e32 v49, v0
	v_mov_b32_e32 v50, v0
	v_mov_b32_e32 v51, v0
	v_mov_b32_e32 v52, v0
	v_mov_b32_e32 v53, v0
	v_mov_b32_e32 v54, v0
	v_mov_b32_e32 v55, v0
	v_mov_b32_e32 v56, v0
	v_mov_b32_e32 v57, v0
	v_mov_b32_e32 v58, v0
	v_mov_b32_e32 v59, v0
	v_mov_b32_e32 v60, v0
	v_mov_b32_e32 v61, v0
	v_mov_b32_e32 v62, v0
	v_mov_b32_e32 v63, v0
	s_waitcnt lgkmcnt(0)
	s_barrier

.LBB0_921:
	s_or_b64 exec, exec, s[0:1]
	v_readlane_b32 s0, v249, 31
	v_lshlrev_b32_e32 v7, 5, v143
	v_lshlrev_b32_e32 v96, 1, v140
	v_readlane_b32 s1, v249, 32
	v_or_b32_e32 v4, 31, v7
	v_lshl_or_b32 v23, v4, 8, v142
	v_lshl_add_u64 v[2:3], s[0:1], 0, v[96:97]
	v_add_u32_e32 v4, s7, v4
	v_add_u32_e32 v23, 0, v23
	v_mad_i64_i32 v[26:27], s[0:1], v4, s74, v[2:3]
	ds_read2st64_b32 v[24:25], v23 offset1:144
	v_or_b32_e32 v134, 31, v7
	v_add_u32_e32 v134, s7, v134
	v_mad_i64_i32 v[136:137], s[0:1], v134, s74, v[2:3]
	global_load_ushort v144, v[136:137], off
	v_or_b32_e32 v134, 30, v7
	v_add_u32_e32 v134, s7, v134
	v_mad_i64_i32 v[136:137], s[0:1], v134, s74, v[2:3]
	global_load_ushort v145, v[136:137], off
	v_or_b32_e32 v134, 29, v7
	v_add_u32_e32 v134, s7, v134
	v_mad_i64_i32 v[136:137], s[0:1], v134, s74, v[2:3]
	global_load_ushort v146, v[136:137], off
	v_or_b32_e32 v134, 28, v7
	v_add_u32_e32 v134, s7, v134
	v_mad_i64_i32 v[136:137], s[0:1], v134, s74, v[2:3]
	global_load_ushort v147, v[136:137], off
	v_or_b32_e32 v134, 27, v7
	v_add_u32_e32 v134, s7, v134
	v_mad_i64_i32 v[136:137], s[0:1], v134, s74, v[2:3]
	global_load_ushort v148, v[136:137], off
	v_or_b32_e32 v134, 26, v7
	v_add_u32_e32 v134, s7, v134
	v_mad_i64_i32 v[136:137], s[0:1], v134, s74, v[2:3]
	global_load_ushort v149, v[136:137], off
	v_or_b32_e32 v134, 25, v7
	v_add_u32_e32 v134, s7, v134
	v_mad_i64_i32 v[136:137], s[0:1], v134, s74, v[2:3]
	global_load_ushort v150, v[136:137], off
	v_or_b32_e32 v134, 24, v7
	v_add_u32_e32 v134, s7, v134
	v_mad_i64_i32 v[136:137], s[0:1], v134, s74, v[2:3]
	global_load_ushort v151, v[136:137], off
	v_or_b32_e32 v134, 23, v7
	v_add_u32_e32 v134, s7, v134
	v_mad_i64_i32 v[136:137], s[0:1], v134, s74, v[2:3]
	global_load_ushort v152, v[136:137], off
	v_or_b32_e32 v134, 22, v7
	v_add_u32_e32 v134, s7, v134
	v_mad_i64_i32 v[136:137], s[0:1], v134, s74, v[2:3]
	global_load_ushort v153, v[136:137], off
	v_or_b32_e32 v134, 21, v7
	v_add_u32_e32 v134, s7, v134
	v_mad_i64_i32 v[136:137], s[0:1], v134, s74, v[2:3]
	global_load_ushort v154, v[136:137], off
	v_or_b32_e32 v134, 20, v7
	v_add_u32_e32 v134, s7, v134
	v_mad_i64_i32 v[136:137], s[0:1], v134, s74, v[2:3]
	global_load_ushort v155, v[136:137], off
	v_or_b32_e32 v134, 19, v7
	v_add_u32_e32 v134, s7, v134
	v_mad_i64_i32 v[136:137], s[0:1], v134, s74, v[2:3]
	global_load_ushort v156, v[136:137], off
	v_or_b32_e32 v134, 18, v7
	v_add_u32_e32 v134, s7, v134
	v_mad_i64_i32 v[136:137], s[0:1], v134, s74, v[2:3]
	global_load_ushort v157, v[136:137], off
	v_or_b32_e32 v134, 17, v7
	v_add_u32_e32 v134, s7, v134
	v_mad_i64_i32 v[136:137], s[0:1], v134, s74, v[2:3]
	global_load_ushort v158, v[136:137], off
	v_or_b32_e32 v134, 16, v7
	v_add_u32_e32 v134, s7, v134
	v_mad_i64_i32 v[136:137], s[0:1], v134, s74, v[2:3]
	global_load_ushort v159, v[136:137], off
	v_or_b32_e32 v134, 15, v7
	v_add_u32_e32 v134, s7, v134
	v_mad_i64_i32 v[136:137], s[0:1], v134, s74, v[2:3]
	global_load_ushort v160, v[136:137], off
	v_or_b32_e32 v134, 14, v7
	v_add_u32_e32 v134, s7, v134
	v_mad_i64_i32 v[136:137], s[0:1], v134, s74, v[2:3]
	global_load_ushort v161, v[136:137], off
	v_or_b32_e32 v134, 13, v7
	v_add_u32_e32 v134, s7, v134
	v_mad_i64_i32 v[136:137], s[0:1], v134, s74, v[2:3]
	global_load_ushort v169, v[136:137], off
	v_or_b32_e32 v134, 12, v7
	v_add_u32_e32 v134, s7, v134
	v_mad_i64_i32 v[136:137], s[0:1], v134, s74, v[2:3]
	global_load_ushort v170, v[136:137], off
	v_or_b32_e32 v134, 11, v7
	v_add_u32_e32 v134, s7, v134
	v_mad_i64_i32 v[136:137], s[0:1], v134, s74, v[2:3]
	global_load_ushort v171, v[136:137], off
	v_or_b32_e32 v134, 10, v7
	v_add_u32_e32 v134, s7, v134
	v_mad_i64_i32 v[136:137], s[0:1], v134, s74, v[2:3]
	global_load_ushort v172, v[136:137], off
	v_or_b32_e32 v134, 9, v7
	v_add_u32_e32 v134, s7, v134
	v_mad_i64_i32 v[136:137], s[0:1], v134, s74, v[2:3]
	global_load_ushort v173, v[136:137], off
	v_or_b32_e32 v134, 8, v7
	v_add_u32_e32 v134, s7, v134
	v_mad_i64_i32 v[136:137], s[0:1], v134, s74, v[2:3]
	global_load_ushort v174, v[136:137], off
	v_or_b32_e32 v134, 7, v7
	v_add_u32_e32 v134, s7, v134
	v_mad_i64_i32 v[136:137], s[0:1], v134, s74, v[2:3]
	global_load_ushort v175, v[136:137], off
	v_or_b32_e32 v134, 6, v7
	v_add_u32_e32 v134, s7, v134
	v_mad_i64_i32 v[136:137], s[0:1], v134, s74, v[2:3]
	global_load_ushort v176, v[136:137], off
	v_or_b32_e32 v134, 5, v7
	v_add_u32_e32 v134, s7, v134
	v_mad_i64_i32 v[136:137], s[0:1], v134, s74, v[2:3]
	global_load_ushort v177, v[136:137], off
	v_or_b32_e32 v134, 4, v7
	v_add_u32_e32 v134, s7, v134
	v_mad_i64_i32 v[136:137], s[0:1], v134, s74, v[2:3]
	global_load_ushort v178, v[136:137], off
	v_or_b32_e32 v134, 3, v7
	v_add_u32_e32 v134, s7, v134
	v_mad_i64_i32 v[136:137], s[0:1], v134, s74, v[2:3]
	global_load_ushort v179, v[136:137], off
	v_or_b32_e32 v134, 2, v7
	v_add_u32_e32 v134, s7, v134
	v_mad_i64_i32 v[136:137], s[0:1], v134, s74, v[2:3]
	global_load_ushort v180, v[136:137], off
	v_or_b32_e32 v134, 1, v7
	v_add_u32_e32 v134, s7, v134
	v_mad_i64_i32 v[136:137], s[0:1], v134, s74, v[2:3]
	global_load_ushort v181, v[136:137], off
	v_or_b32_e32 v134, 0, v7
	v_add_u32_e32 v134, s7, v134
	v_mad_i64_i32 v[136:137], s[0:1], v134, s74, v[2:3]
	global_load_ushort v182, v[136:137], off
	v_fma_f32 v6, v99, v102, v66
	v_fmac_f32_e32 v67, v6, v103
	v_fma_f32 v8, v67, v104, v68
	v_fmac_f32_e32 v69, v8, v105
	v_fma_f32 v9, v69, v106, v70
	v_fmac_f32_e32 v71, v9, v107
	v_fma_f32 v10, v71, v108, v72
	v_fmac_f32_e32 v73, v10, v109
	v_fma_f32 v11, v73, v110, v74
	v_fmac_f32_e32 v75, v11, v111
	v_fma_f32 v12, v75, v112, v76
	v_fmac_f32_e32 v77, v12, v113
	v_fma_f32 v13, v77, v114, v78
	v_fmac_f32_e32 v79, v13, v115
	v_fma_f32 v14, v79, v116, v80
	v_fmac_f32_e32 v81, v14, v117
	v_fma_f32 v15, v81, v118, v82
	v_fmac_f32_e32 v83, v15, v119
	v_fma_f32 v16, v83, v120, v84
	v_fmac_f32_e32 v85, v16, v121
	v_fma_f32 v17, v85, v122, v86
	v_fmac_f32_e32 v87, v17, v123
	v_fma_f32 v18, v87, v124, v88
	v_fmac_f32_e32 v89, v18, v125
	v_fma_f32 v19, v89, v126, v90
	v_fmac_f32_e32 v91, v19, v127
	v_fma_f32 v20, v91, v128, v92
	v_fmac_f32_e32 v93, v20, v129
	v_fma_f32 v21, v93, v130, v94
	v_fmac_f32_e32 v95, v21, v131
	v_fma_f32 v22, v95, v132, v100
	v_fmac_f32_e32 v101, v22, v133
	s_waitcnt lgkmcnt(0)
	v_fmac_f32_e32 v25, v5, v24
	v_ashrrev_i32_e32 v5, 31, v4
	v_add_f32_e32 v24, v101, v25
	v_lshl_add_u64 v[0:1], s[64:65], 0, v[96:97]
	v_lshlrev_b64 v[4:5], 10, v[4:5]
	v_lshl_add_u64 v[4:5], v[0:1], 0, v[4:5]
	s_waitcnt vmcnt(0)
	v_mov_b32_e32 v23, v144
	v_lshlrev_b32_e32 v23, 16, v23
	v_mul_f32_e32 v26, 0x3d372713, v23
	v_mul_f32_e32 v26, v26, v23
	v_fma_f32 v26, v26, v23, v23
	v_mul_f32_e32 v26, 0x3f4c422a, v26
	v_add_f32_e32 v26, v26, v26
	v_mul_f32_e32 v26, 0xbfb8aa3b, v26
	v_exp_f32_e32 v26, v26
	s_nop 0
	v_add_f32_e32 v26, 1.0, v26
	v_rcp_f32_e32 v26, v26
	s_nop 0
	v_mul_f32_e32 v23, v26, v23
	v_mul_f32_e32 v23, v24, v23
	v_cvt_pk_bf16_f32 v23, v23, s0
	global_store_short v[4:5], v23, off
	v_or_b32_e32 v23, 30, v7
	v_lshl_or_b32 v4, v23, 8, v142
	v_add_u32_e32 v4, 0, v4
	ds_read2st64_b32 v[4:5], v4 offset1:144
	v_add_u32_e32 v24, s7, v23
	v_mad_i64_i32 v[26:27], s[0:1], v24, s74, v[2:3]
	s_waitcnt lgkmcnt(0)
	v_fmac_f32_e32 v5, v25, v4
	v_mov_b32_e32 v4, v145
	v_ashrrev_i32_e32 v25, 31, v24
	v_add_f32_e32 v22, v22, v5
	v_lshlrev_b32_e32 v4, 16, v4
	v_mul_f32_e32 v23, 0x3d372713, v4
	v_mul_f32_e32 v23, v23, v4
	v_fma_f32 v23, v23, v4, v4
	v_mul_f32_e32 v23, 0x3f4c422a, v23
	v_add_f32_e32 v23, v23, v23
	v_mul_f32_e32 v23, 0xbfb8aa3b, v23
	v_exp_f32_e32 v23, v23
	s_nop 0
	v_add_f32_e32 v23, 1.0, v23
	v_rcp_f32_e32 v23, v23
	s_nop 0
	v_mul_f32_e32 v4, v23, v4
	v_mul_f32_e32 v4, v22, v4
	v_lshlrev_b64 v[22:23], 10, v[24:25]
	v_cvt_pk_bf16_f32 v4, v4, s0
	v_lshl_add_u64 v[22:23], v[0:1], 0, v[22:23]
	global_store_short v[22:23], v4, off
	v_or_b32_e32 v4, 29, v7
	v_lshl_or_b32 v22, v4, 8, v142
	v_add_u32_e32 v22, 0, v22
	ds_read2st64_b32 v[22:23], v22 offset1:144
	v_add_u32_e32 v4, s7, v4
	v_mad_i64_i32 v[24:25], s[0:1], v4, s74, v[2:3]
	s_waitcnt lgkmcnt(0)
	v_fmac_f32_e32 v23, v5, v22
	v_mov_b32_e32 v22, v146
	v_ashrrev_i32_e32 v5, 31, v4
	v_add_f32_e32 v24, v95, v23
	v_lshlrev_b64 v[4:5], 10, v[4:5]
	v_lshl_add_u64 v[4:5], v[0:1], 0, v[4:5]
	v_lshlrev_b32_e32 v22, 16, v22
	v_mul_f32_e32 v25, 0x3d372713, v22
	v_mul_f32_e32 v25, v25, v22
	v_fma_f32 v25, v25, v22, v22
	v_mul_f32_e32 v25, 0x3f4c422a, v25
	v_add_f32_e32 v25, v25, v25
	v_mul_f32_e32 v25, 0xbfb8aa3b, v25
	v_exp_f32_e32 v25, v25
	s_nop 0
	v_add_f32_e32 v25, 1.0, v25
	v_rcp_f32_e32 v25, v25
	s_nop 0
	v_mul_f32_e32 v22, v25, v22
	v_mul_f32_e32 v22, v24, v22
	v_cvt_pk_bf16_f32 v22, v22, s0
	global_store_short v[4:5], v22, off
	v_or_b32_e32 v22, 28, v7
	v_lshl_or_b32 v4, v22, 8, v142
	v_add_u32_e32 v4, 0, v4
	ds_read2st64_b32 v[4:5], v4 offset1:144
	v_add_u32_e32 v22, s7, v22
	v_mad_i64_i32 v[24:25], s[0:1], v22, s74, v[2:3]
	s_waitcnt lgkmcnt(0)
	v_fmac_f32_e32 v5, v23, v4
	v_mov_b32_e32 v4, v147
	v_ashrrev_i32_e32 v23, 31, v22
	v_add_f32_e32 v21, v21, v5
	v_lshlrev_b64 v[22:23], 10, v[22:23]
	v_lshl_add_u64 v[22:23], v[0:1], 0, v[22:23]
	v_lshlrev_b32_e32 v4, 16, v4
	v_mul_f32_e32 v24, 0x3d372713, v4
	v_mul_f32_e32 v24, v24, v4
	v_fma_f32 v24, v24, v4, v4
	v_mul_f32_e32 v24, 0x3f4c422a, v24
	v_add_f32_e32 v24, v24, v24
	v_mul_f32_e32 v24, 0xbfb8aa3b, v24
	v_exp_f32_e32 v24, v24
	s_nop 0
	v_add_f32_e32 v24, 1.0, v24
	v_rcp_f32_e32 v24, v24
	s_nop 0
	v_mul_f32_e32 v4, v24, v4
	v_mul_f32_e32 v4, v21, v4
	v_cvt_pk_bf16_f32 v4, v4, s0
	global_store_short v[22:23], v4, off
	v_or_b32_e32 v4, 27, v7
	v_lshl_or_b32 v21, v4, 8, v142
	v_add_u32_e32 v4, s7, v4
	v_add_u32_e32 v21, 0, v21
	v_mad_i64_i32 v[24:25], s[0:1], v4, s74, v[2:3]
	ds_read2st64_b32 v[22:23], v21 offset1:144
	v_mov_b32_e32 v21, v148
	s_waitcnt lgkmcnt(0)
	v_fmac_f32_e32 v23, v5, v22
	v_ashrrev_i32_e32 v5, 31, v4
	v_add_f32_e32 v22, v93, v23
	v_lshlrev_b64 v[4:5], 10, v[4:5]
	v_lshl_add_u64 v[4:5], v[0:1], 0, v[4:5]
	v_lshlrev_b32_e32 v21, 16, v21
	v_mul_f32_e32 v24, 0x3d372713, v21
	v_mul_f32_e32 v24, v24, v21
	v_fma_f32 v24, v24, v21, v21
	v_mul_f32_e32 v24, 0x3f4c422a, v24
	v_add_f32_e32 v24, v24, v24
	v_mul_f32_e32 v24, 0xbfb8aa3b, v24
	v_exp_f32_e32 v24, v24
	s_nop 0
	v_add_f32_e32 v24, 1.0, v24
	v_rcp_f32_e32 v24, v24
	s_nop 0
	v_mul_f32_e32 v21, v24, v21
	v_mul_f32_e32 v21, v22, v21
	v_cvt_pk_bf16_f32 v21, v21, s0
	global_store_short v[4:5], v21, off
	v_or_b32_e32 v21, 26, v7
	v_lshl_or_b32 v4, v21, 8, v142
	v_add_u32_e32 v4, 0, v4
	ds_read2st64_b32 v[4:5], v4 offset1:144
	v_add_u32_e32 v22, s7, v21
	v_mad_i64_i32 v[24:25], s[0:1], v22, s74, v[2:3]
	s_waitcnt lgkmcnt(0)
	v_fmac_f32_e32 v5, v23, v4
	v_mov_b32_e32 v4, v149
	v_ashrrev_i32_e32 v23, 31, v22
	v_add_f32_e32 v20, v20, v5
	v_lshlrev_b32_e32 v4, 16, v4
	v_mul_f32_e32 v21, 0x3d372713, v4
	v_mul_f32_e32 v21, v21, v4
	v_fma_f32 v21, v21, v4, v4
	v_mul_f32_e32 v21, 0x3f4c422a, v21
	v_add_f32_e32 v21, v21, v21
	v_mul_f32_e32 v21, 0xbfb8aa3b, v21
	v_exp_f32_e32 v21, v21
	s_nop 0
	v_add_f32_e32 v21, 1.0, v21
	v_rcp_f32_e32 v21, v21
	s_nop 0
	v_mul_f32_e32 v4, v21, v4
	v_mul_f32_e32 v4, v20, v4
	v_lshlrev_b64 v[20:21], 10, v[22:23]
	v_cvt_pk_bf16_f32 v4, v4, s0
	v_lshl_add_u64 v[20:21], v[0:1], 0, v[20:21]
	global_store_short v[20:21], v4, off
	v_or_b32_e32 v4, 25, v7
	v_lshl_or_b32 v20, v4, 8, v142
	v_add_u32_e32 v20, 0, v20
	ds_read2st64_b32 v[20:21], v20 offset1:144
	v_add_u32_e32 v4, s7, v4
	v_mad_i64_i32 v[22:23], s[0:1], v4, s74, v[2:3]
	s_waitcnt lgkmcnt(0)
	v_fmac_f32_e32 v21, v5, v20
	v_mov_b32_e32 v20, v150
	v_ashrrev_i32_e32 v5, 31, v4
	v_add_f32_e32 v22, v91, v21
	v_lshlrev_b64 v[4:5], 10, v[4:5]
	v_lshl_add_u64 v[4:5], v[0:1], 0, v[4:5]
	v_lshlrev_b32_e32 v20, 16, v20
	v_mul_f32_e32 v23, 0x3d372713, v20
	v_mul_f32_e32 v23, v23, v20
	v_fma_f32 v23, v23, v20, v20
	v_mul_f32_e32 v23, 0x3f4c422a, v23
	v_add_f32_e32 v23, v23, v23
	v_mul_f32_e32 v23, 0xbfb8aa3b, v23
	v_exp_f32_e32 v23, v23
	s_nop 0
	v_add_f32_e32 v23, 1.0, v23
	v_rcp_f32_e32 v23, v23
	s_nop 0
	v_mul_f32_e32 v20, v23, v20
	v_mul_f32_e32 v20, v22, v20
	v_cvt_pk_bf16_f32 v20, v20, s0
	global_store_short v[4:5], v20, off
	v_or_b32_e32 v20, 24, v7
	v_lshl_or_b32 v4, v20, 8, v142
	v_add_u32_e32 v4, 0, v4
	ds_read2st64_b32 v[4:5], v4 offset1:144
	v_add_u32_e32 v20, s7, v20
	v_mad_i64_i32 v[22:23], s[0:1], v20, s74, v[2:3]
	s_waitcnt lgkmcnt(0)
	v_fmac_f32_e32 v5, v21, v4
	v_mov_b32_e32 v4, v151
	v_ashrrev_i32_e32 v21, 31, v20
	v_add_f32_e32 v19, v19, v5
	v_lshlrev_b64 v[20:21], 10, v[20:21]
	v_lshl_add_u64 v[20:21], v[0:1], 0, v[20:21]
	v_lshlrev_b32_e32 v4, 16, v4
	v_mul_f32_e32 v22, 0x3d372713, v4
	v_mul_f32_e32 v22, v22, v4
	v_fma_f32 v22, v22, v4, v4
	v_mul_f32_e32 v22, 0x3f4c422a, v22
	v_add_f32_e32 v22, v22, v22
	v_mul_f32_e32 v22, 0xbfb8aa3b, v22
	v_exp_f32_e32 v22, v22
	s_nop 0
	v_add_f32_e32 v22, 1.0, v22
	v_rcp_f32_e32 v22, v22
	s_nop 0
	v_mul_f32_e32 v4, v22, v4
	v_mul_f32_e32 v4, v19, v4
	v_cvt_pk_bf16_f32 v4, v4, s0
	global_store_short v[20:21], v4, off
	v_or_b32_e32 v4, 23, v7
	v_lshl_or_b32 v19, v4, 8, v142
	v_add_u32_e32 v4, s7, v4
	v_add_u32_e32 v19, 0, v19
	v_mad_i64_i32 v[22:23], s[0:1], v4, s74, v[2:3]
	ds_read2st64_b32 v[20:21], v19 offset1:144
	v_mov_b32_e32 v19, v152
	s_waitcnt lgkmcnt(0)
	v_fmac_f32_e32 v21, v5, v20
	v_ashrrev_i32_e32 v5, 31, v4
	v_add_f32_e32 v20, v89, v21
	v_lshlrev_b64 v[4:5], 10, v[4:5]
	v_lshl_add_u64 v[4:5], v[0:1], 0, v[4:5]
	v_lshlrev_b32_e32 v19, 16, v19
	v_mul_f32_e32 v22, 0x3d372713, v19
	v_mul_f32_e32 v22, v22, v19
	v_fma_f32 v22, v22, v19, v19
	v_mul_f32_e32 v22, 0x3f4c422a, v22
	v_add_f32_e32 v22, v22, v22
	v_mul_f32_e32 v22, 0xbfb8aa3b, v22
	v_exp_f32_e32 v22, v22
	s_nop 0
	v_add_f32_e32 v22, 1.0, v22
	v_rcp_f32_e32 v22, v22
	s_nop 0
	v_mul_f32_e32 v19, v22, v19
	v_mul_f32_e32 v19, v20, v19
	v_cvt_pk_bf16_f32 v19, v19, s0
	global_store_short v[4:5], v19, off
	v_or_b32_e32 v19, 22, v7
	v_lshl_or_b32 v4, v19, 8, v142
	v_add_u32_e32 v4, 0, v4
	ds_read2st64_b32 v[4:5], v4 offset1:144
	v_add_u32_e32 v20, s7, v19
	v_mad_i64_i32 v[22:23], s[0:1], v20, s74, v[2:3]
	s_waitcnt lgkmcnt(0)
	v_fmac_f32_e32 v5, v21, v4
	v_mov_b32_e32 v4, v153
	v_ashrrev_i32_e32 v21, 31, v20
	v_add_f32_e32 v18, v18, v5
	v_lshlrev_b32_e32 v4, 16, v4
	v_mul_f32_e32 v19, 0x3d372713, v4
	v_mul_f32_e32 v19, v19, v4
	v_fma_f32 v19, v19, v4, v4
	v_mul_f32_e32 v19, 0x3f4c422a, v19
	v_add_f32_e32 v19, v19, v19
	v_mul_f32_e32 v19, 0xbfb8aa3b, v19
	v_exp_f32_e32 v19, v19
	s_nop 0
	v_add_f32_e32 v19, 1.0, v19
	v_rcp_f32_e32 v19, v19
	s_nop 0
	v_mul_f32_e32 v4, v19, v4
	v_mul_f32_e32 v4, v18, v4
	v_lshlrev_b64 v[18:19], 10, v[20:21]
	v_cvt_pk_bf16_f32 v4, v4, s0
	v_lshl_add_u64 v[18:19], v[0:1], 0, v[18:19]
	global_store_short v[18:19], v4, off
	v_or_b32_e32 v4, 21, v7
	v_lshl_or_b32 v18, v4, 8, v142
	v_add_u32_e32 v18, 0, v18
	ds_read2st64_b32 v[18:19], v18 offset1:144
	v_add_u32_e32 v4, s7, v4
	v_mad_i64_i32 v[20:21], s[0:1], v4, s74, v[2:3]
	s_waitcnt lgkmcnt(0)
	v_fmac_f32_e32 v19, v5, v18
	v_mov_b32_e32 v18, v154
	v_ashrrev_i32_e32 v5, 31, v4
	v_add_f32_e32 v20, v87, v19
	v_lshlrev_b64 v[4:5], 10, v[4:5]
	v_lshl_add_u64 v[4:5], v[0:1], 0, v[4:5]
	v_lshlrev_b32_e32 v18, 16, v18
	v_mul_f32_e32 v21, 0x3d372713, v18
	v_mul_f32_e32 v21, v21, v18
	v_fma_f32 v21, v21, v18, v18
	v_mul_f32_e32 v21, 0x3f4c422a, v21
	v_add_f32_e32 v21, v21, v21
	v_mul_f32_e32 v21, 0xbfb8aa3b, v21
	v_exp_f32_e32 v21, v21
	s_nop 0
	v_add_f32_e32 v21, 1.0, v21
	v_rcp_f32_e32 v21, v21
	s_nop 0
	v_mul_f32_e32 v18, v21, v18
	v_mul_f32_e32 v18, v20, v18
	v_cvt_pk_bf16_f32 v18, v18, s0
	global_store_short v[4:5], v18, off
	v_or_b32_e32 v18, 20, v7
	v_lshl_or_b32 v4, v18, 8, v142
	v_add_u32_e32 v4, 0, v4
	ds_read2st64_b32 v[4:5], v4 offset1:144
	v_add_u32_e32 v18, s7, v18
	v_mad_i64_i32 v[20:21], s[0:1], v18, s74, v[2:3]
	s_waitcnt lgkmcnt(0)
	v_fmac_f32_e32 v5, v19, v4
	v_mov_b32_e32 v4, v155
	v_ashrrev_i32_e32 v19, 31, v18
	v_add_f32_e32 v17, v17, v5
	v_lshlrev_b64 v[18:19], 10, v[18:19]
	v_lshl_add_u64 v[18:19], v[0:1], 0, v[18:19]
	v_lshlrev_b32_e32 v4, 16, v4
	v_mul_f32_e32 v20, 0x3d372713, v4
	v_mul_f32_e32 v20, v20, v4
	v_fma_f32 v20, v20, v4, v4
	v_mul_f32_e32 v20, 0x3f4c422a, v20
	v_add_f32_e32 v20, v20, v20
	v_mul_f32_e32 v20, 0xbfb8aa3b, v20
	v_exp_f32_e32 v20, v20
	s_nop 0
	v_add_f32_e32 v20, 1.0, v20
	v_rcp_f32_e32 v20, v20
	s_nop 0
	v_mul_f32_e32 v4, v20, v4
	v_mul_f32_e32 v4, v17, v4
	v_cvt_pk_bf16_f32 v4, v4, s0
	global_store_short v[18:19], v4, off
	v_or_b32_e32 v4, 19, v7
	v_lshl_or_b32 v17, v4, 8, v142
	v_add_u32_e32 v4, s7, v4
	v_add_u32_e32 v17, 0, v17
	v_mad_i64_i32 v[20:21], s[0:1], v4, s74, v[2:3]
	ds_read2st64_b32 v[18:19], v17 offset1:144
	v_mov_b32_e32 v17, v156
	s_waitcnt lgkmcnt(0)
	v_fmac_f32_e32 v19, v5, v18
	v_ashrrev_i32_e32 v5, 31, v4
	v_add_f32_e32 v18, v85, v19
	v_lshlrev_b64 v[4:5], 10, v[4:5]
	v_lshl_add_u64 v[4:5], v[0:1], 0, v[4:5]
	v_lshlrev_b32_e32 v17, 16, v17
	v_mul_f32_e32 v20, 0x3d372713, v17
	v_mul_f32_e32 v20, v20, v17
	v_fma_f32 v20, v20, v17, v17
	v_mul_f32_e32 v20, 0x3f4c422a, v20
	v_add_f32_e32 v20, v20, v20
	v_mul_f32_e32 v20, 0xbfb8aa3b, v20
	v_exp_f32_e32 v20, v20
	s_nop 0
	v_add_f32_e32 v20, 1.0, v20
	v_rcp_f32_e32 v20, v20
	s_nop 0
	v_mul_f32_e32 v17, v20, v17
	v_mul_f32_e32 v17, v18, v17
	v_cvt_pk_bf16_f32 v17, v17, s0
	global_store_short v[4:5], v17, off
	v_or_b32_e32 v17, 18, v7
	v_lshl_or_b32 v4, v17, 8, v142
	v_add_u32_e32 v4, 0, v4
	ds_read2st64_b32 v[4:5], v4 offset1:144
	v_add_u32_e32 v18, s7, v17
	v_mad_i64_i32 v[20:21], s[0:1], v18, s74, v[2:3]
	s_waitcnt lgkmcnt(0)
	v_fmac_f32_e32 v5, v19, v4
	v_mov_b32_e32 v4, v157
	v_ashrrev_i32_e32 v19, 31, v18
	v_add_f32_e32 v16, v16, v5
	v_lshlrev_b32_e32 v4, 16, v4
	v_mul_f32_e32 v17, 0x3d372713, v4
	v_mul_f32_e32 v17, v17, v4
	v_fma_f32 v17, v17, v4, v4
	v_mul_f32_e32 v17, 0x3f4c422a, v17
	v_add_f32_e32 v17, v17, v17
	v_mul_f32_e32 v17, 0xbfb8aa3b, v17
	v_exp_f32_e32 v17, v17
	s_nop 0
	v_add_f32_e32 v17, 1.0, v17
	v_rcp_f32_e32 v17, v17
	s_nop 0
	v_mul_f32_e32 v4, v17, v4
	v_mul_f32_e32 v4, v16, v4
	v_lshlrev_b64 v[16:17], 10, v[18:19]
	v_cvt_pk_bf16_f32 v4, v4, s0
	v_lshl_add_u64 v[16:17], v[0:1], 0, v[16:17]
	global_store_short v[16:17], v4, off
	v_or_b32_e32 v4, 17, v7
	v_lshl_or_b32 v16, v4, 8, v142
	v_add_u32_e32 v16, 0, v16
	ds_read2st64_b32 v[16:17], v16 offset1:144
	v_add_u32_e32 v4, s7, v4
	v_mad_i64_i32 v[18:19], s[0:1], v4, s74, v[2:3]
	s_waitcnt lgkmcnt(0)
	v_fmac_f32_e32 v17, v5, v16
	v_mov_b32_e32 v16, v158
	v_ashrrev_i32_e32 v5, 31, v4
	v_add_f32_e32 v18, v83, v17
	v_lshlrev_b64 v[4:5], 10, v[4:5]
	v_lshl_add_u64 v[4:5], v[0:1], 0, v[4:5]
	v_lshlrev_b32_e32 v16, 16, v16
	v_mul_f32_e32 v19, 0x3d372713, v16
	v_mul_f32_e32 v19, v19, v16
	v_fma_f32 v19, v19, v16, v16
	v_mul_f32_e32 v19, 0x3f4c422a, v19
	v_add_f32_e32 v19, v19, v19
	v_mul_f32_e32 v19, 0xbfb8aa3b, v19
	v_exp_f32_e32 v19, v19
	s_nop 0
	v_add_f32_e32 v19, 1.0, v19
	v_rcp_f32_e32 v19, v19
	s_nop 0
	v_mul_f32_e32 v16, v19, v16
	v_mul_f32_e32 v16, v18, v16
	v_cvt_pk_bf16_f32 v16, v16, s0
	global_store_short v[4:5], v16, off
	v_or_b32_e32 v16, 16, v7
	v_lshl_or_b32 v4, v16, 8, v142
	v_add_u32_e32 v4, 0, v4
	ds_read2st64_b32 v[4:5], v4 offset1:144
	v_add_u32_e32 v16, s7, v16
	v_mad_i64_i32 v[18:19], s[0:1], v16, s74, v[2:3]
	s_waitcnt lgkmcnt(0)
	v_fmac_f32_e32 v5, v17, v4
	v_mov_b32_e32 v4, v159
	v_ashrrev_i32_e32 v17, 31, v16
	v_add_f32_e32 v15, v15, v5
	v_lshlrev_b64 v[16:17], 10, v[16:17]
	v_lshl_add_u64 v[16:17], v[0:1], 0, v[16:17]
	v_lshlrev_b32_e32 v4, 16, v4
	v_mul_f32_e32 v18, 0x3d372713, v4
	v_mul_f32_e32 v18, v18, v4
	v_fma_f32 v18, v18, v4, v4
	v_mul_f32_e32 v18, 0x3f4c422a, v18
	v_add_f32_e32 v18, v18, v18
	v_mul_f32_e32 v18, 0xbfb8aa3b, v18
	v_exp_f32_e32 v18, v18
	s_nop 0
	v_add_f32_e32 v18, 1.0, v18
	v_rcp_f32_e32 v18, v18
	s_nop 0
	v_mul_f32_e32 v4, v18, v4
	v_mul_f32_e32 v4, v15, v4
	v_cvt_pk_bf16_f32 v4, v4, s0
	global_store_short v[16:17], v4, off
	v_or_b32_e32 v4, 15, v7
	v_lshl_or_b32 v15, v4, 8, v142
	v_add_u32_e32 v4, s7, v4
	v_add_u32_e32 v15, 0, v15
	v_mad_i64_i32 v[18:19], s[0:1], v4, s74, v[2:3]
	ds_read2st64_b32 v[16:17], v15 offset1:144
	v_mov_b32_e32 v15, v160
	s_waitcnt lgkmcnt(0)
	v_fmac_f32_e32 v17, v5, v16
	v_ashrrev_i32_e32 v5, 31, v4
	v_add_f32_e32 v16, v81, v17
	v_lshlrev_b64 v[4:5], 10, v[4:5]
	v_lshl_add_u64 v[4:5], v[0:1], 0, v[4:5]
	v_lshlrev_b32_e32 v15, 16, v15
	v_mul_f32_e32 v18, 0x3d372713, v15
	v_mul_f32_e32 v18, v18, v15
	v_fma_f32 v18, v18, v15, v15
	v_mul_f32_e32 v18, 0x3f4c422a, v18
	v_add_f32_e32 v18, v18, v18
	v_mul_f32_e32 v18, 0xbfb8aa3b, v18
	v_exp_f32_e32 v18, v18
	s_nop 0
	v_add_f32_e32 v18, 1.0, v18
	v_rcp_f32_e32 v18, v18
	s_nop 0
	v_mul_f32_e32 v15, v18, v15
	v_mul_f32_e32 v15, v16, v15
	v_cvt_pk_bf16_f32 v15, v15, s0
	global_store_short v[4:5], v15, off
	v_or_b32_e32 v15, 14, v7
	v_lshl_or_b32 v4, v15, 8, v142
	v_add_u32_e32 v4, 0, v4
	ds_read2st64_b32 v[4:5], v4 offset1:144
	v_add_u32_e32 v16, s7, v15
	v_mad_i64_i32 v[18:19], s[0:1], v16, s74, v[2:3]
	s_waitcnt lgkmcnt(0)
	v_fmac_f32_e32 v5, v17, v4
	v_mov_b32_e32 v4, v161
	v_ashrrev_i32_e32 v17, 31, v16
	v_add_f32_e32 v14, v14, v5
	v_lshlrev_b32_e32 v4, 16, v4
	v_mul_f32_e32 v15, 0x3d372713, v4
	v_mul_f32_e32 v15, v15, v4
	v_fma_f32 v15, v15, v4, v4
	v_mul_f32_e32 v15, 0x3f4c422a, v15
	v_add_f32_e32 v15, v15, v15
	v_mul_f32_e32 v15, 0xbfb8aa3b, v15
	v_exp_f32_e32 v15, v15
	s_nop 0
	v_add_f32_e32 v15, 1.0, v15
	v_rcp_f32_e32 v15, v15
	s_nop 0
	v_mul_f32_e32 v4, v15, v4
	v_mul_f32_e32 v4, v14, v4
	v_lshlrev_b64 v[14:15], 10, v[16:17]
	v_cvt_pk_bf16_f32 v4, v4, s0
	v_lshl_add_u64 v[14:15], v[0:1], 0, v[14:15]
	global_store_short v[14:15], v4, off
	v_or_b32_e32 v4, 13, v7
	v_lshl_or_b32 v14, v4, 8, v142
	v_add_u32_e32 v14, 0, v14
	ds_read2st64_b32 v[14:15], v14 offset1:144
	v_add_u32_e32 v4, s7, v4
	v_mad_i64_i32 v[16:17], s[0:1], v4, s74, v[2:3]
	s_waitcnt lgkmcnt(0)
	v_fmac_f32_e32 v15, v5, v14
	v_mov_b32_e32 v14, v169
	v_ashrrev_i32_e32 v5, 31, v4
	v_add_f32_e32 v16, v79, v15
	v_lshlrev_b64 v[4:5], 10, v[4:5]
	v_lshl_add_u64 v[4:5], v[0:1], 0, v[4:5]
	v_lshlrev_b32_e32 v14, 16, v14
	v_mul_f32_e32 v17, 0x3d372713, v14
	v_mul_f32_e32 v17, v17, v14
	v_fma_f32 v17, v17, v14, v14
	v_mul_f32_e32 v17, 0x3f4c422a, v17
	v_add_f32_e32 v17, v17, v17
	v_mul_f32_e32 v17, 0xbfb8aa3b, v17
	v_exp_f32_e32 v17, v17
	s_nop 0
	v_add_f32_e32 v17, 1.0, v17
	v_rcp_f32_e32 v17, v17
	s_nop 0
	v_mul_f32_e32 v14, v17, v14
	v_mul_f32_e32 v14, v16, v14
	v_cvt_pk_bf16_f32 v14, v14, s0
	global_store_short v[4:5], v14, off
	v_or_b32_e32 v14, 12, v7
	v_lshl_or_b32 v4, v14, 8, v142
	v_add_u32_e32 v4, 0, v4
	ds_read2st64_b32 v[4:5], v4 offset1:144
	v_add_u32_e32 v14, s7, v14
	v_mad_i64_i32 v[16:17], s[0:1], v14, s74, v[2:3]
	s_waitcnt lgkmcnt(0)
	v_fmac_f32_e32 v5, v15, v4
	v_mov_b32_e32 v4, v170
	v_ashrrev_i32_e32 v15, 31, v14
	v_add_f32_e32 v13, v13, v5
	v_lshlrev_b64 v[14:15], 10, v[14:15]
	v_lshl_add_u64 v[14:15], v[0:1], 0, v[14:15]
	v_lshlrev_b32_e32 v4, 16, v4
	v_mul_f32_e32 v16, 0x3d372713, v4
	v_mul_f32_e32 v16, v16, v4
	v_fma_f32 v16, v16, v4, v4
	v_mul_f32_e32 v16, 0x3f4c422a, v16
	v_add_f32_e32 v16, v16, v16
	v_mul_f32_e32 v16, 0xbfb8aa3b, v16
	v_exp_f32_e32 v16, v16
	s_nop 0
	v_add_f32_e32 v16, 1.0, v16
	v_rcp_f32_e32 v16, v16
	s_nop 0
	v_mul_f32_e32 v4, v16, v4
	v_mul_f32_e32 v4, v13, v4
	v_cvt_pk_bf16_f32 v4, v4, s0
	global_store_short v[14:15], v4, off
	v_or_b32_e32 v4, 11, v7
	v_lshl_or_b32 v13, v4, 8, v142
	v_add_u32_e32 v4, s7, v4
	v_add_u32_e32 v13, 0, v13
	v_mad_i64_i32 v[16:17], s[0:1], v4, s74, v[2:3]
	ds_read2st64_b32 v[14:15], v13 offset1:144
	v_mov_b32_e32 v13, v171
	s_waitcnt lgkmcnt(0)
	v_fmac_f32_e32 v15, v5, v14
	v_ashrrev_i32_e32 v5, 31, v4
	v_add_f32_e32 v14, v77, v15
	v_lshlrev_b64 v[4:5], 10, v[4:5]
	v_lshl_add_u64 v[4:5], v[0:1], 0, v[4:5]
	v_lshlrev_b32_e32 v13, 16, v13
	v_mul_f32_e32 v16, 0x3d372713, v13
	v_mul_f32_e32 v16, v16, v13
	v_fma_f32 v16, v16, v13, v13
	v_mul_f32_e32 v16, 0x3f4c422a, v16
	v_add_f32_e32 v16, v16, v16
	v_mul_f32_e32 v16, 0xbfb8aa3b, v16
	v_exp_f32_e32 v16, v16
	s_nop 0
	v_add_f32_e32 v16, 1.0, v16
	v_rcp_f32_e32 v16, v16
	s_nop 0
	v_mul_f32_e32 v13, v16, v13
	v_mul_f32_e32 v13, v14, v13
	v_cvt_pk_bf16_f32 v13, v13, s0
	global_store_short v[4:5], v13, off
	v_or_b32_e32 v13, 10, v7
	v_lshl_or_b32 v4, v13, 8, v142
	v_add_u32_e32 v4, 0, v4
	ds_read2st64_b32 v[4:5], v4 offset1:144
	v_add_u32_e32 v14, s7, v13
	v_mad_i64_i32 v[16:17], s[0:1], v14, s74, v[2:3]
	s_waitcnt lgkmcnt(0)
	v_fmac_f32_e32 v5, v15, v4
	v_mov_b32_e32 v4, v172
	v_ashrrev_i32_e32 v15, 31, v14
	v_add_f32_e32 v12, v12, v5
	v_lshlrev_b32_e32 v4, 16, v4
	v_mul_f32_e32 v13, 0x3d372713, v4
	v_mul_f32_e32 v13, v13, v4
	v_fma_f32 v13, v13, v4, v4
	v_mul_f32_e32 v13, 0x3f4c422a, v13
	v_add_f32_e32 v13, v13, v13
	v_mul_f32_e32 v13, 0xbfb8aa3b, v13
	v_exp_f32_e32 v13, v13
	s_nop 0
	v_add_f32_e32 v13, 1.0, v13
	v_rcp_f32_e32 v13, v13
	s_nop 0
	v_mul_f32_e32 v4, v13, v4
	v_mul_f32_e32 v4, v12, v4
	v_lshlrev_b64 v[12:13], 10, v[14:15]
	v_cvt_pk_bf16_f32 v4, v4, s0
	v_lshl_add_u64 v[12:13], v[0:1], 0, v[12:13]
	global_store_short v[12:13], v4, off
	v_or_b32_e32 v4, 9, v7
	v_lshl_or_b32 v12, v4, 8, v142
	v_add_u32_e32 v12, 0, v12
	ds_read2st64_b32 v[12:13], v12 offset1:144
	v_add_u32_e32 v4, s7, v4
	v_mad_i64_i32 v[14:15], s[0:1], v4, s74, v[2:3]
	s_waitcnt lgkmcnt(0)
	v_fmac_f32_e32 v13, v5, v12
	v_mov_b32_e32 v12, v173
	v_ashrrev_i32_e32 v5, 31, v4
	v_add_f32_e32 v14, v75, v13
	v_lshlrev_b64 v[4:5], 10, v[4:5]
	v_lshl_add_u64 v[4:5], v[0:1], 0, v[4:5]
	v_lshlrev_b32_e32 v12, 16, v12
	v_mul_f32_e32 v15, 0x3d372713, v12
	v_mul_f32_e32 v15, v15, v12
	v_fma_f32 v15, v15, v12, v12
	v_mul_f32_e32 v15, 0x3f4c422a, v15
	v_add_f32_e32 v15, v15, v15
	v_mul_f32_e32 v15, 0xbfb8aa3b, v15
	v_exp_f32_e32 v15, v15
	s_nop 0
	v_add_f32_e32 v15, 1.0, v15
	v_rcp_f32_e32 v15, v15
	s_nop 0
	v_mul_f32_e32 v12, v15, v12
	v_mul_f32_e32 v12, v14, v12
	v_cvt_pk_bf16_f32 v12, v12, s0
	global_store_short v[4:5], v12, off
	v_or_b32_e32 v12, 8, v7
	v_lshl_or_b32 v4, v12, 8, v142
	v_add_u32_e32 v4, 0, v4
	ds_read2st64_b32 v[4:5], v4 offset1:144
	v_add_u32_e32 v12, s7, v12
	v_mad_i64_i32 v[14:15], s[0:1], v12, s74, v[2:3]
	s_waitcnt lgkmcnt(0)
	v_fmac_f32_e32 v5, v13, v4
	v_mov_b32_e32 v4, v174
	v_ashrrev_i32_e32 v13, 31, v12
	v_add_f32_e32 v11, v11, v5
	v_lshlrev_b64 v[12:13], 10, v[12:13]
	v_lshl_add_u64 v[12:13], v[0:1], 0, v[12:13]
	v_lshlrev_b32_e32 v4, 16, v4
	v_mul_f32_e32 v14, 0x3d372713, v4
	v_mul_f32_e32 v14, v14, v4
	v_fma_f32 v14, v14, v4, v4
	v_mul_f32_e32 v14, 0x3f4c422a, v14
	v_add_f32_e32 v14, v14, v14
	v_mul_f32_e32 v14, 0xbfb8aa3b, v14
	v_exp_f32_e32 v14, v14
	s_nop 0
	v_add_f32_e32 v14, 1.0, v14
	v_rcp_f32_e32 v14, v14
	s_nop 0
	v_mul_f32_e32 v4, v14, v4
	v_mul_f32_e32 v4, v11, v4
	v_cvt_pk_bf16_f32 v4, v4, s0
	global_store_short v[12:13], v4, off
	v_or_b32_e32 v4, 7, v7
	v_lshl_or_b32 v11, v4, 8, v142
	v_add_u32_e32 v4, s7, v4
	v_add_u32_e32 v11, 0, v11
	v_mad_i64_i32 v[14:15], s[0:1], v4, s74, v[2:3]
	ds_read2st64_b32 v[12:13], v11 offset1:144
	v_mov_b32_e32 v11, v175
	s_waitcnt lgkmcnt(0)
	v_fmac_f32_e32 v13, v5, v12
	v_ashrrev_i32_e32 v5, 31, v4
	v_add_f32_e32 v12, v73, v13
	v_lshlrev_b64 v[4:5], 10, v[4:5]
	v_lshl_add_u64 v[4:5], v[0:1], 0, v[4:5]
	v_lshlrev_b32_e32 v11, 16, v11
	v_mul_f32_e32 v14, 0x3d372713, v11
	v_mul_f32_e32 v14, v14, v11
	v_fma_f32 v14, v14, v11, v11
	v_mul_f32_e32 v14, 0x3f4c422a, v14
	v_add_f32_e32 v14, v14, v14
	v_mul_f32_e32 v14, 0xbfb8aa3b, v14
	v_exp_f32_e32 v14, v14
	s_nop 0
	v_add_f32_e32 v14, 1.0, v14
	v_rcp_f32_e32 v14, v14
	s_nop 0
	v_mul_f32_e32 v11, v14, v11
	v_mul_f32_e32 v11, v12, v11
	v_cvt_pk_bf16_f32 v11, v11, s0
	global_store_short v[4:5], v11, off
	v_or_b32_e32 v11, 6, v7
	v_lshl_or_b32 v4, v11, 8, v142
	v_add_u32_e32 v4, 0, v4
	ds_read2st64_b32 v[4:5], v4 offset1:144
	v_add_u32_e32 v12, s7, v11
	v_mad_i64_i32 v[14:15], s[0:1], v12, s74, v[2:3]
	s_waitcnt lgkmcnt(0)
	v_fmac_f32_e32 v5, v13, v4
	v_mov_b32_e32 v4, v176
	v_ashrrev_i32_e32 v13, 31, v12
	v_add_f32_e32 v10, v10, v5
	v_lshlrev_b32_e32 v4, 16, v4
	v_mul_f32_e32 v11, 0x3d372713, v4
	v_mul_f32_e32 v11, v11, v4
	v_fma_f32 v11, v11, v4, v4
	v_mul_f32_e32 v11, 0x3f4c422a, v11
	v_add_f32_e32 v11, v11, v11
	v_mul_f32_e32 v11, 0xbfb8aa3b, v11
	v_exp_f32_e32 v11, v11
	s_nop 0
	v_add_f32_e32 v11, 1.0, v11
	v_rcp_f32_e32 v11, v11
	s_nop 0
	v_mul_f32_e32 v4, v11, v4
	v_mul_f32_e32 v4, v10, v4
	v_lshlrev_b64 v[10:11], 10, v[12:13]
	v_cvt_pk_bf16_f32 v4, v4, s0
	v_lshl_add_u64 v[10:11], v[0:1], 0, v[10:11]
	global_store_short v[10:11], v4, off
	v_or_b32_e32 v4, 5, v7
	v_lshl_or_b32 v10, v4, 8, v142
	v_add_u32_e32 v10, 0, v10
	ds_read2st64_b32 v[10:11], v10 offset1:144
	v_add_u32_e32 v4, s7, v4
	v_mad_i64_i32 v[12:13], s[0:1], v4, s74, v[2:3]
	s_waitcnt lgkmcnt(0)
	v_fmac_f32_e32 v11, v5, v10
	v_mov_b32_e32 v10, v177
	v_ashrrev_i32_e32 v5, 31, v4
	v_add_f32_e32 v12, v71, v11
	v_lshlrev_b64 v[4:5], 10, v[4:5]
	v_lshl_add_u64 v[4:5], v[0:1], 0, v[4:5]
	v_lshlrev_b32_e32 v10, 16, v10
	v_mul_f32_e32 v13, 0x3d372713, v10
	v_mul_f32_e32 v13, v13, v10
	v_fma_f32 v13, v13, v10, v10
	v_mul_f32_e32 v13, 0x3f4c422a, v13
	v_add_f32_e32 v13, v13, v13
	v_mul_f32_e32 v13, 0xbfb8aa3b, v13
	v_exp_f32_e32 v13, v13
	s_nop 0
	v_add_f32_e32 v13, 1.0, v13
	v_rcp_f32_e32 v13, v13
	s_nop 0
	v_mul_f32_e32 v10, v13, v10
	v_mul_f32_e32 v10, v12, v10
	v_cvt_pk_bf16_f32 v10, v10, s0
	global_store_short v[4:5], v10, off
	v_or_b32_e32 v10, 4, v7
	v_lshl_or_b32 v4, v10, 8, v142
	v_add_u32_e32 v4, 0, v4
	ds_read2st64_b32 v[4:5], v4 offset1:144
	v_add_u32_e32 v10, s7, v10
	v_mad_i64_i32 v[12:13], s[0:1], v10, s74, v[2:3]
	s_waitcnt lgkmcnt(0)
	v_fmac_f32_e32 v5, v11, v4
	v_mov_b32_e32 v4, v178
	v_ashrrev_i32_e32 v11, 31, v10
	v_add_f32_e32 v9, v9, v5
	v_lshlrev_b64 v[10:11], 10, v[10:11]
	v_lshl_add_u64 v[10:11], v[0:1], 0, v[10:11]
	v_lshlrev_b32_e32 v4, 16, v4
	v_mul_f32_e32 v12, 0x3d372713, v4
	v_mul_f32_e32 v12, v12, v4
	v_fma_f32 v12, v12, v4, v4
	v_mul_f32_e32 v12, 0x3f4c422a, v12
	v_add_f32_e32 v12, v12, v12
	v_mul_f32_e32 v12, 0xbfb8aa3b, v12
	v_exp_f32_e32 v12, v12
	s_nop 0
	v_add_f32_e32 v12, 1.0, v12
	v_rcp_f32_e32 v12, v12
	s_nop 0
	v_mul_f32_e32 v4, v12, v4
	v_mul_f32_e32 v4, v9, v4
	v_cvt_pk_bf16_f32 v4, v4, s0
	global_store_short v[10:11], v4, off
	v_or_b32_e32 v4, 3, v7
	v_lshl_or_b32 v9, v4, 8, v142
	v_add_u32_e32 v4, s7, v4
	v_add_u32_e32 v9, 0, v9
	v_mad_i64_i32 v[12:13], s[0:1], v4, s74, v[2:3]
	ds_read2st64_b32 v[10:11], v9 offset1:144
	v_mov_b32_e32 v9, v179
	s_waitcnt lgkmcnt(0)
	v_fmac_f32_e32 v11, v5, v10
	v_ashrrev_i32_e32 v5, 31, v4
	v_add_f32_e32 v10, v69, v11
	v_lshlrev_b64 v[4:5], 10, v[4:5]
	v_lshl_add_u64 v[4:5], v[0:1], 0, v[4:5]
	v_lshlrev_b32_e32 v9, 16, v9
	v_mul_f32_e32 v12, 0x3d372713, v9
	v_mul_f32_e32 v12, v12, v9
	v_fma_f32 v12, v12, v9, v9
	v_mul_f32_e32 v12, 0x3f4c422a, v12
	v_add_f32_e32 v12, v12, v12
	v_mul_f32_e32 v12, 0xbfb8aa3b, v12
	v_exp_f32_e32 v12, v12
	s_nop 0
	v_add_f32_e32 v12, 1.0, v12
	v_rcp_f32_e32 v12, v12
	s_nop 0
	v_mul_f32_e32 v9, v12, v9
	v_mul_f32_e32 v9, v10, v9
	v_cvt_pk_bf16_f32 v9, v9, s0
	global_store_short v[4:5], v9, off
	v_or_b32_e32 v9, 2, v7
	v_lshl_or_b32 v4, v9, 8, v142
	v_add_u32_e32 v4, 0, v4
	ds_read2st64_b32 v[4:5], v4 offset1:144
	v_add_u32_e32 v10, s7, v9
	v_mad_i64_i32 v[12:13], s[0:1], v10, s74, v[2:3]
	s_waitcnt lgkmcnt(0)
	v_fmac_f32_e32 v5, v11, v4
	v_mov_b32_e32 v4, v180
	v_ashrrev_i32_e32 v11, 31, v10
	v_add_f32_e32 v8, v8, v5
	v_lshlrev_b32_e32 v4, 16, v4
	v_mul_f32_e32 v9, 0x3d372713, v4
	v_mul_f32_e32 v9, v9, v4
	v_fma_f32 v9, v9, v4, v4
	v_mul_f32_e32 v9, 0x3f4c422a, v9
	v_add_f32_e32 v9, v9, v9
	v_mul_f32_e32 v9, 0xbfb8aa3b, v9
	v_exp_f32_e32 v9, v9
	s_nop 0
	v_add_f32_e32 v9, 1.0, v9
	v_rcp_f32_e32 v9, v9
	s_nop 0
	v_mul_f32_e32 v4, v9, v4
	v_mul_f32_e32 v4, v8, v4
	v_lshlrev_b64 v[8:9], 10, v[10:11]
	v_cvt_pk_bf16_f32 v4, v4, s0
	v_lshl_add_u64 v[8:9], v[0:1], 0, v[8:9]
	global_store_short v[8:9], v4, off
	v_or_b32_e32 v4, 1, v7
	v_lshl_or_b32 v8, v4, 8, v142
	v_add_u32_e32 v8, 0, v8
	ds_read2st64_b32 v[8:9], v8 offset1:144
	v_add_u32_e32 v4, s7, v4
	v_mad_i64_i32 v[10:11], s[0:1], v4, s74, v[2:3]
	s_waitcnt lgkmcnt(0)
	v_fmac_f32_e32 v9, v5, v8
	v_mov_b32_e32 v8, v181
	v_ashrrev_i32_e32 v5, 31, v4
	v_add_f32_e32 v10, v67, v9
	v_lshlrev_b64 v[4:5], 10, v[4:5]
	v_lshl_add_u64 v[4:5], v[0:1], 0, v[4:5]
	v_lshlrev_b32_e32 v8, 16, v8
	v_mul_f32_e32 v11, 0x3d372713, v8
	v_mul_f32_e32 v11, v11, v8
	v_fma_f32 v11, v11, v8, v8
	v_mul_f32_e32 v11, 0x3f4c422a, v11
	v_add_f32_e32 v11, v11, v11
	v_mul_f32_e32 v11, 0xbfb8aa3b, v11
	v_exp_f32_e32 v11, v11
	s_nop 0
	v_add_f32_e32 v11, 1.0, v11
	v_rcp_f32_e32 v11, v11
	s_nop 0
	v_mul_f32_e32 v8, v11, v8
	v_mul_f32_e32 v8, v10, v8
	v_cvt_pk_bf16_f32 v8, v8, s0
	global_store_short v[4:5], v8, off
	v_add_u32_e32 v8, s7, v7
	v_mad_i64_i32 v[2:3], s[0:1], v8, s74, v[2:3]
	v_mov_b32_e32 v2, v182
	ds_read2st64_b32 v[4:5], v98 offset1:144
	s_waitcnt lgkmcnt(0)
	v_fmac_f32_e32 v5, v9, v4
	v_add_f32_e32 v3, v6, v5
	v_ashrrev_i32_e32 v9, 31, v8
	v_lshlrev_b32_e32 v2, 16, v2
	v_mul_f32_e32 v4, 0x3d372713, v2
	v_mul_f32_e32 v4, v4, v2
	v_fma_f32 v4, v4, v2, v2
	v_mul_f32_e32 v4, 0x3f4c422a, v4
	v_add_f32_e32 v4, v4, v4
	v_mul_f32_e32 v4, 0xbfb8aa3b, v4
	v_exp_f32_e32 v4, v4
	s_nop 0
	v_add_f32_e32 v4, 1.0, v4
	v_rcp_f32_e32 v4, v4
	s_nop 0
	v_mul_f32_e32 v2, v4, v2
	v_mul_f32_e32 v2, v3, v2
	v_cvt_pk_bf16_f32 v4, v2, s0
	v_lshlrev_b64 v[2:3], 10, v[8:9]
	v_lshl_add_u64 v[0:1], v[0:1], 0, v[2:3]
	s_mov_b64 s[0:1], 0
	global_store_short v[0:1], v4, off

.LBB0_947:
	s_or_b64 exec, exec, s[0:1]
	v_add_f32_e32 v0, 0, v110
	v_add_f32_e32 v0, v0, v111
	v_add_f32_e32 v0, v0, v109
	v_cvt_pk_bf16_f32 v110, v110, v111
	v_cvt_pk_bf16_f32 v111, v109, v112
	v_xor_b32_e32 v109, 16, v105
	v_cmp_lt_i32_e64 s[0:1], v109, v106
	v_add_f32_e32 v118, v0, v112
	v_lshl_add_u32 v113, v99, 3, 0
	v_cndmask_b32_e64 v109, v105, v109, s[0:1]
	v_lshlrev_b32_e32 v229, 2, v109
	v_mul_lo_u32 v0, v100, s87
	v_mov_b32_e32 v109, v118
	v_mov_b32_e32 v255, v118
	s_nop 1
	v_permlane16_swap_b32_e32 v109, v255
	s_nop 1
	v_mov_b32_dpp v109, v255 quad_perm:[0,1,2,3] row_mask:0x5 bank_mask:0xf
	v_add_u32_e32 v0, v113, v0
	ds_write_b64 v0, v[110:111] offset:34816
	v_xor_b32_e32 v110, 8, v105
	v_cmp_lt_i32_e64 s[0:1], v110, v106
	s_waitcnt lgkmcnt(1)
	v_add_f32_e32 v109, v118, v109
	v_cmp_eq_u32_e32 vcc, 0, v99
	v_cndmask_b32_e64 v110, v105, v110, s[0:1]
	v_lshlrev_b32_e32 v230, 2, v110
	v_mov_b32_dpp v110, v109 row_ror:8 row_mask:0xf bank_mask:0xf
	s_waitcnt lgkmcnt(0)
	v_add_f32_e32 v109, v109, v110
	v_xor_b32_e32 v110, 4, v105
	v_cmp_lt_i32_e64 s[0:1], v110, v106
	s_nop 1
	v_cndmask_b32_e64 v110, v105, v110, s[0:1]
	v_lshlrev_b32_e32 v231, 2, v110
	v_mov_b32_dpp v110, v109 row_shl:4 row_mask:0xf bank_mask:0x5
	v_mov_b32_dpp v110, v109 row_shr:4 row_mask:0xf bank_mask:0xa
	s_nop 0
	v_add_f32_e32 v109, v109, v110
	v_xor_b32_e32 v110, 2, v105
	v_cmp_lt_i32_e64 s[0:1], v110, v106
	s_nop 1
	v_cndmask_b32_e64 v110, v105, v110, s[0:1]
	v_lshlrev_b32_e32 v232, 2, v110
	v_mov_b32_dpp v110, v109 quad_perm:[2,3,0,1] row_mask:0xf bank_mask:0xf
	s_nop 0
	v_add_f32_e32 v109, v109, v110
	v_xor_b32_e32 v110, 1, v105
	v_cmp_lt_i32_e64 s[0:1], v110, v106
	s_nop 1
	v_cndmask_b32_e64 v105, v105, v110, s[0:1]
	v_lshlrev_b32_e32 v233, 2, v105
	v_mov_b32_dpp v105, v109 quad_perm:[1,0,3,2] row_mask:0xf bank_mask:0xf
	s_and_saveexec_b64 s[0:1], vcc
	s_cbranch_execz .LBB0_949
	s_waitcnt lgkmcnt(0)
	v_add_f32_e32 v105, v109, v105
	s_waitcnt vmcnt(0)
	v_sub_f32_e32 v106, v96, v108
	v_add_u32_e32 v109, 0x11c00, v107
	v_mul_f32_e32 v106, 0x3fb8aa3b, v106
	ds_read_b32 v109, v109
	v_exp_f32_e32 v106, v106
	s_waitcnt lgkmcnt(0)
	v_fmac_f32_e32 v105, v106, v109
	v_add_u32_e32 v109, 0x11e00, v107
	ds_write_b32 v109, v105
	v_add_u32_e32 v105, 0x12000, v107
	ds_write_b32 v105, v106
	v_add_u32_e32 v105, 0x11800, v107
	ds_read_b32 v105, v105
	v_add_u32_e32 v106, 0x12200, v107
	s_waitcnt lgkmcnt(0)
	v_add_f32_e32 v105, v108, v105
	v_mul_f32_e32 v105, 0xbfb8aa3b, v105
	v_exp_f32_e32 v105, v105
	ds_write_b32 v106, v105

.LBB0_957:
	s_or_b64 exec, exec, s[68:69]
	v_add_f32_e32 v1, 0, v108
	v_add_f32_e32 v1, v1, v107
	v_add_f32_e32 v1, v1, v49
	v_add_f32_e32 v1, v1, v33
	v_mov_b32_e32 v17, v1
	v_mov_b32_e32 v255, v1
	s_nop 1
	v_permlane16_swap_b32_e32 v17, v255
	s_nop 1
	v_mov_b32_dpp v17, v255 quad_perm:[0,1,2,3] row_mask:0x5 bank_mask:0xf
	v_cvt_pk_bf16_f32 v108, v108, v107
	v_cvt_pk_bf16_f32 v109, v49, v33
	ds_write_b64 v0, v[108:109] offset:35088
	s_waitcnt lgkmcnt(1)
	v_add_f32_e32 v1, v1, v17
	s_nop 1
	v_mov_b32_dpp v17, v1 row_ror:8 row_mask:0xf bank_mask:0xf
	s_waitcnt lgkmcnt(0)
	v_add_f32_e32 v1, v1, v17
	s_nop 1
	v_mov_b32_dpp v17, v1 row_shl:4 row_mask:0xf bank_mask:0x5
	v_mov_b32_dpp v17, v1 row_shr:4 row_mask:0xf bank_mask:0xa
	s_nop 0
	v_add_f32_e32 v1, v1, v17
	s_nop 1
	v_mov_b32_dpp v17, v1 quad_perm:[2,3,0,1] row_mask:0xf bank_mask:0xf
	s_nop 0
	v_add_f32_e32 v1, v1, v17
	s_nop 1
	v_mov_b32_dpp v17, v1 quad_perm:[1,0,3,2] row_mask:0xf bank_mask:0xf
	s_and_saveexec_b64 s[0:1], vcc
	s_cbranch_execz .LBB0_959
	s_waitcnt lgkmcnt(0)
	v_add_f32_e32 v1, v1, v17
	s_waitcnt vmcnt(0)
	v_sub_f32_e32 v17, v96, v106
	v_add_u32_e32 v33, 0x11c00, v105
	v_mul_f32_e32 v17, 0x3fb8aa3b, v17
	ds_read_b32 v33, v33
	v_exp_f32_e32 v17, v17
	s_waitcnt lgkmcnt(0)
	v_fmac_f32_e32 v1, v17, v33
	v_add_u32_e32 v33, 0x11e00, v105
	ds_write_b32 v33, v1
	v_add_u32_e32 v1, 0x12000, v105
	ds_write_b32 v1, v17
	v_add_u32_e32 v1, 0x11800, v105
	ds_read_b32 v1, v1
	v_add_u32_e32 v17, 0x12200, v105
	s_waitcnt lgkmcnt(0)
	v_add_f32_e32 v1, v106, v1
	v_mul_f32_e32 v1, 0xbfb8aa3b, v1
	v_exp_f32_e32 v1, v1
	ds_write_b32 v17, v1

.LBB0_967:
	s_or_b64 exec, exec, s[68:69]
	v_add_f32_e32 v2, 0, v49
	v_add_f32_e32 v2, v2, v33
	v_add_f32_e32 v2, v2, v50
	v_add_f32_e32 v2, v2, v34
	v_mov_b32_e32 v18, v2
	v_mov_b32_e32 v255, v2
	s_nop 1
	v_permlane16_swap_b32_e32 v18, v255
	s_nop 1
	v_mov_b32_dpp v18, v255 quad_perm:[0,1,2,3] row_mask:0x5 bank_mask:0xf
	v_cvt_pk_bf16_f32 v106, v49, v33
	v_cvt_pk_bf16_f32 v107, v50, v34
	ds_write_b64 v0, v[106:107] offset:35360
	s_waitcnt lgkmcnt(1)
	v_add_f32_e32 v2, v2, v18
	s_nop 1
	v_mov_b32_dpp v18, v2 row_ror:8 row_mask:0xf bank_mask:0xf
	s_waitcnt lgkmcnt(0)
	v_add_f32_e32 v2, v2, v18
	s_nop 1
	v_mov_b32_dpp v18, v2 row_shl:4 row_mask:0xf bank_mask:0x5
	v_mov_b32_dpp v18, v2 row_shr:4 row_mask:0xf bank_mask:0xa
	s_nop 0
	v_add_f32_e32 v2, v2, v18
	s_nop 1
	v_mov_b32_dpp v18, v2 quad_perm:[2,3,0,1] row_mask:0xf bank_mask:0xf
	s_nop 0
	v_add_f32_e32 v2, v2, v18
	s_nop 1
	v_mov_b32_dpp v18, v2 quad_perm:[1,0,3,2] row_mask:0xf bank_mask:0xf
	s_and_saveexec_b64 s[0:1], vcc
	s_cbranch_execz .LBB0_969
	s_waitcnt lgkmcnt(0)
	v_add_f32_e32 v2, v2, v18
	s_waitcnt vmcnt(0)
	v_sub_f32_e32 v18, v96, v17
	v_add_u32_e32 v33, 0x11c00, v1
	v_mul_f32_e32 v18, 0x3fb8aa3b, v18
	ds_read_b32 v33, v33
	v_exp_f32_e32 v18, v18
	s_waitcnt lgkmcnt(0)
	v_fmac_f32_e32 v2, v18, v33
	v_add_u32_e32 v33, 0x11e00, v1
	ds_write_b32 v33, v2
	v_add_u32_e32 v2, 0x12000, v1
	ds_write_b32 v2, v18
	v_add_u32_e32 v2, 0x11800, v1
	ds_read_b32 v2, v2
	v_add_u32_e32 v1, 0x12200, v1
	s_waitcnt lgkmcnt(0)
	v_add_f32_e32 v2, v17, v2
	v_mul_f32_e32 v2, 0xbfb8aa3b, v2
	v_exp_f32_e32 v2, v2
	ds_write_b32 v1, v2

.LBB0_977:
	s_or_b64 exec, exec, s[68:69]
	v_add_f32_e32 v3, 0, v18
	v_add_f32_e32 v3, v3, v17
	v_add_f32_e32 v3, v3, v35
	v_add_f32_e32 v3, v3, v34
	v_cvt_pk_bf16_f32 v18, v18, v17
	v_mov_b32_e32 v17, v3
	v_mov_b32_e32 v255, v3
	s_nop 1
	v_permlane16_swap_b32_e32 v17, v255
	s_nop 1
	v_mov_b32_dpp v17, v255 quad_perm:[0,1,2,3] row_mask:0x5 bank_mask:0xf
	v_cvt_pk_bf16_f32 v19, v35, v34
	ds_write_b64 v0, v[18:19] offset:35632
	s_waitcnt lgkmcnt(1)
	v_add_f32_e32 v3, v3, v17
	s_nop 1
	v_mov_b32_dpp v17, v3 row_ror:8 row_mask:0xf bank_mask:0xf
	s_waitcnt lgkmcnt(0)
	v_add_f32_e32 v3, v3, v17
	s_nop 1
	v_mov_b32_dpp v17, v3 row_shl:4 row_mask:0xf bank_mask:0x5
	v_mov_b32_dpp v17, v3 row_shr:4 row_mask:0xf bank_mask:0xa
	s_nop 0
	v_add_f32_e32 v3, v3, v17
	s_nop 1
	v_mov_b32_dpp v17, v3 quad_perm:[2,3,0,1] row_mask:0xf bank_mask:0xf
	s_nop 0
	v_add_f32_e32 v3, v3, v17
	s_nop 1
	v_mov_b32_dpp v17, v3 quad_perm:[1,0,3,2] row_mask:0xf bank_mask:0xf
	s_and_saveexec_b64 s[0:1], vcc
	s_cbranch_execz .LBB0_979
	s_waitcnt lgkmcnt(0)
	v_add_f32_e32 v3, v3, v17
	s_waitcnt vmcnt(0)
	v_sub_f32_e32 v17, v96, v2
	v_add_u32_e32 v18, 0x11c00, v1
	v_mul_f32_e32 v17, 0x3fb8aa3b, v17
	ds_read_b32 v18, v18
	v_exp_f32_e32 v17, v17
	s_waitcnt lgkmcnt(0)
	v_fmac_f32_e32 v3, v17, v18
	v_add_u32_e32 v18, 0x11e00, v1
	ds_write_b32 v18, v3
	v_add_u32_e32 v3, 0x12000, v1
	ds_write_b32 v3, v17
	v_add_u32_e32 v3, 0x11800, v1
	ds_read_b32 v3, v3
	v_add_u32_e32 v1, 0x12200, v1
	s_waitcnt lgkmcnt(0)
	v_add_f32_e32 v2, v2, v3
	v_mul_f32_e32 v2, 0xbfb8aa3b, v2
	v_exp_f32_e32 v2, v2
	ds_write_b32 v1, v2

.LBB0_987:
	s_or_b64 exec, exec, s[68:69]
	v_add_f32_e32 v4, 0, v17
	v_add_f32_e32 v4, v4, v3
	v_add_f32_e32 v4, v4, v19
	v_add_f32_e32 v4, v4, v18
	v_cvt_pk_bf16_f32 v34, v17, v3
	v_mov_b32_e32 v3, v4
	v_mov_b32_e32 v255, v4
	s_nop 1
	v_permlane16_swap_b32_e32 v3, v255
	s_nop 1
	v_mov_b32_dpp v3, v255 quad_perm:[0,1,2,3] row_mask:0x5 bank_mask:0xf
	v_cvt_pk_bf16_f32 v35, v19, v18
	ds_write_b64 v0, v[34:35] offset:36992
	s_waitcnt lgkmcnt(1)
	v_add_f32_e32 v3, v4, v3
	s_nop 1
	v_mov_b32_dpp v4, v3 row_ror:8 row_mask:0xf bank_mask:0xf
	s_waitcnt lgkmcnt(0)
	v_add_f32_e32 v3, v3, v4
	s_nop 1
	v_mov_b32_dpp v4, v3 row_shl:4 row_mask:0xf bank_mask:0x5
	v_mov_b32_dpp v4, v3 row_shr:4 row_mask:0xf bank_mask:0xa
	s_nop 0
	v_add_f32_e32 v3, v3, v4
	s_nop 1
	v_mov_b32_dpp v4, v3 quad_perm:[2,3,0,1] row_mask:0xf bank_mask:0xf
	s_nop 0
	v_add_f32_e32 v3, v3, v4
	s_nop 1
	v_mov_b32_dpp v4, v3 quad_perm:[1,0,3,2] row_mask:0xf bank_mask:0xf
	s_and_saveexec_b64 s[0:1], vcc
	s_cbranch_execz .LBB0_989
	v_lshl_add_u32 v2, v2, 2, 0
	s_waitcnt lgkmcnt(0)
	v_add_f32_e32 v3, v3, v4
	s_waitcnt vmcnt(0)
	v_sub_f32_e32 v4, v96, v1
	v_add_u32_e32 v17, 0x11c00, v2
	v_mul_f32_e32 v4, 0x3fb8aa3b, v4
	ds_read_b32 v17, v17
	v_exp_f32_e32 v4, v4
	s_waitcnt lgkmcnt(0)
	v_fmac_f32_e32 v3, v4, v17
	v_add_u32_e32 v17, 0x11e00, v2
	ds_write_b32 v17, v3
	v_add_u32_e32 v3, 0x12000, v2
	ds_write_b32 v3, v4
	v_add_u32_e32 v3, 0x11800, v2
	ds_read_b32 v3, v3
	v_add_u32_e32 v2, 0x12200, v2
	s_waitcnt lgkmcnt(0)
	v_add_f32_e32 v1, v1, v3
	v_mul_f32_e32 v1, 0xbfb8aa3b, v1
	v_exp_f32_e32 v1, v1
	ds_write_b32 v2, v1

.LBB0_997:
	s_or_b64 exec, exec, s[68:69]
	v_add_f32_e32 v5, 0, v4
	v_add_f32_e32 v5, v5, v3
	v_add_f32_e32 v5, v5, v18
	v_add_f32_e32 v19, v5, v17
	v_cvt_pk_bf16_f32 v4, v4, v3
	v_mov_b32_e32 v3, v19
	v_mov_b32_e32 v255, v19
	s_nop 1
	v_permlane16_swap_b32_e32 v3, v255
	s_nop 1
	v_mov_b32_dpp v3, v255 quad_perm:[0,1,2,3] row_mask:0x5 bank_mask:0xf
	v_cvt_pk_bf16_f32 v5, v18, v17
	ds_write_b64 v0, v[4:5] offset:37264
	s_waitcnt lgkmcnt(1)
	v_add_f32_e32 v3, v19, v3
	s_nop 1
	v_mov_b32_dpp v4, v3 row_ror:8 row_mask:0xf bank_mask:0xf
	s_waitcnt lgkmcnt(0)
	v_add_f32_e32 v3, v3, v4
	s_nop 1
	v_mov_b32_dpp v4, v3 row_shl:4 row_mask:0xf bank_mask:0x5
	v_mov_b32_dpp v4, v3 row_shr:4 row_mask:0xf bank_mask:0xa
	s_nop 0
	v_add_f32_e32 v3, v3, v4
	s_nop 1
	v_mov_b32_dpp v4, v3 quad_perm:[2,3,0,1] row_mask:0xf bank_mask:0xf
	s_nop 0
	v_add_f32_e32 v3, v3, v4
	s_nop 1
	v_mov_b32_dpp v4, v3 quad_perm:[1,0,3,2] row_mask:0xf bank_mask:0xf
	s_and_saveexec_b64 s[0:1], vcc
	s_cbranch_execz .LBB0_999
	v_lshl_add_u32 v2, v2, 2, 0
	s_waitcnt lgkmcnt(0)
	v_add_f32_e32 v3, v3, v4
	s_waitcnt vmcnt(0)
	v_sub_f32_e32 v4, v96, v1
	v_add_u32_e32 v5, 0x11c00, v2
	v_mul_f32_e32 v4, 0x3fb8aa3b, v4
	ds_read_b32 v5, v5
	v_exp_f32_e32 v4, v4
	s_waitcnt lgkmcnt(0)
	v_fmac_f32_e32 v3, v4, v5
	v_add_u32_e32 v5, 0x11e00, v2
	ds_write_b32 v5, v3
	v_add_u32_e32 v3, 0x12000, v2
	ds_write_b32 v3, v4
	v_add_u32_e32 v3, 0x11800, v2
	ds_read_b32 v3, v3
	v_add_u32_e32 v2, 0x12200, v2
	s_waitcnt lgkmcnt(0)
	v_add_f32_e32 v1, v1, v3
	v_mul_f32_e32 v1, 0xbfb8aa3b, v1
	v_exp_f32_e32 v1, v1
	ds_write_b32 v2, v1

.LBB0_1007:
	s_or_b64 exec, exec, s[68:69]
	v_add_f32_e32 v6, 0, v4
	v_add_f32_e32 v6, v6, v3
	v_add_f32_e32 v6, v6, v17
	v_add_f32_e32 v6, v6, v5
	v_cvt_pk_bf16_f32 v4, v4, v3
	v_mov_b32_e32 v3, v6
	v_mov_b32_e32 v255, v6
	s_nop 1
	v_permlane16_swap_b32_e32 v3, v255
	s_nop 1
	v_mov_b32_dpp v3, v255 quad_perm:[0,1,2,3] row_mask:0x5 bank_mask:0xf
	v_cvt_pk_bf16_f32 v5, v17, v5
	ds_write_b64 v0, v[4:5] offset:37536
	s_waitcnt lgkmcnt(1)
	v_add_f32_e32 v3, v6, v3
	s_nop 1
	v_mov_b32_dpp v4, v3 row_ror:8 row_mask:0xf bank_mask:0xf
	s_waitcnt lgkmcnt(0)
	v_add_f32_e32 v3, v3, v4
	s_nop 1
	v_mov_b32_dpp v4, v3 row_shl:4 row_mask:0xf bank_mask:0x5
	v_mov_b32_dpp v4, v3 row_shr:4 row_mask:0xf bank_mask:0xa
	s_nop 0
	v_add_f32_e32 v3, v3, v4
	s_nop 1
	v_mov_b32_dpp v4, v3 quad_perm:[2,3,0,1] row_mask:0xf bank_mask:0xf
	s_nop 0
	v_add_f32_e32 v3, v3, v4
	s_nop 1
	v_mov_b32_dpp v4, v3 quad_perm:[1,0,3,2] row_mask:0xf bank_mask:0xf
	s_and_saveexec_b64 s[0:1], vcc
	s_cbranch_execz .LBB0_1009
	v_lshl_add_u32 v2, v2, 2, 0
	s_waitcnt lgkmcnt(0)
	v_add_f32_e32 v3, v3, v4
	s_waitcnt vmcnt(0)
	v_sub_f32_e32 v4, v96, v1
	v_add_u32_e32 v5, 0x11c00, v2
	v_mul_f32_e32 v4, 0x3fb8aa3b, v4
	ds_read_b32 v5, v5
	v_exp_f32_e32 v4, v4
	s_waitcnt lgkmcnt(0)
	v_fmac_f32_e32 v3, v4, v5
	v_add_u32_e32 v5, 0x11e00, v2
	ds_write_b32 v5, v3
	v_add_u32_e32 v3, 0x12000, v2
	ds_write_b32 v3, v4
	v_add_u32_e32 v3, 0x11800, v2
	ds_read_b32 v3, v3
	v_add_u32_e32 v2, 0x12200, v2
	s_waitcnt lgkmcnt(0)
	v_add_f32_e32 v1, v1, v3
	v_mul_f32_e32 v1, 0xbfb8aa3b, v1
	v_exp_f32_e32 v1, v1
	ds_write_b32 v2, v1

.LBB0_1017:
	s_or_b64 exec, exec, s[68:69]
	v_add_f32_e32 v7, 0, v4
	v_add_f32_e32 v7, v7, v3
	v_add_f32_e32 v7, v7, v6
	v_add_f32_e32 v7, v7, v5
	v_cvt_pk_bf16_f32 v4, v4, v3
	v_mov_b32_e32 v3, v7
	v_mov_b32_e32 v255, v7
	s_nop 1
	v_permlane16_swap_b32_e32 v3, v255
	s_nop 1
	v_mov_b32_dpp v3, v255 quad_perm:[0,1,2,3] row_mask:0x5 bank_mask:0xf
	v_cvt_pk_bf16_f32 v5, v6, v5
	ds_write_b64 v0, v[4:5] offset:37808
	s_waitcnt lgkmcnt(1)
	v_add_f32_e32 v3, v7, v3
	s_nop 1
	v_mov_b32_dpp v4, v3 row_ror:8 row_mask:0xf bank_mask:0xf
	s_waitcnt lgkmcnt(0)
	v_add_f32_e32 v3, v3, v4
	s_nop 1
	v_mov_b32_dpp v4, v3 row_shl:4 row_mask:0xf bank_mask:0x5
	v_mov_b32_dpp v4, v3 row_shr:4 row_mask:0xf bank_mask:0xa
	s_nop 0
	v_add_f32_e32 v3, v3, v4
	s_nop 1
	v_mov_b32_dpp v4, v3 quad_perm:[2,3,0,1] row_mask:0xf bank_mask:0xf
	s_nop 0
	v_add_f32_e32 v3, v3, v4
	s_nop 1
	v_mov_b32_dpp v4, v3 quad_perm:[1,0,3,2] row_mask:0xf bank_mask:0xf
	s_and_saveexec_b64 s[0:1], vcc
	s_cbranch_execz .LBB0_1019
	v_lshl_add_u32 v2, v2, 2, 0
	s_waitcnt lgkmcnt(0)
	v_add_f32_e32 v3, v3, v4
	s_waitcnt vmcnt(0)
	v_sub_f32_e32 v4, v96, v1
	v_add_u32_e32 v5, 0x11c00, v2
	v_mul_f32_e32 v4, 0x3fb8aa3b, v4
	ds_read_b32 v5, v5
	v_exp_f32_e32 v4, v4
	s_waitcnt lgkmcnt(0)
	v_fmac_f32_e32 v3, v4, v5
	v_add_u32_e32 v5, 0x11e00, v2
	ds_write_b32 v5, v3
	v_add_u32_e32 v3, 0x12000, v2
	ds_write_b32 v3, v4
	v_add_u32_e32 v3, 0x11800, v2
	ds_read_b32 v3, v3
	v_add_u32_e32 v2, 0x12200, v2
	s_waitcnt lgkmcnt(0)
	v_add_f32_e32 v1, v1, v3
	v_mul_f32_e32 v1, 0xbfb8aa3b, v1
	v_exp_f32_e32 v1, v1
	ds_write_b32 v2, v1

.LBB0_1027:
	s_or_b64 exec, exec, s[68:69]
	v_add_f32_e32 v7, 0, v4
	v_add_f32_e32 v7, v7, v3
	v_add_f32_e32 v7, v7, v6
	v_add_f32_e32 v7, v7, v5
	v_cvt_pk_bf16_f32 v4, v4, v3
	v_mov_b32_e32 v3, v7
	v_mov_b32_e32 v255, v7
	s_nop 1
	v_permlane16_swap_b32_e32 v3, v255
	s_nop 1
	v_mov_b32_dpp v3, v255 quad_perm:[0,1,2,3] row_mask:0x5 bank_mask:0xf
	v_cvt_pk_bf16_f32 v5, v6, v5
	ds_write_b64 v0, v[4:5] offset:39168
	s_waitcnt lgkmcnt(1)
	v_add_f32_e32 v3, v7, v3
	s_nop 1
	v_mov_b32_dpp v4, v3 row_ror:8 row_mask:0xf bank_mask:0xf
	s_waitcnt lgkmcnt(0)
	v_add_f32_e32 v3, v3, v4
	s_nop 1
	v_mov_b32_dpp v4, v3 row_shl:4 row_mask:0xf bank_mask:0x5
	v_mov_b32_dpp v4, v3 row_shr:4 row_mask:0xf bank_mask:0xa
	s_nop 0
	v_add_f32_e32 v3, v3, v4
	s_nop 1
	v_mov_b32_dpp v4, v3 quad_perm:[2,3,0,1] row_mask:0xf bank_mask:0xf
	s_nop 0
	v_add_f32_e32 v3, v3, v4
	s_nop 1
	v_mov_b32_dpp v4, v3 quad_perm:[1,0,3,2] row_mask:0xf bank_mask:0xf
	s_and_saveexec_b64 s[0:1], vcc
	s_cbranch_execz .LBB0_1029
	v_lshl_add_u32 v2, v2, 2, 0
	s_waitcnt lgkmcnt(0)
	v_add_f32_e32 v3, v3, v4
	s_waitcnt vmcnt(0)
	v_sub_f32_e32 v4, v96, v1
	v_add_u32_e32 v5, 0x11c00, v2
	v_mul_f32_e32 v4, 0x3fb8aa3b, v4
	ds_read_b32 v5, v5
	v_exp_f32_e32 v4, v4
	s_waitcnt lgkmcnt(0)
	v_fmac_f32_e32 v3, v4, v5
	v_add_u32_e32 v5, 0x11e00, v2
	ds_write_b32 v5, v3
	v_add_u32_e32 v3, 0x12000, v2
	ds_write_b32 v3, v4
	v_add_u32_e32 v3, 0x11800, v2
	ds_read_b32 v3, v3
	v_add_u32_e32 v2, 0x12200, v2
	s_waitcnt lgkmcnt(0)
	v_add_f32_e32 v1, v1, v3
	v_mul_f32_e32 v1, 0xbfb8aa3b, v1
	v_exp_f32_e32 v1, v1
	ds_write_b32 v2, v1

.LBB0_1037:
	s_or_b64 exec, exec, s[68:69]
	v_add_f32_e32 v7, 0, v4
	v_add_f32_e32 v7, v7, v3
	v_add_f32_e32 v7, v7, v6
	v_add_f32_e32 v7, v7, v5
	v_cvt_pk_bf16_f32 v4, v4, v3
	v_mov_b32_e32 v3, v7
	v_mov_b32_e32 v255, v7
	s_nop 1
	v_permlane16_swap_b32_e32 v3, v255
	s_nop 1
	v_mov_b32_dpp v3, v255 quad_perm:[0,1,2,3] row_mask:0x5 bank_mask:0xf
	v_cvt_pk_bf16_f32 v5, v6, v5
	ds_write_b64 v0, v[4:5] offset:39440
	s_waitcnt lgkmcnt(1)
	v_add_f32_e32 v3, v7, v3
	s_nop 1
	v_mov_b32_dpp v4, v3 row_ror:8 row_mask:0xf bank_mask:0xf
	s_waitcnt lgkmcnt(0)
	v_add_f32_e32 v3, v3, v4
	s_nop 1
	v_mov_b32_dpp v4, v3 row_shl:4 row_mask:0xf bank_mask:0x5
	v_mov_b32_dpp v4, v3 row_shr:4 row_mask:0xf bank_mask:0xa
	s_nop 0
	v_add_f32_e32 v3, v3, v4
	s_nop 1
	v_mov_b32_dpp v4, v3 quad_perm:[2,3,0,1] row_mask:0xf bank_mask:0xf
	s_nop 0
	v_add_f32_e32 v3, v3, v4
	s_nop 1
	v_mov_b32_dpp v4, v3 quad_perm:[1,0,3,2] row_mask:0xf bank_mask:0xf
	s_and_saveexec_b64 s[0:1], vcc
	s_cbranch_execz .LBB0_1039
	v_lshl_add_u32 v2, v2, 2, 0
	s_waitcnt lgkmcnt(0)
	v_add_f32_e32 v3, v3, v4
	s_waitcnt vmcnt(0)
	v_sub_f32_e32 v4, v96, v1
	v_add_u32_e32 v5, 0x11c00, v2
	v_mul_f32_e32 v4, 0x3fb8aa3b, v4
	ds_read_b32 v5, v5
	v_exp_f32_e32 v4, v4
	s_waitcnt lgkmcnt(0)
	v_fmac_f32_e32 v3, v4, v5
	v_add_u32_e32 v5, 0x11e00, v2
	ds_write_b32 v5, v3
	v_add_u32_e32 v3, 0x12000, v2
	ds_write_b32 v3, v4
	v_add_u32_e32 v3, 0x11800, v2
	ds_read_b32 v3, v3
	v_add_u32_e32 v2, 0x12200, v2
	s_waitcnt lgkmcnt(0)
	v_add_f32_e32 v1, v1, v3
	v_mul_f32_e32 v1, 0xbfb8aa3b, v1
	v_exp_f32_e32 v1, v1
	ds_write_b32 v2, v1

.LBB0_1047:
	s_or_b64 exec, exec, s[68:69]
	v_add_f32_e32 v7, 0, v4
	v_add_f32_e32 v7, v7, v3
	v_add_f32_e32 v7, v7, v6
	v_add_f32_e32 v7, v7, v5
	v_cvt_pk_bf16_f32 v4, v4, v3
	v_mov_b32_e32 v3, v7
	v_mov_b32_e32 v255, v7
	s_nop 1
	v_permlane16_swap_b32_e32 v3, v255
	s_nop 1
	v_mov_b32_dpp v3, v255 quad_perm:[0,1,2,3] row_mask:0x5 bank_mask:0xf
	v_cvt_pk_bf16_f32 v5, v6, v5
	ds_write_b64 v0, v[4:5] offset:39712
	s_waitcnt lgkmcnt(1)
	v_add_f32_e32 v3, v7, v3
	s_nop 1
	v_mov_b32_dpp v4, v3 row_ror:8 row_mask:0xf bank_mask:0xf
	s_waitcnt lgkmcnt(0)
	v_add_f32_e32 v3, v3, v4
	s_nop 1
	v_mov_b32_dpp v4, v3 row_shl:4 row_mask:0xf bank_mask:0x5
	v_mov_b32_dpp v4, v3 row_shr:4 row_mask:0xf bank_mask:0xa
	s_nop 0
	v_add_f32_e32 v3, v3, v4
	s_nop 1
	v_mov_b32_dpp v4, v3 quad_perm:[2,3,0,1] row_mask:0xf bank_mask:0xf
	s_nop 0
	v_add_f32_e32 v3, v3, v4
	s_nop 1
	v_mov_b32_dpp v4, v3 quad_perm:[1,0,3,2] row_mask:0xf bank_mask:0xf
	s_and_saveexec_b64 s[0:1], vcc
	s_cbranch_execz .LBB0_1049
	v_lshl_add_u32 v2, v2, 2, 0
	s_waitcnt lgkmcnt(0)
	v_add_f32_e32 v3, v3, v4
	s_waitcnt vmcnt(0)
	v_sub_f32_e32 v4, v96, v1
	v_add_u32_e32 v5, 0x11c00, v2
	v_mul_f32_e32 v4, 0x3fb8aa3b, v4
	ds_read_b32 v5, v5
	v_exp_f32_e32 v4, v4
	s_waitcnt lgkmcnt(0)
	v_fmac_f32_e32 v3, v4, v5
	v_add_u32_e32 v5, 0x11e00, v2
	ds_write_b32 v5, v3
	v_add_u32_e32 v3, 0x12000, v2
	ds_write_b32 v3, v4
	v_add_u32_e32 v3, 0x11800, v2
	ds_read_b32 v3, v3
	v_add_u32_e32 v2, 0x12200, v2
	s_waitcnt lgkmcnt(0)
	v_add_f32_e32 v1, v1, v3
	v_mul_f32_e32 v1, 0xbfb8aa3b, v1
	v_exp_f32_e32 v1, v1
	ds_write_b32 v2, v1

.LBB0_1057:
	s_or_b64 exec, exec, s[68:69]
	v_add_f32_e32 v7, 0, v4
	v_add_f32_e32 v7, v7, v3
	v_add_f32_e32 v7, v7, v6
	v_add_f32_e32 v7, v7, v5
	v_cvt_pk_bf16_f32 v4, v4, v3
	v_mov_b32_e32 v3, v7
	v_mov_b32_e32 v255, v7
	s_nop 1
	v_permlane16_swap_b32_e32 v3, v255
	s_nop 1
	v_mov_b32_dpp v3, v255 quad_perm:[0,1,2,3] row_mask:0x5 bank_mask:0xf
	v_cvt_pk_bf16_f32 v5, v6, v5
	ds_write_b64 v0, v[4:5] offset:39984
	s_waitcnt lgkmcnt(1)
	v_add_f32_e32 v3, v7, v3
	s_nop 1
	v_mov_b32_dpp v4, v3 row_ror:8 row_mask:0xf bank_mask:0xf
	s_waitcnt lgkmcnt(0)
	v_add_f32_e32 v3, v3, v4
	s_nop 1
	v_mov_b32_dpp v4, v3 row_shl:4 row_mask:0xf bank_mask:0x5
	v_mov_b32_dpp v4, v3 row_shr:4 row_mask:0xf bank_mask:0xa
	s_nop 0
	v_add_f32_e32 v3, v3, v4
	s_nop 1
	v_mov_b32_dpp v4, v3 quad_perm:[2,3,0,1] row_mask:0xf bank_mask:0xf
	s_nop 0
	v_add_f32_e32 v3, v3, v4
	s_nop 1
	v_mov_b32_dpp v4, v3 quad_perm:[1,0,3,2] row_mask:0xf bank_mask:0xf
	s_and_saveexec_b64 s[0:1], vcc
	s_cbranch_execz .LBB0_1059
	v_lshl_add_u32 v2, v2, 2, 0
	s_waitcnt lgkmcnt(0)
	v_add_f32_e32 v3, v3, v4
	s_waitcnt vmcnt(0)
	v_sub_f32_e32 v4, v96, v1
	v_add_u32_e32 v5, 0x11c00, v2
	v_mul_f32_e32 v4, 0x3fb8aa3b, v4
	ds_read_b32 v5, v5
	v_exp_f32_e32 v4, v4
	s_waitcnt lgkmcnt(0)
	v_fmac_f32_e32 v3, v4, v5
	v_add_u32_e32 v5, 0x11e00, v2
	ds_write_b32 v5, v3
	v_add_u32_e32 v3, 0x12000, v2
	ds_write_b32 v3, v4
	v_add_u32_e32 v3, 0x11800, v2
	ds_read_b32 v3, v3
	v_add_u32_e32 v2, 0x12200, v2
	s_waitcnt lgkmcnt(0)
	v_add_f32_e32 v1, v1, v3
	v_mul_f32_e32 v1, 0xbfb8aa3b, v1
	v_exp_f32_e32 v1, v1
	ds_write_b32 v2, v1

.LBB0_1067:
	s_or_b64 exec, exec, s[68:69]
	v_add_f32_e32 v7, 0, v4
	v_add_f32_e32 v7, v7, v3
	v_add_f32_e32 v7, v7, v6
	v_add_f32_e32 v7, v7, v5
	v_cvt_pk_bf16_f32 v4, v4, v3
	v_mov_b32_e32 v3, v7
	v_mov_b32_e32 v255, v7
	s_nop 1
	v_permlane16_swap_b32_e32 v3, v255
	s_nop 1
	v_mov_b32_dpp v3, v255 quad_perm:[0,1,2,3] row_mask:0x5 bank_mask:0xf
	v_cvt_pk_bf16_f32 v5, v6, v5
	ds_write_b64 v0, v[4:5] offset:41344
	s_waitcnt lgkmcnt(1)
	v_add_f32_e32 v3, v7, v3
	s_nop 1
	v_mov_b32_dpp v4, v3 row_ror:8 row_mask:0xf bank_mask:0xf
	s_waitcnt lgkmcnt(0)
	v_add_f32_e32 v3, v3, v4
	s_nop 1
	v_mov_b32_dpp v4, v3 row_shl:4 row_mask:0xf bank_mask:0x5
	v_mov_b32_dpp v4, v3 row_shr:4 row_mask:0xf bank_mask:0xa
	s_nop 0
	v_add_f32_e32 v3, v3, v4
	s_nop 1
	v_mov_b32_dpp v4, v3 quad_perm:[2,3,0,1] row_mask:0xf bank_mask:0xf
	s_nop 0
	v_add_f32_e32 v3, v3, v4
	s_nop 1
	v_mov_b32_dpp v4, v3 quad_perm:[1,0,3,2] row_mask:0xf bank_mask:0xf
	s_and_saveexec_b64 s[0:1], vcc
	s_cbranch_execz .LBB0_1069
	v_lshl_add_u32 v2, v2, 2, 0
	s_waitcnt lgkmcnt(0)
	v_add_f32_e32 v3, v3, v4
	s_waitcnt vmcnt(0)
	v_sub_f32_e32 v4, v96, v1
	v_add_u32_e32 v5, 0x11c00, v2
	v_mul_f32_e32 v4, 0x3fb8aa3b, v4
	ds_read_b32 v5, v5
	v_exp_f32_e32 v4, v4
	s_waitcnt lgkmcnt(0)
	v_fmac_f32_e32 v3, v4, v5
	v_add_u32_e32 v5, 0x11e00, v2
	ds_write_b32 v5, v3
	v_add_u32_e32 v3, 0x12000, v2
	ds_write_b32 v3, v4
	v_add_u32_e32 v3, 0x11800, v2
	ds_read_b32 v3, v3
	v_add_u32_e32 v2, 0x12200, v2
	s_waitcnt lgkmcnt(0)
	v_add_f32_e32 v1, v1, v3
	v_mul_f32_e32 v1, 0xbfb8aa3b, v1
	v_exp_f32_e32 v1, v1
	ds_write_b32 v2, v1

.LBB0_1077:
	s_or_b64 exec, exec, s[68:69]
	v_add_f32_e32 v7, 0, v4
	v_add_f32_e32 v7, v7, v3
	v_add_f32_e32 v7, v7, v6
	v_add_f32_e32 v7, v7, v5
	v_cvt_pk_bf16_f32 v4, v4, v3
	v_mov_b32_e32 v3, v7
	v_mov_b32_e32 v255, v7
	s_nop 1
	v_permlane16_swap_b32_e32 v3, v255
	s_nop 1
	v_mov_b32_dpp v3, v255 quad_perm:[0,1,2,3] row_mask:0x5 bank_mask:0xf
	v_cvt_pk_bf16_f32 v5, v6, v5
	ds_write_b64 v0, v[4:5] offset:41616
	s_waitcnt lgkmcnt(1)
	v_add_f32_e32 v3, v7, v3
	s_nop 1
	v_mov_b32_dpp v4, v3 row_ror:8 row_mask:0xf bank_mask:0xf
	s_waitcnt lgkmcnt(0)
	v_add_f32_e32 v3, v3, v4
	s_nop 1
	v_mov_b32_dpp v4, v3 row_shl:4 row_mask:0xf bank_mask:0x5
	v_mov_b32_dpp v4, v3 row_shr:4 row_mask:0xf bank_mask:0xa
	s_nop 0
	v_add_f32_e32 v3, v3, v4
	s_nop 1
	v_mov_b32_dpp v4, v3 quad_perm:[2,3,0,1] row_mask:0xf bank_mask:0xf
	s_nop 0
	v_add_f32_e32 v3, v3, v4
	s_nop 1
	v_mov_b32_dpp v4, v3 quad_perm:[1,0,3,2] row_mask:0xf bank_mask:0xf
	s_and_saveexec_b64 s[0:1], vcc
	s_cbranch_execz .LBB0_1079
	v_lshl_add_u32 v2, v2, 2, 0
	s_waitcnt lgkmcnt(0)
	v_add_f32_e32 v3, v3, v4
	s_waitcnt vmcnt(0)
	v_sub_f32_e32 v4, v96, v1
	v_add_u32_e32 v5, 0x11c00, v2
	v_mul_f32_e32 v4, 0x3fb8aa3b, v4
	ds_read_b32 v5, v5
	v_exp_f32_e32 v4, v4
	s_waitcnt lgkmcnt(0)
	v_fmac_f32_e32 v3, v4, v5
	v_add_u32_e32 v5, 0x11e00, v2
	ds_write_b32 v5, v3
	v_add_u32_e32 v3, 0x12000, v2
	ds_write_b32 v3, v4
	v_add_u32_e32 v3, 0x11800, v2
	ds_read_b32 v3, v3
	v_add_u32_e32 v2, 0x12200, v2
	s_waitcnt lgkmcnt(0)
	v_add_f32_e32 v1, v1, v3
	v_mul_f32_e32 v1, 0xbfb8aa3b, v1
	v_exp_f32_e32 v1, v1
	ds_write_b32 v2, v1

.LBB0_1087:
	s_or_b64 exec, exec, s[68:69]
	v_add_f32_e32 v7, 0, v4
	v_add_f32_e32 v7, v7, v3
	v_add_f32_e32 v7, v7, v6
	v_add_f32_e32 v7, v7, v5
	v_cvt_pk_bf16_f32 v4, v4, v3
	v_mov_b32_e32 v3, v7
	v_mov_b32_e32 v255, v7
	s_nop 1
	v_permlane16_swap_b32_e32 v3, v255
	s_nop 1
	v_mov_b32_dpp v3, v255 quad_perm:[0,1,2,3] row_mask:0x5 bank_mask:0xf
	v_cvt_pk_bf16_f32 v5, v6, v5
	ds_write_b64 v0, v[4:5] offset:41888
	s_waitcnt lgkmcnt(1)
	v_add_f32_e32 v3, v7, v3
	s_nop 1
	v_mov_b32_dpp v4, v3 row_ror:8 row_mask:0xf bank_mask:0xf
	s_waitcnt lgkmcnt(0)
	v_add_f32_e32 v3, v3, v4
	s_nop 1
	v_mov_b32_dpp v4, v3 row_shl:4 row_mask:0xf bank_mask:0x5
	v_mov_b32_dpp v4, v3 row_shr:4 row_mask:0xf bank_mask:0xa
	s_nop 0
	v_add_f32_e32 v3, v3, v4
	s_nop 1
	v_mov_b32_dpp v4, v3 quad_perm:[2,3,0,1] row_mask:0xf bank_mask:0xf
	s_nop 0
	v_add_f32_e32 v3, v3, v4
	s_nop 1
	v_mov_b32_dpp v4, v3 quad_perm:[1,0,3,2] row_mask:0xf bank_mask:0xf
	s_and_saveexec_b64 s[0:1], vcc
	s_cbranch_execz .LBB0_1089
	v_lshl_add_u32 v2, v2, 2, 0
	s_waitcnt lgkmcnt(0)
	v_add_f32_e32 v3, v3, v4
	s_waitcnt vmcnt(0)
	v_sub_f32_e32 v4, v96, v1
	v_add_u32_e32 v5, 0x11c00, v2
	v_mul_f32_e32 v4, 0x3fb8aa3b, v4
	ds_read_b32 v5, v5
	v_exp_f32_e32 v4, v4
	s_waitcnt lgkmcnt(0)
	v_fmac_f32_e32 v3, v4, v5
	v_add_u32_e32 v5, 0x11e00, v2
	ds_write_b32 v5, v3
	v_add_u32_e32 v3, 0x12000, v2
	ds_write_b32 v3, v4
	v_add_u32_e32 v3, 0x11800, v2
	ds_read_b32 v3, v3
	v_add_u32_e32 v2, 0x12200, v2
	s_waitcnt lgkmcnt(0)
	v_add_f32_e32 v1, v1, v3
	v_mul_f32_e32 v1, 0xbfb8aa3b, v1
	v_exp_f32_e32 v1, v1
	ds_write_b32 v2, v1

.LBB0_1097:
	s_or_b64 exec, exec, s[6:7]
	v_add_f32_e32 v7, 0, v4
	v_add_f32_e32 v7, v7, v3
	v_add_f32_e32 v7, v7, v6
	v_add_f32_e32 v7, v7, v5
	v_cvt_pk_bf16_f32 v4, v4, v3
	v_cvt_pk_bf16_f32 v5, v6, v5
	ds_write_b64 v0, v[4:5] offset:42160
	v_mov_b32_e32 v0, v7
	v_mov_b32_e32 v255, v7
	s_nop 1
	v_permlane16_swap_b32_e32 v0, v255
	s_nop 1
	v_mov_b32_dpp v0, v255 quad_perm:[0,1,2,3] row_mask:0x5 bank_mask:0xf
	s_waitcnt lgkmcnt(0)
	v_add_f32_e32 v0, v7, v0
	s_nop 1
	v_mov_b32_dpp v3, v0 row_ror:8 row_mask:0xf bank_mask:0xf
	s_nop 0
	v_add_f32_e32 v0, v0, v3
	s_nop 1
	v_mov_b32_dpp v3, v0 row_shl:4 row_mask:0xf bank_mask:0x5
	v_mov_b32_dpp v3, v0 row_shr:4 row_mask:0xf bank_mask:0xa
	s_nop 0
	v_add_f32_e32 v0, v0, v3
	s_nop 1
	v_mov_b32_dpp v3, v0 quad_perm:[2,3,0,1] row_mask:0xf bank_mask:0xf
	s_nop 0
	v_add_f32_e32 v0, v0, v3
	s_nop 1
	v_mov_b32_dpp v3, v0 quad_perm:[1,0,3,2] row_mask:0xf bank_mask:0xf
	s_and_saveexec_b64 s[0:1], vcc
	s_cbranch_execz .LBB0_1099
	v_lshl_add_u32 v2, v2, 2, 0
	s_waitcnt lgkmcnt(0)
	v_add_f32_e32 v0, v0, v3
	s_waitcnt vmcnt(0)
	v_sub_f32_e32 v3, v96, v1
	v_add_u32_e32 v4, 0x11c00, v2
	v_mul_f32_e32 v3, 0x3fb8aa3b, v3
	ds_read_b32 v4, v4
	v_exp_f32_e32 v3, v3
	s_waitcnt lgkmcnt(0)
	v_fmac_f32_e32 v0, v3, v4
	v_add_u32_e32 v4, 0x11e00, v2
	ds_write_b32 v4, v0
	v_add_u32_e32 v0, 0x12000, v2
	ds_write_b32 v0, v3
	v_add_u32_e32 v0, 0x11800, v2
	ds_read_b32 v0, v0
	s_waitcnt lgkmcnt(0)
	v_add_f32_e32 v0, v1, v0
	v_mul_f32_e32 v0, 0xbfb8aa3b, v0
	v_exp_f32_e32 v0, v0
	v_add_u32_e32 v1, 0x12200, v2
	ds_write_b32 v1, v0

.LBB0_1107:
	ds_read_b128 v[100:103], v98
	ds_read_b128 v[104:107], v96
	s_add_i32 s0, s0, 32
	s_cmpk_lt_u32 s0, 0x70
	s_waitcnt lgkmcnt(0)
	v_mfma_f32_32x32x16_bf16 v[0:15], v[100:103], v[104:107], v[0:15]
	ds_read_b128 v[104:107], v96 offset:8704
	s_waitcnt lgkmcnt(0)
	v_mfma_f32_32x32x16_bf16 v[16:31], v[100:103], v[104:107], v[16:31]
	ds_read_b128 v[104:107], v96 offset:17408
	s_waitcnt lgkmcnt(0)
	v_mfma_f32_32x32x16_bf16 v[32:47], v[100:103], v[104:107], v[32:47]
	ds_read_b128 v[104:107], v96 offset:26112
	s_waitcnt lgkmcnt(0)
	v_mfma_f32_32x32x16_bf16 v[48:63], v[100:103], v[104:107], v[48:63]
	ds_read_b128 v[100:103], v98 offset:32
	ds_read_b128 v[104:107], v96 offset:32
	v_add_u32_e32 v98, 64, v98
	s_waitcnt lgkmcnt(0)
	v_mfma_f32_32x32x16_bf16 v[0:15], v[100:103], v[104:107], v[0:15]
	ds_read_b128 v[104:107], v96 offset:8736
	s_waitcnt lgkmcnt(0)
	v_mfma_f32_32x32x16_bf16 v[16:31], v[100:103], v[104:107], v[16:31]
	ds_read_b128 v[104:107], v96 offset:17440
	s_waitcnt lgkmcnt(0)
	v_mfma_f32_32x32x16_bf16 v[32:47], v[100:103], v[104:107], v[32:47]
	ds_read_b128 v[104:107], v96 offset:26144
	v_add_u32_e32 v96, 64, v96
	s_waitcnt lgkmcnt(0)
	v_mfma_f32_32x32x16_bf16 v[48:63], v[100:103], v[104:107], v[48:63]
	s_cbranch_scc1 .LBB0_1107
	v_mov_b32_e32 v96, v128
	s_mov_b64 s[0:1], -1
	v_ashrrev_i32_e32 v98, 3, v96
	v_and_b32_e32 v98, -4, v98
	v_and_b32_e32 v103, 31, v96
	v_add_u32_e32 v105, v98, v129
	v_lshlrev_b32_e32 v96, 2, v103
	v_lshl_add_u64 v[98:99], s[56:57], 0, v[96:97]
	v_add_u32_e32 v100, s61, v105
	v_or_b32_e32 v96, 1, v105
	v_or_b32_e32 v102, 2, v105
	s_andn2_b64 vcc, exec, s[54:55]
	v_lshlrev_b32_e32 v237, 2, v105
	v_ashrrev_i32_e32 v101, 31, v100
	v_lshlrev_b32_e32 v236, 2, v96
	v_add_u32_e32 v104, s61, v96
	v_lshlrev_b32_e32 v235, 2, v102
	v_add_u32_e32 v102, s61, v102
	v_or_b32_e32 v234, 3, v105
	s_cbranch_vccnz .LBB0_1110
	s_add_i32 s0, 0, 0x11e00
	s_add_i32 s1, 0, 0x12200
	v_add_u32_e32 v238, s0, v237
	v_add_u32_e32 v239, s1, v237
	ds_read_b32 v96, v238
	ds_read_b32 v105, v239
	v_mov_b32_e32 v110, v0
	v_mov_b32_e32 v111, v16
	v_or_b32_e32 v103, s75, v103
	s_waitcnt lgkmcnt(1)
	v_max_f32_e64 v96, |v96|, |v96|
	s_waitcnt lgkmcnt(0)
	v_max_f32_e32 v105, v105, v105
	v_max_f32_e32 v96, v96, v105
	v_div_scale_f32 v105, s[6:7], v96, v96, 1.0
	v_rcp_f32_e32 v106, v105
	v_readlane_b32 s6, v249, 7
	v_readlane_b32 s7, v249, 8
	v_readlane_b32 s12, v251, 20
	v_fma_f32 v107, -v105, v106, 1.0
	v_fmac_f32_e32 v106, v107, v106
	v_div_scale_f32 v107, vcc, 1.0, v96, 1.0
	v_mul_f32_e32 v108, v107, v106
	v_fma_f32 v109, -v105, v108, v107
	v_fmac_f32_e32 v108, v109, v106
	v_fma_f32 v105, -v105, v108, v107
	v_div_fmas_f32 v105, v105, v106, v108
	v_lshlrev_b64 v[106:107], 11, v[100:101]
	v_lshl_add_u64 v[106:107], v[98:99], 0, v[106:107]
	global_load_dword v108, v[106:107], off
	global_load_dword v109, v[106:107], off offset:128
	global_load_dword v112, v[106:107], off offset:256
	global_load_dword v113, v[106:107], off offset:384
	v_div_fixup_f32 v96, v105, v96, 1.0
	v_mov_b32_e32 v106, v32
	v_mov_b32_e32 v107, v48
	v_readlane_b32 s18, v251, 26
	v_readlane_b32 s19, v251, 27
	v_readlane_b32 s14, v251, 22
	v_readlane_b32 s15, v251, 23
	v_readlane_b32 s16, v251, 24
	v_readlane_b32 s17, v251, 25
	v_readlane_b32 s20, v251, 28
	v_readlane_b32 s21, v251, 29
	v_readlane_b32 s22, v251, 30
	v_readlane_b32 s23, v251, 31
	v_readlane_b32 s25, v251, 33
	v_readlane_b32 s14, v248, 4
	s_mov_b64 s[16:17], s[82:83]
	s_mov_b32 s25, 0x85000
	s_mov_b32 s23, 0x59000
	s_mov_b32 s22, 0x2d000
	s_mov_b32 s21, 0x84000
	s_mov_b32 s20, 0x58000
	s_movk_i32 s29, 0x47ff
	s_mov_b32 s28, 0x4800000
	v_readlane_b32 s15, v248, 5
	v_readlane_b32 s13, v251, 21
	v_readlane_b32 s24, v251, 32
	v_readlane_b32 s26, v251, 34
	v_readlane_b32 s27, v251, 35
	s_waitcnt vmcnt(2)
	v_pk_fma_f32 v[110:111], v[110:111], v[96:97], v[108:109] op_sel_hi:[1,0,1]
	s_nop 0
	v_pk_mul_f32 v[108:109], v[110:111], v[110:111]
	s_waitcnt vmcnt(0)
	v_pk_fma_f32 v[124:125], v[106:107], v[96:97], v[112:113] op_sel_hi:[1,0,1]
	v_add_f32_e32 v96, v108, v109
	v_pk_mul_f32 v[106:107], v[124:125], v[124:125]
	s_nop 0
	v_add_f32_e32 v96, v96, v106
	v_add_f32_e32 v96, v96, v107
	v_mov_b32_e32 v105, v96
	v_mov_b32_e32 v255, v96
	s_nop 1
	v_permlane16_swap_b32_e32 v105, v255
	s_nop 1
	v_mov_b32_dpp v105, v255 quad_perm:[0,1,2,3] row_mask:0x5 bank_mask:0xf
	v_mov_b64_e32 v[106:107], s[6:7]
	v_mad_i64_i32 v[108:109], s[6:7], v100, s74, v[106:107]
	v_lshl_add_u64 v[126:127], v[108:109], 0, s[96:97]
	s_nop 0
	v_add_f32_e32 v96, v96, v105
	s_nop 1
	v_mov_b32_dpp v105, v96 row_ror:8 row_mask:0xf bank_mask:0xf
	v_lshlrev_b64 v[108:109], 10, v[100:101]
	v_lshl_add_u64 v[112:113], s[66:67], 0, v[108:109]
	s_nop 0
	v_add_f32_e32 v96, v96, v105
	s_nop 1
	v_mov_b32_dpp v105, v96 row_shl:4 row_mask:0xf bank_mask:0x5
	v_mov_b32_dpp v105, v96 row_shr:4 row_mask:0xf bank_mask:0xa
	s_nop 0
	v_add_f32_e32 v96, v96, v105
	s_nop 1
	v_mov_b32_dpp v105, v96 quad_perm:[2,3,0,1] row_mask:0xf bank_mask:0xf
	s_nop 0
	v_add_f32_e32 v96, v96, v105
	s_nop 1
	v_mov_b32_dpp v105, v96 quad_perm:[1,0,3,2] row_mask:0xf bank_mask:0xf
	s_nop 0
	v_add_f32_e32 v96, v96, v105
	v_fmamk_f32 v96, v96, 0x3c000000, v163
	v_cmp_gt_f32_e32 vcc, s86, v96
	v_mul_f32_e32 v105, 0x4b800000, v96
	s_nop 0
	v_cndmask_b32_e32 v96, v96, v105, vcc
	v_rsq_f32_e32 v96, v96
	s_nop 0
	v_mul_f32_e32 v105, 0x45800000, v96
	v_cndmask_b32_e32 v105, v96, v105, vcc
	v_lshlrev_b32_e32 v96, 1, v103
	v_lshl_add_u64 v[108:109], v[126:127], 0, v[96:97]
	global_load_ushort v108, v[108:109], off
	v_mov_b32_e32 v109, v97
	v_mul_f32_e32 v110, v110, v105
	v_lshl_add_u64 v[122:123], v[112:113], 0, v[96:97]
	v_or_b32_e32 v112, 64, v96
	v_mov_b32_e32 v113, v97
	s_waitcnt vmcnt(0)
	v_lshlrev_b32_e32 v108, 16, v108
	v_mul_f32_e32 v108, 0xbfb8aa3b, v108
	v_exp_f32_e32 v108, v108
	s_nop 0
	v_add_f32_e32 v108, 1.0, v108
	v_rcp_f32_e32 v118, v108
	v_or_b32_e32 v108, s34, v103
	v_lshl_add_u64 v[108:109], v[108:109], 2, s[18:19]
	global_load_dword v119, v[108:109], off
	s_waitcnt vmcnt(0)
	v_mul_f32_e32 v110, v119, v110
	v_mul_f32_e32 v110, v118, v110
	v_cvt_pk_bf16_f32 v110, v110, s0
	v_lshl_add_u64 v[118:119], v[126:127], 0, v[112:113]
	global_store_short v[122:123], v110, off
	global_load_ushort v110, v[118:119], off
	v_mul_f32_e32 v119, v111, v105
	v_mov_b32_e32 v111, v97
	s_waitcnt vmcnt(0)
	v_lshlrev_b32_e32 v110, 16, v110
	v_mul_f32_e32 v110, 0xbfb8aa3b, v110
	v_exp_f32_e32 v110, v110
	s_nop 0
	v_add_f32_e32 v110, 1.0, v110
	v_rcp_f32_e32 v118, v110
	v_add_u32_e32 v110, s34, v103
	v_lshl_add_u64 v[110:111], v[110:111], 2, s[18:19]
	global_load_dword v103, v[110:111], off offset:128
	s_mov_b32 s19, 0x2c000
	s_movk_i32 s18, 0x1600
	s_waitcnt vmcnt(0)
	v_mul_f32_e32 v103, v103, v119
	v_mul_f32_e32 v103, v118, v103
	v_or_b32_e32 v118, 0x80, v96
	v_mov_b32_e32 v119, v97
	v_cvt_pk_bf16_f32 v103, v103, s0
	v_lshl_add_u64 v[120:121], v[126:127], 0, v[118:119]
	global_store_short v[122:123], v103, off offset:64
	global_load_ushort v103, v[120:121], off
	v_mul_f32_e32 v120, v124, v105
	global_load_dword v121, v[110:111], off offset:256
	global_load_dword v124, v[110:111], off offset:384
	v_mul_f32_e32 v105, v125, v105
	s_waitcnt vmcnt(2)
	v_lshlrev_b32_e32 v103, 16, v103
	v_mul_f32_e32 v103, 0xbfb8aa3b, v103
	v_exp_f32_e32 v103, v103
	s_waitcnt vmcnt(1)
	v_mul_f32_e32 v120, v121, v120
	v_mov_b32_e32 v121, v97
	s_waitcnt vmcnt(0)
	v_mul_f32_e32 v105, v124, v105
	v_add_f32_e32 v103, 1.0, v103
	v_rcp_f32_e32 v103, v103
	s_nop 0
	v_mul_f32_e32 v103, v120, v103
	v_or_b32_e32 v120, 0xc0, v96
	v_cvt_pk_bf16_f32 v103, v103, s0
	v_lshl_add_u64 v[126:127], v[126:127], 0, v[120:121]
	global_store_short v[122:123], v103, off offset:128
	global_load_ushort v103, v[126:127], off
	s_waitcnt vmcnt(0)
	v_lshlrev_b32_e32 v103, 16, v103
	v_mul_f32_e32 v103, 0xbfb8aa3b, v103
	v_exp_f32_e32 v103, v103
	s_nop 0
	v_add_f32_e32 v103, 1.0, v103
	v_rcp_f32_e32 v103, v103
	s_nop 0
	v_mul_f32_e32 v103, v105, v103
	v_cvt_pk_bf16_f32 v103, v103, s0
	global_store_short v[122:123], v103, off offset:192
	v_add_u32_e32 v103, s0, v236
	v_add_u32_e32 v105, s1, v236
	ds_read_b32 v103, v103
	ds_read_b32 v105, v105
	v_mov_b32_e32 v242, v1
	v_mov_b32_e32 v243, v17
	s_waitcnt lgkmcnt(1)
	v_max_f32_e64 v103, |v103|, |v103|
	s_waitcnt lgkmcnt(0)
	v_max_f32_e32 v105, v105, v105
	v_max_f32_e32 v103, v103, v105
	v_div_scale_f32 v105, s[6:7], v103, v103, 1.0
	v_rcp_f32_e32 v122, v105
	s_nop 0
	v_fma_f32 v123, -v105, v122, 1.0
	v_fmac_f32_e32 v122, v123, v122
	v_div_scale_f32 v123, vcc, 1.0, v103, 1.0
	v_mul_f32_e32 v124, v123, v122
	v_fma_f32 v125, -v105, v124, v123
	v_fmac_f32_e32 v124, v125, v122
	v_fma_f32 v105, -v105, v124, v123
	v_div_fmas_f32 v105, v105, v122, v124
	v_div_fixup_f32 v122, v105, v103, 1.0
	v_ashrrev_i32_e32 v105, 31, v104
	v_lshlrev_b64 v[124:125], 11, v[104:105]
	v_lshl_add_u64 v[124:125], v[98:99], 0, v[124:125]
	global_load_dword v126, v[124:125], off
	global_load_dword v127, v[124:125], off offset:128
	global_load_dword v244, v[124:125], off offset:256
	global_load_dword v245, v[124:125], off offset:384
	v_mov_b32_e32 v124, v33
	v_mov_b32_e32 v125, v49
	s_waitcnt vmcnt(2)
	v_pk_fma_f32 v[126:127], v[242:243], v[122:123], v[126:127] op_sel_hi:[1,0,1]
	s_nop 0
	v_pk_mul_f32 v[242:243], v[126:127], v[126:127]
	s_waitcnt vmcnt(0)
	v_pk_fma_f32 v[124:125], v[124:125], v[122:123], v[244:245] op_sel_hi:[1,0,1]
	v_add_f32_e32 v103, v242, v243
	v_pk_mul_f32 v[122:123], v[124:125], v[124:125]
	s_nop 0
	v_add_f32_e32 v103, v103, v122
	v_add_f32_e32 v103, v103, v123
	v_mov_b32_e32 v122, v103
	v_mov_b32_e32 v255, v103
	s_nop 1
	v_permlane16_swap_b32_e32 v122, v255
	s_nop 1
	v_mov_b32_dpp v122, v255 quad_perm:[0,1,2,3] row_mask:0x5 bank_mask:0xf
	s_nop 0
	v_add_f32_e32 v103, v103, v122
	s_nop 1
	v_mov_b32_dpp v122, v103 row_ror:8 row_mask:0xf bank_mask:0xf
	s_nop 0
	v_add_f32_e32 v103, v103, v122
	s_nop 1
	v_mov_b32_dpp v122, v103 row_shl:4 row_mask:0xf bank_mask:0x5
	v_mov_b32_dpp v122, v103 row_shr:4 row_mask:0xf bank_mask:0xa
	s_nop 0
	v_add_f32_e32 v103, v103, v122
	s_nop 1
	v_mov_b32_dpp v122, v103 quad_perm:[2,3,0,1] row_mask:0xf bank_mask:0xf
	s_nop 0
	v_add_f32_e32 v103, v103, v122
	s_nop 1
	v_mov_b32_dpp v122, v103 quad_perm:[1,0,3,2] row_mask:0xf bank_mask:0xf
	s_nop 0
	v_add_f32_e32 v103, v103, v122
	v_fmamk_f32 v103, v103, 0x3c000000, v163
	v_cmp_gt_f32_e32 vcc, s86, v103
	v_mul_f32_e32 v122, 0x4b800000, v103
	s_nop 0
	v_cndmask_b32_e32 v103, v103, v122, vcc
	v_rsq_f32_e32 v103, v103
	s_nop 0
	v_mul_f32_e32 v122, 0x45800000, v103
	v_cndmask_b32_e32 v103, v103, v122, vcc
	v_mad_i64_i32 v[122:123], s[6:7], v104, s74, v[106:107]
	v_lshl_add_u64 v[242:243], v[122:123], 0, s[96:97]
	v_lshl_add_u64 v[244:245], v[242:243], 0, v[96:97]
	v_lshlrev_b64 v[122:123], 10, v[104:105]
	global_load_ushort v105, v[244:245], off
	v_mul_f32_e32 v126, v126, v103
	global_load_dword v244, v[108:109], off
	v_lshl_add_u64 v[122:123], s[66:67], 0, v[122:123]
	v_lshl_add_u64 v[122:123], v[122:123], 0, v[96:97]
	v_mul_f32_e32 v124, v124, v103
	s_waitcnt vmcnt(1)
	v_lshlrev_b32_e32 v105, 16, v105
	v_mul_f32_e32 v105, 0xbfb8aa3b, v105
	v_exp_f32_e32 v105, v105
	s_waitcnt vmcnt(0)
	v_mul_f32_e32 v126, v244, v126
	v_lshl_add_u64 v[244:245], v[242:243], 0, v[112:113]
	v_add_f32_e32 v105, 1.0, v105
	v_rcp_f32_e32 v105, v105
	s_nop 0
	v_mul_f32_e32 v105, v105, v126
	v_cvt_pk_bf16_f32 v105, v105, s0
	global_store_short v[122:123], v105, off
	global_load_ushort v105, v[244:245], off
	v_mul_f32_e32 v126, v127, v103
	global_load_dword v127, v[110:111], off offset:128
	v_mul_f32_e32 v103, v125, v103
	s_waitcnt vmcnt(1)
	v_lshlrev_b32_e32 v105, 16, v105
	v_mul_f32_e32 v105, 0xbfb8aa3b, v105
	v_exp_f32_e32 v105, v105
	s_waitcnt vmcnt(0)
	v_mul_f32_e32 v126, v127, v126
	v_add_f32_e32 v105, 1.0, v105
	v_rcp_f32_e32 v105, v105
	s_nop 0
	v_mul_f32_e32 v105, v105, v126
	v_cvt_pk_bf16_f32 v105, v105, s0
	v_lshl_add_u64 v[126:127], v[242:243], 0, v[118:119]
	global_store_short v[122:123], v105, off offset:64
	global_load_ushort v105, v[126:127], off
	s_waitcnt vmcnt(0)
	v_lshlrev_b32_e32 v105, 16, v105
	global_load_dword v126, v[110:111], off offset:256
	v_mul_f32_e32 v105, 0xbfb8aa3b, v105
	v_exp_f32_e32 v105, v105
	s_waitcnt vmcnt(0)
	v_mul_f32_e32 v124, v126, v124
	v_add_f32_e32 v105, 1.0, v105
	v_rcp_f32_e32 v105, v105
	v_lshl_add_u64 v[126:127], v[242:243], 0, v[120:121]
	v_mul_f32_e32 v105, v124, v105
	v_cvt_pk_bf16_f32 v105, v105, s0
	global_store_short v[122:123], v105, off offset:128
	global_load_ushort v105, v[126:127], off
	s_waitcnt vmcnt(0)
	v_lshlrev_b32_e32 v105, 16, v105
	global_load_dword v124, v[110:111], off offset:384
	v_mul_f32_e32 v105, 0xbfb8aa3b, v105
	v_exp_f32_e32 v105, v105
	s_waitcnt vmcnt(0)
	v_mul_f32_e32 v103, v124, v103
	v_add_f32_e32 v105, 1.0, v105
	v_rcp_f32_e32 v105, v105
	s_nop 0
	v_mul_f32_e32 v103, v103, v105
	v_cvt_pk_bf16_f32 v103, v103, s0
	global_store_short v[122:123], v103, off offset:192
	v_add_u32_e32 v103, s0, v235
	v_add_u32_e32 v105, s1, v235
	ds_read_b32 v103, v103
	ds_read_b32 v105, v105
	v_mov_b32_e32 v242, v2
	v_mov_b32_e32 v243, v18
	s_waitcnt lgkmcnt(1)
	v_max_f32_e64 v103, |v103|, |v103|
	s_waitcnt lgkmcnt(0)
	v_max_f32_e32 v105, v105, v105
	v_max_f32_e32 v103, v103, v105
	v_div_scale_f32 v105, s[6:7], v103, v103, 1.0
	v_rcp_f32_e32 v122, v105
	s_nop 0
	v_fma_f32 v123, -v105, v122, 1.0
	v_fmac_f32_e32 v122, v123, v122
	v_div_scale_f32 v123, vcc, 1.0, v103, 1.0
	v_mul_f32_e32 v124, v123, v122
	v_fma_f32 v125, -v105, v124, v123
	v_fmac_f32_e32 v124, v125, v122
	v_fma_f32 v105, -v105, v124, v123
	v_div_fmas_f32 v105, v105, v122, v124
	v_div_fixup_f32 v122, v105, v103, 1.0
	v_ashrrev_i32_e32 v103, 31, v102
	v_lshlrev_b64 v[124:125], 11, v[102:103]
	v_lshl_add_u64 v[124:125], v[98:99], 0, v[124:125]
	global_load_dword v126, v[124:125], off
	global_load_dword v127, v[124:125], off offset:128
	global_load_dword v244, v[124:125], off offset:256
	global_load_dword v245, v[124:125], off offset:384
	v_mov_b32_e32 v124, v34
	v_mov_b32_e32 v125, v50
	s_waitcnt vmcnt(2)
	v_pk_fma_f32 v[126:127], v[242:243], v[122:123], v[126:127] op_sel_hi:[1,0,1]
	s_nop 0
	v_pk_mul_f32 v[242:243], v[126:127], v[126:127]
	s_waitcnt vmcnt(0)
	v_pk_fma_f32 v[124:125], v[124:125], v[122:123], v[244:245] op_sel_hi:[1,0,1]
	v_add_f32_e32 v105, v242, v243
	v_pk_mul_f32 v[122:123], v[124:125], v[124:125]
	s_nop 0
	v_add_f32_e32 v105, v105, v122
	v_add_f32_e32 v105, v105, v123
	v_mov_b32_e32 v122, v105
	v_mov_b32_e32 v255, v105
	s_nop 1
	v_permlane16_swap_b32_e32 v122, v255
	s_nop 1
	v_mov_b32_dpp v122, v255 quad_perm:[0,1,2,3] row_mask:0x5 bank_mask:0xf
	s_nop 0
	v_add_f32_e32 v105, v105, v122
	s_nop 1
	v_mov_b32_dpp v122, v105 row_ror:8 row_mask:0xf bank_mask:0xf
	s_nop 0
	v_add_f32_e32 v105, v105, v122
	s_nop 1
	v_mov_b32_dpp v122, v105 row_shl:4 row_mask:0xf bank_mask:0x5
	v_mov_b32_dpp v122, v105 row_shr:4 row_mask:0xf bank_mask:0xa
	s_nop 0
	v_add_f32_e32 v105, v105, v122
	s_nop 1
	v_mov_b32_dpp v122, v105 quad_perm:[2,3,0,1] row_mask:0xf bank_mask:0xf
	s_nop 0
	v_add_f32_e32 v105, v105, v122
	s_nop 1
	v_mov_b32_dpp v122, v105 quad_perm:[1,0,3,2] row_mask:0xf bank_mask:0xf
	s_nop 0
	v_add_f32_e32 v105, v105, v122
	v_fmamk_f32 v105, v105, 0x3c000000, v163
	v_cmp_gt_f32_e32 vcc, s86, v105
	v_mul_f32_e32 v122, 0x4b800000, v105
	s_nop 0
	v_cndmask_b32_e32 v105, v105, v122, vcc
	v_rsq_f32_e32 v105, v105
	s_nop 0
	v_mul_f32_e32 v122, 0x45800000, v105
	v_cndmask_b32_e32 v105, v105, v122, vcc
	v_mad_i64_i32 v[122:123], s[6:7], v102, s74, v[106:107]
	v_lshl_add_u64 v[242:243], v[122:123], 0, s[96:97]
	v_lshl_add_u64 v[244:245], v[242:243], 0, v[96:97]
	v_lshlrev_b64 v[122:123], 10, v[102:103]
	global_load_ushort v103, v[244:245], off
	v_mul_f32_e32 v126, v126, v105
	global_load_dword v244, v[108:109], off
	v_lshl_add_u64 v[122:123], s[66:67], 0, v[122:123]
	v_lshl_add_u64 v[122:123], v[122:123], 0, v[96:97]
	v_mul_f32_e32 v124, v124, v105
	s_waitcnt vmcnt(1)
	v_lshlrev_b32_e32 v103, 16, v103
	v_mul_f32_e32 v103, 0xbfb8aa3b, v103
	v_exp_f32_e32 v103, v103
	s_waitcnt vmcnt(0)
	v_mul_f32_e32 v126, v244, v126
	v_lshl_add_u64 v[244:245], v[242:243], 0, v[112:113]
	v_add_f32_e32 v103, 1.0, v103
	v_rcp_f32_e32 v103, v103
	s_nop 0
	v_mul_f32_e32 v103, v103, v126
	v_cvt_pk_bf16_f32 v103, v103, s0
	global_store_short v[122:123], v103, off
	global_load_ushort v103, v[244:245], off
	v_mul_f32_e32 v126, v127, v105
	global_load_dword v127, v[110:111], off offset:128
	v_mul_f32_e32 v105, v125, v105
	s_waitcnt vmcnt(1)
	v_lshlrev_b32_e32 v103, 16, v103
	v_mul_f32_e32 v103, 0xbfb8aa3b, v103
	v_exp_f32_e32 v103, v103
	s_waitcnt vmcnt(0)
	v_mul_f32_e32 v126, v127, v126
	v_add_f32_e32 v103, 1.0, v103
	v_rcp_f32_e32 v103, v103
	s_nop 0
	v_mul_f32_e32 v103, v103, v126
	v_cvt_pk_bf16_f32 v103, v103, s0
	v_lshl_add_u64 v[126:127], v[242:243], 0, v[118:119]
	global_store_short v[122:123], v103, off offset:64
	global_load_ushort v103, v[126:127], off
	s_waitcnt vmcnt(0)
	v_lshlrev_b32_e32 v103, 16, v103
	global_load_dword v126, v[110:111], off offset:256
	v_mul_f32_e32 v103, 0xbfb8aa3b, v103
	v_exp_f32_e32 v103, v103
	s_waitcnt vmcnt(0)
	v_mul_f32_e32 v124, v126, v124
	v_add_f32_e32 v103, 1.0, v103
	v_rcp_f32_e32 v103, v103
	v_lshl_add_u64 v[126:127], v[242:243], 0, v[120:121]
	v_mul_f32_e32 v103, v124, v103
	v_cvt_pk_bf16_f32 v103, v103, s0
	global_store_short v[122:123], v103, off offset:128
	global_load_ushort v103, v[126:127], off
	s_waitcnt vmcnt(0)
	v_lshlrev_b32_e32 v103, 16, v103
	global_load_dword v124, v[110:111], off offset:384
	v_mul_f32_e32 v103, 0xbfb8aa3b, v103
	v_exp_f32_e32 v103, v103
	s_waitcnt vmcnt(0)
	v_mul_f32_e32 v105, v124, v105
	v_add_f32_e32 v103, 1.0, v103
	v_rcp_f32_e32 v103, v103
	s_nop 0
	v_mul_f32_e32 v103, v105, v103
	v_cvt_pk_bf16_f32 v103, v103, s0
	global_store_short v[122:123], v103, off offset:192
	v_lshlrev_b32_e32 v103, 2, v234
	v_add_u32_e32 v105, s0, v103
	v_add_u32_e32 v103, s1, v103
	ds_read_b32 v105, v105
	ds_read_b32 v103, v103
	v_add_u32_e32 v126, s61, v234
	v_ashrrev_i32_e32 v127, 31, v126
	v_mov_b32_e32 v244, v3
	s_waitcnt lgkmcnt(1)
	v_max_f32_e64 v105, |v105|, |v105|
	s_waitcnt lgkmcnt(0)
	v_max_f32_e32 v103, v103, v103
	v_max_f32_e32 v103, v105, v103
	v_div_scale_f32 v105, s[0:1], v103, v103, 1.0
	v_rcp_f32_e32 v122, v105
	v_mov_b32_e32 v245, v19
	v_fma_f32 v123, -v105, v122, 1.0
	v_fmac_f32_e32 v122, v123, v122
	v_div_scale_f32 v123, vcc, 1.0, v103, 1.0
	v_mul_f32_e32 v124, v123, v122
	v_fma_f32 v125, -v105, v124, v123
	v_fmac_f32_e32 v124, v125, v122
	v_fma_f32 v105, -v105, v124, v123
	v_div_fmas_f32 v105, v105, v122, v124
	v_lshlrev_b64 v[124:125], 11, v[126:127]
	v_lshl_add_u64 v[124:125], v[98:99], 0, v[124:125]
	global_load_dword v242, v[124:125], off
	global_load_dword v243, v[124:125], off offset:128
	global_load_dword v246, v[124:125], off offset:256
	global_load_dword v247, v[124:125], off offset:384
	v_div_fixup_f32 v122, v105, v103, 1.0
	v_mov_b32_e32 v124, v35
	v_mov_b32_e32 v125, v51
	s_waitcnt vmcnt(2)
	v_pk_fma_f32 v[242:243], v[244:245], v[122:123], v[242:243] op_sel_hi:[1,0,1]
	s_nop 0
	v_pk_mul_f32 v[244:245], v[242:243], v[242:243]
	s_waitcnt vmcnt(0)
	v_pk_fma_f32 v[124:125], v[124:125], v[122:123], v[246:247] op_sel_hi:[1,0,1]
	v_add_f32_e32 v103, v244, v245
	v_pk_mul_f32 v[122:123], v[124:125], v[124:125]
	s_nop 0
	v_add_f32_e32 v103, v103, v122
	v_add_f32_e32 v103, v103, v123
	v_mov_b32_e32 v105, v103
	v_mov_b32_e32 v255, v103
	s_nop 1
	v_permlane16_swap_b32_e32 v105, v255
	s_nop 1
	v_mov_b32_dpp v105, v255 quad_perm:[0,1,2,3] row_mask:0x5 bank_mask:0xf
	v_mad_i64_i32 v[122:123], s[0:1], v126, s74, v[106:107]
	v_lshl_add_u64 v[244:245], v[122:123], 0, s[96:97]
	v_lshlrev_b64 v[122:123], 10, v[126:127]
	s_nop 0
	v_add_f32_e32 v103, v103, v105
	s_nop 1
	v_mov_b32_dpp v105, v103 row_ror:8 row_mask:0xf bank_mask:0xf
	v_lshl_add_u64 v[126:127], v[244:245], 0, v[96:97]
	v_lshl_add_u64 v[122:123], s[66:67], 0, v[122:123]
	v_lshl_add_u64 v[122:123], v[122:123], 0, v[96:97]
	s_nop 0
	v_add_f32_e32 v103, v103, v105
	s_nop 1
	v_mov_b32_dpp v105, v103 row_shl:4 row_mask:0xf bank_mask:0x5
	v_mov_b32_dpp v105, v103 row_shr:4 row_mask:0xf bank_mask:0xa
	s_nop 0
	v_add_f32_e32 v103, v103, v105
	s_nop 1
	v_mov_b32_dpp v105, v103 quad_perm:[2,3,0,1] row_mask:0xf bank_mask:0xf
	s_nop 0
	v_add_f32_e32 v103, v103, v105
	s_nop 1
	v_mov_b32_dpp v105, v103 quad_perm:[1,0,3,2] row_mask:0xf bank_mask:0xf
	s_nop 0
	v_add_f32_e32 v103, v103, v105
	v_fmamk_f32 v103, v103, 0x3c000000, v163
	v_cmp_gt_f32_e32 vcc, s86, v103
	v_mul_f32_e32 v105, 0x4b800000, v103
	s_nop 0
	v_cndmask_b32_e32 v103, v103, v105, vcc
	v_rsq_f32_e32 v103, v103
	s_nop 0
	v_mul_f32_e32 v105, 0x45800000, v103
	v_cndmask_b32_e32 v103, v103, v105, vcc
	global_load_ushort v105, v[126:127], off
	v_mul_f32_e32 v126, v242, v103
	global_load_dword v127, v[108:109], off
	v_mul_f32_e32 v124, v124, v103
	s_waitcnt vmcnt(1)
	v_lshlrev_b32_e32 v105, 16, v105
	v_mul_f32_e32 v105, 0xbfb8aa3b, v105
	v_exp_f32_e32 v105, v105
	s_waitcnt vmcnt(0)
	v_mul_f32_e32 v126, v127, v126
	v_add_f32_e32 v105, 1.0, v105
	v_rcp_f32_e32 v105, v105
	s_nop 0
	v_mul_f32_e32 v105, v105, v126
	v_cvt_pk_bf16_f32 v105, v105, s0
	v_lshl_add_u64 v[126:127], v[244:245], 0, v[112:113]
	global_store_short v[122:123], v105, off
	global_load_ushort v105, v[126:127], off
	v_mul_f32_e32 v126, v243, v103
	global_load_dword v127, v[110:111], off offset:128
	v_mul_f32_e32 v103, v125, v103
	s_waitcnt vmcnt(1)
	v_lshlrev_b32_e32 v105, 16, v105
	v_mul_f32_e32 v105, 0xbfb8aa3b, v105
	v_exp_f32_e32 v105, v105
	s_waitcnt vmcnt(0)
	v_mul_f32_e32 v126, v127, v126
	v_add_f32_e32 v105, 1.0, v105
	v_rcp_f32_e32 v105, v105
	s_nop 0
	v_mul_f32_e32 v105, v105, v126
	v_cvt_pk_bf16_f32 v105, v105, s0
	v_lshl_add_u64 v[126:127], v[244:245], 0, v[118:119]
	global_store_short v[122:123], v105, off offset:64
	global_load_ushort v105, v[126:127], off
	s_waitcnt vmcnt(0)
	v_lshlrev_b32_e32 v105, 16, v105
	global_load_dword v126, v[110:111], off offset:256
	v_mul_f32_e32 v105, 0xbfb8aa3b, v105
	v_exp_f32_e32 v105, v105
	s_waitcnt vmcnt(0)
	v_mul_f32_e32 v124, v126, v124
	v_add_f32_e32 v105, 1.0, v105
	v_rcp_f32_e32 v105, v105
	v_lshl_add_u64 v[126:127], v[244:245], 0, v[120:121]
	v_mul_f32_e32 v105, v124, v105
	v_cvt_pk_bf16_f32 v105, v105, s0
	global_store_short v[122:123], v105, off offset:128
	global_load_ushort v105, v[126:127], off
	s_waitcnt vmcnt(0)
	v_lshlrev_b32_e32 v105, 16, v105
	global_load_dword v124, v[110:111], off offset:384
	v_mul_f32_e32 v105, 0xbfb8aa3b, v105
	v_exp_f32_e32 v105, v105
	s_waitcnt vmcnt(0)
	v_mul_f32_e32 v103, v124, v103
	v_add_f32_e32 v105, 1.0, v105
	v_rcp_f32_e32 v105, v105
	s_nop 0
	v_mul_f32_e32 v103, v103, v105
	v_cvt_pk_bf16_f32 v103, v103, s0
	global_store_short v[122:123], v103, off offset:192
	ds_read_b32 v103, v238 offset:32
	ds_read_b32 v105, v239 offset:32
	v_add_u32_e32 v126, 8, v100
	v_ashrrev_i32_e32 v127, 31, v126
	v_mov_b32_e32 v244, v4
	s_waitcnt lgkmcnt(1)
	v_max_f32_e64 v103, |v103|, |v103|
	s_waitcnt lgkmcnt(0)
	v_max_f32_e32 v105, v105, v105
	v_max_f32_e32 v103, v103, v105
	v_div_scale_f32 v105, s[0:1], v103, v103, 1.0
	v_rcp_f32_e32 v122, v105
	v_mov_b32_e32 v245, v20
	v_fma_f32 v123, -v105, v122, 1.0
	v_fmac_f32_e32 v122, v123, v122
	v_div_scale_f32 v123, vcc, 1.0, v103, 1.0
	v_mul_f32_e32 v124, v123, v122
	v_fma_f32 v125, -v105, v124, v123
	v_fmac_f32_e32 v124, v125, v122
	v_fma_f32 v105, -v105, v124, v123
	v_div_fmas_f32 v105, v105, v122, v124
	v_lshlrev_b64 v[124:125], 11, v[126:127]
	v_lshl_add_u64 v[124:125], v[98:99], 0, v[124:125]
	global_load_dword v242, v[124:125], off
	global_load_dword v243, v[124:125], off offset:128
	global_load_dword v246, v[124:125], off offset:256
	global_load_dword v247, v[124:125], off offset:384
	v_div_fixup_f32 v122, v105, v103, 1.0
	v_mov_b32_e32 v124, v36
	v_mov_b32_e32 v125, v52
	s_waitcnt vmcnt(2)
	v_pk_fma_f32 v[242:243], v[244:245], v[122:123], v[242:243] op_sel_hi:[1,0,1]
	s_nop 0
	v_pk_mul_f32 v[244:245], v[242:243], v[242:243]
	s_waitcnt vmcnt(0)
	v_pk_fma_f32 v[124:125], v[124:125], v[122:123], v[246:247] op_sel_hi:[1,0,1]
	v_add_f32_e32 v103, v244, v245
	v_pk_mul_f32 v[122:123], v[124:125], v[124:125]
	s_nop 0
	v_add_f32_e32 v103, v103, v122
	v_add_f32_e32 v103, v103, v123
	v_mov_b32_e32 v105, v103
	v_mov_b32_e32 v255, v103
	s_nop 1
	v_permlane16_swap_b32_e32 v105, v255
	s_nop 1
	v_mov_b32_dpp v105, v255 quad_perm:[0,1,2,3] row_mask:0x5 bank_mask:0xf
	v_mad_i64_i32 v[122:123], s[0:1], v126, s74, v[106:107]
	v_lshl_add_u64 v[244:245], v[122:123], 0, s[96:97]
	v_lshlrev_b64 v[122:123], 10, v[126:127]
	s_nop 0
	v_add_f32_e32 v103, v103, v105
	s_nop 1
	v_mov_b32_dpp v105, v103 row_ror:8 row_mask:0xf bank_mask:0xf
	v_lshl_add_u64 v[126:127], v[244:245], 0, v[96:97]
	v_lshl_add_u64 v[122:123], s[66:67], 0, v[122:123]
	v_lshl_add_u64 v[122:123], v[122:123], 0, v[96:97]
	s_nop 0
	v_add_f32_e32 v103, v103, v105
	s_nop 1
	v_mov_b32_dpp v105, v103 row_shl:4 row_mask:0xf bank_mask:0x5
	v_mov_b32_dpp v105, v103 row_shr:4 row_mask:0xf bank_mask:0xa
	s_nop 0
	v_add_f32_e32 v103, v103, v105
	s_nop 1
	v_mov_b32_dpp v105, v103 quad_perm:[2,3,0,1] row_mask:0xf bank_mask:0xf
	s_nop 0
	v_add_f32_e32 v103, v103, v105
	s_nop 1
	v_mov_b32_dpp v105, v103 quad_perm:[1,0,3,2] row_mask:0xf bank_mask:0xf
	s_nop 0
	v_add_f32_e32 v103, v103, v105
	v_fmamk_f32 v103, v103, 0x3c000000, v163
	v_cmp_gt_f32_e32 vcc, s86, v103
	v_mul_f32_e32 v105, 0x4b800000, v103
	s_nop 0
	v_cndmask_b32_e32 v103, v103, v105, vcc
	v_rsq_f32_e32 v103, v103
	s_nop 0
	v_mul_f32_e32 v105, 0x45800000, v103
	v_cndmask_b32_e32 v103, v103, v105, vcc
	global_load_ushort v105, v[126:127], off
	v_mul_f32_e32 v126, v242, v103
	global_load_dword v127, v[108:109], off
	v_mul_f32_e32 v124, v124, v103
	s_waitcnt vmcnt(1)
	v_lshlrev_b32_e32 v105, 16, v105
	v_mul_f32_e32 v105, 0xbfb8aa3b, v105
	v_exp_f32_e32 v105, v105
	s_waitcnt vmcnt(0)
	v_mul_f32_e32 v126, v127, v126
	v_add_f32_e32 v105, 1.0, v105
	v_rcp_f32_e32 v105, v105
	s_nop 0
	v_mul_f32_e32 v105, v105, v126
	v_cvt_pk_bf16_f32 v105, v105, s0
	v_lshl_add_u64 v[126:127], v[244:245], 0, v[112:113]
	global_store_short v[122:123], v105, off
	global_load_ushort v105, v[126:127], off
	v_mul_f32_e32 v126, v243, v103
	global_load_dword v127, v[110:111], off offset:128
	v_mul_f32_e32 v103, v125, v103
	s_waitcnt vmcnt(1)
	v_lshlrev_b32_e32 v105, 16, v105
	v_mul_f32_e32 v105, 0xbfb8aa3b, v105
	v_exp_f32_e32 v105, v105
	s_waitcnt vmcnt(0)
	v_mul_f32_e32 v126, v127, v126
	v_add_f32_e32 v105, 1.0, v105
	v_rcp_f32_e32 v105, v105
	s_nop 0
	v_mul_f32_e32 v105, v105, v126
	v_cvt_pk_bf16_f32 v105, v105, s0
	v_lshl_add_u64 v[126:127], v[244:245], 0, v[118:119]
	global_store_short v[122:123], v105, off offset:64
	global_load_ushort v105, v[126:127], off
	s_waitcnt vmcnt(0)
	v_lshlrev_b32_e32 v105, 16, v105
	global_load_dword v126, v[110:111], off offset:256
	v_mul_f32_e32 v105, 0xbfb8aa3b, v105
	v_exp_f32_e32 v105, v105
	s_waitcnt vmcnt(0)
	v_mul_f32_e32 v124, v126, v124
	v_add_f32_e32 v105, 1.0, v105
	v_rcp_f32_e32 v105, v105
	v_lshl_add_u64 v[126:127], v[244:245], 0, v[120:121]
	v_mul_f32_e32 v105, v124, v105
	v_cvt_pk_bf16_f32 v105, v105, s0
	global_store_short v[122:123], v105, off offset:128
	global_load_ushort v105, v[126:127], off
	s_waitcnt vmcnt(0)
	v_lshlrev_b32_e32 v105, 16, v105
	global_load_dword v124, v[110:111], off offset:384
	v_mul_f32_e32 v105, 0xbfb8aa3b, v105
	v_exp_f32_e32 v105, v105
	s_waitcnt vmcnt(0)
	v_mul_f32_e32 v103, v124, v103
	v_add_f32_e32 v105, 1.0, v105
	v_rcp_f32_e32 v105, v105
	s_nop 0
	v_mul_f32_e32 v103, v103, v105
	v_cvt_pk_bf16_f32 v103, v103, s0
	global_store_short v[122:123], v103, off offset:192
	ds_read_b32 v103, v238 offset:36
	ds_read_b32 v105, v239 offset:36
	v_add_u32_e32 v126, 9, v100
	v_ashrrev_i32_e32 v127, 31, v126
	v_mov_b32_e32 v244, v5
	s_waitcnt lgkmcnt(1)
	v_max_f32_e64 v103, |v103|, |v103|
	s_waitcnt lgkmcnt(0)
	v_max_f32_e32 v105, v105, v105
	v_max_f32_e32 v103, v103, v105
	v_div_scale_f32 v105, s[0:1], v103, v103, 1.0
	v_rcp_f32_e32 v122, v105
	v_mov_b32_e32 v245, v21
	v_fma_f32 v123, -v105, v122, 1.0
	v_fmac_f32_e32 v122, v123, v122
	v_div_scale_f32 v123, vcc, 1.0, v103, 1.0
	v_mul_f32_e32 v124, v123, v122
	v_fma_f32 v125, -v105, v124, v123
	v_fmac_f32_e32 v124, v125, v122
	v_fma_f32 v105, -v105, v124, v123
	v_div_fmas_f32 v105, v105, v122, v124
	v_lshlrev_b64 v[124:125], 11, v[126:127]
	v_lshl_add_u64 v[124:125], v[98:99], 0, v[124:125]
	global_load_dword v242, v[124:125], off
	global_load_dword v243, v[124:125], off offset:128
	global_load_dword v246, v[124:125], off offset:256
	global_load_dword v247, v[124:125], off offset:384
	v_div_fixup_f32 v122, v105, v103, 1.0
	v_mov_b32_e32 v124, v37
	v_mov_b32_e32 v125, v53
	s_waitcnt vmcnt(2)
	v_pk_fma_f32 v[242:243], v[244:245], v[122:123], v[242:243] op_sel_hi:[1,0,1]
	s_nop 0
	v_pk_mul_f32 v[244:245], v[242:243], v[242:243]
	s_waitcnt vmcnt(0)
	v_pk_fma_f32 v[124:125], v[124:125], v[122:123], v[246:247] op_sel_hi:[1,0,1]
	v_add_f32_e32 v103, v244, v245
	v_pk_mul_f32 v[122:123], v[124:125], v[124:125]
	s_nop 0
	v_add_f32_e32 v103, v103, v122
	v_add_f32_e32 v103, v103, v123
	v_mov_b32_e32 v105, v103
	v_mov_b32_e32 v255, v103
	s_nop 1
	v_permlane16_swap_b32_e32 v105, v255
	s_nop 1
	v_mov_b32_dpp v105, v255 quad_perm:[0,1,2,3] row_mask:0x5 bank_mask:0xf
	v_mad_i64_i32 v[122:123], s[0:1], v126, s74, v[106:107]
	v_lshl_add_u64 v[244:245], v[122:123], 0, s[96:97]
	v_lshlrev_b64 v[122:123], 10, v[126:127]
	s_nop 0
	v_add_f32_e32 v103, v103, v105
	s_nop 1
	v_mov_b32_dpp v105, v103 row_ror:8 row_mask:0xf bank_mask:0xf
	v_lshl_add_u64 v[126:127], v[244:245], 0, v[96:97]
	v_lshl_add_u64 v[122:123], s[66:67], 0, v[122:123]
	v_lshl_add_u64 v[122:123], v[122:123], 0, v[96:97]
	s_nop 0
	v_add_f32_e32 v103, v103, v105
	s_nop 1
	v_mov_b32_dpp v105, v103 row_shl:4 row_mask:0xf bank_mask:0x5
	v_mov_b32_dpp v105, v103 row_shr:4 row_mask:0xf bank_mask:0xa
	s_nop 0
	v_add_f32_e32 v103, v103, v105
	s_nop 1
	v_mov_b32_dpp v105, v103 quad_perm:[2,3,0,1] row_mask:0xf bank_mask:0xf
	s_nop 0
	v_add_f32_e32 v103, v103, v105
	s_nop 1
	v_mov_b32_dpp v105, v103 quad_perm:[1,0,3,2] row_mask:0xf bank_mask:0xf
	s_nop 0
	v_add_f32_e32 v103, v103, v105
	v_fmamk_f32 v103, v103, 0x3c000000, v163
	v_cmp_gt_f32_e32 vcc, s86, v103
	v_mul_f32_e32 v105, 0x4b800000, v103
	s_nop 0
	v_cndmask_b32_e32 v103, v103, v105, vcc
	v_rsq_f32_e32 v103, v103
	s_nop 0
	v_mul_f32_e32 v105, 0x45800000, v103
	v_cndmask_b32_e32 v103, v103, v105, vcc
	global_load_ushort v105, v[126:127], off
	v_mul_f32_e32 v126, v242, v103
	global_load_dword v127, v[108:109], off
	v_mul_f32_e32 v124, v124, v103
	s_waitcnt vmcnt(1)
	v_lshlrev_b32_e32 v105, 16, v105
	v_mul_f32_e32 v105, 0xbfb8aa3b, v105
	v_exp_f32_e32 v105, v105
	s_waitcnt vmcnt(0)
	v_mul_f32_e32 v126, v127, v126
	v_add_f32_e32 v105, 1.0, v105
	v_rcp_f32_e32 v105, v105
	s_nop 0
	v_mul_f32_e32 v105, v105, v126
	v_cvt_pk_bf16_f32 v105, v105, s0
	v_lshl_add_u64 v[126:127], v[244:245], 0, v[112:113]
	global_store_short v[122:123], v105, off
	global_load_ushort v105, v[126:127], off
	v_mul_f32_e32 v126, v243, v103
	global_load_dword v127, v[110:111], off offset:128
	v_mul_f32_e32 v103, v125, v103
	s_waitcnt vmcnt(1)
	v_lshlrev_b32_e32 v105, 16, v105
	v_mul_f32_e32 v105, 0xbfb8aa3b, v105
	v_exp_f32_e32 v105, v105
	s_waitcnt vmcnt(0)
	v_mul_f32_e32 v126, v127, v126
	v_add_f32_e32 v105, 1.0, v105
	v_rcp_f32_e32 v105, v105
	s_nop 0
	v_mul_f32_e32 v105, v105, v126
	v_cvt_pk_bf16_f32 v105, v105, s0
	v_lshl_add_u64 v[126:127], v[244:245], 0, v[118:119]
	global_store_short v[122:123], v105, off offset:64
	global_load_ushort v105, v[126:127], off
	s_waitcnt vmcnt(0)
	v_lshlrev_b32_e32 v105, 16, v105
	global_load_dword v126, v[110:111], off offset:256
	v_mul_f32_e32 v105, 0xbfb8aa3b, v105
	v_exp_f32_e32 v105, v105
	s_waitcnt vmcnt(0)
	v_mul_f32_e32 v124, v126, v124
	v_add_f32_e32 v105, 1.0, v105
	v_rcp_f32_e32 v105, v105
	v_lshl_add_u64 v[126:127], v[244:245], 0, v[120:121]
	v_mul_f32_e32 v105, v124, v105
	v_cvt_pk_bf16_f32 v105, v105, s0
	global_store_short v[122:123], v105, off offset:128
	global_load_ushort v105, v[126:127], off
	s_waitcnt vmcnt(0)
	v_lshlrev_b32_e32 v105, 16, v105
	global_load_dword v124, v[110:111], off offset:384
	v_mul_f32_e32 v105, 0xbfb8aa3b, v105
	v_exp_f32_e32 v105, v105
	s_waitcnt vmcnt(0)
	v_mul_f32_e32 v103, v124, v103
	v_add_f32_e32 v105, 1.0, v105
	v_rcp_f32_e32 v105, v105
	s_nop 0
	v_mul_f32_e32 v103, v103, v105
	v_cvt_pk_bf16_f32 v103, v103, s0
	global_store_short v[122:123], v103, off offset:192
	ds_read_b32 v103, v238 offset:40
	ds_read_b32 v105, v239 offset:40
	v_add_u32_e32 v126, 10, v100
	v_ashrrev_i32_e32 v127, 31, v126
	v_mov_b32_e32 v244, v6
	s_waitcnt lgkmcnt(1)
	v_max_f32_e64 v103, |v103|, |v103|
	s_waitcnt lgkmcnt(0)
	v_max_f32_e32 v105, v105, v105
	v_max_f32_e32 v103, v103, v105
	v_div_scale_f32 v105, s[0:1], v103, v103, 1.0
	v_rcp_f32_e32 v122, v105
	v_mov_b32_e32 v245, v22
	v_fma_f32 v123, -v105, v122, 1.0
	v_fmac_f32_e32 v122, v123, v122
	v_div_scale_f32 v123, vcc, 1.0, v103, 1.0
	v_mul_f32_e32 v124, v123, v122
	v_fma_f32 v125, -v105, v124, v123
	v_fmac_f32_e32 v124, v125, v122
	v_fma_f32 v105, -v105, v124, v123
	v_div_fmas_f32 v105, v105, v122, v124
	v_lshlrev_b64 v[124:125], 11, v[126:127]
	v_lshl_add_u64 v[124:125], v[98:99], 0, v[124:125]
	global_load_dword v242, v[124:125], off
	global_load_dword v243, v[124:125], off offset:128
	global_load_dword v246, v[124:125], off offset:256
	global_load_dword v247, v[124:125], off offset:384
	v_div_fixup_f32 v122, v105, v103, 1.0
	v_mov_b32_e32 v124, v38
	v_mov_b32_e32 v125, v54
	s_waitcnt vmcnt(2)
	v_pk_fma_f32 v[242:243], v[244:245], v[122:123], v[242:243] op_sel_hi:[1,0,1]
	s_nop 0
	v_pk_mul_f32 v[244:245], v[242:243], v[242:243]
	s_waitcnt vmcnt(0)
	v_pk_fma_f32 v[124:125], v[124:125], v[122:123], v[246:247] op_sel_hi:[1,0,1]
	v_add_f32_e32 v103, v244, v245
	v_pk_mul_f32 v[122:123], v[124:125], v[124:125]
	s_nop 0
	v_add_f32_e32 v103, v103, v122
	v_add_f32_e32 v103, v103, v123
	v_mov_b32_e32 v105, v103
	v_mov_b32_e32 v255, v103
	s_nop 1
	v_permlane16_swap_b32_e32 v105, v255
	s_nop 1
	v_mov_b32_dpp v105, v255 quad_perm:[0,1,2,3] row_mask:0x5 bank_mask:0xf
	v_mad_i64_i32 v[122:123], s[0:1], v126, s74, v[106:107]
	v_lshl_add_u64 v[244:245], v[122:123], 0, s[96:97]
	v_lshlrev_b64 v[122:123], 10, v[126:127]
	s_nop 0
	v_add_f32_e32 v103, v103, v105
	s_nop 1
	v_mov_b32_dpp v105, v103 row_ror:8 row_mask:0xf bank_mask:0xf
	v_lshl_add_u64 v[126:127], v[244:245], 0, v[96:97]
	v_lshl_add_u64 v[122:123], s[66:67], 0, v[122:123]
	v_lshl_add_u64 v[122:123], v[122:123], 0, v[96:97]
	s_nop 0
	v_add_f32_e32 v103, v103, v105
	s_nop 1
	v_mov_b32_dpp v105, v103 row_shl:4 row_mask:0xf bank_mask:0x5
	v_mov_b32_dpp v105, v103 row_shr:4 row_mask:0xf bank_mask:0xa
	s_nop 0
	v_add_f32_e32 v103, v103, v105
	s_nop 1
	v_mov_b32_dpp v105, v103 quad_perm:[2,3,0,1] row_mask:0xf bank_mask:0xf
	s_nop 0
	v_add_f32_e32 v103, v103, v105
	s_nop 1
	v_mov_b32_dpp v105, v103 quad_perm:[1,0,3,2] row_mask:0xf bank_mask:0xf
	s_nop 0
	v_add_f32_e32 v103, v103, v105
	v_fmamk_f32 v103, v103, 0x3c000000, v163
	v_cmp_gt_f32_e32 vcc, s86, v103
	v_mul_f32_e32 v105, 0x4b800000, v103
	s_nop 0
	v_cndmask_b32_e32 v103, v103, v105, vcc
	v_rsq_f32_e32 v103, v103
	s_nop 0
	v_mul_f32_e32 v105, 0x45800000, v103
	v_cndmask_b32_e32 v103, v103, v105, vcc
	global_load_ushort v105, v[126:127], off
	v_mul_f32_e32 v126, v242, v103
	global_load_dword v127, v[108:109], off
	v_mul_f32_e32 v124, v124, v103
	s_waitcnt vmcnt(1)
	v_lshlrev_b32_e32 v105, 16, v105
	v_mul_f32_e32 v105, 0xbfb8aa3b, v105
	v_exp_f32_e32 v105, v105
	s_waitcnt vmcnt(0)
	v_mul_f32_e32 v126, v127, v126
	v_add_f32_e32 v105, 1.0, v105
	v_rcp_f32_e32 v105, v105
	s_nop 0
	v_mul_f32_e32 v105, v105, v126
	v_cvt_pk_bf16_f32 v105, v105, s0
	v_lshl_add_u64 v[126:127], v[244:245], 0, v[112:113]
	global_store_short v[122:123], v105, off
	global_load_ushort v105, v[126:127], off
	v_mul_f32_e32 v126, v243, v103
	global_load_dword v127, v[110:111], off offset:128
	v_mul_f32_e32 v103, v125, v103
	s_waitcnt vmcnt(1)
	v_lshlrev_b32_e32 v105, 16, v105
	v_mul_f32_e32 v105, 0xbfb8aa3b, v105
	v_exp_f32_e32 v105, v105
	s_waitcnt vmcnt(0)
	v_mul_f32_e32 v126, v127, v126
	v_add_f32_e32 v105, 1.0, v105
	v_rcp_f32_e32 v105, v105
	s_nop 0
	v_mul_f32_e32 v105, v105, v126
	v_cvt_pk_bf16_f32 v105, v105, s0
	v_lshl_add_u64 v[126:127], v[244:245], 0, v[118:119]
	global_store_short v[122:123], v105, off offset:64
	global_load_ushort v105, v[126:127], off
	s_waitcnt vmcnt(0)
	v_lshlrev_b32_e32 v105, 16, v105
	global_load_dword v126, v[110:111], off offset:256
	v_mul_f32_e32 v105, 0xbfb8aa3b, v105
	v_exp_f32_e32 v105, v105
	s_waitcnt vmcnt(0)
	v_mul_f32_e32 v124, v126, v124
	v_add_f32_e32 v105, 1.0, v105
	v_rcp_f32_e32 v105, v105
	v_lshl_add_u64 v[126:127], v[244:245], 0, v[120:121]
	v_mul_f32_e32 v105, v124, v105
	v_cvt_pk_bf16_f32 v105, v105, s0
	global_store_short v[122:123], v105, off offset:128
	global_load_ushort v105, v[126:127], off
	s_waitcnt vmcnt(0)
	v_lshlrev_b32_e32 v105, 16, v105
	global_load_dword v124, v[110:111], off offset:384
	v_mul_f32_e32 v105, 0xbfb8aa3b, v105
	v_exp_f32_e32 v105, v105
	s_waitcnt vmcnt(0)
	v_mul_f32_e32 v103, v124, v103
	v_add_f32_e32 v105, 1.0, v105
	v_rcp_f32_e32 v105, v105
	s_nop 0
	v_mul_f32_e32 v103, v103, v105
	v_cvt_pk_bf16_f32 v103, v103, s0
	global_store_short v[122:123], v103, off offset:192
	ds_read_b32 v103, v238 offset:44
	ds_read_b32 v105, v239 offset:44
	v_add_u32_e32 v126, 11, v100
	v_ashrrev_i32_e32 v127, 31, v126
	v_mov_b32_e32 v244, v7
	s_waitcnt lgkmcnt(1)
	v_max_f32_e64 v103, |v103|, |v103|
	s_waitcnt lgkmcnt(0)
	v_max_f32_e32 v105, v105, v105
	v_max_f32_e32 v103, v103, v105
	v_div_scale_f32 v105, s[0:1], v103, v103, 1.0
	v_rcp_f32_e32 v122, v105
	v_mov_b32_e32 v245, v23
	v_fma_f32 v123, -v105, v122, 1.0
	v_fmac_f32_e32 v122, v123, v122
	v_div_scale_f32 v123, vcc, 1.0, v103, 1.0
	v_mul_f32_e32 v124, v123, v122
	v_fma_f32 v125, -v105, v124, v123
	v_fmac_f32_e32 v124, v125, v122
	v_fma_f32 v105, -v105, v124, v123
	v_div_fmas_f32 v105, v105, v122, v124
	v_lshlrev_b64 v[124:125], 11, v[126:127]
	v_lshl_add_u64 v[124:125], v[98:99], 0, v[124:125]
	global_load_dword v242, v[124:125], off
	global_load_dword v243, v[124:125], off offset:128
	global_load_dword v246, v[124:125], off offset:256
	global_load_dword v247, v[124:125], off offset:384
	v_div_fixup_f32 v122, v105, v103, 1.0
	v_mov_b32_e32 v124, v39
	v_mov_b32_e32 v125, v55
	s_waitcnt vmcnt(2)
	v_pk_fma_f32 v[242:243], v[244:245], v[122:123], v[242:243] op_sel_hi:[1,0,1]
	s_nop 0
	v_pk_mul_f32 v[244:245], v[242:243], v[242:243]
	s_waitcnt vmcnt(0)
	v_pk_fma_f32 v[124:125], v[124:125], v[122:123], v[246:247] op_sel_hi:[1,0,1]
	v_add_f32_e32 v103, v244, v245
	v_pk_mul_f32 v[122:123], v[124:125], v[124:125]
	s_nop 0
	v_add_f32_e32 v103, v103, v122
	v_add_f32_e32 v103, v103, v123
	v_mov_b32_e32 v105, v103
	v_mov_b32_e32 v255, v103
	s_nop 1
	v_permlane16_swap_b32_e32 v105, v255
	s_nop 1
	v_mov_b32_dpp v105, v255 quad_perm:[0,1,2,3] row_mask:0x5 bank_mask:0xf
	v_mad_i64_i32 v[122:123], s[0:1], v126, s74, v[106:107]
	v_lshl_add_u64 v[244:245], v[122:123], 0, s[96:97]
	v_lshlrev_b64 v[122:123], 10, v[126:127]
	s_nop 0
	v_add_f32_e32 v103, v103, v105
	s_nop 1
	v_mov_b32_dpp v105, v103 row_ror:8 row_mask:0xf bank_mask:0xf
	v_lshl_add_u64 v[126:127], v[244:245], 0, v[96:97]
	v_lshl_add_u64 v[122:123], s[66:67], 0, v[122:123]
	v_lshl_add_u64 v[122:123], v[122:123], 0, v[96:97]
	s_nop 0
	v_add_f32_e32 v103, v103, v105
	s_nop 1
	v_mov_b32_dpp v105, v103 row_shl:4 row_mask:0xf bank_mask:0x5
	v_mov_b32_dpp v105, v103 row_shr:4 row_mask:0xf bank_mask:0xa
	s_nop 0
	v_add_f32_e32 v103, v103, v105
	s_nop 1
	v_mov_b32_dpp v105, v103 quad_perm:[2,3,0,1] row_mask:0xf bank_mask:0xf
	s_nop 0
	v_add_f32_e32 v103, v103, v105
	s_nop 1
	v_mov_b32_dpp v105, v103 quad_perm:[1,0,3,2] row_mask:0xf bank_mask:0xf
	s_nop 0
	v_add_f32_e32 v103, v103, v105
	v_fmamk_f32 v103, v103, 0x3c000000, v163
	v_cmp_gt_f32_e32 vcc, s86, v103
	v_mul_f32_e32 v105, 0x4b800000, v103
	s_nop 0
	v_cndmask_b32_e32 v103, v103, v105, vcc
	v_rsq_f32_e32 v103, v103
	s_nop 0
	v_mul_f32_e32 v105, 0x45800000, v103
	v_cndmask_b32_e32 v103, v103, v105, vcc
	global_load_ushort v105, v[126:127], off
	v_mul_f32_e32 v126, v242, v103
	global_load_dword v127, v[108:109], off
	v_mul_f32_e32 v124, v124, v103
	s_waitcnt vmcnt(1)
	v_lshlrev_b32_e32 v105, 16, v105
	v_mul_f32_e32 v105, 0xbfb8aa3b, v105
	v_exp_f32_e32 v105, v105
	s_waitcnt vmcnt(0)
	v_mul_f32_e32 v126, v127, v126
	v_add_f32_e32 v105, 1.0, v105
	v_rcp_f32_e32 v105, v105
	s_nop 0
	v_mul_f32_e32 v105, v105, v126
	v_cvt_pk_bf16_f32 v105, v105, s0
	v_lshl_add_u64 v[126:127], v[244:245], 0, v[112:113]
	global_store_short v[122:123], v105, off
	global_load_ushort v105, v[126:127], off
	v_mul_f32_e32 v126, v243, v103
	global_load_dword v127, v[110:111], off offset:128
	v_mul_f32_e32 v103, v125, v103
	s_waitcnt vmcnt(1)
	v_lshlrev_b32_e32 v105, 16, v105
	v_mul_f32_e32 v105, 0xbfb8aa3b, v105
	v_exp_f32_e32 v105, v105
	s_waitcnt vmcnt(0)
	v_mul_f32_e32 v126, v127, v126
	v_add_f32_e32 v105, 1.0, v105
	v_rcp_f32_e32 v105, v105
	s_nop 0
	v_mul_f32_e32 v105, v105, v126
	v_cvt_pk_bf16_f32 v105, v105, s0
	v_lshl_add_u64 v[126:127], v[244:245], 0, v[118:119]
	global_store_short v[122:123], v105, off offset:64
	global_load_ushort v105, v[126:127], off
	s_waitcnt vmcnt(0)
	v_lshlrev_b32_e32 v105, 16, v105
	global_load_dword v126, v[110:111], off offset:256
	v_mul_f32_e32 v105, 0xbfb8aa3b, v105
	v_exp_f32_e32 v105, v105
	s_waitcnt vmcnt(0)
	v_mul_f32_e32 v124, v126, v124
	v_add_f32_e32 v105, 1.0, v105
	v_rcp_f32_e32 v105, v105
	v_lshl_add_u64 v[126:127], v[244:245], 0, v[120:121]
	v_mul_f32_e32 v105, v124, v105
	v_cvt_pk_bf16_f32 v105, v105, s0
	global_store_short v[122:123], v105, off offset:128
	global_load_ushort v105, v[126:127], off
	s_waitcnt vmcnt(0)
	v_lshlrev_b32_e32 v105, 16, v105
	global_load_dword v124, v[110:111], off offset:384
	v_mul_f32_e32 v105, 0xbfb8aa3b, v105
	v_exp_f32_e32 v105, v105
	s_waitcnt vmcnt(0)
	v_mul_f32_e32 v103, v124, v103
	v_add_f32_e32 v105, 1.0, v105
	v_rcp_f32_e32 v105, v105
	s_nop 0
	v_mul_f32_e32 v103, v103, v105
	v_cvt_pk_bf16_f32 v103, v103, s0
	global_store_short v[122:123], v103, off offset:192
	ds_read_b32 v103, v238 offset:64
	ds_read_b32 v105, v239 offset:64
	v_add_u32_e32 v126, 16, v100
	v_ashrrev_i32_e32 v127, 31, v126
	v_mov_b32_e32 v244, v8
	s_waitcnt lgkmcnt(1)
	v_max_f32_e64 v103, |v103|, |v103|
	s_waitcnt lgkmcnt(0)
	v_max_f32_e32 v105, v105, v105
	v_max_f32_e32 v103, v103, v105
	v_div_scale_f32 v105, s[0:1], v103, v103, 1.0
	v_rcp_f32_e32 v122, v105
	v_mov_b32_e32 v245, v24
	v_fma_f32 v123, -v105, v122, 1.0
	v_fmac_f32_e32 v122, v123, v122
	v_div_scale_f32 v123, vcc, 1.0, v103, 1.0
	v_mul_f32_e32 v124, v123, v122
	v_fma_f32 v125, -v105, v124, v123
	v_fmac_f32_e32 v124, v125, v122
	v_fma_f32 v105, -v105, v124, v123
	v_div_fmas_f32 v105, v105, v122, v124
	v_lshlrev_b64 v[124:125], 11, v[126:127]
	v_lshl_add_u64 v[124:125], v[98:99], 0, v[124:125]
	global_load_dword v242, v[124:125], off
	global_load_dword v243, v[124:125], off offset:128
	global_load_dword v246, v[124:125], off offset:256
	global_load_dword v247, v[124:125], off offset:384
	v_div_fixup_f32 v122, v105, v103, 1.0
	v_mov_b32_e32 v124, v40
	v_mov_b32_e32 v125, v56
	s_waitcnt vmcnt(2)
	v_pk_fma_f32 v[242:243], v[244:245], v[122:123], v[242:243] op_sel_hi:[1,0,1]
	s_nop 0
	v_pk_mul_f32 v[244:245], v[242:243], v[242:243]
	s_waitcnt vmcnt(0)
	v_pk_fma_f32 v[124:125], v[124:125], v[122:123], v[246:247] op_sel_hi:[1,0,1]
	v_add_f32_e32 v103, v244, v245
	v_pk_mul_f32 v[122:123], v[124:125], v[124:125]
	s_nop 0
	v_add_f32_e32 v103, v103, v122
	v_add_f32_e32 v103, v103, v123
	v_mov_b32_e32 v105, v103
	v_mov_b32_e32 v255, v103
	s_nop 1
	v_permlane16_swap_b32_e32 v105, v255
	s_nop 1
	v_mov_b32_dpp v105, v255 quad_perm:[0,1,2,3] row_mask:0x5 bank_mask:0xf
	v_mad_i64_i32 v[122:123], s[0:1], v126, s74, v[106:107]
	v_lshl_add_u64 v[244:245], v[122:123], 0, s[96:97]
	v_lshlrev_b64 v[122:123], 10, v[126:127]
	s_nop 0
	v_add_f32_e32 v103, v103, v105
	s_nop 1
	v_mov_b32_dpp v105, v103 row_ror:8 row_mask:0xf bank_mask:0xf
	v_lshl_add_u64 v[126:127], v[244:245], 0, v[96:97]
	v_lshl_add_u64 v[122:123], s[66:67], 0, v[122:123]
	v_lshl_add_u64 v[122:123], v[122:123], 0, v[96:97]
	s_nop 0
	v_add_f32_e32 v103, v103, v105
	s_nop 1
	v_mov_b32_dpp v105, v103 row_shl:4 row_mask:0xf bank_mask:0x5
	v_mov_b32_dpp v105, v103 row_shr:4 row_mask:0xf bank_mask:0xa
	s_nop 0
	v_add_f32_e32 v103, v103, v105
	s_nop 1
	v_mov_b32_dpp v105, v103 quad_perm:[2,3,0,1] row_mask:0xf bank_mask:0xf
	s_nop 0
	v_add_f32_e32 v103, v103, v105
	s_nop 1
	v_mov_b32_dpp v105, v103 quad_perm:[1,0,3,2] row_mask:0xf bank_mask:0xf
	s_nop 0
	v_add_f32_e32 v103, v103, v105
	v_fmamk_f32 v103, v103, 0x3c000000, v163
	v_cmp_gt_f32_e32 vcc, s86, v103
	v_mul_f32_e32 v105, 0x4b800000, v103
	s_nop 0
	v_cndmask_b32_e32 v103, v103, v105, vcc
	v_rsq_f32_e32 v103, v103
	s_nop 0
	v_mul_f32_e32 v105, 0x45800000, v103
	v_cndmask_b32_e32 v103, v103, v105, vcc
	global_load_ushort v105, v[126:127], off
	v_mul_f32_e32 v126, v242, v103
	global_load_dword v127, v[108:109], off
	v_mul_f32_e32 v124, v124, v103
	s_waitcnt vmcnt(1)
	v_lshlrev_b32_e32 v105, 16, v105
	v_mul_f32_e32 v105, 0xbfb8aa3b, v105
	v_exp_f32_e32 v105, v105
	s_waitcnt vmcnt(0)
	v_mul_f32_e32 v126, v127, v126
	v_add_f32_e32 v105, 1.0, v105
	v_rcp_f32_e32 v105, v105
	s_nop 0
	v_mul_f32_e32 v105, v105, v126
	v_cvt_pk_bf16_f32 v105, v105, s0
	v_lshl_add_u64 v[126:127], v[244:245], 0, v[112:113]
	global_store_short v[122:123], v105, off
	global_load_ushort v105, v[126:127], off
	v_mul_f32_e32 v126, v243, v103
	global_load_dword v127, v[110:111], off offset:128
	v_mul_f32_e32 v103, v125, v103
	s_waitcnt vmcnt(1)
	v_lshlrev_b32_e32 v105, 16, v105
	v_mul_f32_e32 v105, 0xbfb8aa3b, v105
	v_exp_f32_e32 v105, v105
	s_waitcnt vmcnt(0)
	v_mul_f32_e32 v126, v127, v126
	v_add_f32_e32 v105, 1.0, v105
	v_rcp_f32_e32 v105, v105
	s_nop 0
	v_mul_f32_e32 v105, v105, v126
	v_cvt_pk_bf16_f32 v105, v105, s0
	v_lshl_add_u64 v[126:127], v[244:245], 0, v[118:119]
	global_store_short v[122:123], v105, off offset:64
	global_load_ushort v105, v[126:127], off
	s_waitcnt vmcnt(0)
	v_lshlrev_b32_e32 v105, 16, v105
	global_load_dword v126, v[110:111], off offset:256
	v_mul_f32_e32 v105, 0xbfb8aa3b, v105
	v_exp_f32_e32 v105, v105
	s_waitcnt vmcnt(0)
	v_mul_f32_e32 v124, v126, v124
	v_add_f32_e32 v105, 1.0, v105
	v_rcp_f32_e32 v105, v105
	v_lshl_add_u64 v[126:127], v[244:245], 0, v[120:121]
	v_mul_f32_e32 v105, v124, v105
	v_cvt_pk_bf16_f32 v105, v105, s0
	global_store_short v[122:123], v105, off offset:128
	global_load_ushort v105, v[126:127], off
	s_waitcnt vmcnt(0)
	v_lshlrev_b32_e32 v105, 16, v105
	global_load_dword v124, v[110:111], off offset:384
	v_mul_f32_e32 v105, 0xbfb8aa3b, v105
	v_exp_f32_e32 v105, v105
	s_waitcnt vmcnt(0)
	v_mul_f32_e32 v103, v124, v103
	v_add_f32_e32 v105, 1.0, v105
	v_rcp_f32_e32 v105, v105
	s_nop 0
	v_mul_f32_e32 v103, v103, v105
	v_cvt_pk_bf16_f32 v103, v103, s0
	global_store_short v[122:123], v103, off offset:192
	ds_read_b32 v103, v238 offset:68
	ds_read_b32 v105, v239 offset:68
	v_add_u32_e32 v126, 17, v100
	v_ashrrev_i32_e32 v127, 31, v126
	v_mov_b32_e32 v244, v9
	s_waitcnt lgkmcnt(1)
	v_max_f32_e64 v103, |v103|, |v103|
	s_waitcnt lgkmcnt(0)
	v_max_f32_e32 v105, v105, v105
	v_max_f32_e32 v103, v103, v105
	v_div_scale_f32 v105, s[0:1], v103, v103, 1.0
	v_rcp_f32_e32 v122, v105
	v_mov_b32_e32 v245, v25
	v_fma_f32 v123, -v105, v122, 1.0
	v_fmac_f32_e32 v122, v123, v122
	v_div_scale_f32 v123, vcc, 1.0, v103, 1.0
	v_mul_f32_e32 v124, v123, v122
	v_fma_f32 v125, -v105, v124, v123
	v_fmac_f32_e32 v124, v125, v122
	v_fma_f32 v105, -v105, v124, v123
	v_div_fmas_f32 v105, v105, v122, v124
	v_lshlrev_b64 v[124:125], 11, v[126:127]
	v_lshl_add_u64 v[124:125], v[98:99], 0, v[124:125]
	global_load_dword v242, v[124:125], off
	global_load_dword v243, v[124:125], off offset:128
	global_load_dword v246, v[124:125], off offset:256
	global_load_dword v247, v[124:125], off offset:384
	v_div_fixup_f32 v122, v105, v103, 1.0
	v_mov_b32_e32 v124, v41
	v_mov_b32_e32 v125, v57
	s_waitcnt vmcnt(2)
	v_pk_fma_f32 v[242:243], v[244:245], v[122:123], v[242:243] op_sel_hi:[1,0,1]
	s_nop 0
	v_pk_mul_f32 v[244:245], v[242:243], v[242:243]
	s_waitcnt vmcnt(0)
	v_pk_fma_f32 v[124:125], v[124:125], v[122:123], v[246:247] op_sel_hi:[1,0,1]
	v_add_f32_e32 v103, v244, v245
	v_pk_mul_f32 v[122:123], v[124:125], v[124:125]
	s_nop 0
	v_add_f32_e32 v103, v103, v122
	v_add_f32_e32 v103, v103, v123
	v_mov_b32_e32 v105, v103
	v_mov_b32_e32 v255, v103
	s_nop 1
	v_permlane16_swap_b32_e32 v105, v255
	s_nop 1
	v_mov_b32_dpp v105, v255 quad_perm:[0,1,2,3] row_mask:0x5 bank_mask:0xf
	v_mad_i64_i32 v[122:123], s[0:1], v126, s74, v[106:107]
	v_lshl_add_u64 v[244:245], v[122:123], 0, s[96:97]
	v_lshlrev_b64 v[122:123], 10, v[126:127]
	s_nop 0
	v_add_f32_e32 v103, v103, v105
	s_nop 1
	v_mov_b32_dpp v105, v103 row_ror:8 row_mask:0xf bank_mask:0xf
	v_lshl_add_u64 v[126:127], v[244:245], 0, v[96:97]
	v_lshl_add_u64 v[122:123], s[66:67], 0, v[122:123]
	v_lshl_add_u64 v[122:123], v[122:123], 0, v[96:97]
	s_nop 0
	v_add_f32_e32 v103, v103, v105
	s_nop 1
	v_mov_b32_dpp v105, v103 row_shl:4 row_mask:0xf bank_mask:0x5
	v_mov_b32_dpp v105, v103 row_shr:4 row_mask:0xf bank_mask:0xa
	s_nop 0
	v_add_f32_e32 v103, v103, v105
	s_nop 1
	v_mov_b32_dpp v105, v103 quad_perm:[2,3,0,1] row_mask:0xf bank_mask:0xf
	s_nop 0
	v_add_f32_e32 v103, v103, v105
	s_nop 1
	v_mov_b32_dpp v105, v103 quad_perm:[1,0,3,2] row_mask:0xf bank_mask:0xf
	s_nop 0
	v_add_f32_e32 v103, v103, v105
	v_fmamk_f32 v103, v103, 0x3c000000, v163
	v_cmp_gt_f32_e32 vcc, s86, v103
	v_mul_f32_e32 v105, 0x4b800000, v103
	s_nop 0
	v_cndmask_b32_e32 v103, v103, v105, vcc
	v_rsq_f32_e32 v103, v103
	s_nop 0
	v_mul_f32_e32 v105, 0x45800000, v103
	v_cndmask_b32_e32 v103, v103, v105, vcc
	global_load_ushort v105, v[126:127], off
	v_mul_f32_e32 v126, v242, v103
	global_load_dword v127, v[108:109], off
	v_mul_f32_e32 v124, v124, v103
	s_waitcnt vmcnt(1)
	v_lshlrev_b32_e32 v105, 16, v105
	v_mul_f32_e32 v105, 0xbfb8aa3b, v105
	v_exp_f32_e32 v105, v105
	s_waitcnt vmcnt(0)
	v_mul_f32_e32 v126, v127, v126
	v_add_f32_e32 v105, 1.0, v105
	v_rcp_f32_e32 v105, v105
	s_nop 0
	v_mul_f32_e32 v105, v105, v126
	v_cvt_pk_bf16_f32 v105, v105, s0
	v_lshl_add_u64 v[126:127], v[244:245], 0, v[112:113]
	global_store_short v[122:123], v105, off
	global_load_ushort v105, v[126:127], off
	v_mul_f32_e32 v126, v243, v103
	global_load_dword v127, v[110:111], off offset:128
	v_mul_f32_e32 v103, v125, v103
	s_waitcnt vmcnt(1)
	v_lshlrev_b32_e32 v105, 16, v105
	v_mul_f32_e32 v105, 0xbfb8aa3b, v105
	v_exp_f32_e32 v105, v105
	s_waitcnt vmcnt(0)
	v_mul_f32_e32 v126, v127, v126
	v_add_f32_e32 v105, 1.0, v105
	v_rcp_f32_e32 v105, v105
	s_nop 0
	v_mul_f32_e32 v105, v105, v126
	v_cvt_pk_bf16_f32 v105, v105, s0
	v_lshl_add_u64 v[126:127], v[244:245], 0, v[118:119]
	global_store_short v[122:123], v105, off offset:64
	global_load_ushort v105, v[126:127], off
	s_waitcnt vmcnt(0)
	v_lshlrev_b32_e32 v105, 16, v105
	global_load_dword v126, v[110:111], off offset:256
	v_mul_f32_e32 v105, 0xbfb8aa3b, v105
	v_exp_f32_e32 v105, v105
	s_waitcnt vmcnt(0)
	v_mul_f32_e32 v124, v126, v124
	v_add_f32_e32 v105, 1.0, v105
	v_rcp_f32_e32 v105, v105
	v_lshl_add_u64 v[126:127], v[244:245], 0, v[120:121]
	v_mul_f32_e32 v105, v124, v105
	v_cvt_pk_bf16_f32 v105, v105, s0
	global_store_short v[122:123], v105, off offset:128
	global_load_ushort v105, v[126:127], off
	s_waitcnt vmcnt(0)
	v_lshlrev_b32_e32 v105, 16, v105
	global_load_dword v124, v[110:111], off offset:384
	v_mul_f32_e32 v105, 0xbfb8aa3b, v105
	v_exp_f32_e32 v105, v105
	s_waitcnt vmcnt(0)
	v_mul_f32_e32 v103, v124, v103
	v_add_f32_e32 v105, 1.0, v105
	v_rcp_f32_e32 v105, v105
	s_nop 0
	v_mul_f32_e32 v103, v103, v105
	v_cvt_pk_bf16_f32 v103, v103, s0
	global_store_short v[122:123], v103, off offset:192
	ds_read_b32 v103, v238 offset:72
	ds_read_b32 v105, v239 offset:72
	v_add_u32_e32 v126, 18, v100
	v_ashrrev_i32_e32 v127, 31, v126
	v_mov_b32_e32 v244, v10
	s_waitcnt lgkmcnt(1)
	v_max_f32_e64 v103, |v103|, |v103|
	s_waitcnt lgkmcnt(0)
	v_max_f32_e32 v105, v105, v105
	v_max_f32_e32 v103, v103, v105
	v_div_scale_f32 v105, s[0:1], v103, v103, 1.0
	v_rcp_f32_e32 v122, v105
	v_mov_b32_e32 v245, v26
	v_fma_f32 v123, -v105, v122, 1.0
	v_fmac_f32_e32 v122, v123, v122
	v_div_scale_f32 v123, vcc, 1.0, v103, 1.0
	v_mul_f32_e32 v124, v123, v122
	v_fma_f32 v125, -v105, v124, v123
	v_fmac_f32_e32 v124, v125, v122
	v_fma_f32 v105, -v105, v124, v123
	v_div_fmas_f32 v105, v105, v122, v124
	v_lshlrev_b64 v[124:125], 11, v[126:127]
	v_lshl_add_u64 v[124:125], v[98:99], 0, v[124:125]
	global_load_dword v242, v[124:125], off
	global_load_dword v243, v[124:125], off offset:128
	global_load_dword v246, v[124:125], off offset:256
	global_load_dword v247, v[124:125], off offset:384
	v_div_fixup_f32 v122, v105, v103, 1.0
	v_mov_b32_e32 v124, v42
	v_mov_b32_e32 v125, v58
	s_waitcnt vmcnt(2)
	v_pk_fma_f32 v[242:243], v[244:245], v[122:123], v[242:243] op_sel_hi:[1,0,1]
	s_nop 0
	v_pk_mul_f32 v[244:245], v[242:243], v[242:243]
	s_waitcnt vmcnt(0)
	v_pk_fma_f32 v[124:125], v[124:125], v[122:123], v[246:247] op_sel_hi:[1,0,1]
	v_add_f32_e32 v103, v244, v245
	v_pk_mul_f32 v[122:123], v[124:125], v[124:125]
	s_nop 0
	v_add_f32_e32 v103, v103, v122
	v_add_f32_e32 v103, v103, v123
	v_mov_b32_e32 v105, v103
	v_mov_b32_e32 v255, v103
	s_nop 1
	v_permlane16_swap_b32_e32 v105, v255
	s_nop 1
	v_mov_b32_dpp v105, v255 quad_perm:[0,1,2,3] row_mask:0x5 bank_mask:0xf
	v_mad_i64_i32 v[122:123], s[0:1], v126, s74, v[106:107]
	v_lshl_add_u64 v[244:245], v[122:123], 0, s[96:97]
	v_lshlrev_b64 v[122:123], 10, v[126:127]
	s_nop 0
	v_add_f32_e32 v103, v103, v105
	s_nop 1
	v_mov_b32_dpp v105, v103 row_ror:8 row_mask:0xf bank_mask:0xf
	v_lshl_add_u64 v[126:127], v[244:245], 0, v[96:97]
	v_lshl_add_u64 v[122:123], s[66:67], 0, v[122:123]
	v_lshl_add_u64 v[122:123], v[122:123], 0, v[96:97]
	s_nop 0
	v_add_f32_e32 v103, v103, v105
	s_nop 1
	v_mov_b32_dpp v105, v103 row_shl:4 row_mask:0xf bank_mask:0x5
	v_mov_b32_dpp v105, v103 row_shr:4 row_mask:0xf bank_mask:0xa
	s_nop 0
	v_add_f32_e32 v103, v103, v105
	s_nop 1
	v_mov_b32_dpp v105, v103 quad_perm:[2,3,0,1] row_mask:0xf bank_mask:0xf
	s_nop 0
	v_add_f32_e32 v103, v103, v105
	s_nop 1
	v_mov_b32_dpp v105, v103 quad_perm:[1,0,3,2] row_mask:0xf bank_mask:0xf
	s_nop 0
	v_add_f32_e32 v103, v103, v105
	v_fmamk_f32 v103, v103, 0x3c000000, v163
	v_cmp_gt_f32_e32 vcc, s86, v103
	v_mul_f32_e32 v105, 0x4b800000, v103
	s_nop 0
	v_cndmask_b32_e32 v103, v103, v105, vcc
	v_rsq_f32_e32 v103, v103
	s_nop 0
	v_mul_f32_e32 v105, 0x45800000, v103
	v_cndmask_b32_e32 v103, v103, v105, vcc
	global_load_ushort v105, v[126:127], off
	v_mul_f32_e32 v126, v242, v103
	global_load_dword v127, v[108:109], off
	v_mul_f32_e32 v124, v124, v103
	s_waitcnt vmcnt(1)
	v_lshlrev_b32_e32 v105, 16, v105
	v_mul_f32_e32 v105, 0xbfb8aa3b, v105
	v_exp_f32_e32 v105, v105
	s_waitcnt vmcnt(0)
	v_mul_f32_e32 v126, v127, v126
	v_add_f32_e32 v105, 1.0, v105
	v_rcp_f32_e32 v105, v105
	s_nop 0
	v_mul_f32_e32 v105, v105, v126
	v_cvt_pk_bf16_f32 v105, v105, s0
	v_lshl_add_u64 v[126:127], v[244:245], 0, v[112:113]
	global_store_short v[122:123], v105, off
	global_load_ushort v105, v[126:127], off
	v_mul_f32_e32 v126, v243, v103
	global_load_dword v127, v[110:111], off offset:128
	v_mul_f32_e32 v103, v125, v103
	s_waitcnt vmcnt(1)
	v_lshlrev_b32_e32 v105, 16, v105
	v_mul_f32_e32 v105, 0xbfb8aa3b, v105
	v_exp_f32_e32 v105, v105
	s_waitcnt vmcnt(0)
	v_mul_f32_e32 v126, v127, v126
	v_add_f32_e32 v105, 1.0, v105
	v_rcp_f32_e32 v105, v105
	s_nop 0
	v_mul_f32_e32 v105, v105, v126
	v_cvt_pk_bf16_f32 v105, v105, s0
	v_lshl_add_u64 v[126:127], v[244:245], 0, v[118:119]
	global_store_short v[122:123], v105, off offset:64
	global_load_ushort v105, v[126:127], off
	s_waitcnt vmcnt(0)
	v_lshlrev_b32_e32 v105, 16, v105
	global_load_dword v126, v[110:111], off offset:256
	v_mul_f32_e32 v105, 0xbfb8aa3b, v105
	v_exp_f32_e32 v105, v105
	s_waitcnt vmcnt(0)
	v_mul_f32_e32 v124, v126, v124
	v_add_f32_e32 v105, 1.0, v105
	v_rcp_f32_e32 v105, v105
	v_lshl_add_u64 v[126:127], v[244:245], 0, v[120:121]
	v_mul_f32_e32 v105, v124, v105
	v_cvt_pk_bf16_f32 v105, v105, s0
	global_store_short v[122:123], v105, off offset:128
	global_load_ushort v105, v[126:127], off
	s_waitcnt vmcnt(0)
	v_lshlrev_b32_e32 v105, 16, v105
	global_load_dword v124, v[110:111], off offset:384
	v_mul_f32_e32 v105, 0xbfb8aa3b, v105
	v_exp_f32_e32 v105, v105
	s_waitcnt vmcnt(0)
	v_mul_f32_e32 v103, v124, v103
	v_add_f32_e32 v105, 1.0, v105
	v_rcp_f32_e32 v105, v105
	s_nop 0
	v_mul_f32_e32 v103, v103, v105
	v_cvt_pk_bf16_f32 v103, v103, s0
	global_store_short v[122:123], v103, off offset:192
	ds_read_b32 v103, v238 offset:76
	ds_read_b32 v105, v239 offset:76
	v_add_u32_e32 v126, 19, v100
	v_ashrrev_i32_e32 v127, 31, v126
	v_mov_b32_e32 v244, v11
	s_waitcnt lgkmcnt(1)
	v_max_f32_e64 v103, |v103|, |v103|
	s_waitcnt lgkmcnt(0)
	v_max_f32_e32 v105, v105, v105
	v_max_f32_e32 v103, v103, v105
	v_div_scale_f32 v105, s[0:1], v103, v103, 1.0
	v_rcp_f32_e32 v122, v105
	v_mov_b32_e32 v245, v27
	v_fma_f32 v123, -v105, v122, 1.0
	v_fmac_f32_e32 v122, v123, v122
	v_div_scale_f32 v123, vcc, 1.0, v103, 1.0
	v_mul_f32_e32 v124, v123, v122
	v_fma_f32 v125, -v105, v124, v123
	v_fmac_f32_e32 v124, v125, v122
	v_fma_f32 v105, -v105, v124, v123
	v_div_fmas_f32 v105, v105, v122, v124
	v_lshlrev_b64 v[124:125], 11, v[126:127]
	v_lshl_add_u64 v[124:125], v[98:99], 0, v[124:125]
	global_load_dword v242, v[124:125], off
	global_load_dword v243, v[124:125], off offset:128
	global_load_dword v246, v[124:125], off offset:256
	global_load_dword v247, v[124:125], off offset:384
	v_div_fixup_f32 v122, v105, v103, 1.0
	v_mov_b32_e32 v124, v43
	v_mov_b32_e32 v125, v59
	s_waitcnt vmcnt(2)
	v_pk_fma_f32 v[242:243], v[244:245], v[122:123], v[242:243] op_sel_hi:[1,0,1]
	s_nop 0
	v_pk_mul_f32 v[244:245], v[242:243], v[242:243]
	s_waitcnt vmcnt(0)
	v_pk_fma_f32 v[124:125], v[124:125], v[122:123], v[246:247] op_sel_hi:[1,0,1]
	v_add_f32_e32 v103, v244, v245
	v_pk_mul_f32 v[122:123], v[124:125], v[124:125]
	s_nop 0
	v_add_f32_e32 v103, v103, v122
	v_add_f32_e32 v103, v103, v123
	v_mov_b32_e32 v105, v103
	v_mov_b32_e32 v255, v103
	s_nop 1
	v_permlane16_swap_b32_e32 v105, v255
	s_nop 1
	v_mov_b32_dpp v105, v255 quad_perm:[0,1,2,3] row_mask:0x5 bank_mask:0xf
	v_mad_i64_i32 v[122:123], s[0:1], v126, s74, v[106:107]
	v_lshl_add_u64 v[244:245], v[122:123], 0, s[96:97]
	v_lshlrev_b64 v[122:123], 10, v[126:127]
	s_nop 0
	v_add_f32_e32 v103, v103, v105
	s_nop 1
	v_mov_b32_dpp v105, v103 row_ror:8 row_mask:0xf bank_mask:0xf
	v_lshl_add_u64 v[126:127], v[244:245], 0, v[96:97]
	v_lshl_add_u64 v[122:123], s[66:67], 0, v[122:123]
	v_lshl_add_u64 v[122:123], v[122:123], 0, v[96:97]
	s_nop 0
	v_add_f32_e32 v103, v103, v105
	s_nop 1
	v_mov_b32_dpp v105, v103 row_shl:4 row_mask:0xf bank_mask:0x5
	v_mov_b32_dpp v105, v103 row_shr:4 row_mask:0xf bank_mask:0xa
	s_nop 0
	v_add_f32_e32 v103, v103, v105
	s_nop 1
	v_mov_b32_dpp v105, v103 quad_perm:[2,3,0,1] row_mask:0xf bank_mask:0xf
	s_nop 0
	v_add_f32_e32 v103, v103, v105
	s_nop 1
	v_mov_b32_dpp v105, v103 quad_perm:[1,0,3,2] row_mask:0xf bank_mask:0xf
	s_nop 0
	v_add_f32_e32 v103, v103, v105
	v_fmamk_f32 v103, v103, 0x3c000000, v163
	v_cmp_gt_f32_e32 vcc, s86, v103
	v_mul_f32_e32 v105, 0x4b800000, v103
	s_nop 0
	v_cndmask_b32_e32 v103, v103, v105, vcc
	v_rsq_f32_e32 v103, v103
	s_nop 0
	v_mul_f32_e32 v105, 0x45800000, v103
	v_cndmask_b32_e32 v103, v103, v105, vcc
	global_load_ushort v105, v[126:127], off
	v_mul_f32_e32 v126, v242, v103
	global_load_dword v127, v[108:109], off
	v_mul_f32_e32 v124, v124, v103
	s_waitcnt vmcnt(1)
	v_lshlrev_b32_e32 v105, 16, v105
	v_mul_f32_e32 v105, 0xbfb8aa3b, v105
	v_exp_f32_e32 v105, v105
	s_waitcnt vmcnt(0)
	v_mul_f32_e32 v126, v127, v126
	v_add_f32_e32 v105, 1.0, v105
	v_rcp_f32_e32 v105, v105
	s_nop 0
	v_mul_f32_e32 v105, v105, v126
	v_cvt_pk_bf16_f32 v105, v105, s0
	v_lshl_add_u64 v[126:127], v[244:245], 0, v[112:113]
	global_store_short v[122:123], v105, off
	global_load_ushort v105, v[126:127], off
	v_mul_f32_e32 v126, v243, v103
	global_load_dword v127, v[110:111], off offset:128
	v_mul_f32_e32 v103, v125, v103
	s_waitcnt vmcnt(1)
	v_lshlrev_b32_e32 v105, 16, v105
	v_mul_f32_e32 v105, 0xbfb8aa3b, v105
	v_exp_f32_e32 v105, v105
	s_waitcnt vmcnt(0)
	v_mul_f32_e32 v126, v127, v126
	v_add_f32_e32 v105, 1.0, v105
	v_rcp_f32_e32 v105, v105
	s_nop 0
	v_mul_f32_e32 v105, v105, v126
	v_cvt_pk_bf16_f32 v105, v105, s0
	v_lshl_add_u64 v[126:127], v[244:245], 0, v[118:119]
	global_store_short v[122:123], v105, off offset:64
	global_load_ushort v105, v[126:127], off
	s_waitcnt vmcnt(0)
	v_lshlrev_b32_e32 v105, 16, v105
	global_load_dword v126, v[110:111], off offset:256
	v_mul_f32_e32 v105, 0xbfb8aa3b, v105
	v_exp_f32_e32 v105, v105
	s_waitcnt vmcnt(0)
	v_mul_f32_e32 v124, v126, v124
	v_add_f32_e32 v105, 1.0, v105
	v_rcp_f32_e32 v105, v105
	v_lshl_add_u64 v[126:127], v[244:245], 0, v[120:121]
	v_mul_f32_e32 v105, v124, v105
	v_cvt_pk_bf16_f32 v105, v105, s0
	global_store_short v[122:123], v105, off offset:128
	global_load_ushort v105, v[126:127], off
	s_waitcnt vmcnt(0)
	v_lshlrev_b32_e32 v105, 16, v105
	global_load_dword v124, v[110:111], off offset:384
	v_mul_f32_e32 v105, 0xbfb8aa3b, v105
	v_exp_f32_e32 v105, v105
	s_waitcnt vmcnt(0)
	v_mul_f32_e32 v103, v124, v103
	v_add_f32_e32 v105, 1.0, v105
	v_rcp_f32_e32 v105, v105
	s_nop 0
	v_mul_f32_e32 v103, v103, v105
	v_cvt_pk_bf16_f32 v103, v103, s0
	global_store_short v[122:123], v103, off offset:192
	ds_read_b32 v103, v238 offset:96
	ds_read_b32 v105, v239 offset:96
	v_add_u32_e32 v126, 24, v100
	v_ashrrev_i32_e32 v127, 31, v126
	v_mov_b32_e32 v244, v12
	s_waitcnt lgkmcnt(1)
	v_max_f32_e64 v103, |v103|, |v103|
	s_waitcnt lgkmcnt(0)
	v_max_f32_e32 v105, v105, v105
	v_max_f32_e32 v103, v103, v105
	v_div_scale_f32 v105, s[0:1], v103, v103, 1.0
	v_rcp_f32_e32 v122, v105
	v_mov_b32_e32 v245, v28
	v_fma_f32 v123, -v105, v122, 1.0
	v_fmac_f32_e32 v122, v123, v122
	v_div_scale_f32 v123, vcc, 1.0, v103, 1.0
	v_mul_f32_e32 v124, v123, v122
	v_fma_f32 v125, -v105, v124, v123
	v_fmac_f32_e32 v124, v125, v122
	v_fma_f32 v105, -v105, v124, v123
	v_div_fmas_f32 v105, v105, v122, v124
	v_lshlrev_b64 v[124:125], 11, v[126:127]
	v_lshl_add_u64 v[124:125], v[98:99], 0, v[124:125]
	global_load_dword v242, v[124:125], off
	global_load_dword v243, v[124:125], off offset:128
	global_load_dword v246, v[124:125], off offset:256
	global_load_dword v247, v[124:125], off offset:384
	v_div_fixup_f32 v122, v105, v103, 1.0
	v_mov_b32_e32 v124, v44
	v_mov_b32_e32 v125, v60
	s_waitcnt vmcnt(2)
	v_pk_fma_f32 v[242:243], v[244:245], v[122:123], v[242:243] op_sel_hi:[1,0,1]
	s_nop 0
	v_pk_mul_f32 v[244:245], v[242:243], v[242:243]
	s_waitcnt vmcnt(0)
	v_pk_fma_f32 v[124:125], v[124:125], v[122:123], v[246:247] op_sel_hi:[1,0,1]
	v_add_f32_e32 v103, v244, v245
	v_pk_mul_f32 v[122:123], v[124:125], v[124:125]
	s_nop 0
	v_add_f32_e32 v103, v103, v122
	v_add_f32_e32 v103, v103, v123
	v_mov_b32_e32 v105, v103
	v_mov_b32_e32 v255, v103
	s_nop 1
	v_permlane16_swap_b32_e32 v105, v255
	s_nop 1
	v_mov_b32_dpp v105, v255 quad_perm:[0,1,2,3] row_mask:0x5 bank_mask:0xf
	v_mad_i64_i32 v[122:123], s[0:1], v126, s74, v[106:107]
	v_lshl_add_u64 v[244:245], v[122:123], 0, s[96:97]
	v_lshlrev_b64 v[122:123], 10, v[126:127]
	s_nop 0
	v_add_f32_e32 v103, v103, v105
	s_nop 1
	v_mov_b32_dpp v105, v103 row_ror:8 row_mask:0xf bank_mask:0xf
	v_lshl_add_u64 v[126:127], v[244:245], 0, v[96:97]
	v_lshl_add_u64 v[122:123], s[66:67], 0, v[122:123]
	v_lshl_add_u64 v[122:123], v[122:123], 0, v[96:97]
	s_nop 0
	v_add_f32_e32 v103, v103, v105
	s_nop 1
	v_mov_b32_dpp v105, v103 row_shl:4 row_mask:0xf bank_mask:0x5
	v_mov_b32_dpp v105, v103 row_shr:4 row_mask:0xf bank_mask:0xa
	s_nop 0
	v_add_f32_e32 v103, v103, v105
	s_nop 1
	v_mov_b32_dpp v105, v103 quad_perm:[2,3,0,1] row_mask:0xf bank_mask:0xf
	s_nop 0
	v_add_f32_e32 v103, v103, v105
	s_nop 1
	v_mov_b32_dpp v105, v103 quad_perm:[1,0,3,2] row_mask:0xf bank_mask:0xf
	s_nop 0
	v_add_f32_e32 v103, v103, v105
	v_fmamk_f32 v103, v103, 0x3c000000, v163
	v_cmp_gt_f32_e32 vcc, s86, v103
	v_mul_f32_e32 v105, 0x4b800000, v103
	s_nop 0
	v_cndmask_b32_e32 v103, v103, v105, vcc
	v_rsq_f32_e32 v103, v103
	s_nop 0
	v_mul_f32_e32 v105, 0x45800000, v103
	v_cndmask_b32_e32 v103, v103, v105, vcc
	global_load_ushort v105, v[126:127], off
	v_mul_f32_e32 v126, v242, v103
	global_load_dword v127, v[108:109], off
	v_mul_f32_e32 v124, v124, v103
	s_waitcnt vmcnt(1)
	v_lshlrev_b32_e32 v105, 16, v105
	v_mul_f32_e32 v105, 0xbfb8aa3b, v105
	v_exp_f32_e32 v105, v105
	s_waitcnt vmcnt(0)
	v_mul_f32_e32 v126, v127, v126
	v_add_f32_e32 v105, 1.0, v105
	v_rcp_f32_e32 v105, v105
	s_nop 0
	v_mul_f32_e32 v105, v105, v126
	v_cvt_pk_bf16_f32 v105, v105, s0
	v_lshl_add_u64 v[126:127], v[244:245], 0, v[112:113]
	global_store_short v[122:123], v105, off
	global_load_ushort v105, v[126:127], off
	v_mul_f32_e32 v126, v243, v103
	global_load_dword v127, v[110:111], off offset:128
	v_mul_f32_e32 v103, v125, v103
	s_waitcnt vmcnt(1)
	v_lshlrev_b32_e32 v105, 16, v105
	v_mul_f32_e32 v105, 0xbfb8aa3b, v105
	v_exp_f32_e32 v105, v105
	s_waitcnt vmcnt(0)
	v_mul_f32_e32 v126, v127, v126
	v_add_f32_e32 v105, 1.0, v105
	v_rcp_f32_e32 v105, v105
	s_nop 0
	v_mul_f32_e32 v105, v105, v126
	v_cvt_pk_bf16_f32 v105, v105, s0
	v_lshl_add_u64 v[126:127], v[244:245], 0, v[118:119]
	global_store_short v[122:123], v105, off offset:64
	global_load_ushort v105, v[126:127], off
	s_waitcnt vmcnt(0)
	v_lshlrev_b32_e32 v105, 16, v105
	global_load_dword v126, v[110:111], off offset:256
	v_mul_f32_e32 v105, 0xbfb8aa3b, v105
	v_exp_f32_e32 v105, v105
	s_waitcnt vmcnt(0)
	v_mul_f32_e32 v124, v126, v124
	v_add_f32_e32 v105, 1.0, v105
	v_rcp_f32_e32 v105, v105
	v_lshl_add_u64 v[126:127], v[244:245], 0, v[120:121]
	v_mul_f32_e32 v105, v124, v105
	v_cvt_pk_bf16_f32 v105, v105, s0
	global_store_short v[122:123], v105, off offset:128
	global_load_ushort v105, v[126:127], off
	s_waitcnt vmcnt(0)
	v_lshlrev_b32_e32 v105, 16, v105
	global_load_dword v124, v[110:111], off offset:384
	v_mul_f32_e32 v105, 0xbfb8aa3b, v105
	v_exp_f32_e32 v105, v105
	s_waitcnt vmcnt(0)
	v_mul_f32_e32 v103, v124, v103
	v_add_f32_e32 v105, 1.0, v105
	v_rcp_f32_e32 v105, v105
	s_nop 0
	v_mul_f32_e32 v103, v103, v105
	v_cvt_pk_bf16_f32 v103, v103, s0
	global_store_short v[122:123], v103, off offset:192
	ds_read_b32 v103, v238 offset:100
	ds_read_b32 v105, v239 offset:100
	v_add_u32_e32 v126, 25, v100
	v_ashrrev_i32_e32 v127, 31, v126
	v_mov_b32_e32 v244, v13
	s_waitcnt lgkmcnt(1)
	v_max_f32_e64 v103, |v103|, |v103|
	s_waitcnt lgkmcnt(0)
	v_max_f32_e32 v105, v105, v105
	v_max_f32_e32 v103, v103, v105
	v_div_scale_f32 v105, s[0:1], v103, v103, 1.0
	v_rcp_f32_e32 v122, v105
	v_mov_b32_e32 v245, v29
	v_fma_f32 v123, -v105, v122, 1.0
	v_fmac_f32_e32 v122, v123, v122
	v_div_scale_f32 v123, vcc, 1.0, v103, 1.0
	v_mul_f32_e32 v124, v123, v122
	v_fma_f32 v125, -v105, v124, v123
	v_fmac_f32_e32 v124, v125, v122
	v_fma_f32 v105, -v105, v124, v123
	v_div_fmas_f32 v105, v105, v122, v124
	v_lshlrev_b64 v[124:125], 11, v[126:127]
	v_lshl_add_u64 v[124:125], v[98:99], 0, v[124:125]
	global_load_dword v242, v[124:125], off
	global_load_dword v243, v[124:125], off offset:128
	global_load_dword v246, v[124:125], off offset:256
	global_load_dword v247, v[124:125], off offset:384
	v_div_fixup_f32 v122, v105, v103, 1.0
	v_mov_b32_e32 v124, v45
	v_mov_b32_e32 v125, v61
	s_waitcnt vmcnt(2)
	v_pk_fma_f32 v[242:243], v[244:245], v[122:123], v[242:243] op_sel_hi:[1,0,1]
	s_nop 0
	v_pk_mul_f32 v[244:245], v[242:243], v[242:243]
	s_waitcnt vmcnt(0)
	v_pk_fma_f32 v[124:125], v[124:125], v[122:123], v[246:247] op_sel_hi:[1,0,1]
	v_add_f32_e32 v103, v244, v245
	v_pk_mul_f32 v[122:123], v[124:125], v[124:125]
	s_nop 0
	v_add_f32_e32 v103, v103, v122
	v_add_f32_e32 v103, v103, v123
	v_mov_b32_e32 v105, v103
	v_mov_b32_e32 v255, v103
	s_nop 1
	v_permlane16_swap_b32_e32 v105, v255
	s_nop 1
	v_mov_b32_dpp v105, v255 quad_perm:[0,1,2,3] row_mask:0x5 bank_mask:0xf
	v_mad_i64_i32 v[122:123], s[0:1], v126, s74, v[106:107]
	v_lshl_add_u64 v[244:245], v[122:123], 0, s[96:97]
	v_lshlrev_b64 v[122:123], 10, v[126:127]
	s_nop 0
	v_add_f32_e32 v103, v103, v105
	s_nop 1
	v_mov_b32_dpp v105, v103 row_ror:8 row_mask:0xf bank_mask:0xf
	v_lshl_add_u64 v[126:127], v[244:245], 0, v[96:97]
	v_lshl_add_u64 v[122:123], s[66:67], 0, v[122:123]
	v_lshl_add_u64 v[122:123], v[122:123], 0, v[96:97]
	s_nop 0
	v_add_f32_e32 v103, v103, v105
	s_nop 1
	v_mov_b32_dpp v105, v103 row_shl:4 row_mask:0xf bank_mask:0x5
	v_mov_b32_dpp v105, v103 row_shr:4 row_mask:0xf bank_mask:0xa
	s_nop 0
	v_add_f32_e32 v103, v103, v105
	s_nop 1
	v_mov_b32_dpp v105, v103 quad_perm:[2,3,0,1] row_mask:0xf bank_mask:0xf
	s_nop 0
	v_add_f32_e32 v103, v103, v105
	s_nop 1
	v_mov_b32_dpp v105, v103 quad_perm:[1,0,3,2] row_mask:0xf bank_mask:0xf
	s_nop 0
	v_add_f32_e32 v103, v103, v105
	v_fmamk_f32 v103, v103, 0x3c000000, v163
	v_cmp_gt_f32_e32 vcc, s86, v103
	v_mul_f32_e32 v105, 0x4b800000, v103
	s_nop 0
	v_cndmask_b32_e32 v103, v103, v105, vcc
	v_rsq_f32_e32 v103, v103
	s_nop 0
	v_mul_f32_e32 v105, 0x45800000, v103
	v_cndmask_b32_e32 v103, v103, v105, vcc
	global_load_ushort v105, v[126:127], off
	v_mul_f32_e32 v126, v242, v103
	global_load_dword v127, v[108:109], off
	v_mul_f32_e32 v124, v124, v103
	s_waitcnt vmcnt(1)
	v_lshlrev_b32_e32 v105, 16, v105
	v_mul_f32_e32 v105, 0xbfb8aa3b, v105
	v_exp_f32_e32 v105, v105
	s_waitcnt vmcnt(0)
	v_mul_f32_e32 v126, v127, v126
	v_add_f32_e32 v105, 1.0, v105
	v_rcp_f32_e32 v105, v105
	s_nop 0
	v_mul_f32_e32 v105, v105, v126
	v_cvt_pk_bf16_f32 v105, v105, s0
	v_lshl_add_u64 v[126:127], v[244:245], 0, v[112:113]
	global_store_short v[122:123], v105, off
	global_load_ushort v105, v[126:127], off
	v_mul_f32_e32 v126, v243, v103
	global_load_dword v127, v[110:111], off offset:128
	v_mul_f32_e32 v103, v125, v103
	s_waitcnt vmcnt(1)
	v_lshlrev_b32_e32 v105, 16, v105
	v_mul_f32_e32 v105, 0xbfb8aa3b, v105
	v_exp_f32_e32 v105, v105
	s_waitcnt vmcnt(0)
	v_mul_f32_e32 v126, v127, v126
	v_add_f32_e32 v105, 1.0, v105
	v_rcp_f32_e32 v105, v105
	s_nop 0
	v_mul_f32_e32 v105, v105, v126
	v_cvt_pk_bf16_f32 v105, v105, s0
	v_lshl_add_u64 v[126:127], v[244:245], 0, v[118:119]
	global_store_short v[122:123], v105, off offset:64
	global_load_ushort v105, v[126:127], off
	s_waitcnt vmcnt(0)
	v_lshlrev_b32_e32 v105, 16, v105
	global_load_dword v126, v[110:111], off offset:256
	v_mul_f32_e32 v105, 0xbfb8aa3b, v105
	v_exp_f32_e32 v105, v105
	s_waitcnt vmcnt(0)
	v_mul_f32_e32 v124, v126, v124
	v_add_f32_e32 v105, 1.0, v105
	v_rcp_f32_e32 v105, v105
	v_lshl_add_u64 v[126:127], v[244:245], 0, v[120:121]
	v_mul_f32_e32 v105, v124, v105
	v_cvt_pk_bf16_f32 v105, v105, s0
	global_store_short v[122:123], v105, off offset:128
	global_load_ushort v105, v[126:127], off
	s_waitcnt vmcnt(0)
	v_lshlrev_b32_e32 v105, 16, v105
	global_load_dword v124, v[110:111], off offset:384
	v_mul_f32_e32 v105, 0xbfb8aa3b, v105
	v_exp_f32_e32 v105, v105
	s_waitcnt vmcnt(0)
	v_mul_f32_e32 v103, v124, v103
	v_add_f32_e32 v105, 1.0, v105
	v_rcp_f32_e32 v105, v105
	s_nop 0
	v_mul_f32_e32 v103, v103, v105
	v_cvt_pk_bf16_f32 v103, v103, s0
	global_store_short v[122:123], v103, off offset:192
	ds_read_b32 v103, v238 offset:104
	ds_read_b32 v105, v239 offset:104
	v_add_u32_e32 v126, 26, v100
	v_ashrrev_i32_e32 v127, 31, v126
	v_mov_b32_e32 v244, v14
	s_waitcnt lgkmcnt(1)
	v_max_f32_e64 v103, |v103|, |v103|
	s_waitcnt lgkmcnt(0)
	v_max_f32_e32 v105, v105, v105
	v_max_f32_e32 v103, v103, v105
	v_div_scale_f32 v105, s[0:1], v103, v103, 1.0
	v_rcp_f32_e32 v122, v105
	v_mov_b32_e32 v245, v30
	v_fma_f32 v123, -v105, v122, 1.0
	v_fmac_f32_e32 v122, v123, v122
	v_div_scale_f32 v123, vcc, 1.0, v103, 1.0
	v_mul_f32_e32 v124, v123, v122
	v_fma_f32 v125, -v105, v124, v123
	v_fmac_f32_e32 v124, v125, v122
	v_fma_f32 v105, -v105, v124, v123
	v_div_fmas_f32 v105, v105, v122, v124
	v_lshlrev_b64 v[124:125], 11, v[126:127]
	v_lshl_add_u64 v[124:125], v[98:99], 0, v[124:125]
	global_load_dword v242, v[124:125], off
	global_load_dword v243, v[124:125], off offset:128
	global_load_dword v246, v[124:125], off offset:256
	global_load_dword v247, v[124:125], off offset:384
	v_div_fixup_f32 v122, v105, v103, 1.0
	v_mov_b32_e32 v124, v46
	v_mov_b32_e32 v125, v62
	s_waitcnt vmcnt(2)
	v_pk_fma_f32 v[242:243], v[244:245], v[122:123], v[242:243] op_sel_hi:[1,0,1]
	s_nop 0
	v_pk_mul_f32 v[244:245], v[242:243], v[242:243]
	s_waitcnt vmcnt(0)
	v_pk_fma_f32 v[124:125], v[124:125], v[122:123], v[246:247] op_sel_hi:[1,0,1]
	v_add_f32_e32 v103, v244, v245
	v_pk_mul_f32 v[122:123], v[124:125], v[124:125]
	s_nop 0
	v_add_f32_e32 v103, v103, v122
	v_add_f32_e32 v103, v103, v123
	v_mov_b32_e32 v105, v103
	v_mov_b32_e32 v255, v103
	s_nop 1
	v_permlane16_swap_b32_e32 v105, v255
	s_nop 1
	v_mov_b32_dpp v105, v255 quad_perm:[0,1,2,3] row_mask:0x5 bank_mask:0xf
	v_mad_i64_i32 v[122:123], s[0:1], v126, s74, v[106:107]
	v_lshl_add_u64 v[244:245], v[122:123], 0, s[96:97]
	v_lshlrev_b64 v[122:123], 10, v[126:127]
	s_nop 0
	v_add_f32_e32 v103, v103, v105
	s_nop 1
	v_mov_b32_dpp v105, v103 row_ror:8 row_mask:0xf bank_mask:0xf
	v_lshl_add_u64 v[126:127], v[244:245], 0, v[96:97]
	v_lshl_add_u64 v[122:123], s[66:67], 0, v[122:123]
	v_lshl_add_u64 v[122:123], v[122:123], 0, v[96:97]
	s_nop 0
	v_add_f32_e32 v103, v103, v105
	s_nop 1
	v_mov_b32_dpp v105, v103 row_shl:4 row_mask:0xf bank_mask:0x5
	v_mov_b32_dpp v105, v103 row_shr:4 row_mask:0xf bank_mask:0xa
	s_nop 0
	v_add_f32_e32 v103, v103, v105
	s_nop 1
	v_mov_b32_dpp v105, v103 quad_perm:[2,3,0,1] row_mask:0xf bank_mask:0xf
	s_nop 0
	v_add_f32_e32 v103, v103, v105
	s_nop 1
	v_mov_b32_dpp v105, v103 quad_perm:[1,0,3,2] row_mask:0xf bank_mask:0xf
	s_nop 0
	v_add_f32_e32 v103, v103, v105
	v_fmamk_f32 v103, v103, 0x3c000000, v163
	v_cmp_gt_f32_e32 vcc, s86, v103
	v_mul_f32_e32 v105, 0x4b800000, v103
	s_nop 0
	v_cndmask_b32_e32 v103, v103, v105, vcc
	v_rsq_f32_e32 v103, v103
	s_nop 0
	v_mul_f32_e32 v105, 0x45800000, v103
	v_cndmask_b32_e32 v103, v103, v105, vcc
	global_load_ushort v105, v[126:127], off
	v_mul_f32_e32 v126, v242, v103
	global_load_dword v127, v[108:109], off
	v_mul_f32_e32 v124, v124, v103
	s_waitcnt vmcnt(1)
	v_lshlrev_b32_e32 v105, 16, v105
	v_mul_f32_e32 v105, 0xbfb8aa3b, v105
	v_exp_f32_e32 v105, v105
	s_waitcnt vmcnt(0)
	v_mul_f32_e32 v126, v127, v126
	v_add_f32_e32 v105, 1.0, v105
	v_rcp_f32_e32 v105, v105
	s_nop 0
	v_mul_f32_e32 v105, v105, v126
	v_cvt_pk_bf16_f32 v105, v105, s0
	v_lshl_add_u64 v[126:127], v[244:245], 0, v[112:113]
	global_store_short v[122:123], v105, off
	global_load_ushort v105, v[126:127], off
	v_mul_f32_e32 v126, v243, v103
	global_load_dword v127, v[110:111], off offset:128
	v_mul_f32_e32 v103, v125, v103
	s_waitcnt vmcnt(1)
	v_lshlrev_b32_e32 v105, 16, v105
	v_mul_f32_e32 v105, 0xbfb8aa3b, v105
	v_exp_f32_e32 v105, v105
	s_waitcnt vmcnt(0)
	v_mul_f32_e32 v126, v127, v126
	v_add_f32_e32 v105, 1.0, v105
	v_rcp_f32_e32 v105, v105
	s_nop 0
	v_mul_f32_e32 v105, v105, v126
	v_cvt_pk_bf16_f32 v105, v105, s0
	v_lshl_add_u64 v[126:127], v[244:245], 0, v[118:119]
	global_store_short v[122:123], v105, off offset:64
	global_load_ushort v105, v[126:127], off
	s_waitcnt vmcnt(0)
	v_lshlrev_b32_e32 v105, 16, v105
	global_load_dword v126, v[110:111], off offset:256
	v_mul_f32_e32 v105, 0xbfb8aa3b, v105
	v_exp_f32_e32 v105, v105
	s_waitcnt vmcnt(0)
	v_mul_f32_e32 v124, v126, v124
	v_add_f32_e32 v105, 1.0, v105
	v_rcp_f32_e32 v105, v105
	v_lshl_add_u64 v[126:127], v[244:245], 0, v[120:121]
	v_mul_f32_e32 v105, v124, v105
	v_cvt_pk_bf16_f32 v105, v105, s0
	global_store_short v[122:123], v105, off offset:128
	global_load_ushort v105, v[126:127], off
	s_waitcnt vmcnt(0)
	v_lshlrev_b32_e32 v105, 16, v105
	global_load_dword v124, v[110:111], off offset:384
	v_mul_f32_e32 v105, 0xbfb8aa3b, v105
	v_exp_f32_e32 v105, v105
	s_waitcnt vmcnt(0)
	v_mul_f32_e32 v103, v124, v103
	v_add_f32_e32 v105, 1.0, v105
	v_rcp_f32_e32 v105, v105
	s_nop 0
	v_mul_f32_e32 v103, v103, v105
	v_cvt_pk_bf16_f32 v103, v103, s0
	global_store_short v[122:123], v103, off offset:192
	v_add_u32_e32 v122, 27, v100
	v_ashrrev_i32_e32 v123, 31, v122
	v_lshlrev_b64 v[124:125], 11, v[122:123]
	v_lshl_add_u64 v[124:125], v[98:99], 0, v[124:125]
	global_load_dword v126, v[124:125], off
	global_load_dword v127, v[124:125], off offset:128
	global_load_dword v242, v[124:125], off offset:256
	global_load_dword v243, v[124:125], off offset:384
	v_mad_i64_i32 v[106:107], s[0:1], v122, s74, v[106:107]
	v_lshl_add_u64 v[106:107], v[106:107], 0, s[96:97]
	v_lshl_add_u64 v[124:125], v[106:107], 0, v[96:97]
	global_load_ushort v103, v[124:125], off
	v_lshl_add_u64 v[112:113], v[106:107], 0, v[112:113]
	v_lshl_add_u64 v[118:119], v[106:107], 0, v[118:119]
	v_lshl_add_u64 v[106:107], v[106:107], 0, v[120:121]
	global_load_ushort v105, v[112:113], off
	s_nop 0
	global_load_ushort v118, v[118:119], off
	s_nop 0
	global_load_ushort v119, v[106:107], off
	global_load_dword v120, v[108:109], off
	global_load_dword v121, v[110:111], off offset:128
	global_load_dword v124, v[110:111], off offset:256
	global_load_dword v125, v[110:111], off offset:384
	ds_read_b32 v109, v239 offset:108
	ds_read_b32 v110, v238 offset:108
	v_mov_b32_e32 v106, v15
	v_mov_b32_e32 v107, v31
	v_mov_b32_e32 v108, v47
	s_waitcnt lgkmcnt(1)
	v_max_f32_e32 v109, v109, v109
	s_waitcnt lgkmcnt(0)
	v_max_f32_e64 v110, |v110|, |v110|
	v_max_f32_e32 v110, v110, v109
	v_div_scale_f32 v111, s[0:1], v110, v110, 1.0
	v_rcp_f32_e32 v112, v111
	v_div_scale_f32 v113, vcc, 1.0, v110, 1.0
	v_mov_b32_e32 v109, v63
	v_fma_f32 v238, -v111, v112, 1.0
	v_fmac_f32_e32 v112, v238, v112
	v_mul_f32_e32 v238, v113, v112
	v_fma_f32 v239, -v111, v238, v113
	v_fmac_f32_e32 v238, v239, v112
	v_fma_f32 v111, -v111, v238, v113
	v_div_fmas_f32 v111, v111, v112, v238
	v_div_fixup_f32 v110, v111, v110, 1.0
	s_waitcnt vmcnt(10)
	v_pk_fma_f32 v[106:107], v[106:107], v[110:111], v[126:127] op_sel_hi:[1,0,1]
	s_waitcnt vmcnt(8)
	v_pk_fma_f32 v[108:109], v[108:109], v[110:111], v[242:243] op_sel_hi:[1,0,1]
	v_pk_mul_f32 v[110:111], v[106:107], v[106:107]
	v_pk_mul_f32 v[112:113], v[108:109], v[108:109]
	v_add_f32_e32 v110, v110, v111
	v_add_f32_e32 v110, v110, v112
	v_add_f32_e32 v112, v110, v113
	v_mov_b32_e32 v113, v112
	v_mov_b32_e32 v255, v112
	s_nop 1
	v_permlane16_swap_b32_e32 v113, v255
	s_nop 1
	v_mov_b32_dpp v113, v255 quad_perm:[0,1,2,3] row_mask:0x5 bank_mask:0xf
	v_lshlrev_b64 v[110:111], 10, v[122:123]
	v_lshl_add_u64 v[110:111], s[66:67], 0, v[110:111]
	v_lshl_add_u64 v[110:111], v[110:111], 0, v[96:97]
	s_waitcnt vmcnt(7)
	v_lshlrev_b32_e32 v96, 16, v103
	s_nop 0
	v_add_f32_e32 v103, v112, v113
	s_nop 1
	v_mov_b32_dpp v112, v103 row_ror:8 row_mask:0xf bank_mask:0xf
	s_waitcnt vmcnt(5)
	v_lshlrev_b32_e32 v113, 16, v118
	s_waitcnt vmcnt(4)
	v_lshlrev_b32_e32 v118, 16, v119
	v_lshlrev_b32_e32 v105, 16, v105
	v_mul_f32_e32 v96, 0xbfb8aa3b, v96
	s_nop 0
	v_add_f32_e32 v103, v103, v112
	s_nop 1
	v_mov_b32_dpp v112, v103 row_shl:4 row_mask:0xf bank_mask:0x5
	v_mov_b32_dpp v112, v103 row_shr:4 row_mask:0xf bank_mask:0xa
	v_mul_f32_e32 v113, 0xbfb8aa3b, v113
	v_mul_f32_e32 v118, 0xbfb8aa3b, v118
	v_mul_f32_e32 v105, 0xbfb8aa3b, v105
	v_exp_f32_e32 v96, v96
	s_nop 0
	v_add_f32_e32 v103, v103, v112
	s_nop 1
	v_mov_b32_dpp v112, v103 quad_perm:[2,3,0,1] row_mask:0xf bank_mask:0xf
	v_exp_f32_e32 v113, v113
	v_exp_f32_e32 v118, v118
	v_exp_f32_e32 v105, v105
	v_add_f32_e32 v96, 1.0, v96
	s_nop 0
	v_add_f32_e32 v103, v103, v112
	s_nop 1
	v_mov_b32_dpp v112, v103 quad_perm:[1,0,3,2] row_mask:0xf bank_mask:0xf
	v_add_f32_e32 v113, 1.0, v113
	v_add_f32_e32 v118, 1.0, v118
	v_add_f32_e32 v105, 1.0, v105
	v_rcp_f32_e32 v96, v96
	s_nop 0
	v_add_f32_e32 v103, v103, v112
	v_fmamk_f32 v103, v103, 0x3c000000, v163
	v_mul_f32_e32 v112, 0x4b800000, v103
	v_cmp_gt_f32_e32 vcc, s86, v103
	v_rcp_f32_e32 v105, v105
	s_nop 0
	v_cndmask_b32_e32 v103, v103, v112, vcc
	v_rsq_f32_e32 v103, v103
	v_rcp_f32_e32 v112, v113
	v_rcp_f32_e32 v113, v118
	v_mul_f32_e32 v118, 0x45800000, v103
	v_cndmask_b32_e32 v103, v103, v118, vcc
	v_mul_f32_e32 v106, v106, v103
	v_mul_f32_e32 v107, v107, v103
	v_mul_f32_e32 v108, v108, v103
	v_mul_f32_e32 v103, v109, v103
	s_waitcnt vmcnt(3)
	v_mul_f32_e32 v106, v120, v106
	s_waitcnt vmcnt(2)
	v_mul_f32_e32 v107, v121, v107
	s_waitcnt vmcnt(1)
	v_mul_f32_e32 v108, v124, v108
	s_waitcnt vmcnt(0)
	v_mul_f32_e32 v103, v125, v103
	v_mul_f32_e32 v96, v96, v106
	v_mul_f32_e32 v105, v105, v107
	v_mul_f32_e32 v106, v108, v112
	v_mul_f32_e32 v103, v103, v113
	v_cvt_pk_bf16_f32 v96, v96, s0
	v_cvt_pk_bf16_f32 v105, v105, s0
	v_cvt_pk_bf16_f32 v106, v106, s0
	v_cvt_pk_bf16_f32 v103, v103, s0
	global_store_short v[110:111], v96, off
	global_store_short v[110:111], v105, off offset:64
	global_store_short v[110:111], v106, off offset:128
	global_store_short v[110:111], v103, off offset:192
	s_cbranch_execnz .LBB0_927
	s_branch .LBB0_1111

.LBB0_1348:
	s_nop 2
	v_mul_f32_e32 v133, 0xbfb8aa3b, v32
	v_exp_f32_e32 v133, v133
	v_and_b32_e32 v98, 64, v196
	v_xor_b32_e32 v96, 32, v196
	v_add_u32_e32 v98, 64, v98
	v_add_f32_e32 v133, 1.0, v133
	v_rcp_f32_e32 v138, v133
	v_mul_f32_e32 v133, 0xbfb8aa3b, v33
	v_exp_f32_e32 v133, v133
	v_cmp_lt_i32_e32 vcc, v96, v98
	v_lshl_or_b32 v134, s6, 6, v174
	v_lshl_add_u32 v132, s12, 7, v169
	v_add_f32_e32 v133, 1.0, v133
	v_rcp_f32_e32 v139, v133
	v_cndmask_b32_e32 v96, v196, v96, vcc
	v_lshlrev_b32_e32 v96, 2, v96
	v_mov_b64_e32 v[98:99], s[56:57]
	v_pk_mul_f32 v[32:33], v[32:33], v[138:139]
	v_ashrrev_i32_e32 v135, 31, v134
	v_pk_mul_f32 v[32:33], v[48:49], v[32:33]
	v_mul_f32_e32 v48, 0xbfb8aa3b, v34
	v_mul_f32_e32 v49, 0xbfb8aa3b, v35
	v_exp_f32_e32 v48, v48
	v_exp_f32_e32 v49, v49
	v_mad_i64_i32 v[136:137], s[6:7], v132, s18, v[98:99]
	v_add_f32_e32 v48, 1.0, v48
	v_add_f32_e32 v49, 1.0, v49
	v_rcp_f32_e32 v48, v48
	v_rcp_f32_e32 v49, v49
	s_waitcnt lgkmcnt(0)
	s_barrier
	v_pk_mul_f32 v[34:35], v[34:35], v[48:49]
	v_cvt_pk_bf16_f32 v48, v32, v33
	v_pk_mul_f32 v[34:35], v[50:51], v[34:35]
	v_mul_f32_e32 v32, 0xbfb8aa3b, v36
	v_cvt_pk_bf16_f32 v49, v34, v35
	v_mul_f32_e32 v33, 0xbfb8aa3b, v37
	v_mul_f32_e32 v34, 0xbfb8aa3b, v38
	v_mul_f32_e32 v35, 0xbfb8aa3b, v39
	v_exp_f32_e32 v32, v32
	v_exp_f32_e32 v33, v33
	v_exp_f32_e32 v34, v34
	v_exp_f32_e32 v35, v35
	v_add_f32_e32 v32, 1.0, v32
	v_add_f32_e32 v33, 1.0, v33
	v_add_f32_e32 v34, 1.0, v34
	v_add_f32_e32 v35, 1.0, v35
	v_rcp_f32_e32 v32, v32
	v_rcp_f32_e32 v33, v33
	v_rcp_f32_e32 v34, v34
	v_rcp_f32_e32 v35, v35
	s_mov_b64 s[48:49], 0
	v_pk_mul_f32 v[32:33], v[36:37], v[32:33]
	s_andn2_b64 vcc, exec, s[2:3]
	v_pk_mul_f32 v[34:35], v[38:39], v[34:35]
	v_pk_mul_f32 v[32:33], v[52:53], v[32:33]
	v_pk_mul_f32 v[34:35], v[54:55], v[34:35]
	v_cvt_pk_bf16_f32 v32, v32, v33
	v_cvt_pk_bf16_f32 v33, v34, v35
	v_cndmask_b32_e64 v34, v48, v32, s[38:39]
	v_cndmask_b32_e64 v35, v49, v33, s[38:39]
	v_mov_b32_e32 v255, v34
	s_nop 1
	v_permlane32_swap_b32_e32 v34, v255
	s_nop 1
	v_mov_b32_dpp v34, v255 quad_perm:[0,1,2,3] row_mask:0x3 bank_mask:0xf
	v_mov_b32_e32 v255, v35
	s_nop 1
	v_permlane32_swap_b32_e32 v35, v255
	s_nop 1
	v_mov_b32_dpp v35, v255 quad_perm:[0,1,2,3] row_mask:0x3 bank_mask:0xf
	s_nop 0
	v_cndmask_b32_e64 v38, v32, v34, s[38:39]
	s_nop 0
	v_cndmask_b32_e64 v39, v33, v35, s[38:39]
	v_lshlrev_b64 v[32:33], 1, v[134:135]
	v_cndmask_b32_e64 v37, v35, v49, s[38:39]
	v_cndmask_b32_e64 v36, v34, v48, s[38:39]
	v_lshl_add_u64 v[34:35], v[136:137], 0, v[32:33]
	global_store_dwordx4 v[34:35], v[36:39], off
	s_nop 1
	v_mul_f32_e32 v36, 0xbfb8aa3b, v40
	v_mul_f32_e32 v37, 0xbfb8aa3b, v41
	v_mul_f32_e32 v38, 0xbfb8aa3b, v42
	v_mul_f32_e32 v39, 0xbfb8aa3b, v43
	v_exp_f32_e32 v36, v36
	v_exp_f32_e32 v37, v37
	v_exp_f32_e32 v38, v38
	v_exp_f32_e32 v39, v39
	v_add_f32_e32 v36, 1.0, v36
	v_add_f32_e32 v37, 1.0, v37
	v_add_f32_e32 v38, 1.0, v38
	v_add_f32_e32 v39, 1.0, v39
	v_rcp_f32_e32 v36, v36
	v_rcp_f32_e32 v37, v37
	v_rcp_f32_e32 v38, v38
	v_rcp_f32_e32 v39, v39
	v_pk_mul_f32 v[36:37], v[40:41], v[36:37]
	s_nop 0
	v_pk_mul_f32 v[36:37], v[56:57], v[36:37]
	v_pk_mul_f32 v[38:39], v[42:43], v[38:39]
	v_cvt_pk_bf16_f32 v40, v36, v37
	v_pk_mul_f32 v[38:39], v[58:59], v[38:39]
	v_mul_f32_e32 v36, 0xbfb8aa3b, v44
	v_cvt_pk_bf16_f32 v41, v38, v39
	v_mul_f32_e32 v37, 0xbfb8aa3b, v45
	v_mul_f32_e32 v38, 0xbfb8aa3b, v46
	v_mul_f32_e32 v39, 0xbfb8aa3b, v47
	v_exp_f32_e32 v36, v36
	v_exp_f32_e32 v37, v37
	v_exp_f32_e32 v38, v38
	v_exp_f32_e32 v39, v39
	v_add_f32_e32 v36, 1.0, v36
	v_add_f32_e32 v37, 1.0, v37
	v_add_f32_e32 v38, 1.0, v38
	v_add_f32_e32 v39, 1.0, v39
	v_rcp_f32_e32 v36, v36
	v_rcp_f32_e32 v37, v37
	v_rcp_f32_e32 v38, v38
	v_rcp_f32_e32 v39, v39
	v_pk_mul_f32 v[36:37], v[44:45], v[36:37]
	s_nop 0
	v_pk_mul_f32 v[36:37], v[60:61], v[36:37]
	v_pk_mul_f32 v[38:39], v[46:47], v[38:39]
	v_cvt_pk_bf16_f32 v36, v36, v37
	v_pk_mul_f32 v[38:39], v[62:63], v[38:39]
	s_nop 0
	v_cvt_pk_bf16_f32 v37, v38, v39
	v_cndmask_b32_e64 v38, v40, v36, s[38:39]
	v_cndmask_b32_e64 v39, v41, v37, s[38:39]
	v_mov_b32_e32 v42, v38
	v_mov_b32_e32 v255, v38
	s_nop 1
	v_permlane32_swap_b32_e32 v42, v255
	s_nop 1
	v_mov_b32_dpp v42, v255 quad_perm:[0,1,2,3] row_mask:0x3 bank_mask:0xf
	v_mov_b32_e32 v43, v39
	v_mov_b32_e32 v255, v39
	s_nop 1
	v_permlane32_swap_b32_e32 v43, v255
	s_nop 1
	v_mov_b32_dpp v43, v255 quad_perm:[0,1,2,3] row_mask:0x3 bank_mask:0xf
	s_nop 0
	v_cndmask_b32_e64 v38, v36, v42, s[38:39]
	s_nop 0
	v_cndmask_b32_e64 v39, v37, v43, s[38:39]
	v_cndmask_b32_e64 v37, v43, v41, s[38:39]
	v_cndmask_b32_e64 v36, v42, v40, s[38:39]
	global_store_dwordx4 v[34:35], v[36:39], off offset:32
	v_or_b32_e32 v34, 32, v132
	v_mad_i64_i32 v[34:35], s[6:7], v34, s18, v[98:99]
	v_mul_f32_e32 v36, 0xbfb8aa3b, v0
	v_mul_f32_e32 v37, 0xbfb8aa3b, v1
	v_exp_f32_e32 v36, v36
	v_exp_f32_e32 v37, v37
	s_mov_b32 s7, s51
	v_add_f32_e32 v36, 1.0, v36
	v_add_f32_e32 v37, 1.0, v37
	v_rcp_f32_e32 v36, v36
	v_rcp_f32_e32 v37, v37
	s_nop 0
	v_pk_mul_f32 v[0:1], v[0:1], v[36:37]
	s_nop 0
	v_pk_mul_f32 v[0:1], v[16:17], v[0:1]
	v_mul_f32_e32 v16, 0xbfb8aa3b, v2
	v_mul_f32_e32 v17, 0xbfb8aa3b, v3
	v_exp_f32_e32 v16, v16
	v_exp_f32_e32 v17, v17
	v_add_f32_e32 v16, 1.0, v16
	v_add_f32_e32 v17, 1.0, v17
	v_rcp_f32_e32 v16, v16
	v_rcp_f32_e32 v17, v17
	s_nop 0
	v_pk_mul_f32 v[2:3], v[2:3], v[16:17]
	s_nop 0
	v_pk_mul_f32 v[2:3], v[18:19], v[2:3]
	v_cvt_pk_bf16_f32 v16, v0, v1
	v_cvt_pk_bf16_f32 v17, v2, v3
	v_mul_f32_e32 v0, 0xbfb8aa3b, v4
	v_mul_f32_e32 v1, 0xbfb8aa3b, v5
	v_mul_f32_e32 v2, 0xbfb8aa3b, v6
	v_mul_f32_e32 v3, 0xbfb8aa3b, v7
	v_exp_f32_e32 v0, v0
	v_exp_f32_e32 v1, v1
	v_exp_f32_e32 v2, v2
	v_exp_f32_e32 v3, v3
	v_add_f32_e32 v0, 1.0, v0
	v_add_f32_e32 v1, 1.0, v1
	v_add_f32_e32 v2, 1.0, v2
	v_add_f32_e32 v3, 1.0, v3
	v_rcp_f32_e32 v0, v0
	v_rcp_f32_e32 v1, v1
	v_rcp_f32_e32 v2, v2
	v_rcp_f32_e32 v3, v3
	v_pk_mul_f32 v[0:1], v[4:5], v[0:1]
	s_nop 0
	v_pk_mul_f32 v[0:1], v[20:21], v[0:1]
	v_pk_mul_f32 v[2:3], v[6:7], v[2:3]
	v_cvt_pk_bf16_f32 v0, v0, v1
	v_pk_mul_f32 v[2:3], v[22:23], v[2:3]
	s_nop 0
	v_cvt_pk_bf16_f32 v1, v2, v3
	v_cndmask_b32_e64 v2, v16, v0, s[38:39]
	v_cndmask_b32_e64 v3, v17, v1, s[38:39]
	v_mov_b32_e32 v255, v2
	s_nop 1
	v_permlane32_swap_b32_e32 v2, v255
	s_nop 1
	v_mov_b32_dpp v2, v255 quad_perm:[0,1,2,3] row_mask:0x3 bank_mask:0xf
	v_mov_b32_e32 v255, v3
	s_nop 1
	v_permlane32_swap_b32_e32 v3, v255
	s_nop 1
	v_mov_b32_dpp v3, v255 quad_perm:[0,1,2,3] row_mask:0x3 bank_mask:0xf
	s_nop 0
	v_cndmask_b32_e64 v4, v0, v2, s[38:39]
	s_nop 0
	v_cndmask_b32_e64 v5, v1, v3, s[38:39]
	v_cndmask_b32_e64 v3, v3, v17, s[38:39]
	v_cndmask_b32_e64 v2, v2, v16, s[38:39]
	v_lshl_add_u64 v[0:1], v[34:35], 0, v[32:33]
	global_store_dwordx4 v[0:1], v[2:5], off
	s_nop 1
	v_mul_f32_e32 v2, 0xbfb8aa3b, v8
	v_mul_f32_e32 v3, 0xbfb8aa3b, v9
	v_mul_f32_e32 v4, 0xbfb8aa3b, v10
	v_mul_f32_e32 v5, 0xbfb8aa3b, v11
	v_exp_f32_e32 v2, v2
	v_exp_f32_e32 v3, v3
	v_exp_f32_e32 v4, v4
	v_exp_f32_e32 v5, v5
	v_add_f32_e32 v2, 1.0, v2
	v_add_f32_e32 v3, 1.0, v3
	v_add_f32_e32 v4, 1.0, v4
	v_add_f32_e32 v5, 1.0, v5
	v_rcp_f32_e32 v2, v2
	v_rcp_f32_e32 v3, v3
	v_rcp_f32_e32 v4, v4
	v_rcp_f32_e32 v5, v5
	v_pk_mul_f32 v[2:3], v[8:9], v[2:3]
	s_nop 0
	v_pk_mul_f32 v[2:3], v[24:25], v[2:3]
	v_pk_mul_f32 v[4:5], v[10:11], v[4:5]
	v_cvt_pk_bf16_f32 v6, v2, v3
	v_pk_mul_f32 v[4:5], v[26:27], v[4:5]
	v_mul_f32_e32 v2, 0xbfb8aa3b, v12
	v_cvt_pk_bf16_f32 v7, v4, v5
	v_mul_f32_e32 v3, 0xbfb8aa3b, v13
	v_mul_f32_e32 v4, 0xbfb8aa3b, v14
	v_mul_f32_e32 v5, 0xbfb8aa3b, v15
	v_exp_f32_e32 v2, v2
	v_exp_f32_e32 v3, v3
	v_exp_f32_e32 v4, v4
	v_exp_f32_e32 v5, v5
	v_add_f32_e32 v2, 1.0, v2
	v_add_f32_e32 v3, 1.0, v3
	v_add_f32_e32 v4, 1.0, v4
	v_add_f32_e32 v5, 1.0, v5
	v_rcp_f32_e32 v2, v2
	v_rcp_f32_e32 v3, v3
	v_rcp_f32_e32 v4, v4
	v_rcp_f32_e32 v5, v5
	v_pk_mul_f32 v[2:3], v[12:13], v[2:3]
	s_nop 0
	v_pk_mul_f32 v[2:3], v[28:29], v[2:3]
	v_pk_mul_f32 v[4:5], v[14:15], v[4:5]
	v_cvt_pk_bf16_f32 v2, v2, v3
	v_pk_mul_f32 v[4:5], v[30:31], v[4:5]
	s_nop 0
	v_cvt_pk_bf16_f32 v3, v4, v5
	v_cndmask_b32_e64 v4, v6, v2, s[38:39]
	v_cndmask_b32_e64 v5, v7, v3, s[38:39]
	v_mov_b32_e32 v8, v4
	v_mov_b32_e32 v255, v4
	s_nop 1
	v_permlane32_swap_b32_e32 v8, v255
	s_nop 1
	v_mov_b32_dpp v8, v255 quad_perm:[0,1,2,3] row_mask:0x3 bank_mask:0xf
	v_mov_b32_e32 v9, v5
	v_mov_b32_e32 v255, v5
	s_nop 1
	v_permlane32_swap_b32_e32 v9, v255
	s_nop 1
	v_mov_b32_dpp v9, v255 quad_perm:[0,1,2,3] row_mask:0x3 bank_mask:0xf
	s_nop 0
	v_cndmask_b32_e64 v4, v2, v8, s[38:39]
	s_nop 0
	v_cndmask_b32_e64 v5, v3, v9, s[38:39]
	v_cndmask_b32_e64 v3, v9, v7, s[38:39]
	v_cndmask_b32_e64 v2, v8, v6, s[38:39]
	global_store_dwordx4 v[0:1], v[2:5], off offset:32
	s_cbranch_vccz .LBB0_1359

	.amdhsa_kernel _Z14fwd_megakernel6Params
		.amdhsa_group_segment_fixed_size 0
		.amdhsa_private_segment_fixed_size 0
		.amdhsa_kernarg_size 472
		.amdhsa_user_sgpr_count 2
		.amdhsa_user_sgpr_dispatch_ptr 0
		.amdhsa_user_sgpr_queue_ptr 0
		.amdhsa_user_sgpr_kernarg_segment_ptr 1
		.amdhsa_user_sgpr_dispatch_id 0
		.amdhsa_user_sgpr_kernarg_preload_length 0
		.amdhsa_user_sgpr_kernarg_preload_offset 0
		.amdhsa_user_sgpr_private_segment_size 0
		.amdhsa_uses_dynamic_stack 0
		.amdhsa_enable_private_segment 0
		.amdhsa_system_sgpr_workgroup_id_x 1
		.amdhsa_system_sgpr_workgroup_id_y 0
		.amdhsa_system_sgpr_workgroup_id_z 0
		.amdhsa_system_sgpr_workgroup_info 0
		.amdhsa_system_vgpr_workitem_id 2
		.amdhsa_next_free_vgpr 256
		.amdhsa_next_free_sgpr 102
		.amdhsa_accum_offset 256
		.amdhsa_reserve_vcc 1
		.amdhsa_float_round_mode_32 0
		.amdhsa_float_round_mode_16_64 0
		.amdhsa_float_denorm_mode_32 3
		.amdhsa_float_denorm_mode_16_64 3
		.amdhsa_dx10_clamp 1
		.amdhsa_ieee_mode 1
		.amdhsa_fp16_overflow 0
		.amdhsa_tg_split 0
		.amdhsa_exception_fp_ieee_invalid_op 0
		.amdhsa_exception_fp_denorm_src 0
		.amdhsa_exception_fp_ieee_div_zero 0
		.amdhsa_exception_fp_ieee_overflow 0
		.amdhsa_exception_fp_ieee_underflow 0
		.amdhsa_exception_fp_ieee_inexact 0
		.amdhsa_exception_int_div_zero 0
	.end_amdhsa_kernel

amdhsa.kernels:
  - .agpr_count:     0
    .args:
      - .offset:         0
        .size:           216
        .value_kind:     by_value
      - .offset:         216
        .size:           4
        .value_kind:     hidden_block_count_x
      - .offset:         220
        .size:           4
        .value_kind:     hidden_block_count_y
      - .offset:         224
        .size:           4
        .value_kind:     hidden_block_count_z
      - .offset:         228
        .size:           2
        .value_kind:     hidden_group_size_x
      - .offset:         230
        .size:           2
        .value_kind:     hidden_group_size_y
      - .offset:         232
        .size:           2
        .value_kind:     hidden_group_size_z
      - .offset:         234
        .size:           2
        .value_kind:     hidden_remainder_x
      - .offset:         236
        .size:           2
        .value_kind:     hidden_remainder_y
      - .offset:         238
        .size:           2
        .value_kind:     hidden_remainder_z
      - .offset:         256
        .size:           8
        .value_kind:     hidden_global_offset_x
      - .offset:         264
        .size:           8
        .value_kind:     hidden_global_offset_y
      - .offset:         272
        .size:           8
        .value_kind:     hidden_global_offset_z
      - .offset:         280
        .size:           2
        .value_kind:     hidden_grid_dims
      - .offset:         304
        .size:           8
        .value_kind:     hidden_multigrid_sync_arg
      - .offset:         336
        .size:           4
        .value_kind:     hidden_dynamic_lds_size
    .group_segment_fixed_size: 0
    .kernarg_segment_align: 8
    .kernarg_segment_size: 472
    .language:       OpenCL C
    .language_version:
      - 2
      - 0
    .max_flat_workgroup_size: 256
    .name:           _Z14fwd_megakernel6Params
    .private_segment_fixed_size: 0
    .sgpr_count:     108
    .sgpr_spill_count: 227
    .symbol:         _Z14fwd_megakernel6Params.kd
    .uniform_work_group_size: 1
    .uses_dynamic_stack: false
    .vgpr_count:     256
    .vgpr_spill_count: 0
    .wavefront_size: 64
